# in-proj epilogue: gelu_tanh division ladder replaced by x*rcp(1+exp2(x*(c1*x*x+c0))) (f32, 256 sites); attention cmp K/V staging loads de-serialised (4 loads in flight, counted vmcnt)
# speedup vs baseline: 1.2520x; 1.0107x over previous
; __device__ __forceinline__ float gelu_tanh(float x) {
;     const float u = 0.7978845608028654f * (x + 0.044715f * x * x * x);
;     return x / (1.f + __expf(-2.f * u));
; }
;     __device__ __forceinline__ void operator()(const f32x4 (&acc)[2][2][4][2], const pg8::Unit& u, int wr, int wc, int fr, int fq) const {
;     ...
;                 } else if (cs < 36) {
;                     const int g = cs - 28;
;                     float y[16];
; #pragma unroll
;                     for (int i = 0; i < 16; ++i) y[i] = gelu_tanh(v[i]);
;                     const float rn = rsqrtf(head_ssq(y) * (1.f / 64.f) + EPS);
.LBB0_170:
	s_mov_b64 s[6:7], -1
	s_and_b64 vcc, exec, s[72:73]
	s_cbranch_vccz .LBB0_186
	s_and_b64 vcc, exec, s[70:71]
	s_cbranch_vccz .LBB0_183
	s_and_b64 vcc, exec, s[42:43]
	s_cbranch_vccz .LBB0_180
	s_andn2_b64 vcc, exec, s[40:41]
	s_cbranch_vccnz .LBB0_175
	s_ashr_i32 s53, s52, 31
	s_lshl_b64 s[56:57], s[52:53], 21
	v_readlane_b32 s36, v254, 33
	s_mov_b64 s[58:59], s[42:43]
	v_mul_f32_e32 v112, v171, v171
	v_mul_f32_e32 v112, 0xbdd2d3e8, v112
	v_add_f32_e32 v112, 0xc0135761, v112
	v_mul_f32_e32 v112, v171, v112
	v_exp_f32_e32 v112, v112
	s_nop 0
	v_add_f32_e32 v112, 1.0, v112
	v_rcp_f32_e32 v113, v112
	s_nop 0
	v_mul_f32_e32 v112, v171, v113
	s_nop 0
	s_nop 0
	v_mul_f32_e32 v113, v173, v173
	v_mul_f32_e32 v113, 0xbdd2d3e8, v113
	v_add_f32_e32 v113, 0xc0135761, v113
	v_mul_f32_e32 v113, v173, v113
	v_exp_f32_e32 v113, v113
	s_nop 0
	v_add_f32_e32 v113, 1.0, v113
	v_rcp_f32_e32 v114, v113
	s_nop 0
	v_mul_f32_e32 v121, v173, v114
	s_nop 0
	s_nop 0
	v_mul_f32_e32 v113, v175, v175
	v_mul_f32_e32 v113, 0xbdd2d3e8, v113
	v_add_f32_e32 v113, 0xc0135761, v113
	v_mul_f32_e32 v113, v175, v113
	v_exp_f32_e32 v113, v113
	s_nop 0
	v_add_f32_e32 v113, 1.0, v113
	v_rcp_f32_e32 v114, v113
	s_nop 0
	v_mul_f32_e32 v167, v175, v114
	s_nop 0
	s_nop 0
	v_mul_f32_e32 v113, v185, v185
	v_mul_f32_e32 v113, 0xbdd2d3e8, v113
	v_add_f32_e32 v113, 0xc0135761, v113
	v_mul_f32_e32 v113, v185, v113
	v_exp_f32_e32 v113, v113
	s_nop 0
	v_add_f32_e32 v113, 1.0, v113
	v_rcp_f32_e32 v114, v113
	s_nop 0
	v_mul_f32_e32 v195, v185, v114
	s_nop 0
	s_nop 0
	v_mul_f32_e32 v113, v187, v187
	v_mul_f32_e32 v113, 0xbdd2d3e8, v113
	v_add_f32_e32 v113, 0xc0135761, v113
	v_mul_f32_e32 v113, v187, v113
	v_exp_f32_e32 v113, v113
	s_nop 0
	v_add_f32_e32 v113, 1.0, v113
	v_rcp_f32_e32 v114, v113
	s_nop 0
	v_mul_f32_e32 v197, v187, v114
	s_nop 0
	s_nop 0
	v_mul_f32_e32 v113, v189, v189
	v_mul_f32_e32 v113, 0xbdd2d3e8, v113
	v_add_f32_e32 v113, 0xc0135761, v113
	v_mul_f32_e32 v113, v189, v113
	v_exp_f32_e32 v113, v113
	s_nop 0
	v_add_f32_e32 v113, 1.0, v113
	v_rcp_f32_e32 v114, v113
	s_nop 0
	v_mul_f32_e32 v199, v189, v114
	s_nop 0
	s_nop 0
	v_mul_f32_e32 v113, v191, v191
	v_mul_f32_e32 v113, 0xbdd2d3e8, v113
	v_add_f32_e32 v113, 0xc0135761, v113
	v_mul_f32_e32 v113, v191, v113
	v_exp_f32_e32 v113, v113
	s_nop 0
	v_add_f32_e32 v113, 1.0, v113
	v_rcp_f32_e32 v114, v113
	s_nop 0
	v_mul_f32_e32 v212, v191, v114
	s_nop 0
	s_nop 0
	v_mul_f32_e32 v113, v193, v193
	v_mul_f32_e32 v113, 0xbdd2d3e8, v113
	v_add_f32_e32 v113, 0xc0135761, v113
	v_mul_f32_e32 v113, v193, v113
	v_exp_f32_e32 v113, v113
	s_nop 0
	v_add_f32_e32 v113, 1.0, v113
	v_rcp_f32_e32 v114, v113
	s_nop 0
	v_mul_f32_e32 v213, v193, v114
	v_mul_f32_e32 v115, v201, v201
	v_mul_f32_e32 v115, 0xbdd2d3e8, v115
	v_add_f32_e32 v115, 0xc0135761, v115
	v_mul_f32_e32 v115, v201, v115
	v_exp_f32_e32 v115, v115
	s_nop 0
	v_add_f32_e32 v115, 1.0, v115
	v_rcp_f32_e32 v136, v115
	s_nop 0
	v_mul_f32_e32 v203, v201, v136
	v_mul_f32_e32 v113, v121, v121
	v_fmac_f32_e32 v113, v112, v112
	v_fmac_f32_e32 v113, v167, v167
	v_fmac_f32_e32 v113, v195, v195
	v_fmac_f32_e32 v113, v197, v197
	v_fmac_f32_e32 v113, v199, v199
	v_fmac_f32_e32 v113, v212, v212
	v_mul_f32_e32 v114, v200, v200
	v_mul_f32_e32 v114, 0xbdd2d3e8, v114
	v_add_f32_e32 v114, 0xc0135761, v114
	v_mul_f32_e32 v114, v200, v114
	v_exp_f32_e32 v114, v114
	s_nop 0
	v_add_f32_e32 v114, 1.0, v114
	v_rcp_f32_e32 v115, v114
	s_nop 0
	v_mul_f32_e32 v202, v200, v115
	v_fmac_f32_e32 v113, v213, v213
	v_pk_mul_f32 v[114:115], v[202:203], v[202:203]
	s_nop 0
	v_add_f32_e32 v113, v114, v113
	v_add_f32_e32 v113, v115, v113
	s_nop 0
	s_nop 0
	v_mul_f32_e32 v115, v127, v127
	v_mul_f32_e32 v115, 0xbdd2d3e8, v115
	v_add_f32_e32 v115, 0xc0135761, v115
	v_mul_f32_e32 v115, v127, v115
	v_exp_f32_e32 v115, v115
	s_nop 0
	v_add_f32_e32 v115, 1.0, v115
	v_rcp_f32_e32 v116, v115
	s_nop 0
	v_mul_f32_e32 v205, v127, v116
	s_nop 0
	v_mul_f32_e32 v114, v126, v126
	v_mul_f32_e32 v114, 0xbdd2d3e8, v114
	v_add_f32_e32 v114, 0xc0135761, v114
	v_mul_f32_e32 v114, v126, v114
	v_exp_f32_e32 v114, v114
	s_nop 0
	v_add_f32_e32 v114, 1.0, v114
	v_rcp_f32_e32 v115, v114
	s_nop 0
	v_mul_f32_e32 v204, v126, v115
	v_pk_mul_f32 v[114:115], v[204:205], v[204:205]
	s_nop 0
	v_add_f32_e32 v113, v114, v113
	v_add_f32_e32 v113, v115, v113
	s_nop 0
	s_nop 0
	v_mul_f32_e32 v115, v125, v125
	v_mul_f32_e32 v115, 0xbdd2d3e8, v115
	v_add_f32_e32 v115, 0xc0135761, v115
	v_mul_f32_e32 v115, v125, v115
	v_exp_f32_e32 v115, v115
	s_nop 0
	v_add_f32_e32 v115, 1.0, v115
	v_rcp_f32_e32 v116, v115
	s_nop 0
	v_mul_f32_e32 v207, v125, v116
	s_nop 0
	v_mul_f32_e32 v114, v124, v124
	v_mul_f32_e32 v114, 0xbdd2d3e8, v114
	v_add_f32_e32 v114, 0xc0135761, v114
	v_mul_f32_e32 v114, v124, v114
	v_exp_f32_e32 v114, v114
	s_nop 0
	v_add_f32_e32 v114, 1.0, v114
	v_rcp_f32_e32 v115, v114
	s_nop 0
	v_mul_f32_e32 v206, v124, v115
	v_pk_mul_f32 v[114:115], v[206:207], v[206:207]
	s_nop 0
	v_add_f32_e32 v113, v114, v113
	v_add_f32_e32 v113, v115, v113
	s_nop 0
	s_nop 0
	v_mul_f32_e32 v115, v123, v123
	v_mul_f32_e32 v115, 0xbdd2d3e8, v115
	v_add_f32_e32 v115, 0xc0135761, v115
	v_mul_f32_e32 v115, v123, v115
	v_exp_f32_e32 v115, v115
	s_nop 0
	v_add_f32_e32 v115, 1.0, v115
	v_rcp_f32_e32 v116, v115
	s_nop 0
	v_mul_f32_e32 v209, v123, v116
	s_lshr_b32 s6, s89, 4
	s_and_b32 s6, s6, 0x78
	s_add_i32 s6, s6, s29
	v_mul_f32_e32 v114, v122, v122
	v_mul_f32_e32 v114, 0xbdd2d3e8, v114
	v_add_f32_e32 v114, 0xc0135761, v114
	v_mul_f32_e32 v114, v122, v114
	v_exp_f32_e32 v114, v114
	s_nop 0
	v_add_f32_e32 v114, 1.0, v114
	v_rcp_f32_e32 v115, v114
	s_nop 0
	v_mul_f32_e32 v208, v122, v115
	v_pk_mul_f32 v[114:115], v[208:209], v[208:209]
	s_mov_b32 s7, s9
	v_add_f32_e32 v113, v114, v113
	v_add_f32_e32 v113, v115, v113
	v_and_b32_e32 v115, 64, v165
	v_xor_b32_e32 v114, 16, v165
	v_add_u32_e32 v115, 64, v115
	v_cmp_lt_i32_e32 vcc, v114, v115
	s_lshl_b64 s[6:7], s[6:7], 14
	s_add_u32 s37, s36, s56
	v_cndmask_b32_e32 v114, v165, v114, vcc
	v_lshlrev_b32_e32 v114, 2, v114
	ds_bpermute_b32 v114, v114, v113
	v_readlane_b32 s36, v254, 35
	s_addc_u32 s53, s36, s57
	s_add_u32 s6, s37, s6
	s_addc_u32 s7, s53, s7
	s_waitcnt lgkmcnt(0)
; __device__ __forceinline__ unsigned f2bf(float f) { unsigned u = __float_as_uint(f); return (u + 0x7fffu + ((u >> 16) & 1u)) >> 16; }
;     __device__ __forceinline__ void operator()(const f32x4 (&acc)[2][2][4][2], const pg8::Unit& u, int wr, int wc, int fr, int fq) const {
;     ...
;                     const float rn = rsqrtf(head_ssq(y) * (1.f / 64.f) + EPS);
;                     bf16_t* p = zvT + (((size_t)b * 16 + (s >> 7)) * 8 + g) * 8192 + (s & 127);
; #pragma unroll
;                     for (int i = 0; i < 16; ++i) { const int d = 32 * (i >> 3) + d0 + (i & 7); p[d * 128] = (bf16_t)f2bf(y[i] * rn * g_sgu[g * 64 + d]); }
	v_add_f32_e32 v113, v113, v114
	v_xor_b32_e32 v114, 32, v165
	v_cmp_lt_i32_e32 vcc, v114, v115
	s_mov_b64 s[56:57], s[40:41]
	s_nop 0
	v_cndmask_b32_e32 v114, v165, v114, vcc
	v_lshlrev_b32_e32 v114, 2, v114
	ds_bpermute_b32 v114, v114, v113
	s_waitcnt lgkmcnt(0)
	v_add_f32_e32 v113, v113, v114
	v_fmamk_f32 v113, v113, 0x3c800000, v161
	v_cmp_gt_f32_e32 vcc, s61, v113
	v_mul_f32_e32 v114, 0x4b800000, v113
	s_nop 0
	v_cndmask_b32_e32 v113, v113, v114, vcc
	v_rsq_f32_e32 v113, v113
	s_nop 0
	v_mul_f32_e32 v114, 0x45800000, v113
	v_cndmask_b32_e32 v214, v113, v114, vcc
	v_and_b32_e32 v113, 0x4f, v120
	v_lshlrev_b32_e32 v136, 1, v113
	v_lshl_add_u64 v[210:211], s[6:7], 0, v[136:137]
	s_mov_b64 s[6:7], s[38:39]
	v_readlane_b32 s36, v254, 8
	v_or_b32_e32 v136, s27, v140
	v_readlane_b32 s37, v254, 9
	v_mul_f32_e32 v166, v112, v214
	v_readlane_b32 s50, v254, 22
	v_lshl_add_u64 v[116:117], v[136:137], 2, s[36:37]
	global_load_dwordx4 v[112:115], v[116:117], off offset:16
	s_nop 0
	global_load_dwordx4 v[116:119], v[116:117], off
	v_readlane_b32 s51, v254, 23
	v_readlane_b32 s38, v254, 10
	v_readlane_b32 s39, v254, 11
	v_readlane_b32 s40, v254, 12
	v_readlane_b32 s41, v254, 13
	v_readlane_b32 s42, v254, 14
	v_readlane_b32 s43, v254, 15
	v_readlane_b32 s49, v254, 21
	v_readlane_b32 s50, v254, 39
	s_mov_b64 s[38:39], s[6:7]
	s_mov_b64 s[42:43], s[58:59]
	s_mov_b64 s[40:41], s[56:57]
	v_readlane_b32 s49, v254, 41
	v_readlane_b32 s51, v254, 40
	s_mov_b64 s[6:7], 0
	v_readlane_b32 s44, v254, 16
	v_readlane_b32 s45, v254, 17
	v_readlane_b32 s46, v254, 18
	v_readlane_b32 s47, v254, 19
	v_readlane_b32 s48, v254, 20
	s_waitcnt vmcnt(0)
	v_mul_f32_e32 v116, v116, v166
	v_bfe_u32 v136, v116, 16, 1
	v_add3_u32 v116, v116, v136, s20
	v_lshlrev_b32_e32 v136, 1, v142
	v_lshl_add_u64 v[216:217], v[210:211], 0, v[136:137]
	global_store_short_d16_hi v[216:217], v116, off
	v_mul_f32_e32 v116, v121, v214
	v_add_u32_e32 v136, s27, v140
	v_mul_f32_e32 v116, v117, v116
	v_lshl_add_u64 v[216:217], v[136:137], 2, s[36:37]
	v_bfe_u32 v117, v116, 16, 1
	v_lshlrev_b32_e32 v136, 1, v144
	v_add3_u32 v121, v116, v117, s20
	v_lshl_add_u64 v[116:117], v[210:211], 0, v[136:137]
	global_store_short_d16_hi v[116:117], v121, off
	v_mul_f32_e32 v116, v167, v214
	v_mul_f32_e32 v116, v118, v116
	v_bfe_u32 v117, v116, 16, 1
	v_lshlrev_b32_e32 v136, 1, v146
	v_add3_u32 v118, v116, v117, s20
	v_lshl_add_u64 v[116:117], v[210:211], 0, v[136:137]
	global_store_short_d16_hi v[116:117], v118, off
	v_mul_f32_e32 v116, v195, v214
	v_mul_f32_e32 v116, v119, v116
	v_bfe_u32 v117, v116, 16, 1
	v_lshlrev_b32_e32 v136, 1, v148
	v_add3_u32 v118, v116, v117, s20
	v_lshl_add_u64 v[116:117], v[210:211], 0, v[136:137]
	global_store_short_d16_hi v[116:117], v118, off
	v_mul_f32_e32 v116, v197, v214
	v_mul_f32_e32 v112, v112, v116
	v_bfe_u32 v116, v112, 16, 1
	v_lshlrev_b32_e32 v136, 1, v150
	v_add3_u32 v112, v112, v116, s20
	v_lshl_add_u64 v[116:117], v[210:211], 0, v[136:137]
	global_store_short_d16_hi v[116:117], v112, off
	v_mul_f32_e32 v112, v199, v214
	v_mul_f32_e32 v112, v112, v113
	v_bfe_u32 v113, v112, 16, 1
	v_lshlrev_b32_e32 v136, 1, v152
	v_add3_u32 v116, v112, v113, s20
	v_lshl_add_u64 v[112:113], v[210:211], 0, v[136:137]
	global_store_short_d16_hi v[112:113], v116, off
	v_mul_f32_e32 v112, v212, v214
	v_mul_f32_e32 v112, v112, v114
	v_bfe_u32 v113, v112, 16, 1
	v_lshlrev_b32_e32 v136, 1, v154
	v_add3_u32 v114, v112, v113, s20
	v_lshl_add_u64 v[112:113], v[210:211], 0, v[136:137]
	global_store_short_d16_hi v[112:113], v114, off
	v_mul_f32_e32 v112, v213, v214
	v_mul_f32_e32 v112, v112, v115
	v_bfe_u32 v113, v112, 16, 1
	v_lshlrev_b32_e32 v136, 1, v156
	v_add3_u32 v114, v112, v113, s20
	v_lshl_add_u64 v[112:113], v[210:211], 0, v[136:137]
	global_store_short_d16_hi v[112:113], v114, off
	global_load_dwordx4 v[112:115], v[216:217], off offset:144
	s_nop 0
	global_load_dwordx4 v[116:119], v[216:217], off offset:128
	v_mul_f32_e32 v121, v202, v214
	v_lshlrev_b32_e32 v136, 1, v158
	v_lshl_add_u64 v[166:167], v[210:211], 0, v[136:137]
	v_lshlrev_b32_e32 v136, 1, v160
	s_waitcnt vmcnt(0)
	v_mul_f32_e32 v116, v121, v116
	v_bfe_u32 v121, v116, 16, 1
	v_add3_u32 v116, v116, v121, s20
	global_store_short_d16_hi v[166:167], v116, off
	v_mul_f32_e32 v116, v203, v214
	v_mul_f32_e32 v116, v116, v117
	v_bfe_u32 v117, v116, 16, 1
	v_add3_u32 v121, v116, v117, s20
	v_lshl_add_u64 v[116:117], v[210:211], 0, v[136:137]
	global_store_short_d16_hi v[116:117], v121, off
	v_mul_f32_e32 v116, v204, v214
	v_mul_f32_e32 v116, v116, v118
	v_bfe_u32 v117, v116, 16, 1
	v_lshlrev_b32_e32 v136, 1, v162
	v_add3_u32 v118, v116, v117, s20
	v_lshl_add_u64 v[116:117], v[210:211], 0, v[136:137]
	global_store_short_d16_hi v[116:117], v118, off
	v_mul_f32_e32 v116, v205, v214
	v_mul_f32_e32 v116, v116, v119
	v_bfe_u32 v117, v116, 16, 1
	v_lshlrev_b32_e32 v136, 1, v164
	v_add3_u32 v118, v116, v117, s20
	v_lshl_add_u64 v[116:117], v[210:211], 0, v[136:137]
	global_store_short_d16_hi v[116:117], v118, off
	v_mul_f32_e32 v116, v206, v214
	v_mul_f32_e32 v112, v116, v112
	v_bfe_u32 v116, v112, 16, 1
	v_add3_u32 v112, v112, v116, s20
	v_or_b32_e32 v116, 0x1200, v142
	v_lshlrev_b32_e32 v136, 1, v116
	v_lshl_add_u64 v[116:117], v[210:211], 0, v[136:137]
	global_store_short_d16_hi v[116:117], v112, off
	v_mul_f32_e32 v112, v207, v214
	v_mul_f32_e32 v112, v112, v113
	v_bfe_u32 v113, v112, 16, 1
	v_add3_u32 v116, v112, v113, s20
	v_or_b32_e32 v112, 0x1280, v142
	v_lshlrev_b32_e32 v136, 1, v112
	v_lshl_add_u64 v[112:113], v[210:211], 0, v[136:137]
	global_store_short_d16_hi v[112:113], v116, off
	v_mul_f32_e32 v112, v208, v214
	v_mul_f32_e32 v112, v112, v114
	v_bfe_u32 v113, v112, 16, 1
	v_add3_u32 v114, v112, v113, s20
	v_or_b32_e32 v112, 0x1300, v142
	v_lshlrev_b32_e32 v136, 1, v112
	v_lshl_add_u64 v[112:113], v[210:211], 0, v[136:137]
	global_store_short_d16_hi v[112:113], v114, off
	v_mul_f32_e32 v112, v209, v214
	v_mul_f32_e32 v112, v112, v115
	v_bfe_u32 v113, v112, 16, 1
	v_lshlrev_b32_e32 v136, 1, v172
	v_add3_u32 v114, v112, v113, s20
	v_lshl_add_u64 v[112:113], v[210:211], 0, v[136:137]
	global_store_short_d16_hi v[112:113], v114, off

; __device__ __forceinline__ float gelu_tanh(float x) {
;     const float u = 0.7978845608028654f * (x + 0.044715f * x * x * x);
;     return x / (1.f + __expf(-2.f * u));
; }
;     __device__ __forceinline__ void operator()(const f32x4 (&acc)[2][2][4][2], const pg8::Unit& u, int wr, int wc, int fr, int fq) const {
;     ...
;                 } else if (cs < 28) {
;                     float y[16];
; #pragma unroll
;                     for (int i = 0; i < 16; ++i) y[i] = gelu_tanh(v[i]);
;                     bf16_t* p = zu + (size_t)row * 512 + (cs - 20) * 64 + d0; store8(p, y); store8(p + 32, y + 8);
.LBB0_180:
	s_andn2_b64 vcc, exec, s[6:7]
	s_cbranch_vccnz .LBB0_182
	s_nop 0
	s_nop 0
	v_mul_f32_e32 v112, v171, v171
	v_mul_f32_e32 v112, 0xbdd2d3e8, v112
	v_add_f32_e32 v112, 0xc0135761, v112
	v_mul_f32_e32 v112, v171, v112
	v_exp_f32_e32 v112, v112
	s_nop 0
	v_add_f32_e32 v112, 1.0, v112
	v_rcp_f32_e32 v113, v112
	s_nop 0
	v_mul_f32_e32 v112, v171, v113
	s_nop 0
	s_nop 0
	v_mul_f32_e32 v113, v173, v173
	v_mul_f32_e32 v113, 0xbdd2d3e8, v113
	v_add_f32_e32 v113, 0xc0135761, v113
	v_mul_f32_e32 v113, v173, v113
	v_exp_f32_e32 v113, v113
	s_nop 0
	v_add_f32_e32 v113, 1.0, v113
	v_rcp_f32_e32 v114, v113
	s_nop 0
	v_mul_f32_e32 v113, v173, v114
	v_cvt_pk_bf16_f32 v112, v112, v113
	s_nop 0
	s_nop 0
	v_mul_f32_e32 v114, v175, v175
	v_mul_f32_e32 v114, 0xbdd2d3e8, v114
	v_add_f32_e32 v114, 0xc0135761, v114
	v_mul_f32_e32 v114, v175, v114
	v_exp_f32_e32 v114, v114
	s_nop 0
	v_add_f32_e32 v114, 1.0, v114
	v_rcp_f32_e32 v115, v114
	s_nop 0
	v_mul_f32_e32 v114, v175, v115
	s_nop 0
	s_nop 0
	v_mul_f32_e32 v115, v185, v185
	v_mul_f32_e32 v115, 0xbdd2d3e8, v115
	v_add_f32_e32 v115, 0xc0135761, v115
	v_mul_f32_e32 v115, v185, v115
	v_exp_f32_e32 v115, v115
	s_nop 0
	v_add_f32_e32 v115, 1.0, v115
	v_rcp_f32_e32 v116, v115
	s_nop 0
	v_mul_f32_e32 v115, v185, v116
	v_cvt_pk_bf16_f32 v113, v114, v115
	s_nop 0
	s_nop 0
	v_mul_f32_e32 v116, v187, v187
	v_mul_f32_e32 v116, 0xbdd2d3e8, v116
	v_add_f32_e32 v116, 0xc0135761, v116
	v_mul_f32_e32 v116, v187, v116
	v_exp_f32_e32 v116, v116
	s_nop 0
	v_add_f32_e32 v116, 1.0, v116
	v_rcp_f32_e32 v117, v116
	s_nop 0
	v_mul_f32_e32 v116, v187, v117
	s_nop 0
	s_nop 0
	v_mul_f32_e32 v117, v189, v189
	v_mul_f32_e32 v117, 0xbdd2d3e8, v117
	v_add_f32_e32 v117, 0xc0135761, v117
	v_mul_f32_e32 v117, v189, v117
	v_exp_f32_e32 v117, v117
	s_nop 0
	v_add_f32_e32 v117, 1.0, v117
	v_rcp_f32_e32 v118, v117
	s_nop 0
	v_mul_f32_e32 v117, v189, v118
	v_cvt_pk_bf16_f32 v114, v116, v117
	s_nop 0
	s_nop 0
	v_mul_f32_e32 v118, v191, v191
	v_mul_f32_e32 v118, 0xbdd2d3e8, v118
	v_add_f32_e32 v118, 0xc0135761, v118
	v_mul_f32_e32 v118, v191, v118
	v_exp_f32_e32 v118, v118
	s_nop 0
	v_add_f32_e32 v118, 1.0, v118
	v_rcp_f32_e32 v119, v118
	s_nop 0
	v_mul_f32_e32 v118, v191, v119
	s_nop 0
	s_nop 0
	v_mul_f32_e32 v119, v193, v193
	v_mul_f32_e32 v119, 0xbdd2d3e8, v119
	v_add_f32_e32 v119, 0xc0135761, v119
	v_mul_f32_e32 v119, v193, v119
	v_exp_f32_e32 v119, v119
	s_nop 0
	v_add_f32_e32 v119, 1.0, v119
	v_rcp_f32_e32 v121, v119
	s_nop 0
	v_mul_f32_e32 v119, v193, v121
	v_cvt_pk_bf16_f32 v115, v118, v119
	s_nop 0
	s_nop 0
	v_mul_f32_e32 v121, v200, v200
	v_mul_f32_e32 v121, 0xbdd2d3e8, v121
	v_add_f32_e32 v121, 0xc0135761, v121
	v_mul_f32_e32 v121, v200, v121
	v_exp_f32_e32 v121, v121
	s_nop 0
	v_add_f32_e32 v121, 1.0, v121
	v_rcp_f32_e32 v136, v121
	s_nop 0
	v_mul_f32_e32 v167, v200, v136
	s_nop 0
	s_nop 0
	v_mul_f32_e32 v121, v201, v201
	v_mul_f32_e32 v121, 0xbdd2d3e8, v121
	v_add_f32_e32 v121, 0xc0135761, v121
	v_mul_f32_e32 v121, v201, v121
	v_exp_f32_e32 v121, v121
	s_nop 0
	v_add_f32_e32 v121, 1.0, v121
	v_rcp_f32_e32 v136, v121
	s_nop 0
	v_mul_f32_e32 v166, v201, v136
	s_nop 0
	s_nop 0
	v_mul_f32_e32 v121, v126, v126
	v_mul_f32_e32 v121, 0xbdd2d3e8, v121
	v_add_f32_e32 v121, 0xc0135761, v121
	v_mul_f32_e32 v121, v126, v121
	v_exp_f32_e32 v121, v121
	s_nop 0
	v_add_f32_e32 v121, 1.0, v121
	v_rcp_f32_e32 v136, v121
	s_nop 0
	v_mul_f32_e32 v168, v126, v136
	s_nop 0
	s_nop 0
	v_mul_f32_e32 v121, v127, v127
	v_mul_f32_e32 v121, 0xbdd2d3e8, v121
	v_add_f32_e32 v121, 0xc0135761, v121
	v_mul_f32_e32 v121, v127, v121
	v_exp_f32_e32 v121, v121
	s_nop 0
	v_add_f32_e32 v121, 1.0, v121
	v_rcp_f32_e32 v136, v121
	s_nop 0
	v_mul_f32_e32 v170, v127, v136
	s_nop 0
	s_nop 0
	v_mul_f32_e32 v121, v124, v124
	v_mul_f32_e32 v121, 0xbdd2d3e8, v121
	v_add_f32_e32 v121, 0xc0135761, v121
	v_mul_f32_e32 v121, v124, v121
	v_exp_f32_e32 v121, v121
	s_nop 0
	v_add_f32_e32 v121, 1.0, v121
	v_rcp_f32_e32 v136, v121
	s_nop 0
	v_mul_f32_e32 v195, v124, v136
	s_nop 0
	s_nop 0
	v_mul_f32_e32 v121, v125, v125
	v_mul_f32_e32 v121, 0xbdd2d3e8, v121
	v_add_f32_e32 v121, 0xc0135761, v121
	v_mul_f32_e32 v121, v125, v121
	v_exp_f32_e32 v121, v121
	s_nop 0
	v_add_f32_e32 v121, 1.0, v121
	v_rcp_f32_e32 v136, v121
	s_nop 0
	v_mul_f32_e32 v197, v125, v136
	s_nop 0
	s_nop 0
	v_mul_f32_e32 v121, v122, v122
	v_mul_f32_e32 v121, 0xbdd2d3e8, v121
	v_add_f32_e32 v121, 0xc0135761, v121
	v_mul_f32_e32 v121, v122, v121
	v_exp_f32_e32 v121, v121
	s_nop 0
	v_add_f32_e32 v121, 1.0, v121
	v_rcp_f32_e32 v136, v121
	s_nop 0
	v_mul_f32_e32 v199, v122, v136
	s_nop 0
	v_readlane_b32 s6, v254, 31
	v_readlane_b32 s7, v254, 32
	v_mul_f32_e32 v121, v123, v123
	v_mul_f32_e32 v121, 0xbdd2d3e8, v121
	v_add_f32_e32 v121, 0xc0135761, v121
	v_mul_f32_e32 v121, v123, v121
	v_exp_f32_e32 v121, v121
	s_nop 0
	v_add_f32_e32 v121, 1.0, v121
	v_rcp_f32_e32 v136, v121
	s_nop 0
	v_mul_f32_e32 v204, v123, v136
	v_ashrrev_i32_e32 v121, 31, v120
	v_lshlrev_b64 v[202:203], 10, v[120:121]
	v_lshl_add_u64 v[202:203], s[6:7], 0, v[202:203]
	v_lshl_add_u64 v[202:203], s[8:9], 1, v[202:203]
	v_lshlrev_b32_e32 v136, 1, v140
	v_lshl_add_u64 v[202:203], v[202:203], 0, v[136:137]
	global_store_dwordx4 v[202:203], v[112:115], off offset:-2560
	s_nop 1
	v_cvt_pk_bf16_f32 v112, v167, v166
	v_cvt_pk_bf16_f32 v113, v168, v170
	v_cvt_pk_bf16_f32 v114, v195, v197
	v_cvt_pk_bf16_f32 v115, v199, v204
	global_store_dwordx4 v[202:203], v[112:115], off offset:-2496

; __device__ __forceinline__ float gelu_tanh(float x) {
;     const float u = 0.7978845608028654f * (x + 0.044715f * x * x * x);
;     return x / (1.f + __expf(-2.f * u));
; }
;     __device__ __forceinline__ void operator()(const f32x4 (&acc)[2][2][4][2], const pg8::Unit& u, int wr, int wc, int fr, int fq) const {
;     ...
;                 } else if (cs < 36) {
;                     const int g = cs - 28;
;                     float y[16];
; #pragma unroll
;                     for (int i = 0; i < 16; ++i) y[i] = gelu_tanh(v[i]);
;                     const float rn = rsqrtf(head_ssq(y) * (1.f / 64.f) + EPS);
.LBB0_203:
	s_andn2_b64 vcc, exec, s[72:73]
	s_mov_b64 s[54:55], -1
	s_cbranch_vccnz .LBB0_219
	s_andn2_b64 vcc, exec, s[70:71]
	s_cbranch_vccnz .LBB0_216
	s_andn2_b64 vcc, exec, s[42:43]
	s_cbranch_vccnz .LBB0_213
	s_andn2_b64 vcc, exec, s[40:41]
	s_cbranch_vccnz .LBB0_208
	s_ashr_i32 s53, s52, 31
	s_lshl_b64 s[56:57], s[52:53], 21
	v_readlane_b32 s36, v254, 33
	s_mov_b64 s[58:59], s[42:43]
	v_mul_f32_e32 v96, v126, v126
	v_mul_f32_e32 v96, 0xbdd2d3e8, v96
	v_add_f32_e32 v96, 0xc0135761, v96
	v_mul_f32_e32 v96, v126, v96
	v_exp_f32_e32 v96, v96
	s_nop 0
	v_add_f32_e32 v96, 1.0, v96
	v_rcp_f32_e32 v97, v96
	s_nop 0
	v_mul_f32_e32 v96, v126, v97
	s_nop 0
	s_nop 0
	v_mul_f32_e32 v97, v127, v127
	v_mul_f32_e32 v97, 0xbdd2d3e8, v97
	v_add_f32_e32 v97, 0xc0135761, v97
	v_mul_f32_e32 v97, v127, v97
	v_exp_f32_e32 v97, v97
	s_nop 0
	v_add_f32_e32 v97, 1.0, v97
	v_rcp_f32_e32 v98, v97
	s_nop 0
	v_mul_f32_e32 v105, v127, v98
	s_nop 0
	s_nop 0
	v_mul_f32_e32 v97, v169, v169
	v_mul_f32_e32 v97, 0xbdd2d3e8, v97
	v_add_f32_e32 v97, 0xc0135761, v97
	v_mul_f32_e32 v97, v169, v97
	v_exp_f32_e32 v97, v97
	s_nop 0
	v_add_f32_e32 v97, 1.0, v97
	v_rcp_f32_e32 v98, v97
	s_nop 0
	v_mul_f32_e32 v189, v169, v98
	s_nop 0
	s_nop 0
	v_mul_f32_e32 v97, v171, v171
	v_mul_f32_e32 v97, 0xbdd2d3e8, v97
	v_add_f32_e32 v97, 0xc0135761, v97
	v_mul_f32_e32 v97, v171, v97
	v_exp_f32_e32 v97, v97
	s_nop 0
	v_add_f32_e32 v97, 1.0, v97
	v_rcp_f32_e32 v98, v97
	s_nop 0
	v_mul_f32_e32 v191, v171, v98
	s_nop 0
	s_nop 0
	v_mul_f32_e32 v97, v173, v173
	v_mul_f32_e32 v97, 0xbdd2d3e8, v97
	v_add_f32_e32 v97, 0xc0135761, v97
	v_mul_f32_e32 v97, v173, v97
	v_exp_f32_e32 v97, v97
	s_nop 0
	v_add_f32_e32 v97, 1.0, v97
	v_rcp_f32_e32 v98, v97
	s_nop 0
	v_mul_f32_e32 v193, v173, v98
	s_nop 0
	s_nop 0
	v_mul_f32_e32 v97, v175, v175
	v_mul_f32_e32 v97, 0xbdd2d3e8, v97
	v_add_f32_e32 v97, 0xc0135761, v97
	v_mul_f32_e32 v97, v175, v97
	v_exp_f32_e32 v97, v97
	s_nop 0
	v_add_f32_e32 v97, 1.0, v97
	v_rcp_f32_e32 v98, v97
	s_nop 0
	v_mul_f32_e32 v195, v175, v98
	s_nop 0
	s_nop 0
	v_mul_f32_e32 v97, v185, v185
	v_mul_f32_e32 v97, 0xbdd2d3e8, v97
	v_add_f32_e32 v97, 0xc0135761, v97
	v_mul_f32_e32 v97, v185, v97
	v_exp_f32_e32 v97, v97
	s_nop 0
	v_add_f32_e32 v97, 1.0, v97
	v_rcp_f32_e32 v98, v97
	s_nop 0
	v_mul_f32_e32 v197, v185, v98
	s_nop 0
	s_nop 0
	v_mul_f32_e32 v97, v187, v187
	v_mul_f32_e32 v97, 0xbdd2d3e8, v97
	v_add_f32_e32 v97, 0xc0135761, v97
	v_mul_f32_e32 v97, v187, v97
	v_exp_f32_e32 v97, v97
	s_nop 0
	v_add_f32_e32 v97, 1.0, v97
	v_rcp_f32_e32 v98, v97
	s_nop 0
	v_mul_f32_e32 v198, v187, v98
	v_mul_f32_e32 v99, v109, v109
	v_mul_f32_e32 v99, 0xbdd2d3e8, v99
	v_add_f32_e32 v99, 0xc0135761, v99
	v_mul_f32_e32 v99, v109, v99
	v_exp_f32_e32 v99, v99
	s_nop 0
	v_add_f32_e32 v99, 1.0, v99
	v_rcp_f32_e32 v114, v99
	s_nop 0
	v_mul_f32_e32 v115, v109, v114
	v_mul_f32_e32 v97, v105, v105
	v_fmac_f32_e32 v97, v96, v96
	v_fmac_f32_e32 v97, v189, v189
	v_fmac_f32_e32 v97, v191, v191
	v_fmac_f32_e32 v97, v193, v193
	v_fmac_f32_e32 v97, v195, v195
	v_fmac_f32_e32 v97, v197, v197
	v_mul_f32_e32 v98, v108, v108
	v_mul_f32_e32 v98, 0xbdd2d3e8, v98
	v_add_f32_e32 v98, 0xc0135761, v98
	v_mul_f32_e32 v98, v108, v98
	v_exp_f32_e32 v98, v98
	s_nop 0
	v_add_f32_e32 v98, 1.0, v98
	v_rcp_f32_e32 v99, v98
	s_nop 0
	v_mul_f32_e32 v114, v108, v99
	v_fmac_f32_e32 v97, v198, v198
	v_pk_mul_f32 v[98:99], v[114:115], v[114:115]
	s_nop 0
	v_add_f32_e32 v97, v98, v97
	v_add_f32_e32 v97, v99, v97
	s_nop 0
	s_nop 0
	v_mul_f32_e32 v99, v113, v113
	v_mul_f32_e32 v99, 0xbdd2d3e8, v99
	v_add_f32_e32 v99, 0xc0135761, v99
	v_mul_f32_e32 v99, v113, v99
	v_exp_f32_e32 v99, v99
	s_nop 0
	v_add_f32_e32 v99, 1.0, v99
	v_rcp_f32_e32 v100, v99
	s_nop 0
	v_mul_f32_e32 v117, v113, v100
	s_nop 0
	v_mul_f32_e32 v98, v112, v112
	v_mul_f32_e32 v98, 0xbdd2d3e8, v98
	v_add_f32_e32 v98, 0xc0135761, v98
	v_mul_f32_e32 v98, v112, v98
	v_exp_f32_e32 v98, v98
	s_nop 0
	v_add_f32_e32 v98, 1.0, v98
	v_rcp_f32_e32 v99, v98
	s_nop 0
	v_mul_f32_e32 v116, v112, v99
	v_pk_mul_f32 v[98:99], v[116:117], v[116:117]
	s_nop 0
	v_add_f32_e32 v97, v98, v97
	v_add_f32_e32 v97, v99, v97
	s_nop 0
	s_nop 0
	v_mul_f32_e32 v99, v111, v111
	v_mul_f32_e32 v99, 0xbdd2d3e8, v99
	v_add_f32_e32 v99, 0xc0135761, v99
	v_mul_f32_e32 v99, v111, v99
	v_exp_f32_e32 v99, v99
	s_nop 0
	v_add_f32_e32 v99, 1.0, v99
	v_rcp_f32_e32 v100, v99
	s_nop 0
	v_mul_f32_e32 v119, v111, v100
	s_nop 0
	v_mul_f32_e32 v98, v110, v110
	v_mul_f32_e32 v98, 0xbdd2d3e8, v98
	v_add_f32_e32 v98, 0xc0135761, v98
	v_mul_f32_e32 v98, v110, v98
	v_exp_f32_e32 v98, v98
	s_nop 0
	v_add_f32_e32 v98, 1.0, v98
	v_rcp_f32_e32 v99, v98
	s_nop 0
	v_mul_f32_e32 v118, v110, v99
	v_pk_mul_f32 v[98:99], v[118:119], v[118:119]
	s_nop 0
	v_add_f32_e32 v97, v98, v97
	v_add_f32_e32 v97, v99, v97
	s_nop 0
	s_nop 0
	v_mul_f32_e32 v99, v107, v107
	v_mul_f32_e32 v99, 0xbdd2d3e8, v99
	v_add_f32_e32 v99, 0xc0135761, v99
	v_mul_f32_e32 v99, v107, v99
	v_exp_f32_e32 v99, v99
	s_nop 0
	v_add_f32_e32 v99, 1.0, v99
	v_rcp_f32_e32 v100, v99
	s_nop 0
	v_mul_f32_e32 v123, v107, v100
	s_lshr_b32 s54, s89, 4
	s_and_b32 s54, s54, 0x78
	s_add_i32 s54, s54, s29
	v_mul_f32_e32 v98, v106, v106
	v_mul_f32_e32 v98, 0xbdd2d3e8, v98
	v_add_f32_e32 v98, 0xc0135761, v98
	v_mul_f32_e32 v98, v106, v98
	v_exp_f32_e32 v98, v98
	s_nop 0
	v_add_f32_e32 v98, 1.0, v98
	v_rcp_f32_e32 v99, v98
	s_nop 0
	v_mul_f32_e32 v122, v106, v99
	v_pk_mul_f32 v[98:99], v[122:123], v[122:123]
	s_mov_b32 s55, s9
	v_add_f32_e32 v97, v98, v97
	v_add_f32_e32 v97, v99, v97
	v_and_b32_e32 v99, 64, v165
	v_xor_b32_e32 v98, 16, v165
	v_add_u32_e32 v99, 64, v99
	v_cmp_lt_i32_e32 vcc, v98, v99
	s_lshl_b64 s[54:55], s[54:55], 14
	s_add_u32 s53, s36, s56
	v_cndmask_b32_e32 v98, v165, v98, vcc
	v_lshlrev_b32_e32 v98, 2, v98
	ds_bpermute_b32 v98, v98, v97
	v_readlane_b32 s36, v254, 35
	s_addc_u32 s56, s36, s57
	s_add_u32 s54, s53, s54
	s_addc_u32 s55, s56, s55
	s_waitcnt lgkmcnt(0)
; __device__ __forceinline__ unsigned f2bf(float f) { unsigned u = __float_as_uint(f); return (u + 0x7fffu + ((u >> 16) & 1u)) >> 16; }
;     __device__ __forceinline__ void operator()(const f32x4 (&acc)[2][2][4][2], const pg8::Unit& u, int wr, int wc, int fr, int fq) const {
;     ...
;                     const float rn = rsqrtf(head_ssq(y) * (1.f / 64.f) + EPS);
;                     bf16_t* p = zvT + (((size_t)b * 16 + (s >> 7)) * 8 + g) * 8192 + (s & 127);
; #pragma unroll
;                     for (int i = 0; i < 16; ++i) { const int d = 32 * (i >> 3) + d0 + (i & 7); p[d * 128] = (bf16_t)f2bf(y[i] * rn * g_sgu[g * 64 + d]); }
	v_add_f32_e32 v97, v97, v98
	v_xor_b32_e32 v98, 32, v165
	v_cmp_lt_i32_e32 vcc, v98, v99
	s_mov_b64 s[56:57], s[40:41]
	s_nop 0
	v_cndmask_b32_e32 v98, v165, v98, vcc
	v_lshlrev_b32_e32 v98, 2, v98
	ds_bpermute_b32 v98, v98, v97
	s_waitcnt lgkmcnt(0)
	v_add_f32_e32 v97, v97, v98
	v_fmamk_f32 v97, v97, 0x3c800000, v161
	v_cmp_gt_f32_e32 vcc, s61, v97
	v_mul_f32_e32 v98, 0x4b800000, v97
	s_nop 0
	v_cndmask_b32_e32 v97, v97, v98, vcc
	v_rsq_f32_e32 v97, v97
	s_nop 0
	v_mul_f32_e32 v98, 0x45800000, v97
	v_cndmask_b32_e32 v199, v97, v98, vcc
	v_and_b32_e32 v97, 0x5f, v104
	v_lshlrev_b32_e32 v136, 1, v97
	v_lshl_add_u64 v[124:125], s[54:55], 0, v[136:137]
	s_mov_b64 s[54:55], s[38:39]
	v_readlane_b32 s36, v254, 8
	v_or_b32_e32 v136, s27, v140
	v_readlane_b32 s37, v254, 9
	v_mul_f32_e32 v166, v96, v199
	v_readlane_b32 s50, v254, 22
	v_lshl_add_u64 v[100:101], v[136:137], 2, s[36:37]
	global_load_dwordx4 v[96:99], v[100:101], off offset:16
	s_nop 0
	global_load_dwordx4 v[100:103], v[100:101], off
	v_readlane_b32 s51, v254, 23
	v_readlane_b32 s38, v254, 10
	v_readlane_b32 s39, v254, 11
	v_readlane_b32 s40, v254, 12
	v_readlane_b32 s41, v254, 13
	v_readlane_b32 s42, v254, 14
	v_readlane_b32 s43, v254, 15
	v_readlane_b32 s49, v254, 21
	v_readlane_b32 s50, v254, 39
	s_mov_b64 s[38:39], s[54:55]
	s_mov_b64 s[42:43], s[58:59]
	s_mov_b64 s[40:41], s[56:57]
	v_readlane_b32 s49, v254, 41
	v_readlane_b32 s51, v254, 40
	s_mov_b64 s[54:55], 0
	v_readlane_b32 s44, v254, 16
	v_readlane_b32 s45, v254, 17
	v_readlane_b32 s46, v254, 18
	v_readlane_b32 s47, v254, 19
	v_readlane_b32 s48, v254, 20
	s_waitcnt vmcnt(0)
	v_mul_f32_e32 v100, v100, v166
	v_bfe_u32 v136, v100, 16, 1
	v_add3_u32 v100, v100, v136, s20
	v_lshlrev_b32_e32 v136, 1, v142
	v_lshl_add_u64 v[200:201], v[124:125], 0, v[136:137]
	global_store_short_d16_hi v[200:201], v100, off
	v_mul_f32_e32 v100, v105, v199
	v_add_u32_e32 v136, s27, v140
	v_mul_f32_e32 v100, v101, v100
	v_lshl_add_u64 v[200:201], v[136:137], 2, s[36:37]
	v_bfe_u32 v101, v100, 16, 1
	v_lshlrev_b32_e32 v136, 1, v144
	v_add3_u32 v105, v100, v101, s20
	v_lshl_add_u64 v[100:101], v[124:125], 0, v[136:137]
	global_store_short_d16_hi v[100:101], v105, off
	v_mul_f32_e32 v100, v189, v199
	v_mul_f32_e32 v100, v102, v100
	v_bfe_u32 v101, v100, 16, 1
	v_lshlrev_b32_e32 v136, 1, v146
	v_add3_u32 v102, v100, v101, s20
	v_lshl_add_u64 v[100:101], v[124:125], 0, v[136:137]
	global_store_short_d16_hi v[100:101], v102, off
	v_mul_f32_e32 v100, v191, v199
	v_mul_f32_e32 v100, v103, v100
	v_bfe_u32 v101, v100, 16, 1
	v_lshlrev_b32_e32 v136, 1, v148
	v_add3_u32 v102, v100, v101, s20
	v_lshl_add_u64 v[100:101], v[124:125], 0, v[136:137]
	global_store_short_d16_hi v[100:101], v102, off
	v_mul_f32_e32 v100, v193, v199
	v_mul_f32_e32 v96, v96, v100
	v_bfe_u32 v100, v96, 16, 1
	v_lshlrev_b32_e32 v136, 1, v150
	v_add3_u32 v96, v96, v100, s20
	v_lshl_add_u64 v[100:101], v[124:125], 0, v[136:137]
	global_store_short_d16_hi v[100:101], v96, off
	v_mul_f32_e32 v96, v195, v199
	v_mul_f32_e32 v96, v96, v97
	v_bfe_u32 v97, v96, 16, 1
	v_lshlrev_b32_e32 v136, 1, v152
	v_add3_u32 v100, v96, v97, s20
	v_lshl_add_u64 v[96:97], v[124:125], 0, v[136:137]
	global_store_short_d16_hi v[96:97], v100, off
	v_mul_f32_e32 v96, v197, v199
	v_mul_f32_e32 v96, v96, v98
	v_bfe_u32 v97, v96, 16, 1
	v_lshlrev_b32_e32 v136, 1, v154
	v_add3_u32 v98, v96, v97, s20
	v_lshl_add_u64 v[96:97], v[124:125], 0, v[136:137]
	global_store_short_d16_hi v[96:97], v98, off
	v_mul_f32_e32 v96, v198, v199
	v_mul_f32_e32 v96, v96, v99
	v_bfe_u32 v97, v96, 16, 1
	v_lshlrev_b32_e32 v136, 1, v156
	v_add3_u32 v98, v96, v97, s20
	v_lshl_add_u64 v[96:97], v[124:125], 0, v[136:137]
	global_store_short_d16_hi v[96:97], v98, off
	global_load_dwordx4 v[96:99], v[200:201], off offset:144
	s_nop 0
	global_load_dwordx4 v[100:103], v[200:201], off offset:128
	v_mul_f32_e32 v105, v114, v199
	v_lshlrev_b32_e32 v136, 1, v158
	v_lshl_add_u64 v[200:201], v[124:125], 0, v[136:137]
	v_lshlrev_b32_e32 v136, 1, v160
	s_waitcnt vmcnt(0)
	v_mul_f32_e32 v100, v105, v100
	v_bfe_u32 v105, v100, 16, 1
	v_add3_u32 v100, v100, v105, s20
	global_store_short_d16_hi v[200:201], v100, off
	v_mul_f32_e32 v100, v115, v199
	v_mul_f32_e32 v100, v100, v101
	v_bfe_u32 v101, v100, 16, 1
	v_add3_u32 v105, v100, v101, s20
	v_lshl_add_u64 v[100:101], v[124:125], 0, v[136:137]
	global_store_short_d16_hi v[100:101], v105, off
	v_mul_f32_e32 v100, v116, v199
	v_mul_f32_e32 v100, v100, v102
	v_bfe_u32 v101, v100, 16, 1
	v_lshlrev_b32_e32 v136, 1, v162
	v_add3_u32 v102, v100, v101, s20
	v_lshl_add_u64 v[100:101], v[124:125], 0, v[136:137]
	global_store_short_d16_hi v[100:101], v102, off
	v_mul_f32_e32 v100, v117, v199
	v_mul_f32_e32 v100, v100, v103
	v_bfe_u32 v101, v100, 16, 1
	v_lshlrev_b32_e32 v136, 1, v164
	v_add3_u32 v102, v100, v101, s20
	v_lshl_add_u64 v[100:101], v[124:125], 0, v[136:137]
	global_store_short_d16_hi v[100:101], v102, off
	v_mul_f32_e32 v100, v118, v199
	v_mul_f32_e32 v96, v100, v96
	v_bfe_u32 v100, v96, 16, 1
	v_add3_u32 v96, v96, v100, s20
	v_or_b32_e32 v100, 0x1200, v142
	v_lshlrev_b32_e32 v136, 1, v100
	v_lshl_add_u64 v[100:101], v[124:125], 0, v[136:137]
	global_store_short_d16_hi v[100:101], v96, off
	v_mul_f32_e32 v96, v119, v199
	v_mul_f32_e32 v96, v96, v97
	v_bfe_u32 v97, v96, 16, 1
	v_add3_u32 v100, v96, v97, s20
	v_or_b32_e32 v96, 0x1280, v142
	v_lshlrev_b32_e32 v136, 1, v96
	v_lshl_add_u64 v[96:97], v[124:125], 0, v[136:137]
	global_store_short_d16_hi v[96:97], v100, off
	v_mul_f32_e32 v96, v122, v199
	v_mul_f32_e32 v96, v96, v98
	v_bfe_u32 v97, v96, 16, 1
	v_add3_u32 v98, v96, v97, s20
	v_or_b32_e32 v96, 0x1300, v142
	v_lshlrev_b32_e32 v136, 1, v96
	v_lshl_add_u64 v[96:97], v[124:125], 0, v[136:137]
	global_store_short_d16_hi v[96:97], v98, off
	v_mul_f32_e32 v96, v123, v199
	v_mul_f32_e32 v96, v96, v99
	v_bfe_u32 v97, v96, 16, 1
	v_lshlrev_b32_e32 v136, 1, v172
	v_add3_u32 v98, v96, v97, s20
	v_lshl_add_u64 v[96:97], v[124:125], 0, v[136:137]
	global_store_short_d16_hi v[96:97], v98, off

; __device__ __forceinline__ float gelu_tanh(float x) {
;     const float u = 0.7978845608028654f * (x + 0.044715f * x * x * x);
;     return x / (1.f + __expf(-2.f * u));
; }
;     __device__ __forceinline__ void operator()(const f32x4 (&acc)[2][2][4][2], const pg8::Unit& u, int wr, int wc, int fr, int fq) const {
;     ...
;                 } else if (cs < 28) {
;                     float y[16];
; #pragma unroll
;                     for (int i = 0; i < 16; ++i) y[i] = gelu_tanh(v[i]);
;                     bf16_t* p = zu + (size_t)row * 512 + (cs - 20) * 64 + d0; store8(p, y); store8(p + 32, y + 8);
.LBB0_213:
	s_andn2_b64 vcc, exec, s[54:55]
	s_cbranch_vccnz .LBB0_215
	v_readlane_b32 s36, v254, 31
	v_readlane_b32 s37, v254, 32
	s_nop 0
	v_mul_f32_e32 v96, v126, v126
	v_mul_f32_e32 v96, 0xbdd2d3e8, v96
	v_add_f32_e32 v96, 0xc0135761, v96
	v_mul_f32_e32 v96, v126, v96
	v_exp_f32_e32 v96, v96
	s_nop 0
	v_add_f32_e32 v96, 1.0, v96
	v_rcp_f32_e32 v97, v96
	s_nop 0
	v_mul_f32_e32 v96, v126, v97
	s_nop 0
	s_nop 0
	v_mul_f32_e32 v97, v127, v127
	v_mul_f32_e32 v97, 0xbdd2d3e8, v97
	v_add_f32_e32 v97, 0xc0135761, v97
	v_mul_f32_e32 v97, v127, v97
	v_exp_f32_e32 v97, v97
	s_nop 0
	v_add_f32_e32 v97, 1.0, v97
	v_rcp_f32_e32 v98, v97
	s_nop 0
	v_mul_f32_e32 v97, v127, v98
	v_cvt_pk_bf16_f32 v96, v96, v97
	s_nop 0
	s_nop 0
	v_mul_f32_e32 v98, v169, v169
	v_mul_f32_e32 v98, 0xbdd2d3e8, v98
	v_add_f32_e32 v98, 0xc0135761, v98
	v_mul_f32_e32 v98, v169, v98
	v_exp_f32_e32 v98, v98
	s_nop 0
	v_add_f32_e32 v98, 1.0, v98
	v_rcp_f32_e32 v99, v98
	s_nop 0
	v_mul_f32_e32 v98, v169, v99
	s_nop 0
	s_nop 0
	v_mul_f32_e32 v99, v171, v171
	v_mul_f32_e32 v99, 0xbdd2d3e8, v99
	v_add_f32_e32 v99, 0xc0135761, v99
	v_mul_f32_e32 v99, v171, v99
	v_exp_f32_e32 v99, v99
	s_nop 0
	v_add_f32_e32 v99, 1.0, v99
	v_rcp_f32_e32 v100, v99
	s_nop 0
	v_mul_f32_e32 v99, v171, v100
	v_cvt_pk_bf16_f32 v97, v98, v99
	s_nop 0
	s_nop 0
	v_mul_f32_e32 v100, v173, v173
	v_mul_f32_e32 v100, 0xbdd2d3e8, v100
	v_add_f32_e32 v100, 0xc0135761, v100
	v_mul_f32_e32 v100, v173, v100
	v_exp_f32_e32 v100, v100
	s_nop 0
	v_add_f32_e32 v100, 1.0, v100
	v_rcp_f32_e32 v101, v100
	s_nop 0
	v_mul_f32_e32 v100, v173, v101
	s_nop 0
	s_nop 0
	v_mul_f32_e32 v101, v175, v175
	v_mul_f32_e32 v101, 0xbdd2d3e8, v101
	v_add_f32_e32 v101, 0xc0135761, v101
	v_mul_f32_e32 v101, v175, v101
	v_exp_f32_e32 v101, v101
	s_nop 0
	v_add_f32_e32 v101, 1.0, v101
	v_rcp_f32_e32 v102, v101
	s_nop 0
	v_mul_f32_e32 v101, v175, v102
	v_cvt_pk_bf16_f32 v98, v100, v101
	s_nop 0
	s_nop 0
	v_mul_f32_e32 v102, v185, v185
	v_mul_f32_e32 v102, 0xbdd2d3e8, v102
	v_add_f32_e32 v102, 0xc0135761, v102
	v_mul_f32_e32 v102, v185, v102
	v_exp_f32_e32 v102, v102
	s_nop 0
	v_add_f32_e32 v102, 1.0, v102
	v_rcp_f32_e32 v103, v102
	s_nop 0
	v_mul_f32_e32 v102, v185, v103
	s_nop 0
	s_nop 0
	v_mul_f32_e32 v103, v187, v187
	v_mul_f32_e32 v103, 0xbdd2d3e8, v103
	v_add_f32_e32 v103, 0xc0135761, v103
	v_mul_f32_e32 v103, v187, v103
	v_exp_f32_e32 v103, v103
	s_nop 0
	v_add_f32_e32 v103, 1.0, v103
	v_rcp_f32_e32 v105, v103
	s_nop 0
	v_mul_f32_e32 v103, v187, v105
	v_cvt_pk_bf16_f32 v99, v102, v103
	s_nop 0
	s_nop 0
	v_mul_f32_e32 v105, v108, v108
	v_mul_f32_e32 v105, 0xbdd2d3e8, v105
	v_add_f32_e32 v105, 0xc0135761, v105
	v_mul_f32_e32 v105, v108, v105
	v_exp_f32_e32 v105, v105
	s_nop 0
	v_add_f32_e32 v105, 1.0, v105
	v_rcp_f32_e32 v114, v105
	s_nop 0
	v_mul_f32_e32 v114, v108, v114
	s_nop 0
	s_nop 0
	v_mul_f32_e32 v105, v109, v109
	v_mul_f32_e32 v105, 0xbdd2d3e8, v105
	v_add_f32_e32 v105, 0xc0135761, v105
	v_mul_f32_e32 v105, v109, v105
	v_exp_f32_e32 v105, v105
	s_nop 0
	v_add_f32_e32 v105, 1.0, v105
	v_rcp_f32_e32 v115, v105
	s_nop 0
	v_mul_f32_e32 v115, v109, v115
	s_nop 0
	s_nop 0
	v_mul_f32_e32 v105, v112, v112
	v_mul_f32_e32 v105, 0xbdd2d3e8, v105
	v_add_f32_e32 v105, 0xc0135761, v105
	v_mul_f32_e32 v105, v112, v105
	v_exp_f32_e32 v105, v105
	s_nop 0
	v_add_f32_e32 v105, 1.0, v105
	v_rcp_f32_e32 v116, v105
	s_nop 0
	v_mul_f32_e32 v118, v112, v116
	s_nop 0
	s_nop 0
	v_mul_f32_e32 v105, v113, v113
	v_mul_f32_e32 v105, 0xbdd2d3e8, v105
	v_add_f32_e32 v105, 0xc0135761, v105
	v_mul_f32_e32 v105, v113, v105
	v_exp_f32_e32 v105, v105
	s_nop 0
	v_add_f32_e32 v105, 1.0, v105
	v_rcp_f32_e32 v116, v105
	s_nop 0
	v_mul_f32_e32 v119, v113, v116
	s_nop 0
	s_nop 0
	v_mul_f32_e32 v105, v110, v110
	v_mul_f32_e32 v105, 0xbdd2d3e8, v105
	v_add_f32_e32 v105, 0xc0135761, v105
	v_mul_f32_e32 v105, v110, v105
	v_exp_f32_e32 v105, v105
	s_nop 0
	v_add_f32_e32 v105, 1.0, v105
	v_rcp_f32_e32 v116, v105
	s_nop 0
	v_mul_f32_e32 v122, v110, v116
	s_nop 0
	s_nop 0
	v_mul_f32_e32 v105, v111, v111
	v_mul_f32_e32 v105, 0xbdd2d3e8, v105
	v_add_f32_e32 v105, 0xc0135761, v105
	v_mul_f32_e32 v105, v111, v105
	v_exp_f32_e32 v105, v105
	s_nop 0
	v_add_f32_e32 v105, 1.0, v105
	v_rcp_f32_e32 v116, v105
	s_nop 0
	v_mul_f32_e32 v123, v111, v116
	s_nop 0
	s_nop 0
	v_mul_f32_e32 v105, v106, v106
	v_mul_f32_e32 v105, 0xbdd2d3e8, v105
	v_add_f32_e32 v105, 0xc0135761, v105
	v_mul_f32_e32 v105, v106, v105
	v_exp_f32_e32 v105, v105
	s_nop 0
	v_add_f32_e32 v105, 1.0, v105
	v_rcp_f32_e32 v116, v105
	s_nop 0
	v_mul_f32_e32 v124, v106, v116
	s_nop 0
	s_nop 0
	v_mul_f32_e32 v105, v107, v107
	v_mul_f32_e32 v105, 0xbdd2d3e8, v105
	v_add_f32_e32 v105, 0xc0135761, v105
	v_mul_f32_e32 v105, v107, v105
	v_exp_f32_e32 v105, v105
	s_nop 0
	v_add_f32_e32 v105, 1.0, v105
	v_rcp_f32_e32 v116, v105
	s_nop 0
	v_mul_f32_e32 v125, v107, v116
	v_ashrrev_i32_e32 v105, 31, v104
	v_lshlrev_b64 v[116:117], 10, v[104:105]
	v_lshl_add_u64 v[116:117], s[36:37], 0, v[116:117]
	v_lshl_add_u64 v[116:117], s[8:9], 1, v[116:117]
	v_lshlrev_b32_e32 v136, 1, v140
	v_lshl_add_u64 v[116:117], v[116:117], 0, v[136:137]
	global_store_dwordx4 v[116:117], v[96:99], off offset:-2560
	s_nop 1
	v_cvt_pk_bf16_f32 v96, v114, v115
	v_cvt_pk_bf16_f32 v97, v118, v119
	v_cvt_pk_bf16_f32 v98, v122, v123
	v_cvt_pk_bf16_f32 v99, v124, v125
	global_store_dwordx4 v[116:117], v[96:99], off offset:-2496

; __device__ __forceinline__ float gelu_tanh(float x) {
;     const float u = 0.7978845608028654f * (x + 0.044715f * x * x * x);
;     return x / (1.f + __expf(-2.f * u));
; }
;     __device__ __forceinline__ void operator()(const f32x4 (&acc)[2][2][4][2], const pg8::Unit& u, int wr, int wc, int fr, int fq) const {
;     ...
;                 } else if (cs < 36) {
;                     const int g = cs - 28;
;                     float y[16];
; #pragma unroll
;                     for (int i = 0; i < 16; ++i) y[i] = gelu_tanh(v[i]);
;                     const float rn = rsqrtf(head_ssq(y) * (1.f / 64.f) + EPS);
.LBB0_236:
	s_andn2_b64 vcc, exec, s[72:73]
	s_mov_b64 s[54:55], -1
	s_cbranch_vccnz .LBB0_252
	s_andn2_b64 vcc, exec, s[70:71]
	s_cbranch_vccnz .LBB0_249
	s_andn2_b64 vcc, exec, s[42:43]
	s_cbranch_vccnz .LBB0_246
	s_andn2_b64 vcc, exec, s[40:41]
	s_cbranch_vccnz .LBB0_241
	s_ashr_i32 s53, s52, 31
	s_lshl_b64 s[56:57], s[52:53], 21
	v_readlane_b32 s36, v254, 33
	s_mov_b64 s[58:59], s[42:43]
	v_mul_f32_e32 v80, v109, v109
	v_mul_f32_e32 v80, 0xbdd2d3e8, v80
	v_add_f32_e32 v80, 0xc0135761, v80
	v_mul_f32_e32 v80, v109, v80
	v_exp_f32_e32 v80, v80
	s_nop 0
	v_add_f32_e32 v80, 1.0, v80
	v_rcp_f32_e32 v81, v80
	s_nop 0
	v_mul_f32_e32 v80, v109, v81
	s_nop 0
	s_nop 0
	v_mul_f32_e32 v81, v110, v110
	v_mul_f32_e32 v81, 0xbdd2d3e8, v81
	v_add_f32_e32 v81, 0xc0135761, v81
	v_mul_f32_e32 v81, v110, v81
	v_exp_f32_e32 v81, v81
	s_nop 0
	v_add_f32_e32 v81, 1.0, v81
	v_rcp_f32_e32 v82, v81
	s_nop 0
	v_mul_f32_e32 v89, v110, v82
	s_nop 0
	s_nop 0
	v_mul_f32_e32 v81, v111, v111
	v_mul_f32_e32 v81, 0xbdd2d3e8, v81
	v_add_f32_e32 v81, 0xc0135761, v81
	v_mul_f32_e32 v81, v111, v81
	v_exp_f32_e32 v81, v81
	s_nop 0
	v_add_f32_e32 v81, 1.0, v81
	v_rcp_f32_e32 v82, v81
	s_nop 0
	v_mul_f32_e32 v117, v111, v82
	s_nop 0
	s_nop 0
	v_mul_f32_e32 v81, v112, v112
	v_mul_f32_e32 v81, 0xbdd2d3e8, v81
	v_add_f32_e32 v81, 0xc0135761, v81
	v_mul_f32_e32 v81, v112, v81
	v_exp_f32_e32 v81, v81
	s_nop 0
	v_add_f32_e32 v81, 1.0, v81
	v_rcp_f32_e32 v82, v81
	s_nop 0
	v_mul_f32_e32 v118, v112, v82
	s_nop 0
	s_nop 0
	v_mul_f32_e32 v81, v113, v113
	v_mul_f32_e32 v81, 0xbdd2d3e8, v81
	v_add_f32_e32 v81, 0xc0135761, v81
	v_mul_f32_e32 v81, v113, v81
	v_exp_f32_e32 v81, v81
	s_nop 0
	v_add_f32_e32 v81, 1.0, v81
	v_rcp_f32_e32 v82, v81
	s_nop 0
	v_mul_f32_e32 v119, v113, v82
	s_nop 0
	s_nop 0
	v_mul_f32_e32 v81, v114, v114
	v_mul_f32_e32 v81, 0xbdd2d3e8, v81
	v_add_f32_e32 v81, 0xc0135761, v81
	v_mul_f32_e32 v81, v114, v81
	v_exp_f32_e32 v81, v81
	s_nop 0
	v_add_f32_e32 v81, 1.0, v81
	v_rcp_f32_e32 v82, v81
	s_nop 0
	v_mul_f32_e32 v121, v114, v82
	s_nop 0
	s_nop 0
	v_mul_f32_e32 v81, v115, v115
	v_mul_f32_e32 v81, 0xbdd2d3e8, v81
	v_add_f32_e32 v81, 0xc0135761, v81
	v_mul_f32_e32 v81, v115, v81
	v_exp_f32_e32 v81, v81
	s_nop 0
	v_add_f32_e32 v81, 1.0, v81
	v_rcp_f32_e32 v82, v81
	s_nop 0
	v_mul_f32_e32 v122, v115, v82
	s_nop 0
	s_nop 0
	v_mul_f32_e32 v81, v116, v116
	v_mul_f32_e32 v81, 0xbdd2d3e8, v81
	v_add_f32_e32 v81, 0xc0135761, v81
	v_mul_f32_e32 v81, v116, v81
	v_exp_f32_e32 v81, v81
	s_nop 0
	v_add_f32_e32 v81, 1.0, v81
	v_rcp_f32_e32 v82, v81
	s_nop 0
	v_mul_f32_e32 v123, v116, v82
	v_mul_f32_e32 v83, v93, v93
	v_mul_f32_e32 v83, 0xbdd2d3e8, v83
	v_add_f32_e32 v83, 0xc0135761, v83
	v_mul_f32_e32 v83, v93, v83
	v_exp_f32_e32 v83, v83
	s_nop 0
	v_add_f32_e32 v83, 1.0, v83
	v_rcp_f32_e32 v98, v83
	s_nop 0
	v_mul_f32_e32 v99, v93, v98
	v_mul_f32_e32 v81, v89, v89
	v_fmac_f32_e32 v81, v80, v80
	v_fmac_f32_e32 v81, v117, v117
	v_fmac_f32_e32 v81, v118, v118
	v_fmac_f32_e32 v81, v119, v119
	v_fmac_f32_e32 v81, v121, v121
	v_fmac_f32_e32 v81, v122, v122
	v_mul_f32_e32 v82, v92, v92
	v_mul_f32_e32 v82, 0xbdd2d3e8, v82
	v_add_f32_e32 v82, 0xc0135761, v82
	v_mul_f32_e32 v82, v92, v82
	v_exp_f32_e32 v82, v82
	s_nop 0
	v_add_f32_e32 v82, 1.0, v82
	v_rcp_f32_e32 v83, v82
	s_nop 0
	v_mul_f32_e32 v98, v92, v83
	v_fmac_f32_e32 v81, v123, v123
	v_pk_mul_f32 v[82:83], v[98:99], v[98:99]
	s_nop 0
	v_add_f32_e32 v81, v82, v81
	v_add_f32_e32 v81, v83, v81
	s_nop 0
	s_nop 0
	v_mul_f32_e32 v83, v97, v97
	v_mul_f32_e32 v83, 0xbdd2d3e8, v83
	v_add_f32_e32 v83, 0xc0135761, v83
	v_mul_f32_e32 v83, v97, v83
	v_exp_f32_e32 v83, v83
	s_nop 0
	v_add_f32_e32 v83, 1.0, v83
	v_rcp_f32_e32 v84, v83
	s_nop 0
	v_mul_f32_e32 v101, v97, v84
	s_nop 0
	v_mul_f32_e32 v82, v96, v96
	v_mul_f32_e32 v82, 0xbdd2d3e8, v82
	v_add_f32_e32 v82, 0xc0135761, v82
	v_mul_f32_e32 v82, v96, v82
	v_exp_f32_e32 v82, v82
	s_nop 0
	v_add_f32_e32 v82, 1.0, v82
	v_rcp_f32_e32 v83, v82
	s_nop 0
	v_mul_f32_e32 v100, v96, v83
	v_pk_mul_f32 v[82:83], v[100:101], v[100:101]
	s_nop 0
	v_add_f32_e32 v81, v82, v81
	v_add_f32_e32 v81, v83, v81
	s_nop 0
	s_nop 0
	v_mul_f32_e32 v83, v95, v95
	v_mul_f32_e32 v83, 0xbdd2d3e8, v83
	v_add_f32_e32 v83, 0xc0135761, v83
	v_mul_f32_e32 v83, v95, v83
	v_exp_f32_e32 v83, v83
	s_nop 0
	v_add_f32_e32 v83, 1.0, v83
	v_rcp_f32_e32 v84, v83
	s_nop 0
	v_mul_f32_e32 v103, v95, v84
	s_nop 0
	v_mul_f32_e32 v82, v94, v94
	v_mul_f32_e32 v82, 0xbdd2d3e8, v82
	v_add_f32_e32 v82, 0xc0135761, v82
	v_mul_f32_e32 v82, v94, v82
	v_exp_f32_e32 v82, v82
	s_nop 0
	v_add_f32_e32 v82, 1.0, v82
	v_rcp_f32_e32 v83, v82
	s_nop 0
	v_mul_f32_e32 v102, v94, v83
	v_pk_mul_f32 v[82:83], v[102:103], v[102:103]
	s_nop 0
	v_add_f32_e32 v81, v82, v81
	v_add_f32_e32 v81, v83, v81
	s_nop 0
	s_nop 0
	v_mul_f32_e32 v83, v91, v91
	v_mul_f32_e32 v83, 0xbdd2d3e8, v83
	v_add_f32_e32 v83, 0xc0135761, v83
	v_mul_f32_e32 v83, v91, v83
	v_exp_f32_e32 v83, v83
	s_nop 0
	v_add_f32_e32 v83, 1.0, v83
	v_rcp_f32_e32 v84, v83
	s_nop 0
	v_mul_f32_e32 v105, v91, v84
	s_lshr_b32 s54, s89, 4
	s_and_b32 s54, s54, 0x78
	s_add_i32 s54, s54, s29
	v_mul_f32_e32 v82, v90, v90
	v_mul_f32_e32 v82, 0xbdd2d3e8, v82
	v_add_f32_e32 v82, 0xc0135761, v82
	v_mul_f32_e32 v82, v90, v82
	v_exp_f32_e32 v82, v82
	s_nop 0
	v_add_f32_e32 v82, 1.0, v82
	v_rcp_f32_e32 v83, v82
	s_nop 0
	v_mul_f32_e32 v104, v90, v83
	v_pk_mul_f32 v[82:83], v[104:105], v[104:105]
	s_mov_b32 s55, s9
	v_add_f32_e32 v81, v82, v81
	v_add_f32_e32 v81, v83, v81
	v_and_b32_e32 v83, 64, v165
	v_xor_b32_e32 v82, 16, v165
	v_add_u32_e32 v83, 64, v83
	v_cmp_lt_i32_e32 vcc, v82, v83
	s_lshl_b64 s[54:55], s[54:55], 14
	s_add_u32 s53, s36, s56
	v_cndmask_b32_e32 v82, v165, v82, vcc
	v_lshlrev_b32_e32 v82, 2, v82
	ds_bpermute_b32 v82, v82, v81
	v_readlane_b32 s36, v254, 35
	s_addc_u32 s56, s36, s57
	s_add_u32 s54, s53, s54
	s_addc_u32 s55, s56, s55
	s_waitcnt lgkmcnt(0)
; __device__ __forceinline__ unsigned f2bf(float f) { unsigned u = __float_as_uint(f); return (u + 0x7fffu + ((u >> 16) & 1u)) >> 16; }
;     __device__ __forceinline__ void operator()(const f32x4 (&acc)[2][2][4][2], const pg8::Unit& u, int wr, int wc, int fr, int fq) const {
;     ...
;                     const float rn = rsqrtf(head_ssq(y) * (1.f / 64.f) + EPS);
;                     bf16_t* p = zvT + (((size_t)b * 16 + (s >> 7)) * 8 + g) * 8192 + (s & 127);
; #pragma unroll
;                     for (int i = 0; i < 16; ++i) { const int d = 32 * (i >> 3) + d0 + (i & 7); p[d * 128] = (bf16_t)f2bf(y[i] * rn * g_sgu[g * 64 + d]); }
	v_add_f32_e32 v81, v81, v82
	v_xor_b32_e32 v82, 32, v165
	v_cmp_lt_i32_e32 vcc, v82, v83
	s_mov_b64 s[56:57], s[40:41]
	s_nop 0
	v_cndmask_b32_e32 v82, v165, v82, vcc
	v_lshlrev_b32_e32 v82, 2, v82
	ds_bpermute_b32 v82, v82, v81
	s_waitcnt lgkmcnt(0)
	v_add_f32_e32 v81, v81, v82
	v_fmamk_f32 v81, v81, 0x3c800000, v161
	v_cmp_gt_f32_e32 vcc, s61, v81
	v_mul_f32_e32 v82, 0x4b800000, v81
	s_nop 0
	v_cndmask_b32_e32 v81, v81, v82, vcc
	v_rsq_f32_e32 v81, v81
	s_nop 0
	v_mul_f32_e32 v82, 0x45800000, v81
	v_cndmask_b32_e32 v124, v81, v82, vcc
	v_and_b32_e32 v81, 0x6f, v88
	v_lshlrev_b32_e32 v136, 1, v81
	v_lshl_add_u64 v[106:107], s[54:55], 0, v[136:137]
	s_mov_b64 s[54:55], s[38:39]
	v_readlane_b32 s36, v254, 8
	v_or_b32_e32 v136, s27, v140
	v_readlane_b32 s37, v254, 9
	v_mul_f32_e32 v125, v80, v124
	v_readlane_b32 s50, v254, 22
	v_lshl_add_u64 v[84:85], v[136:137], 2, s[36:37]
	global_load_dwordx4 v[80:83], v[84:85], off offset:16
	s_nop 0
	global_load_dwordx4 v[84:87], v[84:85], off
	v_lshlrev_b32_e32 v136, 1, v142
	v_lshl_add_u64 v[126:127], v[106:107], 0, v[136:137]
	v_add_u32_e32 v136, s27, v140
	v_readlane_b32 s51, v254, 23
	v_readlane_b32 s38, v254, 10
	v_readlane_b32 s39, v254, 11
	v_readlane_b32 s40, v254, 12
	v_readlane_b32 s41, v254, 13
	v_readlane_b32 s42, v254, 14
	v_readlane_b32 s43, v254, 15
	v_readlane_b32 s49, v254, 21
	v_readlane_b32 s50, v254, 39
	s_mov_b64 s[38:39], s[54:55]
	s_mov_b64 s[42:43], s[58:59]
	s_mov_b64 s[40:41], s[56:57]
	v_readlane_b32 s49, v254, 41
	v_readlane_b32 s51, v254, 40
	s_mov_b64 s[54:55], 0
	v_readlane_b32 s44, v254, 16
	v_readlane_b32 s45, v254, 17
	v_readlane_b32 s46, v254, 18
	v_readlane_b32 s47, v254, 19
	v_readlane_b32 s48, v254, 20
	s_waitcnt vmcnt(0)
	v_mul_f32_e32 v84, v84, v125
	v_bfe_u32 v125, v84, 16, 1
	v_add3_u32 v84, v84, v125, s20
	global_store_short_d16_hi v[126:127], v84, off
	v_mul_f32_e32 v84, v89, v124
	v_mul_f32_e32 v84, v85, v84
	v_lshl_add_u64 v[126:127], v[136:137], 2, s[36:37]
	v_bfe_u32 v85, v84, 16, 1
	v_lshlrev_b32_e32 v136, 1, v144
	v_add3_u32 v89, v84, v85, s20
	v_lshl_add_u64 v[84:85], v[106:107], 0, v[136:137]
	global_store_short_d16_hi v[84:85], v89, off
	v_mul_f32_e32 v84, v117, v124
	v_mul_f32_e32 v84, v86, v84
	v_bfe_u32 v85, v84, 16, 1
	v_lshlrev_b32_e32 v136, 1, v146
	v_add3_u32 v86, v84, v85, s20
	v_lshl_add_u64 v[84:85], v[106:107], 0, v[136:137]
	global_store_short_d16_hi v[84:85], v86, off
	v_mul_f32_e32 v84, v118, v124
	v_mul_f32_e32 v84, v87, v84
	v_bfe_u32 v85, v84, 16, 1
	v_lshlrev_b32_e32 v136, 1, v148
	v_add3_u32 v86, v84, v85, s20
	v_lshl_add_u64 v[84:85], v[106:107], 0, v[136:137]
	global_store_short_d16_hi v[84:85], v86, off
	v_mul_f32_e32 v84, v119, v124
	v_mul_f32_e32 v80, v80, v84
	v_bfe_u32 v84, v80, 16, 1
	v_lshlrev_b32_e32 v136, 1, v150
	v_add3_u32 v80, v80, v84, s20
	v_lshl_add_u64 v[84:85], v[106:107], 0, v[136:137]
	global_store_short_d16_hi v[84:85], v80, off
	v_mul_f32_e32 v80, v121, v124
	v_mul_f32_e32 v80, v80, v81
	v_bfe_u32 v81, v80, 16, 1
	v_lshlrev_b32_e32 v136, 1, v152
	v_add3_u32 v84, v80, v81, s20
	v_lshl_add_u64 v[80:81], v[106:107], 0, v[136:137]
	global_store_short_d16_hi v[80:81], v84, off
	v_mul_f32_e32 v80, v122, v124
	v_mul_f32_e32 v80, v80, v82
	v_bfe_u32 v81, v80, 16, 1
	v_lshlrev_b32_e32 v136, 1, v154
	v_add3_u32 v82, v80, v81, s20
	v_lshl_add_u64 v[80:81], v[106:107], 0, v[136:137]
	global_store_short_d16_hi v[80:81], v82, off
	v_mul_f32_e32 v80, v123, v124
	v_mul_f32_e32 v80, v80, v83
	v_bfe_u32 v81, v80, 16, 1
	v_lshlrev_b32_e32 v136, 1, v156
	v_add3_u32 v82, v80, v81, s20
	v_lshl_add_u64 v[80:81], v[106:107], 0, v[136:137]
	global_store_short_d16_hi v[80:81], v82, off
	global_load_dwordx4 v[80:83], v[126:127], off offset:144
	s_nop 0
	global_load_dwordx4 v[84:87], v[126:127], off offset:128
	v_mul_f32_e32 v89, v98, v124
	v_lshlrev_b32_e32 v136, 1, v158
	v_lshl_add_u64 v[118:119], v[106:107], 0, v[136:137]
	v_lshlrev_b32_e32 v136, 1, v160
	s_waitcnt vmcnt(0)
	v_mul_f32_e32 v84, v89, v84
	v_bfe_u32 v89, v84, 16, 1
	v_add3_u32 v84, v84, v89, s20
	global_store_short_d16_hi v[118:119], v84, off
	v_mul_f32_e32 v84, v99, v124
	v_mul_f32_e32 v84, v84, v85
	v_bfe_u32 v85, v84, 16, 1
	v_add3_u32 v89, v84, v85, s20
	v_lshl_add_u64 v[84:85], v[106:107], 0, v[136:137]
	global_store_short_d16_hi v[84:85], v89, off
	v_mul_f32_e32 v84, v100, v124
	v_mul_f32_e32 v84, v84, v86
	v_bfe_u32 v85, v84, 16, 1
	v_lshlrev_b32_e32 v136, 1, v162
	v_add3_u32 v86, v84, v85, s20
	v_lshl_add_u64 v[84:85], v[106:107], 0, v[136:137]
	global_store_short_d16_hi v[84:85], v86, off
	v_mul_f32_e32 v84, v101, v124
	v_mul_f32_e32 v84, v84, v87
	v_bfe_u32 v85, v84, 16, 1
	v_lshlrev_b32_e32 v136, 1, v164
	v_add3_u32 v86, v84, v85, s20
	v_lshl_add_u64 v[84:85], v[106:107], 0, v[136:137]
	global_store_short_d16_hi v[84:85], v86, off
	v_mul_f32_e32 v84, v102, v124
	v_mul_f32_e32 v80, v84, v80
	v_bfe_u32 v84, v80, 16, 1
	v_add3_u32 v80, v80, v84, s20
	v_or_b32_e32 v84, 0x1200, v142
	v_lshlrev_b32_e32 v136, 1, v84
	v_lshl_add_u64 v[84:85], v[106:107], 0, v[136:137]
	global_store_short_d16_hi v[84:85], v80, off
	v_mul_f32_e32 v80, v103, v124
	v_mul_f32_e32 v80, v80, v81
	v_bfe_u32 v81, v80, 16, 1
	v_add3_u32 v84, v80, v81, s20
	v_or_b32_e32 v80, 0x1280, v142
	v_lshlrev_b32_e32 v136, 1, v80
	v_lshl_add_u64 v[80:81], v[106:107], 0, v[136:137]
	global_store_short_d16_hi v[80:81], v84, off
	v_mul_f32_e32 v80, v104, v124
	v_mul_f32_e32 v80, v80, v82
	v_bfe_u32 v81, v80, 16, 1
	v_add3_u32 v82, v80, v81, s20
	v_or_b32_e32 v80, 0x1300, v142
	v_lshlrev_b32_e32 v136, 1, v80
	v_lshl_add_u64 v[80:81], v[106:107], 0, v[136:137]
	global_store_short_d16_hi v[80:81], v82, off
	v_mul_f32_e32 v80, v105, v124
	v_mul_f32_e32 v80, v80, v83
	v_bfe_u32 v81, v80, 16, 1
	v_lshlrev_b32_e32 v136, 1, v172
	v_add3_u32 v82, v80, v81, s20
	v_lshl_add_u64 v[80:81], v[106:107], 0, v[136:137]
	global_store_short_d16_hi v[80:81], v82, off

; __device__ __forceinline__ float gelu_tanh(float x) {
;     const float u = 0.7978845608028654f * (x + 0.044715f * x * x * x);
;     return x / (1.f + __expf(-2.f * u));
; }
;     __device__ __forceinline__ void operator()(const f32x4 (&acc)[2][2][4][2], const pg8::Unit& u, int wr, int wc, int fr, int fq) const {
;     ...
;                 } else if (cs < 28) {
;                     float y[16];
; #pragma unroll
;                     for (int i = 0; i < 16; ++i) y[i] = gelu_tanh(v[i]);
;                     bf16_t* p = zu + (size_t)row * 512 + (cs - 20) * 64 + d0; store8(p, y); store8(p + 32, y + 8);
.LBB0_246:
	s_andn2_b64 vcc, exec, s[54:55]
	s_cbranch_vccnz .LBB0_248
	v_readlane_b32 s36, v254, 31
	v_readlane_b32 s37, v254, 32
	v_lshlrev_b32_e32 v136, 1, v140
	s_nop 0
	v_mul_f32_e32 v80, v109, v109
	v_mul_f32_e32 v80, 0xbdd2d3e8, v80
	v_add_f32_e32 v80, 0xc0135761, v80
	v_mul_f32_e32 v80, v109, v80
	v_exp_f32_e32 v80, v80
	s_nop 0
	v_add_f32_e32 v80, 1.0, v80
	v_rcp_f32_e32 v81, v80
	s_nop 0
	v_mul_f32_e32 v80, v109, v81
	s_nop 0
	s_nop 0
	v_mul_f32_e32 v81, v110, v110
	v_mul_f32_e32 v81, 0xbdd2d3e8, v81
	v_add_f32_e32 v81, 0xc0135761, v81
	v_mul_f32_e32 v81, v110, v81
	v_exp_f32_e32 v81, v81
	s_nop 0
	v_add_f32_e32 v81, 1.0, v81
	v_rcp_f32_e32 v82, v81
	s_nop 0
	v_mul_f32_e32 v81, v110, v82
	v_cvt_pk_bf16_f32 v80, v80, v81
	s_nop 0
	s_nop 0
	v_mul_f32_e32 v82, v111, v111
	v_mul_f32_e32 v82, 0xbdd2d3e8, v82
	v_add_f32_e32 v82, 0xc0135761, v82
	v_mul_f32_e32 v82, v111, v82
	v_exp_f32_e32 v82, v82
	s_nop 0
	v_add_f32_e32 v82, 1.0, v82
	v_rcp_f32_e32 v83, v82
	s_nop 0
	v_mul_f32_e32 v82, v111, v83
	s_nop 0
	s_nop 0
	v_mul_f32_e32 v83, v112, v112
	v_mul_f32_e32 v83, 0xbdd2d3e8, v83
	v_add_f32_e32 v83, 0xc0135761, v83
	v_mul_f32_e32 v83, v112, v83
	v_exp_f32_e32 v83, v83
	s_nop 0
	v_add_f32_e32 v83, 1.0, v83
	v_rcp_f32_e32 v84, v83
	s_nop 0
	v_mul_f32_e32 v83, v112, v84
	v_cvt_pk_bf16_f32 v81, v82, v83
	s_nop 0
	s_nop 0
	v_mul_f32_e32 v84, v113, v113
	v_mul_f32_e32 v84, 0xbdd2d3e8, v84
	v_add_f32_e32 v84, 0xc0135761, v84
	v_mul_f32_e32 v84, v113, v84
	v_exp_f32_e32 v84, v84
	s_nop 0
	v_add_f32_e32 v84, 1.0, v84
	v_rcp_f32_e32 v85, v84
	s_nop 0
	v_mul_f32_e32 v84, v113, v85
	s_nop 0
	s_nop 0
	v_mul_f32_e32 v85, v114, v114
	v_mul_f32_e32 v85, 0xbdd2d3e8, v85
	v_add_f32_e32 v85, 0xc0135761, v85
	v_mul_f32_e32 v85, v114, v85
	v_exp_f32_e32 v85, v85
	s_nop 0
	v_add_f32_e32 v85, 1.0, v85
	v_rcp_f32_e32 v86, v85
	s_nop 0
	v_mul_f32_e32 v85, v114, v86
	v_cvt_pk_bf16_f32 v82, v84, v85
	s_nop 0
	s_nop 0
	v_mul_f32_e32 v86, v115, v115
	v_mul_f32_e32 v86, 0xbdd2d3e8, v86
	v_add_f32_e32 v86, 0xc0135761, v86
	v_mul_f32_e32 v86, v115, v86
	v_exp_f32_e32 v86, v86
	s_nop 0
	v_add_f32_e32 v86, 1.0, v86
	v_rcp_f32_e32 v87, v86
	s_nop 0
	v_mul_f32_e32 v86, v115, v87
	s_nop 0
	s_nop 0
	v_mul_f32_e32 v87, v116, v116
	v_mul_f32_e32 v87, 0xbdd2d3e8, v87
	v_add_f32_e32 v87, 0xc0135761, v87
	v_mul_f32_e32 v87, v116, v87
	v_exp_f32_e32 v87, v87
	s_nop 0
	v_add_f32_e32 v87, 1.0, v87
	v_rcp_f32_e32 v89, v87
	s_nop 0
	v_mul_f32_e32 v87, v116, v89
	v_cvt_pk_bf16_f32 v83, v86, v87
	s_nop 0
	s_nop 0
	v_mul_f32_e32 v89, v92, v92
	v_mul_f32_e32 v89, 0xbdd2d3e8, v89
	v_add_f32_e32 v89, 0xc0135761, v89
	v_mul_f32_e32 v89, v92, v89
	v_exp_f32_e32 v89, v89
	s_nop 0
	v_add_f32_e32 v89, 1.0, v89
	v_rcp_f32_e32 v98, v89
	s_nop 0
	v_mul_f32_e32 v98, v92, v98
	s_nop 0
	s_nop 0
	v_mul_f32_e32 v89, v93, v93
	v_mul_f32_e32 v89, 0xbdd2d3e8, v89
	v_add_f32_e32 v89, 0xc0135761, v89
	v_mul_f32_e32 v89, v93, v89
	v_exp_f32_e32 v89, v89
	s_nop 0
	v_add_f32_e32 v89, 1.0, v89
	v_rcp_f32_e32 v99, v89
	s_nop 0
	v_mul_f32_e32 v99, v93, v99
	s_nop 0
	s_nop 0
	v_mul_f32_e32 v89, v96, v96
	v_mul_f32_e32 v89, 0xbdd2d3e8, v89
	v_add_f32_e32 v89, 0xc0135761, v89
	v_mul_f32_e32 v89, v96, v89
	v_exp_f32_e32 v89, v89
	s_nop 0
	v_add_f32_e32 v89, 1.0, v89
	v_rcp_f32_e32 v100, v89
	s_nop 0
	v_mul_f32_e32 v102, v96, v100
	s_nop 0
	s_nop 0
	v_mul_f32_e32 v89, v97, v97
	v_mul_f32_e32 v89, 0xbdd2d3e8, v89
	v_add_f32_e32 v89, 0xc0135761, v89
	v_mul_f32_e32 v89, v97, v89
	v_exp_f32_e32 v89, v89
	s_nop 0
	v_add_f32_e32 v89, 1.0, v89
	v_rcp_f32_e32 v100, v89
	s_nop 0
	v_mul_f32_e32 v103, v97, v100
	s_nop 0
	s_nop 0
	v_mul_f32_e32 v89, v94, v94
	v_mul_f32_e32 v89, 0xbdd2d3e8, v89
	v_add_f32_e32 v89, 0xc0135761, v89
	v_mul_f32_e32 v89, v94, v89
	v_exp_f32_e32 v89, v89
	s_nop 0
	v_add_f32_e32 v89, 1.0, v89
	v_rcp_f32_e32 v100, v89
	s_nop 0
	v_mul_f32_e32 v104, v94, v100
	s_nop 0
	s_nop 0
	v_mul_f32_e32 v89, v95, v95
	v_mul_f32_e32 v89, 0xbdd2d3e8, v89
	v_add_f32_e32 v89, 0xc0135761, v89
	v_mul_f32_e32 v89, v95, v89
	v_exp_f32_e32 v89, v89
	s_nop 0
	v_add_f32_e32 v89, 1.0, v89
	v_rcp_f32_e32 v100, v89
	s_nop 0
	v_mul_f32_e32 v105, v95, v100
	s_nop 0
	s_nop 0
	v_mul_f32_e32 v89, v90, v90
	v_mul_f32_e32 v89, 0xbdd2d3e8, v89
	v_add_f32_e32 v89, 0xc0135761, v89
	v_mul_f32_e32 v89, v90, v89
	v_exp_f32_e32 v89, v89
	s_nop 0
	v_add_f32_e32 v89, 1.0, v89
	v_rcp_f32_e32 v100, v89
	s_nop 0
	v_mul_f32_e32 v106, v90, v100
	s_nop 0
	s_nop 0
	v_mul_f32_e32 v89, v91, v91
	v_mul_f32_e32 v89, 0xbdd2d3e8, v89
	v_add_f32_e32 v89, 0xc0135761, v89
	v_mul_f32_e32 v89, v91, v89
	v_exp_f32_e32 v89, v89
	s_nop 0
	v_add_f32_e32 v89, 1.0, v89
	v_rcp_f32_e32 v100, v89
	s_nop 0
	v_mul_f32_e32 v107, v91, v100
	v_ashrrev_i32_e32 v89, 31, v88
	v_lshlrev_b64 v[100:101], 10, v[88:89]
	v_lshl_add_u64 v[100:101], s[36:37], 0, v[100:101]
	v_lshl_add_u64 v[100:101], s[8:9], 1, v[100:101]
	v_lshl_add_u64 v[100:101], v[100:101], 0, v[136:137]
	global_store_dwordx4 v[100:101], v[80:83], off offset:-2560
	s_nop 1
	v_cvt_pk_bf16_f32 v80, v98, v99
	v_cvt_pk_bf16_f32 v81, v102, v103
	v_cvt_pk_bf16_f32 v82, v104, v105
	v_cvt_pk_bf16_f32 v83, v106, v107
	global_store_dwordx4 v[100:101], v[80:83], off offset:-2496

; __device__ __forceinline__ float gelu_tanh(float x) {
;     const float u = 0.7978845608028654f * (x + 0.044715f * x * x * x);
;     return x / (1.f + __expf(-2.f * u));
; }
;     __device__ __forceinline__ void operator()(const f32x4 (&acc)[2][2][4][2], const pg8::Unit& u, int wr, int wc, int fr, int fq) const {
;     ...
;                 } else if (cs < 36) {
;                     const int g = cs - 28;
;                     float y[16];
; #pragma unroll
;                     for (int i = 0; i < 16; ++i) y[i] = gelu_tanh(v[i]);
;                     const float rn = rsqrtf(head_ssq(y) * (1.f / 64.f) + EPS);
.LBB0_269:
	s_andn2_b64 vcc, exec, s[72:73]
	s_mov_b64 s[54:55], -1
	s_cbranch_vccnz .LBB0_285
	s_andn2_b64 vcc, exec, s[70:71]
	s_cbranch_vccnz .LBB0_282
	s_andn2_b64 vcc, exec, s[42:43]
	s_cbranch_vccnz .LBB0_279
	s_andn2_b64 vcc, exec, s[40:41]
	s_cbranch_vccnz .LBB0_274
	s_ashr_i32 s53, s52, 31
	s_lshl_b64 s[56:57], s[52:53], 21
	v_readlane_b32 s36, v254, 33
	s_mov_b64 s[58:59], s[42:43]
	v_mul_f32_e32 v64, v93, v93
	v_mul_f32_e32 v64, 0xbdd2d3e8, v64
	v_add_f32_e32 v64, 0xc0135761, v64
	v_mul_f32_e32 v64, v93, v64
	v_exp_f32_e32 v64, v64
	s_nop 0
	v_add_f32_e32 v64, 1.0, v64
	v_rcp_f32_e32 v65, v64
	s_nop 0
	v_mul_f32_e32 v64, v93, v65
	s_nop 0
	s_nop 0
	v_mul_f32_e32 v65, v94, v94
	v_mul_f32_e32 v65, 0xbdd2d3e8, v65
	v_add_f32_e32 v65, 0xc0135761, v65
	v_mul_f32_e32 v65, v94, v65
	v_exp_f32_e32 v65, v65
	s_nop 0
	v_add_f32_e32 v65, 1.0, v65
	v_rcp_f32_e32 v66, v65
	s_nop 0
	v_mul_f32_e32 v81, v94, v66
	s_nop 0
	s_nop 0
	v_mul_f32_e32 v65, v95, v95
	v_mul_f32_e32 v65, 0xbdd2d3e8, v65
	v_add_f32_e32 v65, 0xc0135761, v65
	v_mul_f32_e32 v65, v95, v65
	v_exp_f32_e32 v65, v65
	s_nop 0
	v_add_f32_e32 v65, 1.0, v65
	v_rcp_f32_e32 v66, v65
	s_nop 0
	v_mul_f32_e32 v101, v95, v66
	s_nop 0
	s_nop 0
	v_mul_f32_e32 v65, v96, v96
	v_mul_f32_e32 v65, 0xbdd2d3e8, v65
	v_add_f32_e32 v65, 0xc0135761, v65
	v_mul_f32_e32 v65, v96, v65
	v_exp_f32_e32 v65, v65
	s_nop 0
	v_add_f32_e32 v65, 1.0, v65
	v_rcp_f32_e32 v66, v65
	s_nop 0
	v_mul_f32_e32 v102, v96, v66
	s_nop 0
	s_nop 0
	v_mul_f32_e32 v65, v97, v97
	v_mul_f32_e32 v65, 0xbdd2d3e8, v65
	v_add_f32_e32 v65, 0xc0135761, v65
	v_mul_f32_e32 v65, v97, v65
	v_exp_f32_e32 v65, v65
	s_nop 0
	v_add_f32_e32 v65, 1.0, v65
	v_rcp_f32_e32 v66, v65
	s_nop 0
	v_mul_f32_e32 v103, v97, v66
	s_nop 0
	s_nop 0
	v_mul_f32_e32 v65, v98, v98
	v_mul_f32_e32 v65, 0xbdd2d3e8, v65
	v_add_f32_e32 v65, 0xc0135761, v65
	v_mul_f32_e32 v65, v98, v65
	v_exp_f32_e32 v65, v65
	s_nop 0
	v_add_f32_e32 v65, 1.0, v65
	v_rcp_f32_e32 v66, v65
	s_nop 0
	v_mul_f32_e32 v104, v98, v66
	s_nop 0
	s_nop 0
	v_mul_f32_e32 v65, v99, v99
	v_mul_f32_e32 v65, 0xbdd2d3e8, v65
	v_add_f32_e32 v65, 0xc0135761, v65
	v_mul_f32_e32 v65, v99, v65
	v_exp_f32_e32 v65, v65
	s_nop 0
	v_add_f32_e32 v65, 1.0, v65
	v_rcp_f32_e32 v66, v65
	s_nop 0
	v_mul_f32_e32 v105, v99, v66
	s_nop 0
	s_nop 0
	v_mul_f32_e32 v65, v100, v100
	v_mul_f32_e32 v65, 0xbdd2d3e8, v65
	v_add_f32_e32 v65, 0xc0135761, v65
	v_mul_f32_e32 v65, v100, v65
	v_exp_f32_e32 v65, v65
	s_nop 0
	v_add_f32_e32 v65, 1.0, v65
	v_rcp_f32_e32 v66, v65
	s_nop 0
	v_mul_f32_e32 v106, v100, v66
	v_mul_f32_e32 v67, v85, v85
	v_mul_f32_e32 v67, 0xbdd2d3e8, v67
	v_add_f32_e32 v67, 0xc0135761, v67
	v_mul_f32_e32 v67, v85, v67
	v_exp_f32_e32 v67, v67
	s_nop 0
	v_add_f32_e32 v67, 1.0, v67
	v_rcp_f32_e32 v72, v67
	s_nop 0
	v_mul_f32_e32 v73, v85, v72
	v_mul_f32_e32 v65, v81, v81
	v_fmac_f32_e32 v65, v64, v64
	v_fmac_f32_e32 v65, v101, v101
	v_fmac_f32_e32 v65, v102, v102
	v_fmac_f32_e32 v65, v103, v103
	v_fmac_f32_e32 v65, v104, v104
	v_fmac_f32_e32 v65, v105, v105
	v_mul_f32_e32 v66, v84, v84
	v_mul_f32_e32 v66, 0xbdd2d3e8, v66
	v_add_f32_e32 v66, 0xc0135761, v66
	v_mul_f32_e32 v66, v84, v66
	v_exp_f32_e32 v66, v66
	s_nop 0
	v_add_f32_e32 v66, 1.0, v66
	v_rcp_f32_e32 v67, v66
	s_nop 0
	v_mul_f32_e32 v72, v84, v67
	v_fmac_f32_e32 v65, v106, v106
	v_pk_mul_f32 v[66:67], v[72:73], v[72:73]
	s_nop 0
	v_add_f32_e32 v65, v66, v65
	v_add_f32_e32 v65, v67, v65
	s_nop 0
	s_nop 0
	v_mul_f32_e32 v67, v89, v89
	v_mul_f32_e32 v67, 0xbdd2d3e8, v67
	v_add_f32_e32 v67, 0xc0135761, v67
	v_mul_f32_e32 v67, v89, v67
	v_exp_f32_e32 v67, v67
	s_nop 0
	v_add_f32_e32 v67, 1.0, v67
	v_rcp_f32_e32 v68, v67
	s_nop 0
	v_mul_f32_e32 v75, v89, v68
	s_nop 0
	v_mul_f32_e32 v66, v88, v88
	v_mul_f32_e32 v66, 0xbdd2d3e8, v66
	v_add_f32_e32 v66, 0xc0135761, v66
	v_mul_f32_e32 v66, v88, v66
	v_exp_f32_e32 v66, v66
	s_nop 0
	v_add_f32_e32 v66, 1.0, v66
	v_rcp_f32_e32 v67, v66
	s_nop 0
	v_mul_f32_e32 v74, v88, v67
	v_pk_mul_f32 v[66:67], v[74:75], v[74:75]
	s_nop 0
	v_add_f32_e32 v65, v66, v65
	v_add_f32_e32 v65, v67, v65
	s_nop 0
	s_nop 0
	v_mul_f32_e32 v67, v87, v87
	v_mul_f32_e32 v67, 0xbdd2d3e8, v67
	v_add_f32_e32 v67, 0xc0135761, v67
	v_mul_f32_e32 v67, v87, v67
	v_exp_f32_e32 v67, v67
	s_nop 0
	v_add_f32_e32 v67, 1.0, v67
	v_rcp_f32_e32 v68, v67
	s_nop 0
	v_mul_f32_e32 v77, v87, v68
	s_nop 0
	v_mul_f32_e32 v66, v86, v86
	v_mul_f32_e32 v66, 0xbdd2d3e8, v66
	v_add_f32_e32 v66, 0xc0135761, v66
	v_mul_f32_e32 v66, v86, v66
	v_exp_f32_e32 v66, v66
	s_nop 0
	v_add_f32_e32 v66, 1.0, v66
	v_rcp_f32_e32 v67, v66
	s_nop 0
	v_mul_f32_e32 v76, v86, v67
	v_pk_mul_f32 v[66:67], v[76:77], v[76:77]
	s_nop 0
	v_add_f32_e32 v65, v66, v65
	v_add_f32_e32 v65, v67, v65
	s_nop 0
	s_nop 0
	v_mul_f32_e32 v67, v83, v83
	v_mul_f32_e32 v67, 0xbdd2d3e8, v67
	v_add_f32_e32 v67, 0xc0135761, v67
	v_mul_f32_e32 v67, v83, v67
	v_exp_f32_e32 v67, v67
	s_nop 0
	v_add_f32_e32 v67, 1.0, v67
	v_rcp_f32_e32 v68, v67
	s_nop 0
	v_mul_f32_e32 v79, v83, v68
	s_lshr_b32 s54, s89, 4
	s_and_b32 s54, s54, 0x78
	s_add_i32 s54, s54, s29
	v_mul_f32_e32 v66, v82, v82
	v_mul_f32_e32 v66, 0xbdd2d3e8, v66
	v_add_f32_e32 v66, 0xc0135761, v66
	v_mul_f32_e32 v66, v82, v66
	v_exp_f32_e32 v66, v66
	s_nop 0
	v_add_f32_e32 v66, 1.0, v66
	v_rcp_f32_e32 v67, v66
	s_nop 0
	v_mul_f32_e32 v78, v82, v67
	v_pk_mul_f32 v[66:67], v[78:79], v[78:79]
	s_mov_b32 s55, s9
	v_add_f32_e32 v65, v66, v65
	v_add_f32_e32 v65, v67, v65
	v_and_b32_e32 v67, 64, v165
	v_xor_b32_e32 v66, 16, v165
	v_add_u32_e32 v67, 64, v67
	v_cmp_lt_i32_e32 vcc, v66, v67
	s_lshl_b64 s[54:55], s[54:55], 14
	s_add_u32 s53, s36, s56
	v_cndmask_b32_e32 v66, v165, v66, vcc
	v_lshlrev_b32_e32 v66, 2, v66
	ds_bpermute_b32 v66, v66, v65
	v_readlane_b32 s36, v254, 35
	s_addc_u32 s56, s36, s57
	s_add_u32 s54, s53, s54
	s_addc_u32 s55, s56, s55
	s_waitcnt lgkmcnt(0)
; __device__ __forceinline__ unsigned f2bf(float f) { unsigned u = __float_as_uint(f); return (u + 0x7fffu + ((u >> 16) & 1u)) >> 16; }
; __device__ __forceinline__ float head_ssq(const float (&v)[16]) {
;     ...
;     s += __shfl_xor(s, 16); s += __shfl_xor(s, 32);
;     __device__ __forceinline__ void operator()(const f32x4 (&acc)[2][2][4][2], const pg8::Unit& u, int wr, int wc, int fr, int fq) const {
;     ...
;                     const float rn = rsqrtf(head_ssq(y) * (1.f / 64.f) + EPS);
;                     bf16_t* p = zvT + (((size_t)b * 16 + (s >> 7)) * 8 + g) * 8192 + (s & 127);
; #pragma unroll
;                     for (int i = 0; i < 16; ++i) { const int d = 32 * (i >> 3) + d0 + (i & 7); p[d * 128] = (bf16_t)f2bf(y[i] * rn * g_sgu[g * 64 + d]); }
	v_add_f32_e32 v65, v65, v66
	v_xor_b32_e32 v66, 32, v165
	v_cmp_lt_i32_e32 vcc, v66, v67
	s_mov_b64 s[56:57], s[40:41]
	s_nop 0
	v_cndmask_b32_e32 v66, v165, v66, vcc
	v_lshlrev_b32_e32 v66, 2, v66
	ds_bpermute_b32 v66, v66, v65
	s_waitcnt lgkmcnt(0)
	v_add_f32_e32 v65, v65, v66
	v_fmamk_f32 v65, v65, 0x3c800000, v161
	v_cmp_gt_f32_e32 vcc, s61, v65
	v_mul_f32_e32 v66, 0x4b800000, v65
	s_nop 0
	v_cndmask_b32_e32 v65, v65, v66, vcc
	v_rsq_f32_e32 v65, v65
	s_nop 0
	v_mul_f32_e32 v66, 0x45800000, v65
	v_cndmask_b32_e32 v107, v65, v66, vcc
	v_and_b32_e32 v65, 0x7f, v80
	v_lshlrev_b32_e32 v136, 1, v65
	v_lshl_add_u64 v[90:91], s[54:55], 0, v[136:137]
	s_mov_b64 s[54:55], s[38:39]
	v_readlane_b32 s36, v254, 8
	v_or_b32_e32 v136, s27, v140
	v_readlane_b32 s37, v254, 9
	v_mul_f32_e32 v108, v64, v107
	v_mul_f32_e32 v72, v72, v107
	v_lshl_add_u64 v[68:69], v[136:137], 2, s[36:37]
	global_load_dwordx4 v[64:67], v[68:69], off offset:16
	s_nop 0
	global_load_dwordx4 v[68:71], v[68:69], off
	v_lshlrev_b32_e32 v136, 1, v142
	v_readlane_b32 s50, v254, 22
	v_readlane_b32 s51, v254, 23
	v_readlane_b32 s38, v254, 10
	v_readlane_b32 s39, v254, 11
	v_readlane_b32 s40, v254, 12
	v_readlane_b32 s41, v254, 13
	v_readlane_b32 s42, v254, 14
	v_readlane_b32 s43, v254, 15
	v_readlane_b32 s49, v254, 21
	v_readlane_b32 s50, v254, 39
	s_mov_b64 s[38:39], s[54:55]
	s_mov_b64 s[42:43], s[58:59]
	s_mov_b64 s[40:41], s[56:57]
	v_readlane_b32 s49, v254, 41
	v_readlane_b32 s51, v254, 40
	s_mov_b64 s[54:55], 0
	v_readlane_b32 s44, v254, 16
	v_readlane_b32 s45, v254, 17
	v_readlane_b32 s46, v254, 18
	v_readlane_b32 s47, v254, 19
	v_readlane_b32 s48, v254, 20
	s_waitcnt vmcnt(0)
	v_mul_f32_e32 v68, v68, v108
	v_bfe_u32 v108, v68, 16, 1
	v_add3_u32 v68, v68, v108, s20
	v_lshl_add_u64 v[108:109], v[90:91], 0, v[136:137]
	global_store_short_d16_hi v[108:109], v68, off
	v_mul_f32_e32 v68, v81, v107
	v_add_u32_e32 v136, s27, v140
	v_mul_f32_e32 v68, v69, v68
	v_lshl_add_u64 v[108:109], v[136:137], 2, s[36:37]
	v_bfe_u32 v69, v68, 16, 1
	v_lshlrev_b32_e32 v136, 1, v144
	v_add3_u32 v81, v68, v69, s20
	v_lshl_add_u64 v[68:69], v[90:91], 0, v[136:137]
	global_store_short_d16_hi v[68:69], v81, off
	v_mul_f32_e32 v68, v101, v107
	v_mul_f32_e32 v68, v70, v68
	v_bfe_u32 v69, v68, 16, 1
	v_lshlrev_b32_e32 v136, 1, v146
	v_add3_u32 v70, v68, v69, s20
	v_lshl_add_u64 v[68:69], v[90:91], 0, v[136:137]
	global_store_short_d16_hi v[68:69], v70, off
	v_mul_f32_e32 v68, v102, v107
	v_mul_f32_e32 v68, v71, v68
	v_bfe_u32 v69, v68, 16, 1
	v_lshlrev_b32_e32 v136, 1, v148
	v_add3_u32 v70, v68, v69, s20
	v_lshl_add_u64 v[68:69], v[90:91], 0, v[136:137]
	global_store_short_d16_hi v[68:69], v70, off
	v_mul_f32_e32 v68, v103, v107
	v_mul_f32_e32 v64, v64, v68
	v_bfe_u32 v68, v64, 16, 1
	v_lshlrev_b32_e32 v136, 1, v150
	v_add3_u32 v64, v64, v68, s20
	v_lshl_add_u64 v[68:69], v[90:91], 0, v[136:137]
	global_store_short_d16_hi v[68:69], v64, off
	v_mul_f32_e32 v64, v104, v107
	v_mul_f32_e32 v64, v64, v65
	v_bfe_u32 v65, v64, 16, 1
	v_lshlrev_b32_e32 v136, 1, v152
	v_add3_u32 v68, v64, v65, s20
	v_lshl_add_u64 v[64:65], v[90:91], 0, v[136:137]
	global_store_short_d16_hi v[64:65], v68, off
	v_mul_f32_e32 v64, v105, v107
	v_mul_f32_e32 v64, v64, v66
	v_bfe_u32 v65, v64, 16, 1
	v_lshlrev_b32_e32 v136, 1, v154
	v_add3_u32 v66, v64, v65, s20
	v_lshl_add_u64 v[64:65], v[90:91], 0, v[136:137]
	global_store_short_d16_hi v[64:65], v66, off
	v_mul_f32_e32 v64, v106, v107
	v_mul_f32_e32 v64, v64, v67
	v_bfe_u32 v65, v64, 16, 1
	v_lshlrev_b32_e32 v136, 1, v156
	v_add3_u32 v66, v64, v65, s20
	v_lshl_add_u64 v[64:65], v[90:91], 0, v[136:137]
	global_store_short_d16_hi v[64:65], v66, off
	global_load_dwordx4 v[64:67], v[108:109], off offset:144
	s_nop 0
	global_load_dwordx4 v[68:71], v[108:109], off offset:128
	v_lshlrev_b32_e32 v136, 1, v158
	v_lshl_add_u64 v[102:103], v[90:91], 0, v[136:137]
	v_lshlrev_b32_e32 v136, 1, v160
	s_waitcnt vmcnt(0)
	v_mul_f32_e32 v68, v72, v68
	v_bfe_u32 v72, v68, 16, 1
	v_add3_u32 v68, v68, v72, s20
	global_store_short_d16_hi v[102:103], v68, off
	v_mul_f32_e32 v68, v73, v107
	v_mul_f32_e32 v68, v68, v69
	v_bfe_u32 v69, v68, 16, 1
	v_add3_u32 v72, v68, v69, s20
	v_lshl_add_u64 v[68:69], v[90:91], 0, v[136:137]
	global_store_short_d16_hi v[68:69], v72, off
	v_mul_f32_e32 v68, v74, v107
	v_mul_f32_e32 v68, v68, v70
	v_bfe_u32 v69, v68, 16, 1
	v_lshlrev_b32_e32 v136, 1, v162
	v_add3_u32 v70, v68, v69, s20
	v_lshl_add_u64 v[68:69], v[90:91], 0, v[136:137]
	global_store_short_d16_hi v[68:69], v70, off
	v_mul_f32_e32 v68, v75, v107
	v_mul_f32_e32 v68, v68, v71
	v_bfe_u32 v69, v68, 16, 1
	v_lshlrev_b32_e32 v136, 1, v164
	v_add3_u32 v70, v68, v69, s20
	v_lshl_add_u64 v[68:69], v[90:91], 0, v[136:137]
	global_store_short_d16_hi v[68:69], v70, off
	v_mul_f32_e32 v68, v76, v107
	v_mul_f32_e32 v64, v68, v64
	v_bfe_u32 v68, v64, 16, 1
	v_add3_u32 v64, v64, v68, s20
	v_or_b32_e32 v68, 0x1200, v142
	v_lshlrev_b32_e32 v136, 1, v68
	v_lshl_add_u64 v[68:69], v[90:91], 0, v[136:137]
	global_store_short_d16_hi v[68:69], v64, off
	v_mul_f32_e32 v64, v77, v107
	v_mul_f32_e32 v64, v64, v65
	v_bfe_u32 v65, v64, 16, 1
	v_add3_u32 v68, v64, v65, s20
	v_or_b32_e32 v64, 0x1280, v142
	v_lshlrev_b32_e32 v136, 1, v64
	v_lshl_add_u64 v[64:65], v[90:91], 0, v[136:137]
	global_store_short_d16_hi v[64:65], v68, off
	v_mul_f32_e32 v64, v78, v107
	v_mul_f32_e32 v64, v64, v66
	v_bfe_u32 v65, v64, 16, 1
	v_add3_u32 v66, v64, v65, s20
	v_or_b32_e32 v64, 0x1300, v142
	v_lshlrev_b32_e32 v136, 1, v64
	v_lshl_add_u64 v[64:65], v[90:91], 0, v[136:137]
	global_store_short_d16_hi v[64:65], v66, off
	v_mul_f32_e32 v64, v79, v107
	v_mul_f32_e32 v64, v64, v67
	v_bfe_u32 v65, v64, 16, 1
	v_lshlrev_b32_e32 v136, 1, v172
	v_add3_u32 v66, v64, v65, s20
	v_lshl_add_u64 v[64:65], v[90:91], 0, v[136:137]
	global_store_short_d16_hi v[64:65], v66, off

; __device__ __forceinline__ float gelu_tanh(float x) {
;     const float u = 0.7978845608028654f * (x + 0.044715f * x * x * x);
;     return x / (1.f + __expf(-2.f * u));
; }
;     __device__ __forceinline__ void operator()(const f32x4 (&acc)[2][2][4][2], const pg8::Unit& u, int wr, int wc, int fr, int fq) const {
;     ...
;                 } else if (cs < 28) {
;                     float y[16];
; #pragma unroll
;                     for (int i = 0; i < 16; ++i) y[i] = gelu_tanh(v[i]);
;                     bf16_t* p = zu + (size_t)row * 512 + (cs - 20) * 64 + d0; store8(p, y); store8(p + 32, y + 8);
.LBB0_279:
	s_andn2_b64 vcc, exec, s[54:55]
	s_cbranch_vccnz .LBB0_281
	v_readlane_b32 s36, v254, 31
	v_readlane_b32 s37, v254, 32
	v_lshlrev_b32_e32 v136, 1, v140
	s_nop 0
	v_mul_f32_e32 v64, v93, v93
	v_mul_f32_e32 v64, 0xbdd2d3e8, v64
	v_add_f32_e32 v64, 0xc0135761, v64
	v_mul_f32_e32 v64, v93, v64
	v_exp_f32_e32 v64, v64
	s_nop 0
	v_add_f32_e32 v64, 1.0, v64
	v_rcp_f32_e32 v65, v64
	s_nop 0
	v_mul_f32_e32 v64, v93, v65
	s_nop 0
	s_nop 0
	v_mul_f32_e32 v65, v94, v94
	v_mul_f32_e32 v65, 0xbdd2d3e8, v65
	v_add_f32_e32 v65, 0xc0135761, v65
	v_mul_f32_e32 v65, v94, v65
	v_exp_f32_e32 v65, v65
	s_nop 0
	v_add_f32_e32 v65, 1.0, v65
	v_rcp_f32_e32 v66, v65
	s_nop 0
	v_mul_f32_e32 v65, v94, v66
	v_cvt_pk_bf16_f32 v64, v64, v65
	s_nop 0
	s_nop 0
	v_mul_f32_e32 v66, v95, v95
	v_mul_f32_e32 v66, 0xbdd2d3e8, v66
	v_add_f32_e32 v66, 0xc0135761, v66
	v_mul_f32_e32 v66, v95, v66
	v_exp_f32_e32 v66, v66
	s_nop 0
	v_add_f32_e32 v66, 1.0, v66
	v_rcp_f32_e32 v67, v66
	s_nop 0
	v_mul_f32_e32 v66, v95, v67
	s_nop 0
	s_nop 0
	v_mul_f32_e32 v67, v96, v96
	v_mul_f32_e32 v67, 0xbdd2d3e8, v67
	v_add_f32_e32 v67, 0xc0135761, v67
	v_mul_f32_e32 v67, v96, v67
	v_exp_f32_e32 v67, v67
	s_nop 0
	v_add_f32_e32 v67, 1.0, v67
	v_rcp_f32_e32 v68, v67
	s_nop 0
	v_mul_f32_e32 v67, v96, v68
	v_cvt_pk_bf16_f32 v65, v66, v67
	s_nop 0
	s_nop 0
	v_mul_f32_e32 v68, v97, v97
	v_mul_f32_e32 v68, 0xbdd2d3e8, v68
	v_add_f32_e32 v68, 0xc0135761, v68
	v_mul_f32_e32 v68, v97, v68
	v_exp_f32_e32 v68, v68
	s_nop 0
	v_add_f32_e32 v68, 1.0, v68
	v_rcp_f32_e32 v69, v68
	s_nop 0
	v_mul_f32_e32 v68, v97, v69
	s_nop 0
	s_nop 0
	v_mul_f32_e32 v69, v98, v98
	v_mul_f32_e32 v69, 0xbdd2d3e8, v69
	v_add_f32_e32 v69, 0xc0135761, v69
	v_mul_f32_e32 v69, v98, v69
	v_exp_f32_e32 v69, v69
	s_nop 0
	v_add_f32_e32 v69, 1.0, v69
	v_rcp_f32_e32 v70, v69
	s_nop 0
	v_mul_f32_e32 v69, v98, v70
	v_cvt_pk_bf16_f32 v66, v68, v69
	s_nop 0
	s_nop 0
	v_mul_f32_e32 v70, v99, v99
	v_mul_f32_e32 v70, 0xbdd2d3e8, v70
	v_add_f32_e32 v70, 0xc0135761, v70
	v_mul_f32_e32 v70, v99, v70
	v_exp_f32_e32 v70, v70
	s_nop 0
	v_add_f32_e32 v70, 1.0, v70
	v_rcp_f32_e32 v71, v70
	s_nop 0
	v_mul_f32_e32 v70, v99, v71
	s_nop 0
	s_nop 0
	v_mul_f32_e32 v71, v100, v100
	v_mul_f32_e32 v71, 0xbdd2d3e8, v71
	v_add_f32_e32 v71, 0xc0135761, v71
	v_mul_f32_e32 v71, v100, v71
	v_exp_f32_e32 v71, v71
	s_nop 0
	v_add_f32_e32 v71, 1.0, v71
	v_rcp_f32_e32 v72, v71
	s_nop 0
	v_mul_f32_e32 v71, v100, v72
	v_cvt_pk_bf16_f32 v67, v70, v71
	s_nop 0
	s_nop 0
	v_mul_f32_e32 v72, v84, v84
	v_mul_f32_e32 v72, 0xbdd2d3e8, v72
	v_add_f32_e32 v72, 0xc0135761, v72
	v_mul_f32_e32 v72, v84, v72
	v_exp_f32_e32 v72, v72
	s_nop 0
	v_add_f32_e32 v72, 1.0, v72
	v_rcp_f32_e32 v73, v72
	s_nop 0
	v_mul_f32_e32 v72, v84, v73
	s_nop 0
	s_nop 0
	v_mul_f32_e32 v73, v85, v85
	v_mul_f32_e32 v73, 0xbdd2d3e8, v73
	v_add_f32_e32 v73, 0xc0135761, v73
	v_mul_f32_e32 v73, v85, v73
	v_exp_f32_e32 v73, v73
	s_nop 0
	v_add_f32_e32 v73, 1.0, v73
	v_rcp_f32_e32 v74, v73
	s_nop 0
	v_mul_f32_e32 v73, v85, v74
	s_nop 0
	s_nop 0
	v_mul_f32_e32 v74, v88, v88
	v_mul_f32_e32 v74, 0xbdd2d3e8, v74
	v_add_f32_e32 v74, 0xc0135761, v74
	v_mul_f32_e32 v74, v88, v74
	v_exp_f32_e32 v74, v74
	s_nop 0
	v_add_f32_e32 v74, 1.0, v74
	v_rcp_f32_e32 v75, v74
	s_nop 0
	v_mul_f32_e32 v76, v88, v75
	s_nop 0
	s_nop 0
	v_mul_f32_e32 v74, v89, v89
	v_mul_f32_e32 v74, 0xbdd2d3e8, v74
	v_add_f32_e32 v74, 0xc0135761, v74
	v_mul_f32_e32 v74, v89, v74
	v_exp_f32_e32 v74, v74
	s_nop 0
	v_add_f32_e32 v74, 1.0, v74
	v_rcp_f32_e32 v75, v74
	s_nop 0
	v_mul_f32_e32 v77, v89, v75
	s_nop 0
	s_nop 0
	v_mul_f32_e32 v74, v86, v86
	v_mul_f32_e32 v74, 0xbdd2d3e8, v74
	v_add_f32_e32 v74, 0xc0135761, v74
	v_mul_f32_e32 v74, v86, v74
	v_exp_f32_e32 v74, v74
	s_nop 0
	v_add_f32_e32 v74, 1.0, v74
	v_rcp_f32_e32 v75, v74
	s_nop 0
	v_mul_f32_e32 v78, v86, v75
	s_nop 0
	s_nop 0
	v_mul_f32_e32 v74, v87, v87
	v_mul_f32_e32 v74, 0xbdd2d3e8, v74
	v_add_f32_e32 v74, 0xc0135761, v74
	v_mul_f32_e32 v74, v87, v74
	v_exp_f32_e32 v74, v74
	s_nop 0
	v_add_f32_e32 v74, 1.0, v74
	v_rcp_f32_e32 v75, v74
	s_nop 0
	v_mul_f32_e32 v79, v87, v75
	s_nop 0
	s_nop 0
	v_mul_f32_e32 v74, v82, v82
	v_mul_f32_e32 v74, 0xbdd2d3e8, v74
	v_add_f32_e32 v74, 0xc0135761, v74
	v_mul_f32_e32 v74, v82, v74
	v_exp_f32_e32 v74, v74
	s_nop 0
	v_add_f32_e32 v74, 1.0, v74
	v_rcp_f32_e32 v75, v74
	s_nop 0
	v_mul_f32_e32 v90, v82, v75
	s_nop 0
	s_nop 0
	v_ashrrev_i32_e32 v81, 31, v80
	v_mul_f32_e32 v74, v83, v83
	v_mul_f32_e32 v74, 0xbdd2d3e8, v74
	v_add_f32_e32 v74, 0xc0135761, v74
	v_mul_f32_e32 v74, v83, v74
	v_exp_f32_e32 v74, v74
	s_nop 0
	v_add_f32_e32 v74, 1.0, v74
	v_rcp_f32_e32 v75, v74
	s_nop 0
	v_mul_f32_e32 v91, v83, v75
	v_lshlrev_b64 v[74:75], 10, v[80:81]
	v_lshl_add_u64 v[74:75], s[36:37], 0, v[74:75]
	v_lshl_add_u64 v[74:75], s[8:9], 1, v[74:75]
	v_lshl_add_u64 v[74:75], v[74:75], 0, v[136:137]
	global_store_dwordx4 v[74:75], v[64:67], off offset:-2560
	s_nop 1
	v_cvt_pk_bf16_f32 v64, v72, v73
	v_cvt_pk_bf16_f32 v65, v76, v77
	v_cvt_pk_bf16_f32 v66, v78, v79
	v_cvt_pk_bf16_f32 v67, v90, v91
	global_store_dwordx4 v[74:75], v[64:67], off offset:-2496

; __device__ __forceinline__ float gelu_tanh(float x) {
;     const float u = 0.7978845608028654f * (x + 0.044715f * x * x * x);
;     return x / (1.f + __expf(-2.f * u));
; }
;     __device__ __forceinline__ void operator()(const f32x4 (&acc)[2][2][4][2], const pg8::Unit& u, int wr, int wc, int fr, int fq) const {
;     ...
;                 } else if (cs < 36) {
;                     const int g = cs - 28;
;                     float y[16];
; #pragma unroll
;                     for (int i = 0; i < 16; ++i) y[i] = gelu_tanh(v[i]);
;                     const float rn = rsqrtf(head_ssq(y) * (1.f / 64.f) + EPS);
.LBB0_302:
	s_andn2_b64 vcc, exec, s[72:73]
	s_mov_b64 s[54:55], -1
	s_cbranch_vccnz .LBB0_318
	s_andn2_b64 vcc, exec, s[70:71]
	s_cbranch_vccnz .LBB0_315
	s_andn2_b64 vcc, exec, s[42:43]
	s_cbranch_vccnz .LBB0_312
	s_andn2_b64 vcc, exec, s[40:41]
	s_cbranch_vccnz .LBB0_307
	s_ashr_i32 s53, s52, 31
	s_lshl_b64 s[56:57], s[52:53], 21
	v_readlane_b32 s36, v254, 33
	s_mov_b64 s[58:59], s[42:43]
	v_mul_f32_e32 v48, v77, v77
	v_mul_f32_e32 v48, 0xbdd2d3e8, v48
	v_add_f32_e32 v48, 0xc0135761, v48
	v_mul_f32_e32 v48, v77, v48
	v_exp_f32_e32 v48, v48
	s_nop 0
	v_add_f32_e32 v48, 1.0, v48
	v_rcp_f32_e32 v49, v48
	s_nop 0
	v_mul_f32_e32 v48, v77, v49
	s_nop 0
	s_nop 0
	v_mul_f32_e32 v49, v78, v78
	v_mul_f32_e32 v49, 0xbdd2d3e8, v49
	v_add_f32_e32 v49, 0xc0135761, v49
	v_mul_f32_e32 v49, v78, v49
	v_exp_f32_e32 v49, v49
	s_nop 0
	v_add_f32_e32 v49, 1.0, v49
	v_rcp_f32_e32 v50, v49
	s_nop 0
	v_mul_f32_e32 v57, v78, v50
	s_nop 0
	s_nop 0
	v_mul_f32_e32 v49, v79, v79
	v_mul_f32_e32 v49, 0xbdd2d3e8, v49
	v_add_f32_e32 v49, 0xc0135761, v49
	v_mul_f32_e32 v49, v79, v49
	v_exp_f32_e32 v49, v49
	s_nop 0
	v_add_f32_e32 v49, 1.0, v49
	v_rcp_f32_e32 v50, v49
	s_nop 0
	v_mul_f32_e32 v85, v79, v50
	s_nop 0
	s_nop 0
	v_mul_f32_e32 v49, v80, v80
	v_mul_f32_e32 v49, 0xbdd2d3e8, v49
	v_add_f32_e32 v49, 0xc0135761, v49
	v_mul_f32_e32 v49, v80, v49
	v_exp_f32_e32 v49, v49
	s_nop 0
	v_add_f32_e32 v49, 1.0, v49
	v_rcp_f32_e32 v50, v49
	s_nop 0
	v_mul_f32_e32 v86, v80, v50
	s_nop 0
	s_nop 0
	v_mul_f32_e32 v49, v81, v81
	v_mul_f32_e32 v49, 0xbdd2d3e8, v49
	v_add_f32_e32 v49, 0xc0135761, v49
	v_mul_f32_e32 v49, v81, v49
	v_exp_f32_e32 v49, v49
	s_nop 0
	v_add_f32_e32 v49, 1.0, v49
	v_rcp_f32_e32 v50, v49
	s_nop 0
	v_mul_f32_e32 v87, v81, v50
	s_nop 0
	s_nop 0
	v_mul_f32_e32 v49, v82, v82
	v_mul_f32_e32 v49, 0xbdd2d3e8, v49
	v_add_f32_e32 v49, 0xc0135761, v49
	v_mul_f32_e32 v49, v82, v49
	v_exp_f32_e32 v49, v49
	s_nop 0
	v_add_f32_e32 v49, 1.0, v49
	v_rcp_f32_e32 v50, v49
	s_nop 0
	v_mul_f32_e32 v88, v82, v50
	s_nop 0
	s_nop 0
	v_mul_f32_e32 v49, v83, v83
	v_mul_f32_e32 v49, 0xbdd2d3e8, v49
	v_add_f32_e32 v49, 0xc0135761, v49
	v_mul_f32_e32 v49, v83, v49
	v_exp_f32_e32 v49, v49
	s_nop 0
	v_add_f32_e32 v49, 1.0, v49
	v_rcp_f32_e32 v50, v49
	s_nop 0
	v_mul_f32_e32 v89, v83, v50
	s_nop 0
	s_nop 0
	v_mul_f32_e32 v49, v84, v84
	v_mul_f32_e32 v49, 0xbdd2d3e8, v49
	v_add_f32_e32 v49, 0xc0135761, v49
	v_mul_f32_e32 v49, v84, v49
	v_exp_f32_e32 v49, v49
	s_nop 0
	v_add_f32_e32 v49, 1.0, v49
	v_rcp_f32_e32 v50, v49
	s_nop 0
	v_mul_f32_e32 v90, v84, v50
	v_mul_f32_e32 v51, v61, v61
	v_mul_f32_e32 v51, 0xbdd2d3e8, v51
	v_add_f32_e32 v51, 0xc0135761, v51
	v_mul_f32_e32 v51, v61, v51
	v_exp_f32_e32 v51, v51
	s_nop 0
	v_add_f32_e32 v51, 1.0, v51
	v_rcp_f32_e32 v66, v51
	s_nop 0
	v_mul_f32_e32 v67, v61, v66
	v_mul_f32_e32 v49, v57, v57
	v_fmac_f32_e32 v49, v48, v48
	v_fmac_f32_e32 v49, v85, v85
	v_fmac_f32_e32 v49, v86, v86
	v_fmac_f32_e32 v49, v87, v87
	v_fmac_f32_e32 v49, v88, v88
	v_fmac_f32_e32 v49, v89, v89
	v_mul_f32_e32 v50, v60, v60
	v_mul_f32_e32 v50, 0xbdd2d3e8, v50
	v_add_f32_e32 v50, 0xc0135761, v50
	v_mul_f32_e32 v50, v60, v50
	v_exp_f32_e32 v50, v50
	s_nop 0
	v_add_f32_e32 v50, 1.0, v50
	v_rcp_f32_e32 v51, v50
	s_nop 0
	v_mul_f32_e32 v66, v60, v51
	v_fmac_f32_e32 v49, v90, v90
	v_pk_mul_f32 v[50:51], v[66:67], v[66:67]
	s_nop 0
	v_add_f32_e32 v49, v50, v49
	v_add_f32_e32 v49, v51, v49
	s_nop 0
	s_nop 0
	v_mul_f32_e32 v51, v65, v65
	v_mul_f32_e32 v51, 0xbdd2d3e8, v51
	v_add_f32_e32 v51, 0xc0135761, v51
	v_mul_f32_e32 v51, v65, v51
	v_exp_f32_e32 v51, v51
	s_nop 0
	v_add_f32_e32 v51, 1.0, v51
	v_rcp_f32_e32 v52, v51
	s_nop 0
	v_mul_f32_e32 v69, v65, v52
	s_nop 0
	v_mul_f32_e32 v50, v64, v64
	v_mul_f32_e32 v50, 0xbdd2d3e8, v50
	v_add_f32_e32 v50, 0xc0135761, v50
	v_mul_f32_e32 v50, v64, v50
	v_exp_f32_e32 v50, v50
	s_nop 0
	v_add_f32_e32 v50, 1.0, v50
	v_rcp_f32_e32 v51, v50
	s_nop 0
	v_mul_f32_e32 v68, v64, v51
	v_pk_mul_f32 v[50:51], v[68:69], v[68:69]
	s_nop 0
	v_add_f32_e32 v49, v50, v49
	v_add_f32_e32 v49, v51, v49
	s_nop 0
	s_nop 0
	v_mul_f32_e32 v51, v63, v63
	v_mul_f32_e32 v51, 0xbdd2d3e8, v51
	v_add_f32_e32 v51, 0xc0135761, v51
	v_mul_f32_e32 v51, v63, v51
	v_exp_f32_e32 v51, v51
	s_nop 0
	v_add_f32_e32 v51, 1.0, v51
	v_rcp_f32_e32 v52, v51
	s_nop 0
	v_mul_f32_e32 v71, v63, v52
	s_nop 0
	v_mul_f32_e32 v50, v62, v62
	v_mul_f32_e32 v50, 0xbdd2d3e8, v50
	v_add_f32_e32 v50, 0xc0135761, v50
	v_mul_f32_e32 v50, v62, v50
	v_exp_f32_e32 v50, v50
	s_nop 0
	v_add_f32_e32 v50, 1.0, v50
	v_rcp_f32_e32 v51, v50
	s_nop 0
	v_mul_f32_e32 v70, v62, v51
	v_pk_mul_f32 v[50:51], v[70:71], v[70:71]
	s_nop 0
	v_add_f32_e32 v49, v50, v49
	v_add_f32_e32 v49, v51, v49
	s_nop 0
	s_nop 0
	v_mul_f32_e32 v51, v59, v59
	v_mul_f32_e32 v51, 0xbdd2d3e8, v51
	v_add_f32_e32 v51, 0xc0135761, v51
	v_mul_f32_e32 v51, v59, v51
	v_exp_f32_e32 v51, v51
	s_nop 0
	v_add_f32_e32 v51, 1.0, v51
	v_rcp_f32_e32 v52, v51
	s_nop 0
	v_mul_f32_e32 v73, v59, v52
	s_lshr_b32 s54, s89, 4
	s_and_b32 s54, s54, 0x78
	s_add_i32 s54, s54, s29
	v_mul_f32_e32 v50, v58, v58
	v_mul_f32_e32 v50, 0xbdd2d3e8, v50
	v_add_f32_e32 v50, 0xc0135761, v50
	v_mul_f32_e32 v50, v58, v50
	v_exp_f32_e32 v50, v50
	s_nop 0
	v_add_f32_e32 v50, 1.0, v50
	v_rcp_f32_e32 v51, v50
	s_nop 0
	v_mul_f32_e32 v72, v58, v51
	v_pk_mul_f32 v[50:51], v[72:73], v[72:73]
	s_mov_b32 s55, s9
	v_add_f32_e32 v49, v50, v49
	v_add_f32_e32 v49, v51, v49
	v_and_b32_e32 v51, 64, v165
	v_xor_b32_e32 v50, 16, v165
	v_add_u32_e32 v51, 64, v51
	v_cmp_lt_i32_e32 vcc, v50, v51
	s_lshl_b64 s[54:55], s[54:55], 14
	s_add_u32 s53, s36, s56
	v_cndmask_b32_e32 v50, v165, v50, vcc
	v_lshlrev_b32_e32 v50, 2, v50
	ds_bpermute_b32 v50, v50, v49
	v_readlane_b32 s36, v254, 35
	s_addc_u32 s56, s36, s57
	s_add_u32 s54, s53, s54
	s_addc_u32 s55, s56, s55
	s_waitcnt lgkmcnt(0)
; __device__ __forceinline__ unsigned f2bf(float f) { unsigned u = __float_as_uint(f); return (u + 0x7fffu + ((u >> 16) & 1u)) >> 16; }
; __device__ __forceinline__ float head_ssq(const float (&v)[16]) {
;     ...
;     s += __shfl_xor(s, 16); s += __shfl_xor(s, 32);
;     __device__ __forceinline__ void operator()(const f32x4 (&acc)[2][2][4][2], const pg8::Unit& u, int wr, int wc, int fr, int fq) const {
;     ...
;                     const float rn = rsqrtf(head_ssq(y) * (1.f / 64.f) + EPS);
;                     bf16_t* p = zvT + (((size_t)b * 16 + (s >> 7)) * 8 + g) * 8192 + (s & 127);
; #pragma unroll
;                     for (int i = 0; i < 16; ++i) { const int d = 32 * (i >> 3) + d0 + (i & 7); p[d * 128] = (bf16_t)f2bf(y[i] * rn * g_sgu[g * 64 + d]); }
	v_add_f32_e32 v49, v49, v50
	v_xor_b32_e32 v50, 32, v165
	v_cmp_lt_i32_e32 vcc, v50, v51
	s_mov_b64 s[56:57], s[40:41]
	s_nop 0
	v_cndmask_b32_e32 v50, v165, v50, vcc
	v_lshlrev_b32_e32 v50, 2, v50
	ds_bpermute_b32 v50, v50, v49
	s_waitcnt lgkmcnt(0)
	v_add_f32_e32 v49, v49, v50
	v_fmamk_f32 v49, v49, 0x3c800000, v161
	v_cmp_gt_f32_e32 vcc, s61, v49
	v_mul_f32_e32 v50, 0x4b800000, v49
	s_nop 0
	v_cndmask_b32_e32 v49, v49, v50, vcc
	v_rsq_f32_e32 v49, v49
	s_nop 0
	v_mul_f32_e32 v50, 0x45800000, v49
	v_cndmask_b32_e32 v91, v49, v50, vcc
	v_and_b32_e32 v49, 0x4f, v56
	v_lshlrev_b32_e32 v136, 1, v49
	v_lshl_add_u64 v[74:75], s[54:55], 0, v[136:137]
	s_mov_b64 s[54:55], s[38:39]
	v_readlane_b32 s36, v254, 8
	v_or_b32_e32 v136, s27, v140
	v_readlane_b32 s37, v254, 9
	v_mul_f32_e32 v92, v48, v91
	v_readlane_b32 s50, v254, 22
	v_lshl_add_u64 v[52:53], v[136:137], 2, s[36:37]
	global_load_dwordx4 v[48:51], v[52:53], off offset:16
	s_nop 0
	global_load_dwordx4 v[52:55], v[52:53], off
	v_lshlrev_b32_e32 v136, 1, v142
	v_readlane_b32 s51, v254, 23
	v_readlane_b32 s38, v254, 10
	v_readlane_b32 s39, v254, 11
	v_readlane_b32 s40, v254, 12
	v_readlane_b32 s41, v254, 13
	v_readlane_b32 s42, v254, 14
	v_readlane_b32 s43, v254, 15
	v_readlane_b32 s49, v254, 21
	v_readlane_b32 s50, v254, 39
	s_mov_b64 s[38:39], s[54:55]
	s_mov_b64 s[42:43], s[58:59]
	s_mov_b64 s[40:41], s[56:57]
	v_readlane_b32 s49, v254, 41
	v_readlane_b32 s51, v254, 40
	s_mov_b64 s[54:55], 0
	v_readlane_b32 s44, v254, 16
	v_readlane_b32 s45, v254, 17
	v_readlane_b32 s46, v254, 18
	v_readlane_b32 s47, v254, 19
	v_readlane_b32 s48, v254, 20
	s_waitcnt vmcnt(0)
	v_mul_f32_e32 v52, v52, v92
	v_bfe_u32 v92, v52, 16, 1
	v_add3_u32 v52, v52, v92, s20
	v_lshl_add_u64 v[92:93], v[74:75], 0, v[136:137]
	global_store_short_d16_hi v[92:93], v52, off
	v_mul_f32_e32 v52, v57, v91
	v_add_u32_e32 v136, s27, v140
	v_mul_f32_e32 v52, v53, v52
	v_lshl_add_u64 v[92:93], v[136:137], 2, s[36:37]
	v_bfe_u32 v53, v52, 16, 1
	v_lshlrev_b32_e32 v136, 1, v144
	v_add3_u32 v57, v52, v53, s20
	v_lshl_add_u64 v[52:53], v[74:75], 0, v[136:137]
	global_store_short_d16_hi v[52:53], v57, off
	v_mul_f32_e32 v52, v85, v91
	v_mul_f32_e32 v52, v54, v52
	v_bfe_u32 v53, v52, 16, 1
	v_lshlrev_b32_e32 v136, 1, v146
	v_add3_u32 v54, v52, v53, s20
	v_lshl_add_u64 v[52:53], v[74:75], 0, v[136:137]
	global_store_short_d16_hi v[52:53], v54, off
	v_mul_f32_e32 v52, v86, v91
	v_mul_f32_e32 v52, v55, v52
	v_bfe_u32 v53, v52, 16, 1
	v_lshlrev_b32_e32 v136, 1, v148
	v_add3_u32 v54, v52, v53, s20
	v_lshl_add_u64 v[52:53], v[74:75], 0, v[136:137]
	global_store_short_d16_hi v[52:53], v54, off
	v_mul_f32_e32 v52, v87, v91
	v_mul_f32_e32 v48, v48, v52
	v_bfe_u32 v52, v48, 16, 1
	v_lshlrev_b32_e32 v136, 1, v150
	v_add3_u32 v48, v48, v52, s20
	v_lshl_add_u64 v[52:53], v[74:75], 0, v[136:137]
	global_store_short_d16_hi v[52:53], v48, off
	v_mul_f32_e32 v48, v88, v91
	v_mul_f32_e32 v48, v48, v49
	v_bfe_u32 v49, v48, 16, 1
	v_lshlrev_b32_e32 v136, 1, v152
	v_add3_u32 v52, v48, v49, s20
	v_lshl_add_u64 v[48:49], v[74:75], 0, v[136:137]
	global_store_short_d16_hi v[48:49], v52, off
	v_mul_f32_e32 v48, v89, v91
	v_mul_f32_e32 v48, v48, v50
	v_bfe_u32 v49, v48, 16, 1
	v_lshlrev_b32_e32 v136, 1, v154
	v_add3_u32 v50, v48, v49, s20
	v_lshl_add_u64 v[48:49], v[74:75], 0, v[136:137]
	global_store_short_d16_hi v[48:49], v50, off
	v_mul_f32_e32 v48, v90, v91
	v_mul_f32_e32 v48, v48, v51
	v_bfe_u32 v49, v48, 16, 1
	v_lshlrev_b32_e32 v136, 1, v156
	v_add3_u32 v50, v48, v49, s20
	v_lshl_add_u64 v[48:49], v[74:75], 0, v[136:137]
	global_store_short_d16_hi v[48:49], v50, off
	global_load_dwordx4 v[48:51], v[92:93], off offset:144
	s_nop 0
	global_load_dwordx4 v[52:55], v[92:93], off offset:128
	v_mul_f32_e32 v57, v66, v91
	v_lshlrev_b32_e32 v136, 1, v158
	v_lshl_add_u64 v[86:87], v[74:75], 0, v[136:137]
	v_lshlrev_b32_e32 v136, 1, v160
	s_waitcnt vmcnt(0)
	v_mul_f32_e32 v52, v57, v52
	v_bfe_u32 v57, v52, 16, 1
	v_add3_u32 v52, v52, v57, s20
	global_store_short_d16_hi v[86:87], v52, off
	v_mul_f32_e32 v52, v67, v91
	v_mul_f32_e32 v52, v52, v53
	v_bfe_u32 v53, v52, 16, 1
	v_add3_u32 v57, v52, v53, s20
	v_lshl_add_u64 v[52:53], v[74:75], 0, v[136:137]
	global_store_short_d16_hi v[52:53], v57, off
	v_mul_f32_e32 v52, v68, v91
	v_mul_f32_e32 v52, v52, v54
	v_bfe_u32 v53, v52, 16, 1
	v_lshlrev_b32_e32 v136, 1, v162
	v_add3_u32 v54, v52, v53, s20
	v_lshl_add_u64 v[52:53], v[74:75], 0, v[136:137]
	global_store_short_d16_hi v[52:53], v54, off
	v_mul_f32_e32 v52, v69, v91
	v_mul_f32_e32 v52, v52, v55
	v_bfe_u32 v53, v52, 16, 1
	v_lshlrev_b32_e32 v136, 1, v164
	v_add3_u32 v54, v52, v53, s20
	v_lshl_add_u64 v[52:53], v[74:75], 0, v[136:137]
	global_store_short_d16_hi v[52:53], v54, off
	v_mul_f32_e32 v52, v70, v91
	v_mul_f32_e32 v48, v52, v48
	v_bfe_u32 v52, v48, 16, 1
	v_add3_u32 v48, v48, v52, s20
	v_or_b32_e32 v52, 0x1200, v142
	v_lshlrev_b32_e32 v136, 1, v52
	v_lshl_add_u64 v[52:53], v[74:75], 0, v[136:137]
	global_store_short_d16_hi v[52:53], v48, off
	v_mul_f32_e32 v48, v71, v91
	v_mul_f32_e32 v48, v48, v49
	v_bfe_u32 v49, v48, 16, 1
	v_add3_u32 v52, v48, v49, s20
	v_or_b32_e32 v48, 0x1280, v142
	v_lshlrev_b32_e32 v136, 1, v48
	v_lshl_add_u64 v[48:49], v[74:75], 0, v[136:137]
	global_store_short_d16_hi v[48:49], v52, off
	v_mul_f32_e32 v48, v72, v91
	v_mul_f32_e32 v48, v48, v50
	v_bfe_u32 v49, v48, 16, 1
	v_add3_u32 v50, v48, v49, s20
	v_or_b32_e32 v48, 0x1300, v142
	v_lshlrev_b32_e32 v136, 1, v48
	v_lshl_add_u64 v[48:49], v[74:75], 0, v[136:137]
	global_store_short_d16_hi v[48:49], v50, off
	v_mul_f32_e32 v48, v73, v91
	v_mul_f32_e32 v48, v48, v51
	v_bfe_u32 v49, v48, 16, 1
	v_lshlrev_b32_e32 v136, 1, v172
	v_add3_u32 v50, v48, v49, s20
	v_lshl_add_u64 v[48:49], v[74:75], 0, v[136:137]
	global_store_short_d16_hi v[48:49], v50, off

; __device__ __forceinline__ float gelu_tanh(float x) {
;     const float u = 0.7978845608028654f * (x + 0.044715f * x * x * x);
;     return x / (1.f + __expf(-2.f * u));
; }
;     __device__ __forceinline__ void operator()(const f32x4 (&acc)[2][2][4][2], const pg8::Unit& u, int wr, int wc, int fr, int fq) const {
;     ...
;                 } else if (cs < 28) {
;                     float y[16];
; #pragma unroll
;                     for (int i = 0; i < 16; ++i) y[i] = gelu_tanh(v[i]);
;                     bf16_t* p = zu + (size_t)row * 512 + (cs - 20) * 64 + d0; store8(p, y); store8(p + 32, y + 8);
.LBB0_312:
	s_andn2_b64 vcc, exec, s[54:55]
	s_cbranch_vccnz .LBB0_314
	v_readlane_b32 s36, v254, 31
	v_readlane_b32 s37, v254, 32
	v_lshlrev_b32_e32 v136, 1, v140
	s_nop 0
	v_mul_f32_e32 v48, v77, v77
	v_mul_f32_e32 v48, 0xbdd2d3e8, v48
	v_add_f32_e32 v48, 0xc0135761, v48
	v_mul_f32_e32 v48, v77, v48
	v_exp_f32_e32 v48, v48
	s_nop 0
	v_add_f32_e32 v48, 1.0, v48
	v_rcp_f32_e32 v49, v48
	s_nop 0
	v_mul_f32_e32 v48, v77, v49
	s_nop 0
	s_nop 0
	v_mul_f32_e32 v49, v78, v78
	v_mul_f32_e32 v49, 0xbdd2d3e8, v49
	v_add_f32_e32 v49, 0xc0135761, v49
	v_mul_f32_e32 v49, v78, v49
	v_exp_f32_e32 v49, v49
	s_nop 0
	v_add_f32_e32 v49, 1.0, v49
	v_rcp_f32_e32 v50, v49
	s_nop 0
	v_mul_f32_e32 v49, v78, v50
	v_cvt_pk_bf16_f32 v48, v48, v49
	s_nop 0
	s_nop 0
	v_mul_f32_e32 v50, v79, v79
	v_mul_f32_e32 v50, 0xbdd2d3e8, v50
	v_add_f32_e32 v50, 0xc0135761, v50
	v_mul_f32_e32 v50, v79, v50
	v_exp_f32_e32 v50, v50
	s_nop 0
	v_add_f32_e32 v50, 1.0, v50
	v_rcp_f32_e32 v51, v50
	s_nop 0
	v_mul_f32_e32 v50, v79, v51
	s_nop 0
	s_nop 0
	v_mul_f32_e32 v51, v80, v80
	v_mul_f32_e32 v51, 0xbdd2d3e8, v51
	v_add_f32_e32 v51, 0xc0135761, v51
	v_mul_f32_e32 v51, v80, v51
	v_exp_f32_e32 v51, v51
	s_nop 0
	v_add_f32_e32 v51, 1.0, v51
	v_rcp_f32_e32 v52, v51
	s_nop 0
	v_mul_f32_e32 v51, v80, v52
	v_cvt_pk_bf16_f32 v49, v50, v51
	s_nop 0
	s_nop 0
	v_mul_f32_e32 v52, v81, v81
	v_mul_f32_e32 v52, 0xbdd2d3e8, v52
	v_add_f32_e32 v52, 0xc0135761, v52
	v_mul_f32_e32 v52, v81, v52
	v_exp_f32_e32 v52, v52
	s_nop 0
	v_add_f32_e32 v52, 1.0, v52
	v_rcp_f32_e32 v53, v52
	s_nop 0
	v_mul_f32_e32 v52, v81, v53
	s_nop 0
	s_nop 0
	v_mul_f32_e32 v53, v82, v82
	v_mul_f32_e32 v53, 0xbdd2d3e8, v53
	v_add_f32_e32 v53, 0xc0135761, v53
	v_mul_f32_e32 v53, v82, v53
	v_exp_f32_e32 v53, v53
	s_nop 0
	v_add_f32_e32 v53, 1.0, v53
	v_rcp_f32_e32 v54, v53
	s_nop 0
	v_mul_f32_e32 v53, v82, v54
	v_cvt_pk_bf16_f32 v50, v52, v53
	s_nop 0
	s_nop 0
	v_mul_f32_e32 v54, v83, v83
	v_mul_f32_e32 v54, 0xbdd2d3e8, v54
	v_add_f32_e32 v54, 0xc0135761, v54
	v_mul_f32_e32 v54, v83, v54
	v_exp_f32_e32 v54, v54
	s_nop 0
	v_add_f32_e32 v54, 1.0, v54
	v_rcp_f32_e32 v55, v54
	s_nop 0
	v_mul_f32_e32 v54, v83, v55
	s_nop 0
	s_nop 0
	v_mul_f32_e32 v55, v84, v84
	v_mul_f32_e32 v55, 0xbdd2d3e8, v55
	v_add_f32_e32 v55, 0xc0135761, v55
	v_mul_f32_e32 v55, v84, v55
	v_exp_f32_e32 v55, v55
	s_nop 0
	v_add_f32_e32 v55, 1.0, v55
	v_rcp_f32_e32 v57, v55
	s_nop 0
	v_mul_f32_e32 v55, v84, v57
	v_cvt_pk_bf16_f32 v51, v54, v55
	s_nop 0
	s_nop 0
	v_mul_f32_e32 v57, v60, v60
	v_mul_f32_e32 v57, 0xbdd2d3e8, v57
	v_add_f32_e32 v57, 0xc0135761, v57
	v_mul_f32_e32 v57, v60, v57
	v_exp_f32_e32 v57, v57
	s_nop 0
	v_add_f32_e32 v57, 1.0, v57
	v_rcp_f32_e32 v66, v57
	s_nop 0
	v_mul_f32_e32 v66, v60, v66
	s_nop 0
	s_nop 0
	v_mul_f32_e32 v57, v61, v61
	v_mul_f32_e32 v57, 0xbdd2d3e8, v57
	v_add_f32_e32 v57, 0xc0135761, v57
	v_mul_f32_e32 v57, v61, v57
	v_exp_f32_e32 v57, v57
	s_nop 0
	v_add_f32_e32 v57, 1.0, v57
	v_rcp_f32_e32 v67, v57
	s_nop 0
	v_mul_f32_e32 v67, v61, v67
	s_nop 0
	s_nop 0
	v_mul_f32_e32 v57, v64, v64
	v_mul_f32_e32 v57, 0xbdd2d3e8, v57
	v_add_f32_e32 v57, 0xc0135761, v57
	v_mul_f32_e32 v57, v64, v57
	v_exp_f32_e32 v57, v57
	s_nop 0
	v_add_f32_e32 v57, 1.0, v57
	v_rcp_f32_e32 v68, v57
	s_nop 0
	v_mul_f32_e32 v70, v64, v68
	s_nop 0
	s_nop 0
	v_mul_f32_e32 v57, v65, v65
	v_mul_f32_e32 v57, 0xbdd2d3e8, v57
	v_add_f32_e32 v57, 0xc0135761, v57
	v_mul_f32_e32 v57, v65, v57
	v_exp_f32_e32 v57, v57
	s_nop 0
	v_add_f32_e32 v57, 1.0, v57
	v_rcp_f32_e32 v68, v57
	s_nop 0
	v_mul_f32_e32 v71, v65, v68
	s_nop 0
	s_nop 0
	v_mul_f32_e32 v57, v62, v62
	v_mul_f32_e32 v57, 0xbdd2d3e8, v57
	v_add_f32_e32 v57, 0xc0135761, v57
	v_mul_f32_e32 v57, v62, v57
	v_exp_f32_e32 v57, v57
	s_nop 0
	v_add_f32_e32 v57, 1.0, v57
	v_rcp_f32_e32 v68, v57
	s_nop 0
	v_mul_f32_e32 v72, v62, v68
	s_nop 0
	s_nop 0
	v_mul_f32_e32 v57, v63, v63
	v_mul_f32_e32 v57, 0xbdd2d3e8, v57
	v_add_f32_e32 v57, 0xc0135761, v57
	v_mul_f32_e32 v57, v63, v57
	v_exp_f32_e32 v57, v57
	s_nop 0
	v_add_f32_e32 v57, 1.0, v57
	v_rcp_f32_e32 v68, v57
	s_nop 0
	v_mul_f32_e32 v73, v63, v68
	s_nop 0
	s_nop 0
	v_mul_f32_e32 v57, v58, v58
	v_mul_f32_e32 v57, 0xbdd2d3e8, v57
	v_add_f32_e32 v57, 0xc0135761, v57
	v_mul_f32_e32 v57, v58, v57
	v_exp_f32_e32 v57, v57
	s_nop 0
	v_add_f32_e32 v57, 1.0, v57
	v_rcp_f32_e32 v68, v57
	s_nop 0
	v_mul_f32_e32 v74, v58, v68
	s_nop 0
	s_nop 0
	v_mul_f32_e32 v57, v59, v59
	v_mul_f32_e32 v57, 0xbdd2d3e8, v57
	v_add_f32_e32 v57, 0xc0135761, v57
	v_mul_f32_e32 v57, v59, v57
	v_exp_f32_e32 v57, v57
	s_nop 0
	v_add_f32_e32 v57, 1.0, v57
	v_rcp_f32_e32 v68, v57
	s_nop 0
	v_mul_f32_e32 v75, v59, v68
	v_ashrrev_i32_e32 v57, 31, v56
	v_lshlrev_b64 v[68:69], 10, v[56:57]
	v_lshl_add_u64 v[68:69], s[36:37], 0, v[68:69]
	v_lshl_add_u64 v[68:69], s[8:9], 1, v[68:69]
	v_lshl_add_u64 v[68:69], v[68:69], 0, v[136:137]
	global_store_dwordx4 v[68:69], v[48:51], off offset:-2560
	s_nop 1
	v_cvt_pk_bf16_f32 v48, v66, v67
	v_cvt_pk_bf16_f32 v49, v70, v71
	v_cvt_pk_bf16_f32 v50, v72, v73
	v_cvt_pk_bf16_f32 v51, v74, v75
	global_store_dwordx4 v[68:69], v[48:51], off offset:-2496

; __device__ __forceinline__ float gelu_tanh(float x) {
;     const float u = 0.7978845608028654f * (x + 0.044715f * x * x * x);
;     return x / (1.f + __expf(-2.f * u));
; }
;     __device__ __forceinline__ void operator()(const f32x4 (&acc)[2][2][4][2], const pg8::Unit& u, int wr, int wc, int fr, int fq) const {
;     ...
;                 } else if (cs < 36) {
;                     const int g = cs - 28;
;                     float y[16];
; #pragma unroll
;                     for (int i = 0; i < 16; ++i) y[i] = gelu_tanh(v[i]);
;                     const float rn = rsqrtf(head_ssq(y) * (1.f / 64.f) + EPS);
.LBB0_335:
	s_andn2_b64 vcc, exec, s[72:73]
	s_mov_b64 s[54:55], -1
	s_cbranch_vccnz .LBB0_351
	s_andn2_b64 vcc, exec, s[70:71]
	s_cbranch_vccnz .LBB0_348
	s_andn2_b64 vcc, exec, s[42:43]
	s_cbranch_vccnz .LBB0_345
	s_andn2_b64 vcc, exec, s[40:41]
	s_cbranch_vccnz .LBB0_340
	s_ashr_i32 s53, s52, 31
	s_lshl_b64 s[56:57], s[52:53], 21
	v_readlane_b32 s36, v254, 33
	s_mov_b64 s[58:59], s[42:43]
	v_mul_f32_e32 v32, v69, v69
	v_mul_f32_e32 v32, 0xbdd2d3e8, v32
	v_add_f32_e32 v32, 0xc0135761, v32
	v_mul_f32_e32 v32, v69, v32
	v_exp_f32_e32 v32, v32
	s_nop 0
	v_add_f32_e32 v32, 1.0, v32
	v_rcp_f32_e32 v33, v32
	s_nop 0
	v_mul_f32_e32 v32, v69, v33
	s_nop 0
	s_nop 0
	v_mul_f32_e32 v33, v68, v68
	v_mul_f32_e32 v33, 0xbdd2d3e8, v33
	v_add_f32_e32 v33, 0xc0135761, v33
	v_mul_f32_e32 v33, v68, v33
	v_exp_f32_e32 v33, v33
	s_nop 0
	v_add_f32_e32 v33, 1.0, v33
	v_rcp_f32_e32 v34, v33
	s_nop 0
	v_mul_f32_e32 v41, v68, v34
	s_nop 0
	s_nop 0
	v_mul_f32_e32 v33, v67, v67
	v_mul_f32_e32 v33, 0xbdd2d3e8, v33
	v_add_f32_e32 v33, 0xc0135761, v33
	v_mul_f32_e32 v33, v67, v33
	v_exp_f32_e32 v33, v33
	s_nop 0
	v_add_f32_e32 v33, 1.0, v33
	v_rcp_f32_e32 v34, v33
	s_nop 0
	v_mul_f32_e32 v70, v67, v34
	s_nop 0
	s_nop 0
	v_mul_f32_e32 v33, v66, v66
	v_mul_f32_e32 v33, 0xbdd2d3e8, v33
	v_add_f32_e32 v33, 0xc0135761, v33
	v_mul_f32_e32 v33, v66, v33
	v_exp_f32_e32 v33, v33
	s_nop 0
	v_add_f32_e32 v33, 1.0, v33
	v_rcp_f32_e32 v34, v33
	s_nop 0
	v_mul_f32_e32 v71, v66, v34
	s_nop 0
	s_nop 0
	v_mul_f32_e32 v33, v65, v65
	v_mul_f32_e32 v33, 0xbdd2d3e8, v33
	v_add_f32_e32 v33, 0xc0135761, v33
	v_mul_f32_e32 v33, v65, v33
	v_exp_f32_e32 v33, v33
	s_nop 0
	v_add_f32_e32 v33, 1.0, v33
	v_rcp_f32_e32 v34, v33
	s_nop 0
	v_mul_f32_e32 v72, v65, v34
	s_nop 0
	s_nop 0
	v_mul_f32_e32 v33, v64, v64
	v_mul_f32_e32 v33, 0xbdd2d3e8, v33
	v_add_f32_e32 v33, 0xc0135761, v33
	v_mul_f32_e32 v33, v64, v33
	v_exp_f32_e32 v33, v33
	s_nop 0
	v_add_f32_e32 v33, 1.0, v33
	v_rcp_f32_e32 v34, v33
	s_nop 0
	v_mul_f32_e32 v73, v64, v34
	s_nop 0
	s_nop 0
	v_mul_f32_e32 v33, v63, v63
	v_mul_f32_e32 v33, 0xbdd2d3e8, v33
	v_add_f32_e32 v33, 0xc0135761, v33
	v_mul_f32_e32 v33, v63, v33
	v_exp_f32_e32 v33, v33
	s_nop 0
	v_add_f32_e32 v33, 1.0, v33
	v_rcp_f32_e32 v34, v33
	s_nop 0
	v_mul_f32_e32 v74, v63, v34
	s_nop 0
	s_nop 0
	v_mul_f32_e32 v33, v62, v62
	v_mul_f32_e32 v33, 0xbdd2d3e8, v33
	v_add_f32_e32 v33, 0xc0135761, v33
	v_mul_f32_e32 v33, v62, v33
	v_exp_f32_e32 v33, v33
	s_nop 0
	v_add_f32_e32 v33, 1.0, v33
	v_rcp_f32_e32 v34, v33
	s_nop 0
	v_mul_f32_e32 v75, v62, v34
	v_mul_f32_e32 v35, v49, v49
	v_mul_f32_e32 v35, 0xbdd2d3e8, v35
	v_add_f32_e32 v35, 0xc0135761, v35
	v_mul_f32_e32 v35, v49, v35
	v_exp_f32_e32 v35, v35
	s_nop 0
	v_add_f32_e32 v35, 1.0, v35
	v_rcp_f32_e32 v50, v35
	s_nop 0
	v_mul_f32_e32 v51, v49, v50
	v_mul_f32_e32 v33, v41, v41
	v_fmac_f32_e32 v33, v32, v32
	v_fmac_f32_e32 v33, v70, v70
	v_fmac_f32_e32 v33, v71, v71
	v_fmac_f32_e32 v33, v72, v72
	v_fmac_f32_e32 v33, v73, v73
	v_fmac_f32_e32 v33, v74, v74
	v_mul_f32_e32 v34, v48, v48
	v_mul_f32_e32 v34, 0xbdd2d3e8, v34
	v_add_f32_e32 v34, 0xc0135761, v34
	v_mul_f32_e32 v34, v48, v34
	v_exp_f32_e32 v34, v34
	s_nop 0
	v_add_f32_e32 v34, 1.0, v34
	v_rcp_f32_e32 v35, v34
	s_nop 0
	v_mul_f32_e32 v50, v48, v35
	v_fmac_f32_e32 v33, v75, v75
	v_pk_mul_f32 v[34:35], v[50:51], v[50:51]
	s_nop 0
	v_add_f32_e32 v33, v34, v33
	v_add_f32_e32 v33, v35, v33
	s_nop 0
	s_nop 0
	v_mul_f32_e32 v35, v47, v47
	v_mul_f32_e32 v35, 0xbdd2d3e8, v35
	v_add_f32_e32 v35, 0xc0135761, v35
	v_mul_f32_e32 v35, v47, v35
	v_exp_f32_e32 v35, v35
	s_nop 0
	v_add_f32_e32 v35, 1.0, v35
	v_rcp_f32_e32 v36, v35
	s_nop 0
	v_mul_f32_e32 v53, v47, v36
	s_nop 0
	v_mul_f32_e32 v34, v46, v46
	v_mul_f32_e32 v34, 0xbdd2d3e8, v34
	v_add_f32_e32 v34, 0xc0135761, v34
	v_mul_f32_e32 v34, v46, v34
	v_exp_f32_e32 v34, v34
	s_nop 0
	v_add_f32_e32 v34, 1.0, v34
	v_rcp_f32_e32 v35, v34
	s_nop 0
	v_mul_f32_e32 v52, v46, v35
	v_pk_mul_f32 v[34:35], v[52:53], v[52:53]
	s_nop 0
	v_add_f32_e32 v33, v34, v33
	v_add_f32_e32 v33, v35, v33
	s_nop 0
	s_nop 0
	v_mul_f32_e32 v35, v45, v45
	v_mul_f32_e32 v35, 0xbdd2d3e8, v35
	v_add_f32_e32 v35, 0xc0135761, v35
	v_mul_f32_e32 v35, v45, v35
	v_exp_f32_e32 v35, v35
	s_nop 0
	v_add_f32_e32 v35, 1.0, v35
	v_rcp_f32_e32 v36, v35
	s_nop 0
	v_mul_f32_e32 v55, v45, v36
	s_nop 0
	v_mul_f32_e32 v34, v44, v44
	v_mul_f32_e32 v34, 0xbdd2d3e8, v34
	v_add_f32_e32 v34, 0xc0135761, v34
	v_mul_f32_e32 v34, v44, v34
	v_exp_f32_e32 v34, v34
	s_nop 0
	v_add_f32_e32 v34, 1.0, v34
	v_rcp_f32_e32 v35, v34
	s_nop 0
	v_mul_f32_e32 v54, v44, v35
	v_pk_mul_f32 v[34:35], v[54:55], v[54:55]
	s_nop 0
	v_add_f32_e32 v33, v34, v33
	v_add_f32_e32 v33, v35, v33
	s_nop 0
	s_nop 0
	v_mul_f32_e32 v35, v43, v43
	v_mul_f32_e32 v35, 0xbdd2d3e8, v35
	v_add_f32_e32 v35, 0xc0135761, v35
	v_mul_f32_e32 v35, v43, v35
	v_exp_f32_e32 v35, v35
	s_nop 0
	v_add_f32_e32 v35, 1.0, v35
	v_rcp_f32_e32 v36, v35
	s_nop 0
	v_mul_f32_e32 v59, v43, v36
	s_lshr_b32 s54, s89, 4
	s_and_b32 s54, s54, 0x78
	s_add_i32 s54, s54, s29
	v_mul_f32_e32 v34, v42, v42
	v_mul_f32_e32 v34, 0xbdd2d3e8, v34
	v_add_f32_e32 v34, 0xc0135761, v34
	v_mul_f32_e32 v34, v42, v34
	v_exp_f32_e32 v34, v34
	s_nop 0
	v_add_f32_e32 v34, 1.0, v34
	v_rcp_f32_e32 v35, v34
	s_nop 0
	v_mul_f32_e32 v58, v42, v35
	v_pk_mul_f32 v[34:35], v[58:59], v[58:59]
	s_mov_b32 s55, s9
	v_add_f32_e32 v33, v34, v33
	v_add_f32_e32 v33, v35, v33
	v_and_b32_e32 v35, 64, v165
	v_xor_b32_e32 v34, 16, v165
	v_add_u32_e32 v35, 64, v35
	v_cmp_lt_i32_e32 vcc, v34, v35
	s_lshl_b64 s[54:55], s[54:55], 14
	s_add_u32 s53, s36, s56
	v_cndmask_b32_e32 v34, v165, v34, vcc
	v_lshlrev_b32_e32 v34, 2, v34
	ds_bpermute_b32 v34, v34, v33
	v_readlane_b32 s36, v254, 35
	s_addc_u32 s56, s36, s57
	s_add_u32 s54, s53, s54
	s_addc_u32 s55, s56, s55
	s_waitcnt lgkmcnt(0)
; __device__ __forceinline__ unsigned f2bf(float f) { unsigned u = __float_as_uint(f); return (u + 0x7fffu + ((u >> 16) & 1u)) >> 16; }
; __device__ __forceinline__ float head_ssq(const float (&v)[16]) {
;     ...
;     s += __shfl_xor(s, 16); s += __shfl_xor(s, 32);
;     __device__ __forceinline__ void operator()(const f32x4 (&acc)[2][2][4][2], const pg8::Unit& u, int wr, int wc, int fr, int fq) const {
;     ...
;                     const float rn = rsqrtf(head_ssq(y) * (1.f / 64.f) + EPS);
;                     bf16_t* p = zvT + (((size_t)b * 16 + (s >> 7)) * 8 + g) * 8192 + (s & 127);
; #pragma unroll
;                     for (int i = 0; i < 16; ++i) { const int d = 32 * (i >> 3) + d0 + (i & 7); p[d * 128] = (bf16_t)f2bf(y[i] * rn * g_sgu[g * 64 + d]); }
	v_add_f32_e32 v33, v33, v34
	v_xor_b32_e32 v34, 32, v165
	v_cmp_lt_i32_e32 vcc, v34, v35
	s_mov_b64 s[56:57], s[40:41]
	s_nop 0
	v_cndmask_b32_e32 v34, v165, v34, vcc
	v_lshlrev_b32_e32 v34, 2, v34
	ds_bpermute_b32 v34, v34, v33
	s_waitcnt lgkmcnt(0)
	v_add_f32_e32 v33, v33, v34
	v_fmamk_f32 v33, v33, 0x3c800000, v161
	v_cmp_gt_f32_e32 vcc, s61, v33
	v_mul_f32_e32 v34, 0x4b800000, v33
	s_nop 0
	v_cndmask_b32_e32 v33, v33, v34, vcc
	v_rsq_f32_e32 v33, v33
	s_nop 0
	v_mul_f32_e32 v34, 0x45800000, v33
	v_cndmask_b32_e32 v76, v33, v34, vcc
	v_and_b32_e32 v33, 0x5f, v40
	v_lshlrev_b32_e32 v136, 1, v33
	v_lshl_add_u64 v[60:61], s[54:55], 0, v[136:137]
	s_mov_b64 s[54:55], s[38:39]
	v_readlane_b32 s36, v254, 8
	v_or_b32_e32 v136, s27, v140
	v_readlane_b32 s37, v254, 9
	v_mul_f32_e32 v77, v32, v76
	v_readlane_b32 s50, v254, 22
	v_lshl_add_u64 v[36:37], v[136:137], 2, s[36:37]
	global_load_dwordx4 v[32:35], v[36:37], off offset:16
	s_nop 0
	global_load_dwordx4 v[36:39], v[36:37], off
	v_lshlrev_b32_e32 v136, 1, v142
	v_lshl_add_u64 v[78:79], v[60:61], 0, v[136:137]
	v_add_u32_e32 v136, s27, v140
	v_readlane_b32 s51, v254, 23
	v_readlane_b32 s38, v254, 10
	v_readlane_b32 s39, v254, 11
	v_readlane_b32 s40, v254, 12
	v_readlane_b32 s41, v254, 13
	v_readlane_b32 s42, v254, 14
	v_readlane_b32 s43, v254, 15
	v_readlane_b32 s49, v254, 21
	v_readlane_b32 s50, v254, 39
	s_mov_b64 s[38:39], s[54:55]
	s_mov_b64 s[42:43], s[58:59]
	s_mov_b64 s[40:41], s[56:57]
	v_readlane_b32 s49, v254, 41
	v_readlane_b32 s51, v254, 40
	s_mov_b64 s[54:55], 0
	v_readlane_b32 s44, v254, 16
	v_readlane_b32 s45, v254, 17
	v_readlane_b32 s46, v254, 18
	v_readlane_b32 s47, v254, 19
	v_readlane_b32 s48, v254, 20
	s_waitcnt vmcnt(0)
	v_mul_f32_e32 v36, v36, v77
	v_bfe_u32 v77, v36, 16, 1
	v_add3_u32 v36, v36, v77, s20
	global_store_short_d16_hi v[78:79], v36, off
	v_mul_f32_e32 v36, v41, v76
	v_mul_f32_e32 v36, v37, v36
	v_lshl_add_u64 v[78:79], v[136:137], 2, s[36:37]
	v_bfe_u32 v37, v36, 16, 1
	v_lshlrev_b32_e32 v136, 1, v144
	v_add3_u32 v41, v36, v37, s20
	v_lshl_add_u64 v[36:37], v[60:61], 0, v[136:137]
	global_store_short_d16_hi v[36:37], v41, off
	v_mul_f32_e32 v36, v70, v76
	v_mul_f32_e32 v36, v38, v36
	v_bfe_u32 v37, v36, 16, 1
	v_lshlrev_b32_e32 v136, 1, v146
	v_add3_u32 v38, v36, v37, s20
	v_lshl_add_u64 v[36:37], v[60:61], 0, v[136:137]
	global_store_short_d16_hi v[36:37], v38, off
	v_mul_f32_e32 v36, v71, v76
	v_mul_f32_e32 v36, v39, v36
	v_bfe_u32 v37, v36, 16, 1
	v_lshlrev_b32_e32 v136, 1, v148
	v_add3_u32 v38, v36, v37, s20
	v_lshl_add_u64 v[36:37], v[60:61], 0, v[136:137]
	global_store_short_d16_hi v[36:37], v38, off
	v_mul_f32_e32 v36, v72, v76
	v_mul_f32_e32 v32, v32, v36
	v_bfe_u32 v36, v32, 16, 1
	v_lshlrev_b32_e32 v136, 1, v150
	v_add3_u32 v32, v32, v36, s20
	v_lshl_add_u64 v[36:37], v[60:61], 0, v[136:137]
	global_store_short_d16_hi v[36:37], v32, off
	v_mul_f32_e32 v32, v73, v76
	v_mul_f32_e32 v32, v32, v33
	v_bfe_u32 v33, v32, 16, 1
	v_lshlrev_b32_e32 v136, 1, v152
	v_add3_u32 v36, v32, v33, s20
	v_lshl_add_u64 v[32:33], v[60:61], 0, v[136:137]
	global_store_short_d16_hi v[32:33], v36, off
	v_mul_f32_e32 v32, v74, v76
	v_mul_f32_e32 v32, v32, v34
	v_bfe_u32 v33, v32, 16, 1
	v_lshlrev_b32_e32 v136, 1, v154
	v_add3_u32 v34, v32, v33, s20
	v_lshl_add_u64 v[32:33], v[60:61], 0, v[136:137]
	global_store_short_d16_hi v[32:33], v34, off
	v_mul_f32_e32 v32, v75, v76
	v_mul_f32_e32 v32, v32, v35
	v_bfe_u32 v33, v32, 16, 1
	v_lshlrev_b32_e32 v136, 1, v156
	v_add3_u32 v34, v32, v33, s20
	v_lshl_add_u64 v[32:33], v[60:61], 0, v[136:137]
	global_store_short_d16_hi v[32:33], v34, off
	global_load_dwordx4 v[32:35], v[78:79], off offset:144
	s_nop 0
	global_load_dwordx4 v[36:39], v[78:79], off offset:128
	v_mul_f32_e32 v41, v50, v76
	v_lshlrev_b32_e32 v136, 1, v158
	v_lshl_add_u64 v[70:71], v[60:61], 0, v[136:137]
	v_lshlrev_b32_e32 v136, 1, v160
	s_waitcnt vmcnt(0)
	v_mul_f32_e32 v36, v41, v36
	v_bfe_u32 v41, v36, 16, 1
	v_add3_u32 v36, v36, v41, s20
	global_store_short_d16_hi v[70:71], v36, off
	v_mul_f32_e32 v36, v51, v76
	v_mul_f32_e32 v36, v36, v37
	v_bfe_u32 v37, v36, 16, 1
	v_add3_u32 v41, v36, v37, s20
	v_lshl_add_u64 v[36:37], v[60:61], 0, v[136:137]
	global_store_short_d16_hi v[36:37], v41, off
	v_mul_f32_e32 v36, v52, v76
	v_mul_f32_e32 v36, v36, v38
	v_bfe_u32 v37, v36, 16, 1
	v_lshlrev_b32_e32 v136, 1, v162
	v_add3_u32 v38, v36, v37, s20
	v_lshl_add_u64 v[36:37], v[60:61], 0, v[136:137]
	global_store_short_d16_hi v[36:37], v38, off
	v_mul_f32_e32 v36, v53, v76
	v_mul_f32_e32 v36, v36, v39
	v_bfe_u32 v37, v36, 16, 1
	v_lshlrev_b32_e32 v136, 1, v164
	v_add3_u32 v38, v36, v37, s20
	v_lshl_add_u64 v[36:37], v[60:61], 0, v[136:137]
	global_store_short_d16_hi v[36:37], v38, off
	v_mul_f32_e32 v36, v54, v76
	v_mul_f32_e32 v32, v36, v32
	v_bfe_u32 v36, v32, 16, 1
	v_add3_u32 v32, v32, v36, s20
	v_or_b32_e32 v36, 0x1200, v142
	v_lshlrev_b32_e32 v136, 1, v36
	v_lshl_add_u64 v[36:37], v[60:61], 0, v[136:137]
	global_store_short_d16_hi v[36:37], v32, off
	v_mul_f32_e32 v32, v55, v76
	v_mul_f32_e32 v32, v32, v33
	v_bfe_u32 v33, v32, 16, 1
	v_add3_u32 v36, v32, v33, s20
	v_or_b32_e32 v32, 0x1280, v142
	v_lshlrev_b32_e32 v136, 1, v32
	v_lshl_add_u64 v[32:33], v[60:61], 0, v[136:137]
	global_store_short_d16_hi v[32:33], v36, off
	v_mul_f32_e32 v32, v58, v76
	v_mul_f32_e32 v32, v32, v34
	v_bfe_u32 v33, v32, 16, 1
	v_add3_u32 v34, v32, v33, s20
	v_or_b32_e32 v32, 0x1300, v142
	v_lshlrev_b32_e32 v136, 1, v32
	v_lshl_add_u64 v[32:33], v[60:61], 0, v[136:137]
	global_store_short_d16_hi v[32:33], v34, off
	v_mul_f32_e32 v32, v59, v76
	v_mul_f32_e32 v32, v32, v35
	v_bfe_u32 v33, v32, 16, 1
	v_lshlrev_b32_e32 v136, 1, v172
	v_add3_u32 v34, v32, v33, s20
	v_lshl_add_u64 v[32:33], v[60:61], 0, v[136:137]
	global_store_short_d16_hi v[32:33], v34, off

; __device__ __forceinline__ float gelu_tanh(float x) {
;     const float u = 0.7978845608028654f * (x + 0.044715f * x * x * x);
;     return x / (1.f + __expf(-2.f * u));
; }
;     __device__ __forceinline__ void operator()(const f32x4 (&acc)[2][2][4][2], const pg8::Unit& u, int wr, int wc, int fr, int fq) const {
;     ...
;                 } else if (cs < 28) {
;                     float y[16];
; #pragma unroll
;                     for (int i = 0; i < 16; ++i) y[i] = gelu_tanh(v[i]);
;                     bf16_t* p = zu + (size_t)row * 512 + (cs - 20) * 64 + d0; store8(p, y); store8(p + 32, y + 8);
.LBB0_345:
	s_andn2_b64 vcc, exec, s[54:55]
	s_cbranch_vccnz .LBB0_347
	v_readlane_b32 s36, v254, 31
	v_readlane_b32 s37, v254, 32
	v_lshlrev_b32_e32 v136, 1, v140
	s_nop 0
	v_mul_f32_e32 v32, v69, v69
	v_mul_f32_e32 v32, 0xbdd2d3e8, v32
	v_add_f32_e32 v32, 0xc0135761, v32
	v_mul_f32_e32 v32, v69, v32
	v_exp_f32_e32 v32, v32
	s_nop 0
	v_add_f32_e32 v32, 1.0, v32
	v_rcp_f32_e32 v33, v32
	s_nop 0
	v_mul_f32_e32 v32, v69, v33
	s_nop 0
	s_nop 0
	v_mul_f32_e32 v33, v68, v68
	v_mul_f32_e32 v33, 0xbdd2d3e8, v33
	v_add_f32_e32 v33, 0xc0135761, v33
	v_mul_f32_e32 v33, v68, v33
	v_exp_f32_e32 v33, v33
	s_nop 0
	v_add_f32_e32 v33, 1.0, v33
	v_rcp_f32_e32 v34, v33
	s_nop 0
	v_mul_f32_e32 v33, v68, v34
	v_cvt_pk_bf16_f32 v32, v32, v33
	s_nop 0
	s_nop 0
	v_mul_f32_e32 v34, v67, v67
	v_mul_f32_e32 v34, 0xbdd2d3e8, v34
	v_add_f32_e32 v34, 0xc0135761, v34
	v_mul_f32_e32 v34, v67, v34
	v_exp_f32_e32 v34, v34
	s_nop 0
	v_add_f32_e32 v34, 1.0, v34
	v_rcp_f32_e32 v35, v34
	s_nop 0
	v_mul_f32_e32 v34, v67, v35
	s_nop 0
	s_nop 0
	v_mul_f32_e32 v35, v66, v66
	v_mul_f32_e32 v35, 0xbdd2d3e8, v35
	v_add_f32_e32 v35, 0xc0135761, v35
	v_mul_f32_e32 v35, v66, v35
	v_exp_f32_e32 v35, v35
	s_nop 0
	v_add_f32_e32 v35, 1.0, v35
	v_rcp_f32_e32 v36, v35
	s_nop 0
	v_mul_f32_e32 v35, v66, v36
	v_cvt_pk_bf16_f32 v33, v34, v35
	s_nop 0
	s_nop 0
	v_mul_f32_e32 v36, v65, v65
	v_mul_f32_e32 v36, 0xbdd2d3e8, v36
	v_add_f32_e32 v36, 0xc0135761, v36
	v_mul_f32_e32 v36, v65, v36
	v_exp_f32_e32 v36, v36
	s_nop 0
	v_add_f32_e32 v36, 1.0, v36
	v_rcp_f32_e32 v37, v36
	s_nop 0
	v_mul_f32_e32 v36, v65, v37
	s_nop 0
	s_nop 0
	v_mul_f32_e32 v37, v64, v64
	v_mul_f32_e32 v37, 0xbdd2d3e8, v37
	v_add_f32_e32 v37, 0xc0135761, v37
	v_mul_f32_e32 v37, v64, v37
	v_exp_f32_e32 v37, v37
	s_nop 0
	v_add_f32_e32 v37, 1.0, v37
	v_rcp_f32_e32 v38, v37
	s_nop 0
	v_mul_f32_e32 v37, v64, v38
	v_cvt_pk_bf16_f32 v34, v36, v37
	s_nop 0
	s_nop 0
	v_mul_f32_e32 v38, v63, v63
	v_mul_f32_e32 v38, 0xbdd2d3e8, v38
	v_add_f32_e32 v38, 0xc0135761, v38
	v_mul_f32_e32 v38, v63, v38
	v_exp_f32_e32 v38, v38
	s_nop 0
	v_add_f32_e32 v38, 1.0, v38
	v_rcp_f32_e32 v39, v38
	s_nop 0
	v_mul_f32_e32 v38, v63, v39
	s_nop 0
	s_nop 0
	v_mul_f32_e32 v39, v62, v62
	v_mul_f32_e32 v39, 0xbdd2d3e8, v39
	v_add_f32_e32 v39, 0xc0135761, v39
	v_mul_f32_e32 v39, v62, v39
	v_exp_f32_e32 v39, v39
	s_nop 0
	v_add_f32_e32 v39, 1.0, v39
	v_rcp_f32_e32 v41, v39
	s_nop 0
	v_mul_f32_e32 v39, v62, v41
	v_cvt_pk_bf16_f32 v35, v38, v39
	s_nop 0
	s_nop 0
	v_mul_f32_e32 v41, v48, v48
	v_mul_f32_e32 v41, 0xbdd2d3e8, v41
	v_add_f32_e32 v41, 0xc0135761, v41
	v_mul_f32_e32 v41, v48, v41
	v_exp_f32_e32 v41, v41
	s_nop 0
	v_add_f32_e32 v41, 1.0, v41
	v_rcp_f32_e32 v50, v41
	s_nop 0
	v_mul_f32_e32 v50, v48, v50
	s_nop 0
	s_nop 0
	v_mul_f32_e32 v41, v49, v49
	v_mul_f32_e32 v41, 0xbdd2d3e8, v41
	v_add_f32_e32 v41, 0xc0135761, v41
	v_mul_f32_e32 v41, v49, v41
	v_exp_f32_e32 v41, v41
	s_nop 0
	v_add_f32_e32 v41, 1.0, v41
	v_rcp_f32_e32 v51, v41
	s_nop 0
	v_mul_f32_e32 v51, v49, v51
	s_nop 0
	s_nop 0
	v_mul_f32_e32 v41, v46, v46
	v_mul_f32_e32 v41, 0xbdd2d3e8, v41
	v_add_f32_e32 v41, 0xc0135761, v41
	v_mul_f32_e32 v41, v46, v41
	v_exp_f32_e32 v41, v41
	s_nop 0
	v_add_f32_e32 v41, 1.0, v41
	v_rcp_f32_e32 v52, v41
	s_nop 0
	v_mul_f32_e32 v54, v46, v52
	s_nop 0
	s_nop 0
	v_mul_f32_e32 v41, v47, v47
	v_mul_f32_e32 v41, 0xbdd2d3e8, v41
	v_add_f32_e32 v41, 0xc0135761, v41
	v_mul_f32_e32 v41, v47, v41
	v_exp_f32_e32 v41, v41
	s_nop 0
	v_add_f32_e32 v41, 1.0, v41
	v_rcp_f32_e32 v52, v41
	s_nop 0
	v_mul_f32_e32 v55, v47, v52
	s_nop 0
	s_nop 0
	v_mul_f32_e32 v41, v44, v44
	v_mul_f32_e32 v41, 0xbdd2d3e8, v41
	v_add_f32_e32 v41, 0xc0135761, v41
	v_mul_f32_e32 v41, v44, v41
	v_exp_f32_e32 v41, v41
	s_nop 0
	v_add_f32_e32 v41, 1.0, v41
	v_rcp_f32_e32 v52, v41
	s_nop 0
	v_mul_f32_e32 v58, v44, v52
	s_nop 0
	s_nop 0
	v_mul_f32_e32 v41, v45, v45
	v_mul_f32_e32 v41, 0xbdd2d3e8, v41
	v_add_f32_e32 v41, 0xc0135761, v41
	v_mul_f32_e32 v41, v45, v41
	v_exp_f32_e32 v41, v41
	s_nop 0
	v_add_f32_e32 v41, 1.0, v41
	v_rcp_f32_e32 v52, v41
	s_nop 0
	v_mul_f32_e32 v59, v45, v52
	s_nop 0
	s_nop 0
	v_mul_f32_e32 v41, v42, v42
	v_mul_f32_e32 v41, 0xbdd2d3e8, v41
	v_add_f32_e32 v41, 0xc0135761, v41
	v_mul_f32_e32 v41, v42, v41
	v_exp_f32_e32 v41, v41
	s_nop 0
	v_add_f32_e32 v41, 1.0, v41
	v_rcp_f32_e32 v52, v41
	s_nop 0
	v_mul_f32_e32 v60, v42, v52
	s_nop 0
	s_nop 0
	v_mul_f32_e32 v41, v43, v43
	v_mul_f32_e32 v41, 0xbdd2d3e8, v41
	v_add_f32_e32 v41, 0xc0135761, v41
	v_mul_f32_e32 v41, v43, v41
	v_exp_f32_e32 v41, v41
	s_nop 0
	v_add_f32_e32 v41, 1.0, v41
	v_rcp_f32_e32 v52, v41
	s_nop 0
	v_mul_f32_e32 v61, v43, v52
	v_ashrrev_i32_e32 v41, 31, v40
	v_lshlrev_b64 v[52:53], 10, v[40:41]
	v_lshl_add_u64 v[52:53], s[36:37], 0, v[52:53]
	v_lshl_add_u64 v[52:53], s[8:9], 1, v[52:53]
	v_lshl_add_u64 v[52:53], v[52:53], 0, v[136:137]
	global_store_dwordx4 v[52:53], v[32:35], off offset:-2560
	s_nop 1
	v_cvt_pk_bf16_f32 v32, v50, v51
	v_cvt_pk_bf16_f32 v33, v54, v55
	v_cvt_pk_bf16_f32 v34, v58, v59
	v_cvt_pk_bf16_f32 v35, v60, v61
	global_store_dwordx4 v[52:53], v[32:35], off offset:-2496

; __device__ __forceinline__ float gelu_tanh(float x) {
;     const float u = 0.7978845608028654f * (x + 0.044715f * x * x * x);
;     return x / (1.f + __expf(-2.f * u));
; }
;     __device__ __forceinline__ void operator()(const f32x4 (&acc)[2][2][4][2], const pg8::Unit& u, int wr, int wc, int fr, int fq) const {
;     ...
;                 } else if (cs < 36) {
;                     const int g = cs - 28;
;                     float y[16];
; #pragma unroll
;                     for (int i = 0; i < 16; ++i) y[i] = gelu_tanh(v[i]);
;                     const float rn = rsqrtf(head_ssq(y) * (1.f / 64.f) + EPS);
.LBB0_368:
	s_andn2_b64 vcc, exec, s[72:73]
	s_mov_b64 s[54:55], -1
	s_cbranch_vccnz .LBB0_384
	s_andn2_b64 vcc, exec, s[70:71]
	s_cbranch_vccnz .LBB0_381
	s_andn2_b64 vcc, exec, s[42:43]
	s_cbranch_vccnz .LBB0_378
	s_andn2_b64 vcc, exec, s[40:41]
	s_cbranch_vccnz .LBB0_373
	s_ashr_i32 s53, s52, 31
	s_lshl_b64 s[56:57], s[52:53], 21
	v_readlane_b32 s36, v254, 33
	s_mov_b64 s[58:59], s[42:43]
	v_mul_f32_e32 v16, v45, v45
	v_mul_f32_e32 v16, 0xbdd2d3e8, v16
	v_add_f32_e32 v16, 0xc0135761, v16
	v_mul_f32_e32 v16, v45, v16
	v_exp_f32_e32 v16, v16
	s_nop 0
	v_add_f32_e32 v16, 1.0, v16
	v_rcp_f32_e32 v17, v16
	s_nop 0
	v_mul_f32_e32 v16, v45, v17
	s_nop 0
	s_nop 0
	v_mul_f32_e32 v17, v46, v46
	v_mul_f32_e32 v17, 0xbdd2d3e8, v17
	v_add_f32_e32 v17, 0xc0135761, v17
	v_mul_f32_e32 v17, v46, v17
	v_exp_f32_e32 v17, v17
	s_nop 0
	v_add_f32_e32 v17, 1.0, v17
	v_rcp_f32_e32 v18, v17
	s_nop 0
	v_mul_f32_e32 v25, v46, v18
	s_nop 0
	s_nop 0
	v_mul_f32_e32 v17, v47, v47
	v_mul_f32_e32 v17, 0xbdd2d3e8, v17
	v_add_f32_e32 v17, 0xc0135761, v17
	v_mul_f32_e32 v17, v47, v17
	v_exp_f32_e32 v17, v17
	s_nop 0
	v_add_f32_e32 v17, 1.0, v17
	v_rcp_f32_e32 v18, v17
	s_nop 0
	v_mul_f32_e32 v53, v47, v18
	s_nop 0
	s_nop 0
	v_mul_f32_e32 v17, v48, v48
	v_mul_f32_e32 v17, 0xbdd2d3e8, v17
	v_add_f32_e32 v17, 0xc0135761, v17
	v_mul_f32_e32 v17, v48, v17
	v_exp_f32_e32 v17, v17
	s_nop 0
	v_add_f32_e32 v17, 1.0, v17
	v_rcp_f32_e32 v18, v17
	s_nop 0
	v_mul_f32_e32 v54, v48, v18
	s_nop 0
	s_nop 0
	v_mul_f32_e32 v17, v49, v49
	v_mul_f32_e32 v17, 0xbdd2d3e8, v17
	v_add_f32_e32 v17, 0xc0135761, v17
	v_mul_f32_e32 v17, v49, v17
	v_exp_f32_e32 v17, v17
	s_nop 0
	v_add_f32_e32 v17, 1.0, v17
	v_rcp_f32_e32 v18, v17
	s_nop 0
	v_mul_f32_e32 v55, v49, v18
	s_nop 0
	s_nop 0
	v_mul_f32_e32 v17, v50, v50
	v_mul_f32_e32 v17, 0xbdd2d3e8, v17
	v_add_f32_e32 v17, 0xc0135761, v17
	v_mul_f32_e32 v17, v50, v17
	v_exp_f32_e32 v17, v17
	s_nop 0
	v_add_f32_e32 v17, 1.0, v17
	v_rcp_f32_e32 v18, v17
	s_nop 0
	v_mul_f32_e32 v57, v50, v18
	s_nop 0
	s_nop 0
	v_mul_f32_e32 v17, v51, v51
	v_mul_f32_e32 v17, 0xbdd2d3e8, v17
	v_add_f32_e32 v17, 0xc0135761, v17
	v_mul_f32_e32 v17, v51, v17
	v_exp_f32_e32 v17, v17
	s_nop 0
	v_add_f32_e32 v17, 1.0, v17
	v_rcp_f32_e32 v18, v17
	s_nop 0
	v_mul_f32_e32 v58, v51, v18
	s_nop 0
	s_nop 0
	v_mul_f32_e32 v17, v52, v52
	v_mul_f32_e32 v17, 0xbdd2d3e8, v17
	v_add_f32_e32 v17, 0xc0135761, v17
	v_mul_f32_e32 v17, v52, v17
	v_exp_f32_e32 v17, v17
	s_nop 0
	v_add_f32_e32 v17, 1.0, v17
	v_rcp_f32_e32 v18, v17
	s_nop 0
	v_mul_f32_e32 v59, v52, v18
	v_mul_f32_e32 v19, v29, v29
	v_mul_f32_e32 v19, 0xbdd2d3e8, v19
	v_add_f32_e32 v19, 0xc0135761, v19
	v_mul_f32_e32 v19, v29, v19
	v_exp_f32_e32 v19, v19
	s_nop 0
	v_add_f32_e32 v19, 1.0, v19
	v_rcp_f32_e32 v34, v19
	s_nop 0
	v_mul_f32_e32 v35, v29, v34
	v_mul_f32_e32 v17, v25, v25
	v_fmac_f32_e32 v17, v16, v16
	v_fmac_f32_e32 v17, v53, v53
	v_fmac_f32_e32 v17, v54, v54
	v_fmac_f32_e32 v17, v55, v55
	v_fmac_f32_e32 v17, v57, v57
	v_fmac_f32_e32 v17, v58, v58
	v_mul_f32_e32 v18, v28, v28
	v_mul_f32_e32 v18, 0xbdd2d3e8, v18
	v_add_f32_e32 v18, 0xc0135761, v18
	v_mul_f32_e32 v18, v28, v18
	v_exp_f32_e32 v18, v18
	s_nop 0
	v_add_f32_e32 v18, 1.0, v18
	v_rcp_f32_e32 v19, v18
	s_nop 0
	v_mul_f32_e32 v34, v28, v19
	v_fmac_f32_e32 v17, v59, v59
	v_pk_mul_f32 v[18:19], v[34:35], v[34:35]
	s_nop 0
	v_add_f32_e32 v17, v18, v17
	v_add_f32_e32 v17, v19, v17
	s_nop 0
	s_nop 0
	v_mul_f32_e32 v19, v33, v33
	v_mul_f32_e32 v19, 0xbdd2d3e8, v19
	v_add_f32_e32 v19, 0xc0135761, v19
	v_mul_f32_e32 v19, v33, v19
	v_exp_f32_e32 v19, v19
	s_nop 0
	v_add_f32_e32 v19, 1.0, v19
	v_rcp_f32_e32 v20, v19
	s_nop 0
	v_mul_f32_e32 v37, v33, v20
	s_nop 0
	v_mul_f32_e32 v18, v32, v32
	v_mul_f32_e32 v18, 0xbdd2d3e8, v18
	v_add_f32_e32 v18, 0xc0135761, v18
	v_mul_f32_e32 v18, v32, v18
	v_exp_f32_e32 v18, v18
	s_nop 0
	v_add_f32_e32 v18, 1.0, v18
	v_rcp_f32_e32 v19, v18
	s_nop 0
	v_mul_f32_e32 v36, v32, v19
	v_pk_mul_f32 v[18:19], v[36:37], v[36:37]
	s_nop 0
	v_add_f32_e32 v17, v18, v17
	v_add_f32_e32 v17, v19, v17
	s_nop 0
	s_nop 0
	v_mul_f32_e32 v19, v31, v31
	v_mul_f32_e32 v19, 0xbdd2d3e8, v19
	v_add_f32_e32 v19, 0xc0135761, v19
	v_mul_f32_e32 v19, v31, v19
	v_exp_f32_e32 v19, v19
	s_nop 0
	v_add_f32_e32 v19, 1.0, v19
	v_rcp_f32_e32 v20, v19
	s_nop 0
	v_mul_f32_e32 v39, v31, v20
	s_nop 0
	v_mul_f32_e32 v18, v30, v30
	v_mul_f32_e32 v18, 0xbdd2d3e8, v18
	v_add_f32_e32 v18, 0xc0135761, v18
	v_mul_f32_e32 v18, v30, v18
	v_exp_f32_e32 v18, v18
	s_nop 0
	v_add_f32_e32 v18, 1.0, v18
	v_rcp_f32_e32 v19, v18
	s_nop 0
	v_mul_f32_e32 v38, v30, v19
	v_pk_mul_f32 v[18:19], v[38:39], v[38:39]
	s_nop 0
	v_add_f32_e32 v17, v18, v17
	v_add_f32_e32 v17, v19, v17
	s_nop 0
	s_nop 0
	v_mul_f32_e32 v19, v27, v27
	v_mul_f32_e32 v19, 0xbdd2d3e8, v19
	v_add_f32_e32 v19, 0xc0135761, v19
	v_mul_f32_e32 v19, v27, v19
	v_exp_f32_e32 v19, v19
	s_nop 0
	v_add_f32_e32 v19, 1.0, v19
	v_rcp_f32_e32 v20, v19
	s_nop 0
	v_mul_f32_e32 v41, v27, v20
	s_lshr_b32 s54, s89, 4
	s_and_b32 s54, s54, 0x78
	s_add_i32 s54, s54, s29
	v_mul_f32_e32 v18, v26, v26
	v_mul_f32_e32 v18, 0xbdd2d3e8, v18
	v_add_f32_e32 v18, 0xc0135761, v18
	v_mul_f32_e32 v18, v26, v18
	v_exp_f32_e32 v18, v18
	s_nop 0
	v_add_f32_e32 v18, 1.0, v18
	v_rcp_f32_e32 v19, v18
	s_nop 0
	v_mul_f32_e32 v40, v26, v19
	v_pk_mul_f32 v[18:19], v[40:41], v[40:41]
	s_mov_b32 s55, s9
	v_add_f32_e32 v17, v18, v17
	v_add_f32_e32 v17, v19, v17
	v_and_b32_e32 v19, 64, v165
	v_xor_b32_e32 v18, 16, v165
	v_add_u32_e32 v19, 64, v19
	v_cmp_lt_i32_e32 vcc, v18, v19
	s_lshl_b64 s[54:55], s[54:55], 14
	s_add_u32 s53, s36, s56
	v_cndmask_b32_e32 v18, v165, v18, vcc
	v_lshlrev_b32_e32 v18, 2, v18
	ds_bpermute_b32 v18, v18, v17
	v_readlane_b32 s36, v254, 35
	s_addc_u32 s56, s36, s57
	s_add_u32 s54, s53, s54
	s_addc_u32 s55, s56, s55
	s_waitcnt lgkmcnt(0)
; __device__ __forceinline__ unsigned f2bf(float f) { unsigned u = __float_as_uint(f); return (u + 0x7fffu + ((u >> 16) & 1u)) >> 16; }
; __device__ __forceinline__ float head_ssq(const float (&v)[16]) {
;     ...
;     s += __shfl_xor(s, 16); s += __shfl_xor(s, 32);
;     __device__ __forceinline__ void operator()(const f32x4 (&acc)[2][2][4][2], const pg8::Unit& u, int wr, int wc, int fr, int fq) const {
;     ...
;                     const float rn = rsqrtf(head_ssq(y) * (1.f / 64.f) + EPS);
;                     bf16_t* p = zvT + (((size_t)b * 16 + (s >> 7)) * 8 + g) * 8192 + (s & 127);
; #pragma unroll
;                     for (int i = 0; i < 16; ++i) { const int d = 32 * (i >> 3) + d0 + (i & 7); p[d * 128] = (bf16_t)f2bf(y[i] * rn * g_sgu[g * 64 + d]); }
	v_add_f32_e32 v17, v17, v18
	v_xor_b32_e32 v18, 32, v165
	v_cmp_lt_i32_e32 vcc, v18, v19
	s_mov_b64 s[56:57], s[40:41]
	s_nop 0
	v_cndmask_b32_e32 v18, v165, v18, vcc
	v_lshlrev_b32_e32 v18, 2, v18
	ds_bpermute_b32 v18, v18, v17
	s_waitcnt lgkmcnt(0)
	v_add_f32_e32 v17, v17, v18
	v_fmamk_f32 v17, v17, 0x3c800000, v161
	v_cmp_gt_f32_e32 vcc, s61, v17
	v_mul_f32_e32 v18, 0x4b800000, v17
	s_nop 0
	v_cndmask_b32_e32 v17, v17, v18, vcc
	v_rsq_f32_e32 v17, v17
	s_nop 0
	v_mul_f32_e32 v18, 0x45800000, v17
	v_cndmask_b32_e32 v60, v17, v18, vcc
	v_and_b32_e32 v17, 0x6f, v24
	v_lshlrev_b32_e32 v136, 1, v17
	v_lshl_add_u64 v[42:43], s[54:55], 0, v[136:137]
	s_mov_b64 s[54:55], s[38:39]
	v_readlane_b32 s36, v254, 8
	v_or_b32_e32 v136, s27, v140
	v_readlane_b32 s37, v254, 9
	v_mul_f32_e32 v61, v16, v60
	v_readlane_b32 s50, v254, 22
	v_lshl_add_u64 v[20:21], v[136:137], 2, s[36:37]
	global_load_dwordx4 v[16:19], v[20:21], off offset:16
	s_nop 0
	global_load_dwordx4 v[20:23], v[20:21], off
	v_lshlrev_b32_e32 v136, 1, v142
	v_lshl_add_u64 v[62:63], v[42:43], 0, v[136:137]
	v_add_u32_e32 v136, s27, v140
	v_readlane_b32 s51, v254, 23
	v_readlane_b32 s38, v254, 10
	v_readlane_b32 s39, v254, 11
	v_readlane_b32 s40, v254, 12
	v_readlane_b32 s41, v254, 13
	v_readlane_b32 s42, v254, 14
	v_readlane_b32 s43, v254, 15
	v_readlane_b32 s49, v254, 21
	v_readlane_b32 s50, v254, 39
	s_mov_b64 s[38:39], s[54:55]
	s_mov_b64 s[42:43], s[58:59]
	s_mov_b64 s[40:41], s[56:57]
	v_readlane_b32 s49, v254, 41
	v_readlane_b32 s51, v254, 40
	s_mov_b64 s[54:55], 0
	v_readlane_b32 s44, v254, 16
	v_readlane_b32 s45, v254, 17
	v_readlane_b32 s46, v254, 18
	v_readlane_b32 s47, v254, 19
	v_readlane_b32 s48, v254, 20
	s_waitcnt vmcnt(0)
	v_mul_f32_e32 v20, v20, v61
	v_bfe_u32 v61, v20, 16, 1
	v_add3_u32 v20, v20, v61, s20
	global_store_short_d16_hi v[62:63], v20, off
	v_mul_f32_e32 v20, v25, v60
	v_mul_f32_e32 v20, v21, v20
	v_lshl_add_u64 v[62:63], v[136:137], 2, s[36:37]
	v_bfe_u32 v21, v20, 16, 1
	v_lshlrev_b32_e32 v136, 1, v144
	v_add3_u32 v25, v20, v21, s20
	v_lshl_add_u64 v[20:21], v[42:43], 0, v[136:137]
	global_store_short_d16_hi v[20:21], v25, off
	v_mul_f32_e32 v20, v53, v60
	v_mul_f32_e32 v20, v22, v20
	v_bfe_u32 v21, v20, 16, 1
	v_lshlrev_b32_e32 v136, 1, v146
	v_add3_u32 v22, v20, v21, s20
	v_lshl_add_u64 v[20:21], v[42:43], 0, v[136:137]
	global_store_short_d16_hi v[20:21], v22, off
	v_mul_f32_e32 v20, v54, v60
	v_mul_f32_e32 v20, v23, v20
	v_bfe_u32 v21, v20, 16, 1
	v_lshlrev_b32_e32 v136, 1, v148
	v_add3_u32 v22, v20, v21, s20
	v_lshl_add_u64 v[20:21], v[42:43], 0, v[136:137]
	global_store_short_d16_hi v[20:21], v22, off
	v_mul_f32_e32 v20, v55, v60
	v_mul_f32_e32 v16, v16, v20
	v_bfe_u32 v20, v16, 16, 1
	v_lshlrev_b32_e32 v136, 1, v150
	v_add3_u32 v16, v16, v20, s20
	v_lshl_add_u64 v[20:21], v[42:43], 0, v[136:137]
	global_store_short_d16_hi v[20:21], v16, off
	v_mul_f32_e32 v16, v57, v60
	v_mul_f32_e32 v16, v16, v17
	v_bfe_u32 v17, v16, 16, 1
	v_lshlrev_b32_e32 v136, 1, v152
	v_add3_u32 v20, v16, v17, s20
	v_lshl_add_u64 v[16:17], v[42:43], 0, v[136:137]
	global_store_short_d16_hi v[16:17], v20, off
	v_mul_f32_e32 v16, v58, v60
	v_mul_f32_e32 v16, v16, v18
	v_bfe_u32 v17, v16, 16, 1
	v_lshlrev_b32_e32 v136, 1, v154
	v_add3_u32 v18, v16, v17, s20
	v_lshl_add_u64 v[16:17], v[42:43], 0, v[136:137]
	global_store_short_d16_hi v[16:17], v18, off
	v_mul_f32_e32 v16, v59, v60
	v_mul_f32_e32 v16, v16, v19
	v_bfe_u32 v17, v16, 16, 1
	v_lshlrev_b32_e32 v136, 1, v156
	v_add3_u32 v18, v16, v17, s20
	v_lshl_add_u64 v[16:17], v[42:43], 0, v[136:137]
	global_store_short_d16_hi v[16:17], v18, off
	global_load_dwordx4 v[16:19], v[62:63], off offset:144
	s_nop 0
	global_load_dwordx4 v[20:23], v[62:63], off offset:128
	v_mul_f32_e32 v25, v34, v60
	v_lshlrev_b32_e32 v136, 1, v158
	v_lshl_add_u64 v[54:55], v[42:43], 0, v[136:137]
	v_lshlrev_b32_e32 v136, 1, v160
	s_waitcnt vmcnt(0)
	v_mul_f32_e32 v20, v25, v20
	v_bfe_u32 v25, v20, 16, 1
	v_add3_u32 v20, v20, v25, s20
	global_store_short_d16_hi v[54:55], v20, off
	v_mul_f32_e32 v20, v35, v60
	v_mul_f32_e32 v20, v20, v21
	v_bfe_u32 v21, v20, 16, 1
	v_add3_u32 v25, v20, v21, s20
	v_lshl_add_u64 v[20:21], v[42:43], 0, v[136:137]
	global_store_short_d16_hi v[20:21], v25, off
	v_mul_f32_e32 v20, v36, v60
	v_mul_f32_e32 v20, v20, v22
	v_bfe_u32 v21, v20, 16, 1
	v_lshlrev_b32_e32 v136, 1, v162
	v_add3_u32 v22, v20, v21, s20
	v_lshl_add_u64 v[20:21], v[42:43], 0, v[136:137]
	global_store_short_d16_hi v[20:21], v22, off
	v_mul_f32_e32 v20, v37, v60
	v_mul_f32_e32 v20, v20, v23
	v_bfe_u32 v21, v20, 16, 1
	v_lshlrev_b32_e32 v136, 1, v164
	v_add3_u32 v22, v20, v21, s20
	v_lshl_add_u64 v[20:21], v[42:43], 0, v[136:137]
	global_store_short_d16_hi v[20:21], v22, off
	v_mul_f32_e32 v20, v38, v60
	v_mul_f32_e32 v16, v20, v16
	v_bfe_u32 v20, v16, 16, 1
	v_add3_u32 v16, v16, v20, s20
	v_or_b32_e32 v20, 0x1200, v142
	v_lshlrev_b32_e32 v136, 1, v20
	v_lshl_add_u64 v[20:21], v[42:43], 0, v[136:137]
	global_store_short_d16_hi v[20:21], v16, off
	v_mul_f32_e32 v16, v39, v60
	v_mul_f32_e32 v16, v16, v17
	v_bfe_u32 v17, v16, 16, 1
	v_add3_u32 v20, v16, v17, s20
	v_or_b32_e32 v16, 0x1280, v142
	v_lshlrev_b32_e32 v136, 1, v16
	v_lshl_add_u64 v[16:17], v[42:43], 0, v[136:137]
	global_store_short_d16_hi v[16:17], v20, off
	v_mul_f32_e32 v16, v40, v60
	v_mul_f32_e32 v16, v16, v18
	v_bfe_u32 v17, v16, 16, 1
	v_add3_u32 v18, v16, v17, s20
	v_or_b32_e32 v16, 0x1300, v142
	v_lshlrev_b32_e32 v136, 1, v16
	v_lshl_add_u64 v[16:17], v[42:43], 0, v[136:137]
	global_store_short_d16_hi v[16:17], v18, off
	v_mul_f32_e32 v16, v41, v60
	v_mul_f32_e32 v16, v16, v19
	v_bfe_u32 v17, v16, 16, 1
	v_lshlrev_b32_e32 v136, 1, v172
	v_add3_u32 v18, v16, v17, s20
	v_lshl_add_u64 v[16:17], v[42:43], 0, v[136:137]
	global_store_short_d16_hi v[16:17], v18, off

; __device__ __forceinline__ float gelu_tanh(float x) {
;     const float u = 0.7978845608028654f * (x + 0.044715f * x * x * x);
;     return x / (1.f + __expf(-2.f * u));
; }
;     __device__ __forceinline__ void operator()(const f32x4 (&acc)[2][2][4][2], const pg8::Unit& u, int wr, int wc, int fr, int fq) const {
;     ...
;                 } else if (cs < 28) {
;                     float y[16];
; #pragma unroll
;                     for (int i = 0; i < 16; ++i) y[i] = gelu_tanh(v[i]);
;                     bf16_t* p = zu + (size_t)row * 512 + (cs - 20) * 64 + d0; store8(p, y); store8(p + 32, y + 8);
.LBB0_378:
	s_andn2_b64 vcc, exec, s[54:55]
	s_cbranch_vccnz .LBB0_380
	v_readlane_b32 s36, v254, 31
	v_readlane_b32 s37, v254, 32
	v_lshlrev_b32_e32 v136, 1, v140
	s_nop 0
	v_mul_f32_e32 v16, v45, v45
	v_mul_f32_e32 v16, 0xbdd2d3e8, v16
	v_add_f32_e32 v16, 0xc0135761, v16
	v_mul_f32_e32 v16, v45, v16
	v_exp_f32_e32 v16, v16
	s_nop 0
	v_add_f32_e32 v16, 1.0, v16
	v_rcp_f32_e32 v17, v16
	s_nop 0
	v_mul_f32_e32 v16, v45, v17
	s_nop 0
	s_nop 0
	v_mul_f32_e32 v17, v46, v46
	v_mul_f32_e32 v17, 0xbdd2d3e8, v17
	v_add_f32_e32 v17, 0xc0135761, v17
	v_mul_f32_e32 v17, v46, v17
	v_exp_f32_e32 v17, v17
	s_nop 0
	v_add_f32_e32 v17, 1.0, v17
	v_rcp_f32_e32 v18, v17
	s_nop 0
	v_mul_f32_e32 v17, v46, v18
	v_cvt_pk_bf16_f32 v16, v16, v17
	s_nop 0
	s_nop 0
	v_mul_f32_e32 v18, v47, v47
	v_mul_f32_e32 v18, 0xbdd2d3e8, v18
	v_add_f32_e32 v18, 0xc0135761, v18
	v_mul_f32_e32 v18, v47, v18
	v_exp_f32_e32 v18, v18
	s_nop 0
	v_add_f32_e32 v18, 1.0, v18
	v_rcp_f32_e32 v19, v18
	s_nop 0
	v_mul_f32_e32 v18, v47, v19
	s_nop 0
	s_nop 0
	v_mul_f32_e32 v19, v48, v48
	v_mul_f32_e32 v19, 0xbdd2d3e8, v19
	v_add_f32_e32 v19, 0xc0135761, v19
	v_mul_f32_e32 v19, v48, v19
	v_exp_f32_e32 v19, v19
	s_nop 0
	v_add_f32_e32 v19, 1.0, v19
	v_rcp_f32_e32 v20, v19
	s_nop 0
	v_mul_f32_e32 v19, v48, v20
	v_cvt_pk_bf16_f32 v17, v18, v19
	s_nop 0
	s_nop 0
	v_mul_f32_e32 v20, v49, v49
	v_mul_f32_e32 v20, 0xbdd2d3e8, v20
	v_add_f32_e32 v20, 0xc0135761, v20
	v_mul_f32_e32 v20, v49, v20
	v_exp_f32_e32 v20, v20
	s_nop 0
	v_add_f32_e32 v20, 1.0, v20
	v_rcp_f32_e32 v21, v20
	s_nop 0
	v_mul_f32_e32 v20, v49, v21
	s_nop 0
	s_nop 0
	v_mul_f32_e32 v21, v50, v50
	v_mul_f32_e32 v21, 0xbdd2d3e8, v21
	v_add_f32_e32 v21, 0xc0135761, v21
	v_mul_f32_e32 v21, v50, v21
	v_exp_f32_e32 v21, v21
	s_nop 0
	v_add_f32_e32 v21, 1.0, v21
	v_rcp_f32_e32 v22, v21
	s_nop 0
	v_mul_f32_e32 v21, v50, v22
	v_cvt_pk_bf16_f32 v18, v20, v21
	s_nop 0
	s_nop 0
	v_mul_f32_e32 v22, v51, v51
	v_mul_f32_e32 v22, 0xbdd2d3e8, v22
	v_add_f32_e32 v22, 0xc0135761, v22
	v_mul_f32_e32 v22, v51, v22
	v_exp_f32_e32 v22, v22
	s_nop 0
	v_add_f32_e32 v22, 1.0, v22
	v_rcp_f32_e32 v23, v22
	s_nop 0
	v_mul_f32_e32 v22, v51, v23
	s_nop 0
	s_nop 0
	v_mul_f32_e32 v23, v52, v52
	v_mul_f32_e32 v23, 0xbdd2d3e8, v23
	v_add_f32_e32 v23, 0xc0135761, v23
	v_mul_f32_e32 v23, v52, v23
	v_exp_f32_e32 v23, v23
	s_nop 0
	v_add_f32_e32 v23, 1.0, v23
	v_rcp_f32_e32 v25, v23
	s_nop 0
	v_mul_f32_e32 v23, v52, v25
	v_cvt_pk_bf16_f32 v19, v22, v23
	s_nop 0
	s_nop 0
	v_mul_f32_e32 v25, v28, v28
	v_mul_f32_e32 v25, 0xbdd2d3e8, v25
	v_add_f32_e32 v25, 0xc0135761, v25
	v_mul_f32_e32 v25, v28, v25
	v_exp_f32_e32 v25, v25
	s_nop 0
	v_add_f32_e32 v25, 1.0, v25
	v_rcp_f32_e32 v34, v25
	s_nop 0
	v_mul_f32_e32 v34, v28, v34
	s_nop 0
	s_nop 0
	v_mul_f32_e32 v25, v29, v29
	v_mul_f32_e32 v25, 0xbdd2d3e8, v25
	v_add_f32_e32 v25, 0xc0135761, v25
	v_mul_f32_e32 v25, v29, v25
	v_exp_f32_e32 v25, v25
	s_nop 0
	v_add_f32_e32 v25, 1.0, v25
	v_rcp_f32_e32 v35, v25
	s_nop 0
	v_mul_f32_e32 v35, v29, v35
	s_nop 0
	s_nop 0
	v_mul_f32_e32 v25, v32, v32
	v_mul_f32_e32 v25, 0xbdd2d3e8, v25
	v_add_f32_e32 v25, 0xc0135761, v25
	v_mul_f32_e32 v25, v32, v25
	v_exp_f32_e32 v25, v25
	s_nop 0
	v_add_f32_e32 v25, 1.0, v25
	v_rcp_f32_e32 v36, v25
	s_nop 0
	v_mul_f32_e32 v38, v32, v36
	s_nop 0
	s_nop 0
	v_mul_f32_e32 v25, v33, v33
	v_mul_f32_e32 v25, 0xbdd2d3e8, v25
	v_add_f32_e32 v25, 0xc0135761, v25
	v_mul_f32_e32 v25, v33, v25
	v_exp_f32_e32 v25, v25
	s_nop 0
	v_add_f32_e32 v25, 1.0, v25
	v_rcp_f32_e32 v36, v25
	s_nop 0
	v_mul_f32_e32 v39, v33, v36
	s_nop 0
	s_nop 0
	v_mul_f32_e32 v25, v30, v30
	v_mul_f32_e32 v25, 0xbdd2d3e8, v25
	v_add_f32_e32 v25, 0xc0135761, v25
	v_mul_f32_e32 v25, v30, v25
	v_exp_f32_e32 v25, v25
	s_nop 0
	v_add_f32_e32 v25, 1.0, v25
	v_rcp_f32_e32 v36, v25
	s_nop 0
	v_mul_f32_e32 v40, v30, v36
	s_nop 0
	s_nop 0
	v_mul_f32_e32 v25, v31, v31
	v_mul_f32_e32 v25, 0xbdd2d3e8, v25
	v_add_f32_e32 v25, 0xc0135761, v25
	v_mul_f32_e32 v25, v31, v25
	v_exp_f32_e32 v25, v25
	s_nop 0
	v_add_f32_e32 v25, 1.0, v25
	v_rcp_f32_e32 v36, v25
	s_nop 0
	v_mul_f32_e32 v41, v31, v36
	s_nop 0
	s_nop 0
	v_mul_f32_e32 v25, v26, v26
	v_mul_f32_e32 v25, 0xbdd2d3e8, v25
	v_add_f32_e32 v25, 0xc0135761, v25
	v_mul_f32_e32 v25, v26, v25
	v_exp_f32_e32 v25, v25
	s_nop 0
	v_add_f32_e32 v25, 1.0, v25
	v_rcp_f32_e32 v36, v25
	s_nop 0
	v_mul_f32_e32 v42, v26, v36
	s_nop 0
	s_nop 0
	v_mul_f32_e32 v25, v27, v27
	v_mul_f32_e32 v25, 0xbdd2d3e8, v25
	v_add_f32_e32 v25, 0xc0135761, v25
	v_mul_f32_e32 v25, v27, v25
	v_exp_f32_e32 v25, v25
	s_nop 0
	v_add_f32_e32 v25, 1.0, v25
	v_rcp_f32_e32 v36, v25
	s_nop 0
	v_mul_f32_e32 v43, v27, v36
	v_ashrrev_i32_e32 v25, 31, v24
	v_lshlrev_b64 v[36:37], 10, v[24:25]
	v_lshl_add_u64 v[36:37], s[36:37], 0, v[36:37]
	v_lshl_add_u64 v[36:37], s[8:9], 1, v[36:37]
	v_lshl_add_u64 v[36:37], v[36:37], 0, v[136:137]
	global_store_dwordx4 v[36:37], v[16:19], off offset:-2560
	s_nop 1
	v_cvt_pk_bf16_f32 v16, v34, v35
	v_cvt_pk_bf16_f32 v17, v38, v39
	v_cvt_pk_bf16_f32 v18, v40, v41
	v_cvt_pk_bf16_f32 v19, v42, v43
	global_store_dwordx4 v[36:37], v[16:19], off offset:-2496

; __device__ __forceinline__ float gelu_tanh(float x) {
;     const float u = 0.7978845608028654f * (x + 0.044715f * x * x * x);
;     return x / (1.f + __expf(-2.f * u));
;     __device__ __forceinline__ void operator()(const f32x4 (&acc)[2][2][4][2], const pg8::Unit& u, int wr, int wc, int fr, int fq) const {
;     ...
;                     const int g = cs - 28;
;                     float y[16];
; #pragma unroll
;                     for (int i = 0; i < 16; ++i) y[i] = gelu_tanh(v[i]);
;                     const float rn = rsqrtf(head_ssq(y) * (1.f / 64.f) + EPS);
.LBB0_401:
	s_andn2_b64 vcc, exec, s[72:73]
	s_mov_b64 s[50:51], -1
	s_cbranch_vccnz .LBB0_417
	s_andn2_b64 vcc, exec, s[70:71]
	s_mov_b64 s[48:49], -1
	s_cbranch_vccnz .LBB0_414
	s_andn2_b64 vcc, exec, s[42:43]
	s_mov_b64 s[46:47], -1
	s_cbranch_vccnz .LBB0_411
	s_andn2_b64 vcc, exec, s[40:41]
	s_mov_b64 s[44:45], -1
	s_cbranch_vccnz .LBB0_406
	s_ashr_i32 s53, s52, 31
	s_lshl_b64 s[46:47], s[52:53], 21
	v_readlane_b32 s36, v254, 35
	s_mov_b64 s[54:55], s[38:39]
	v_mul_f32_e32 v0, v36, v36
	v_mul_f32_e32 v0, 0xbdd2d3e8, v0
	v_add_f32_e32 v0, 0xc0135761, v0
	v_mul_f32_e32 v0, v36, v0
	v_exp_f32_e32 v0, v0
	s_nop 0
	v_add_f32_e32 v0, 1.0, v0
	v_rcp_f32_e32 v1, v0
	s_nop 0
	v_mul_f32_e32 v0, v36, v1
	s_nop 0
	s_nop 0
	v_mul_f32_e32 v1, v35, v35
	v_mul_f32_e32 v1, 0xbdd2d3e8, v1
	v_add_f32_e32 v1, 0xc0135761, v1
	v_mul_f32_e32 v1, v35, v1
	v_exp_f32_e32 v1, v1
	s_nop 0
	v_add_f32_e32 v1, 1.0, v1
	v_rcp_f32_e32 v2, v1
	s_nop 0
	v_mul_f32_e32 v9, v35, v2
	s_nop 0
	s_nop 0
	v_mul_f32_e32 v1, v34, v34
	v_mul_f32_e32 v1, 0xbdd2d3e8, v1
	v_add_f32_e32 v1, 0xc0135761, v1
	v_mul_f32_e32 v1, v34, v1
	v_exp_f32_e32 v1, v1
	s_nop 0
	v_add_f32_e32 v1, 1.0, v1
	v_rcp_f32_e32 v2, v1
	s_nop 0
	v_mul_f32_e32 v37, v34, v2
	s_nop 0
	s_nop 0
	v_mul_f32_e32 v1, v33, v33
	v_mul_f32_e32 v1, 0xbdd2d3e8, v1
	v_add_f32_e32 v1, 0xc0135761, v1
	v_mul_f32_e32 v1, v33, v1
	v_exp_f32_e32 v1, v1
	s_nop 0
	v_add_f32_e32 v1, 1.0, v1
	v_rcp_f32_e32 v2, v1
	s_nop 0
	v_mul_f32_e32 v38, v33, v2
	s_nop 0
	s_nop 0
	v_mul_f32_e32 v1, v32, v32
	v_mul_f32_e32 v1, 0xbdd2d3e8, v1
	v_add_f32_e32 v1, 0xc0135761, v1
	v_mul_f32_e32 v1, v32, v1
	v_exp_f32_e32 v1, v1
	s_nop 0
	v_add_f32_e32 v1, 1.0, v1
	v_rcp_f32_e32 v2, v1
	s_nop 0
	v_mul_f32_e32 v39, v32, v2
	s_nop 0
	s_nop 0
	v_mul_f32_e32 v1, v31, v31
	v_mul_f32_e32 v1, 0xbdd2d3e8, v1
	v_add_f32_e32 v1, 0xc0135761, v1
	v_mul_f32_e32 v1, v31, v1
	v_exp_f32_e32 v1, v1
	s_nop 0
	v_add_f32_e32 v1, 1.0, v1
	v_rcp_f32_e32 v2, v1
	s_nop 0
	v_mul_f32_e32 v40, v31, v2
	s_nop 0
	s_nop 0
	v_mul_f32_e32 v1, v30, v30
	v_mul_f32_e32 v1, 0xbdd2d3e8, v1
	v_add_f32_e32 v1, 0xc0135761, v1
	v_mul_f32_e32 v1, v30, v1
	v_exp_f32_e32 v1, v1
	s_nop 0
	v_add_f32_e32 v1, 1.0, v1
	v_rcp_f32_e32 v2, v1
	s_nop 0
	v_mul_f32_e32 v41, v30, v2
	s_nop 0
	s_nop 0
	v_mul_f32_e32 v1, v29, v29
	v_mul_f32_e32 v1, 0xbdd2d3e8, v1
	v_add_f32_e32 v1, 0xc0135761, v1
	v_mul_f32_e32 v1, v29, v1
	v_exp_f32_e32 v1, v1
	s_nop 0
	v_add_f32_e32 v1, 1.0, v1
	v_rcp_f32_e32 v2, v1
	s_nop 0
	v_mul_f32_e32 v42, v29, v2
	v_mul_f32_e32 v3, v17, v17
	v_mul_f32_e32 v3, 0xbdd2d3e8, v3
	v_add_f32_e32 v3, 0xc0135761, v3
	v_mul_f32_e32 v3, v17, v3
	v_exp_f32_e32 v3, v3
	s_nop 0
	v_add_f32_e32 v3, 1.0, v3
	v_rcp_f32_e32 v18, v3
	s_nop 0
	v_mul_f32_e32 v19, v17, v18
	v_mul_f32_e32 v1, v9, v9
	v_fmac_f32_e32 v1, v0, v0
	v_fmac_f32_e32 v1, v37, v37
	v_fmac_f32_e32 v1, v38, v38
	v_fmac_f32_e32 v1, v39, v39
	v_fmac_f32_e32 v1, v40, v40
	v_fmac_f32_e32 v1, v41, v41
	v_mul_f32_e32 v2, v16, v16
	v_mul_f32_e32 v2, 0xbdd2d3e8, v2
	v_add_f32_e32 v2, 0xc0135761, v2
	v_mul_f32_e32 v2, v16, v2
	v_exp_f32_e32 v2, v2
	s_nop 0
	v_add_f32_e32 v2, 1.0, v2
	v_rcp_f32_e32 v3, v2
	s_nop 0
	v_mul_f32_e32 v18, v16, v3
	v_fmac_f32_e32 v1, v42, v42
	v_pk_mul_f32 v[2:3], v[18:19], v[18:19]
	s_nop 0
	v_add_f32_e32 v1, v2, v1
	v_add_f32_e32 v1, v3, v1
	s_nop 0
	s_nop 0
	v_mul_f32_e32 v3, v15, v15
	v_mul_f32_e32 v3, 0xbdd2d3e8, v3
	v_add_f32_e32 v3, 0xc0135761, v3
	v_mul_f32_e32 v3, v15, v3
	v_exp_f32_e32 v3, v3
	s_nop 0
	v_add_f32_e32 v3, 1.0, v3
	v_rcp_f32_e32 v4, v3
	s_nop 0
	v_mul_f32_e32 v21, v15, v4
	s_nop 0
	v_mul_f32_e32 v2, v14, v14
	v_mul_f32_e32 v2, 0xbdd2d3e8, v2
	v_add_f32_e32 v2, 0xc0135761, v2
	v_mul_f32_e32 v2, v14, v2
	v_exp_f32_e32 v2, v2
	s_nop 0
	v_add_f32_e32 v2, 1.0, v2
	v_rcp_f32_e32 v3, v2
	s_nop 0
	v_mul_f32_e32 v20, v14, v3
	v_pk_mul_f32 v[2:3], v[20:21], v[20:21]
	s_nop 0
	v_add_f32_e32 v1, v2, v1
	v_add_f32_e32 v1, v3, v1
	s_nop 0
	s_nop 0
	v_mul_f32_e32 v3, v13, v13
	v_mul_f32_e32 v3, 0xbdd2d3e8, v3
	v_add_f32_e32 v3, 0xc0135761, v3
	v_mul_f32_e32 v3, v13, v3
	v_exp_f32_e32 v3, v3
	s_nop 0
	v_add_f32_e32 v3, 1.0, v3
	v_rcp_f32_e32 v4, v3
	s_nop 0
	v_mul_f32_e32 v23, v13, v4
	s_nop 0
	v_mul_f32_e32 v2, v12, v12
	v_mul_f32_e32 v2, 0xbdd2d3e8, v2
	v_add_f32_e32 v2, 0xc0135761, v2
	v_mul_f32_e32 v2, v12, v2
	v_exp_f32_e32 v2, v2
	s_nop 0
	v_add_f32_e32 v2, 1.0, v2
	v_rcp_f32_e32 v3, v2
	s_nop 0
	v_mul_f32_e32 v22, v12, v3
	v_pk_mul_f32 v[2:3], v[22:23], v[22:23]
	s_nop 0
	v_add_f32_e32 v1, v2, v1
	v_add_f32_e32 v1, v3, v1
	s_nop 0
	s_nop 0
	v_mul_f32_e32 v3, v11, v11
	v_mul_f32_e32 v3, 0xbdd2d3e8, v3
	v_add_f32_e32 v3, 0xc0135761, v3
	v_mul_f32_e32 v3, v11, v3
	v_exp_f32_e32 v3, v3
	s_nop 0
	v_add_f32_e32 v3, 1.0, v3
	v_rcp_f32_e32 v4, v3
	s_nop 0
	v_mul_f32_e32 v25, v11, v4
	s_lshr_b32 s44, s89, 4
	s_and_b32 s44, s44, 0x78
	s_add_i32 s44, s44, s29
	v_mul_f32_e32 v2, v10, v10
	v_mul_f32_e32 v2, 0xbdd2d3e8, v2
	v_add_f32_e32 v2, 0xc0135761, v2
	v_mul_f32_e32 v2, v10, v2
	v_exp_f32_e32 v2, v2
	s_nop 0
	v_add_f32_e32 v2, 1.0, v2
	v_rcp_f32_e32 v3, v2
	s_nop 0
	v_mul_f32_e32 v24, v10, v3
	v_pk_mul_f32 v[2:3], v[24:25], v[24:25]
	s_mov_b32 s45, s9
	v_add_f32_e32 v1, v2, v1
	v_add_f32_e32 v1, v3, v1
	v_and_b32_e32 v3, 64, v165
	v_xor_b32_e32 v2, 16, v165
	v_add_u32_e32 v3, 64, v3
	v_cmp_lt_i32_e32 vcc, v2, v3
	s_lshl_b64 s[44:45], s[44:45], 14
	v_readlane_b32 s29, v254, 33
	v_cndmask_b32_e32 v2, v165, v2, vcc
	v_lshlrev_b32_e32 v2, 2, v2
	ds_bpermute_b32 v2, v2, v1
	s_add_u32 s29, s29, s46
	s_addc_u32 s46, s36, s47
	s_add_u32 s44, s29, s44
	s_addc_u32 s45, s46, s45
	s_waitcnt lgkmcnt(0)
; __device__ __forceinline__ unsigned f2bf(float f) { unsigned u = __float_as_uint(f); return (u + 0x7fffu + ((u >> 16) & 1u)) >> 16; }
;     __device__ __forceinline__ void operator()(const f32x4 (&acc)[2][2][4][2], const pg8::Unit& u, int wr, int wc, int fr, int fq) const {
;     ...
;                     const float rn = rsqrtf(head_ssq(y) * (1.f / 64.f) + EPS);
;                     bf16_t* p = zvT + (((size_t)b * 16 + (s >> 7)) * 8 + g) * 8192 + (s & 127);
; #pragma unroll
;                     for (int i = 0; i < 16; ++i) { const int d = 32 * (i >> 3) + d0 + (i & 7); p[d * 128] = (bf16_t)f2bf(y[i] * rn * g_sgu[g * 64 + d]); }
	v_add_f32_e32 v1, v1, v2
	v_xor_b32_e32 v2, 32, v165
	v_cmp_lt_i32_e32 vcc, v2, v3
	s_nop 1
	v_cndmask_b32_e32 v2, v165, v2, vcc
	v_lshlrev_b32_e32 v2, 2, v2
	ds_bpermute_b32 v2, v2, v1
	s_waitcnt lgkmcnt(0)
	v_add_f32_e32 v1, v1, v2
	v_fmamk_f32 v1, v1, 0x3c800000, v161
	v_cmp_gt_f32_e32 vcc, s61, v1
	v_mul_f32_e32 v2, 0x4b800000, v1
	s_nop 0
	v_cndmask_b32_e32 v1, v1, v2, vcc
	v_rsq_f32_e32 v1, v1
	s_nop 0
	v_mul_f32_e32 v2, 0x45800000, v1
	v_cndmask_b32_e32 v43, v1, v2, vcc
	v_and_b32_e32 v1, 0x7f, v8
	v_lshlrev_b32_e32 v136, 1, v1
	v_lshl_add_u64 v[26:27], s[44:45], 0, v[136:137]
	v_readlane_b32 s36, v254, 8
	v_or_b32_e32 v136, s27, v140
	v_readlane_b32 s37, v254, 9
	v_mul_f32_e32 v44, v0, v43
	v_readlane_b32 s38, v254, 10
	v_lshl_add_u64 v[4:5], v[136:137], 2, s[36:37]
	global_load_dwordx4 v[0:3], v[4:5], off offset:16
	s_nop 0
	global_load_dwordx4 v[4:7], v[4:5], off
	v_lshlrev_b32_e32 v136, 1, v142
	v_readlane_b32 s39, v254, 11
	v_readlane_b32 s44, v254, 16
	v_readlane_b32 s45, v254, 17
	s_mov_b64 s[38:39], s[54:55]
	s_mov_b64 s[44:45], 0
	v_readlane_b32 s40, v254, 12
	v_readlane_b32 s41, v254, 13
	v_readlane_b32 s42, v254, 14
	v_readlane_b32 s43, v254, 15
	v_readlane_b32 s46, v254, 18
	v_readlane_b32 s47, v254, 19
	v_readlane_b32 s48, v254, 20
	v_readlane_b32 s49, v254, 21
	v_readlane_b32 s50, v254, 22
	v_readlane_b32 s51, v254, 23
	s_waitcnt vmcnt(0)
	v_mul_f32_e32 v4, v4, v44
	v_bfe_u32 v44, v4, 16, 1
	v_add3_u32 v4, v4, v44, s20
	v_lshl_add_u64 v[44:45], v[26:27], 0, v[136:137]
	global_store_short_d16_hi v[44:45], v4, off
	v_mul_f32_e32 v4, v9, v43
	v_add_u32_e32 v136, s27, v140
	v_mul_f32_e32 v4, v5, v4
	v_lshl_add_u64 v[44:45], v[136:137], 2, s[36:37]
	v_bfe_u32 v5, v4, 16, 1
	v_lshlrev_b32_e32 v136, 1, v144
	v_add3_u32 v9, v4, v5, s20
	v_lshl_add_u64 v[4:5], v[26:27], 0, v[136:137]
	global_store_short_d16_hi v[4:5], v9, off
	v_mul_f32_e32 v4, v37, v43
	v_mul_f32_e32 v4, v6, v4
	v_bfe_u32 v5, v4, 16, 1
	v_lshlrev_b32_e32 v136, 1, v146
	v_add3_u32 v6, v4, v5, s20
	v_lshl_add_u64 v[4:5], v[26:27], 0, v[136:137]
	global_store_short_d16_hi v[4:5], v6, off
	v_mul_f32_e32 v4, v38, v43
	v_mul_f32_e32 v4, v7, v4
	v_bfe_u32 v5, v4, 16, 1
	v_lshlrev_b32_e32 v136, 1, v148
	v_add3_u32 v6, v4, v5, s20
	v_lshl_add_u64 v[4:5], v[26:27], 0, v[136:137]
	global_store_short_d16_hi v[4:5], v6, off
	v_mul_f32_e32 v4, v39, v43
	v_mul_f32_e32 v0, v0, v4
	v_bfe_u32 v4, v0, 16, 1
	v_lshlrev_b32_e32 v136, 1, v150
	v_add3_u32 v0, v0, v4, s20
	v_lshl_add_u64 v[4:5], v[26:27], 0, v[136:137]
	global_store_short_d16_hi v[4:5], v0, off
	v_mul_f32_e32 v0, v40, v43
	v_mul_f32_e32 v0, v0, v1
	v_bfe_u32 v1, v0, 16, 1
	v_lshlrev_b32_e32 v136, 1, v152
	v_add3_u32 v4, v0, v1, s20
	v_lshl_add_u64 v[0:1], v[26:27], 0, v[136:137]
	global_store_short_d16_hi v[0:1], v4, off
	v_mul_f32_e32 v0, v41, v43
	v_mul_f32_e32 v0, v0, v2
	v_bfe_u32 v1, v0, 16, 1
	v_lshlrev_b32_e32 v136, 1, v154
	v_add3_u32 v2, v0, v1, s20
	v_lshl_add_u64 v[0:1], v[26:27], 0, v[136:137]
	global_store_short_d16_hi v[0:1], v2, off
	v_mul_f32_e32 v0, v42, v43
	v_mul_f32_e32 v0, v0, v3
	v_bfe_u32 v1, v0, 16, 1
	v_lshlrev_b32_e32 v136, 1, v156
	v_add3_u32 v2, v0, v1, s20
	v_lshl_add_u64 v[0:1], v[26:27], 0, v[136:137]
	global_store_short_d16_hi v[0:1], v2, off
	global_load_dwordx4 v[0:3], v[44:45], off offset:144
	s_nop 0
	global_load_dwordx4 v[4:7], v[44:45], off offset:128
	v_mul_f32_e32 v9, v18, v43
	v_lshlrev_b32_e32 v136, 1, v158
	v_lshl_add_u64 v[38:39], v[26:27], 0, v[136:137]
	v_lshlrev_b32_e32 v136, 1, v160
	s_waitcnt vmcnt(0)
	v_mul_f32_e32 v4, v9, v4
	v_bfe_u32 v9, v4, 16, 1
	v_add3_u32 v4, v4, v9, s20
	global_store_short_d16_hi v[38:39], v4, off
	v_mul_f32_e32 v4, v19, v43
	v_mul_f32_e32 v4, v4, v5
	v_bfe_u32 v5, v4, 16, 1
	v_add3_u32 v9, v4, v5, s20
	v_lshl_add_u64 v[4:5], v[26:27], 0, v[136:137]
	global_store_short_d16_hi v[4:5], v9, off
	v_mul_f32_e32 v4, v20, v43
	v_mul_f32_e32 v4, v4, v6
	v_bfe_u32 v5, v4, 16, 1
	v_lshlrev_b32_e32 v136, 1, v162
	v_add3_u32 v6, v4, v5, s20
	v_lshl_add_u64 v[4:5], v[26:27], 0, v[136:137]
	global_store_short_d16_hi v[4:5], v6, off
	v_mul_f32_e32 v4, v21, v43
	v_mul_f32_e32 v4, v4, v7
	v_bfe_u32 v5, v4, 16, 1
	v_lshlrev_b32_e32 v136, 1, v164
	v_add3_u32 v6, v4, v5, s20
	v_lshl_add_u64 v[4:5], v[26:27], 0, v[136:137]
	global_store_short_d16_hi v[4:5], v6, off
	v_mul_f32_e32 v4, v22, v43
	v_mul_f32_e32 v0, v4, v0
	v_bfe_u32 v4, v0, 16, 1
	v_add3_u32 v0, v0, v4, s20
	v_or_b32_e32 v4, 0x1200, v142
	v_lshlrev_b32_e32 v136, 1, v4
	v_lshl_add_u64 v[4:5], v[26:27], 0, v[136:137]
	global_store_short_d16_hi v[4:5], v0, off
	v_mul_f32_e32 v0, v23, v43
	v_mul_f32_e32 v0, v0, v1
	v_bfe_u32 v1, v0, 16, 1
	v_add3_u32 v4, v0, v1, s20
	v_or_b32_e32 v0, 0x1280, v142
	v_lshlrev_b32_e32 v136, 1, v0
	v_lshl_add_u64 v[0:1], v[26:27], 0, v[136:137]
	global_store_short_d16_hi v[0:1], v4, off
	v_mul_f32_e32 v0, v24, v43
	v_mul_f32_e32 v0, v0, v2
	v_bfe_u32 v1, v0, 16, 1
	v_add3_u32 v2, v0, v1, s20
	v_or_b32_e32 v0, 0x1300, v142
	v_lshlrev_b32_e32 v136, 1, v0
	v_lshl_add_u64 v[0:1], v[26:27], 0, v[136:137]
	global_store_short_d16_hi v[0:1], v2, off
	v_mul_f32_e32 v0, v25, v43
	v_mul_f32_e32 v0, v0, v3
	v_bfe_u32 v1, v0, 16, 1
	v_lshlrev_b32_e32 v136, 1, v172
	v_add3_u32 v2, v0, v1, s20
	v_lshl_add_u64 v[0:1], v[26:27], 0, v[136:137]
	global_store_short_d16_hi v[0:1], v2, off

; __device__ __forceinline__ float gelu_tanh(float x) {
;     const float u = 0.7978845608028654f * (x + 0.044715f * x * x * x);
;     return x / (1.f + __expf(-2.f * u));
;     __device__ __forceinline__ void operator()(const f32x4 (&acc)[2][2][4][2], const pg8::Unit& u, int wr, int wc, int fr, int fq) const {
;     ...
;                 } else if (cs < 28) {
;                     float y[16];
; #pragma unroll
;                     for (int i = 0; i < 16; ++i) y[i] = gelu_tanh(v[i]);
;                     bf16_t* p = zu + (size_t)row * 512 + (cs - 20) * 64 + d0; store8(p, y); store8(p + 32, y + 8);
.LBB0_411:
	s_andn2_b64 vcc, exec, s[46:47]
	s_cbranch_vccnz .LBB0_413
	v_readlane_b32 s36, v254, 31
	v_readlane_b32 s37, v254, 32
	v_lshlrev_b32_e32 v136, 1, v140
	s_nop 0
	v_mul_f32_e32 v0, v36, v36
	v_mul_f32_e32 v0, 0xbdd2d3e8, v0
	v_add_f32_e32 v0, 0xc0135761, v0
	v_mul_f32_e32 v0, v36, v0
	v_exp_f32_e32 v0, v0
	s_nop 0
	v_add_f32_e32 v0, 1.0, v0
	v_rcp_f32_e32 v1, v0
	s_nop 0
	v_mul_f32_e32 v0, v36, v1
	s_nop 0
	s_nop 0
	v_mul_f32_e32 v1, v35, v35
	v_mul_f32_e32 v1, 0xbdd2d3e8, v1
	v_add_f32_e32 v1, 0xc0135761, v1
	v_mul_f32_e32 v1, v35, v1
	v_exp_f32_e32 v1, v1
	s_nop 0
	v_add_f32_e32 v1, 1.0, v1
	v_rcp_f32_e32 v2, v1
	s_nop 0
	v_mul_f32_e32 v1, v35, v2
	v_cvt_pk_bf16_f32 v0, v0, v1
	s_nop 0
	s_nop 0
	v_mul_f32_e32 v2, v34, v34
	v_mul_f32_e32 v2, 0xbdd2d3e8, v2
	v_add_f32_e32 v2, 0xc0135761, v2
	v_mul_f32_e32 v2, v34, v2
	v_exp_f32_e32 v2, v2
	s_nop 0
	v_add_f32_e32 v2, 1.0, v2
	v_rcp_f32_e32 v3, v2
	s_nop 0
	v_mul_f32_e32 v2, v34, v3
	s_nop 0
	s_nop 0
	v_mul_f32_e32 v3, v33, v33
	v_mul_f32_e32 v3, 0xbdd2d3e8, v3
	v_add_f32_e32 v3, 0xc0135761, v3
	v_mul_f32_e32 v3, v33, v3
	v_exp_f32_e32 v3, v3
	s_nop 0
	v_add_f32_e32 v3, 1.0, v3
	v_rcp_f32_e32 v4, v3
	s_nop 0
	v_mul_f32_e32 v3, v33, v4
	v_cvt_pk_bf16_f32 v1, v2, v3
	s_nop 0
	s_nop 0
	v_mul_f32_e32 v4, v32, v32
	v_mul_f32_e32 v4, 0xbdd2d3e8, v4
	v_add_f32_e32 v4, 0xc0135761, v4
	v_mul_f32_e32 v4, v32, v4
	v_exp_f32_e32 v4, v4
	s_nop 0
	v_add_f32_e32 v4, 1.0, v4
	v_rcp_f32_e32 v5, v4
	s_nop 0
	v_mul_f32_e32 v4, v32, v5
	s_nop 0
	s_nop 0
	v_mul_f32_e32 v5, v31, v31
	v_mul_f32_e32 v5, 0xbdd2d3e8, v5
	v_add_f32_e32 v5, 0xc0135761, v5
	v_mul_f32_e32 v5, v31, v5
	v_exp_f32_e32 v5, v5
	s_nop 0
	v_add_f32_e32 v5, 1.0, v5
	v_rcp_f32_e32 v6, v5
	s_nop 0
	v_mul_f32_e32 v5, v31, v6
	v_cvt_pk_bf16_f32 v2, v4, v5
	s_nop 0
	s_nop 0
	v_mul_f32_e32 v6, v30, v30
	v_mul_f32_e32 v6, 0xbdd2d3e8, v6
	v_add_f32_e32 v6, 0xc0135761, v6
	v_mul_f32_e32 v6, v30, v6
	v_exp_f32_e32 v6, v6
	s_nop 0
	v_add_f32_e32 v6, 1.0, v6
	v_rcp_f32_e32 v7, v6
	s_nop 0
	v_mul_f32_e32 v6, v30, v7
	s_nop 0
	s_nop 0
	v_mul_f32_e32 v7, v29, v29
	v_mul_f32_e32 v7, 0xbdd2d3e8, v7
	v_add_f32_e32 v7, 0xc0135761, v7
	v_mul_f32_e32 v7, v29, v7
	v_exp_f32_e32 v7, v7
	s_nop 0
	v_add_f32_e32 v7, 1.0, v7
	v_rcp_f32_e32 v9, v7
	s_nop 0
	v_mul_f32_e32 v7, v29, v9
	v_cvt_pk_bf16_f32 v3, v6, v7
	s_nop 0
	s_nop 0
	v_mul_f32_e32 v9, v16, v16
	v_mul_f32_e32 v9, 0xbdd2d3e8, v9
	v_add_f32_e32 v9, 0xc0135761, v9
	v_mul_f32_e32 v9, v16, v9
	v_exp_f32_e32 v9, v9
	s_nop 0
	v_add_f32_e32 v9, 1.0, v9
	v_rcp_f32_e32 v18, v9
	s_nop 0
	v_mul_f32_e32 v18, v16, v18
	s_nop 0
	s_nop 0
	v_mul_f32_e32 v9, v17, v17
	v_mul_f32_e32 v9, 0xbdd2d3e8, v9
	v_add_f32_e32 v9, 0xc0135761, v9
	v_mul_f32_e32 v9, v17, v9
	v_exp_f32_e32 v9, v9
	s_nop 0
	v_add_f32_e32 v9, 1.0, v9
	v_rcp_f32_e32 v19, v9
	s_nop 0
	v_mul_f32_e32 v19, v17, v19
	s_nop 0
	s_nop 0
	v_mul_f32_e32 v9, v14, v14
	v_mul_f32_e32 v9, 0xbdd2d3e8, v9
	v_add_f32_e32 v9, 0xc0135761, v9
	v_mul_f32_e32 v9, v14, v9
	v_exp_f32_e32 v9, v9
	s_nop 0
	v_add_f32_e32 v9, 1.0, v9
	v_rcp_f32_e32 v20, v9
	s_nop 0
	v_mul_f32_e32 v22, v14, v20
	s_nop 0
	s_nop 0
	v_mul_f32_e32 v9, v15, v15
	v_mul_f32_e32 v9, 0xbdd2d3e8, v9
	v_add_f32_e32 v9, 0xc0135761, v9
	v_mul_f32_e32 v9, v15, v9
	v_exp_f32_e32 v9, v9
	s_nop 0
	v_add_f32_e32 v9, 1.0, v9
	v_rcp_f32_e32 v20, v9
	s_nop 0
	v_mul_f32_e32 v23, v15, v20
	s_nop 0
	s_nop 0
	v_mul_f32_e32 v9, v12, v12
	v_mul_f32_e32 v9, 0xbdd2d3e8, v9
	v_add_f32_e32 v9, 0xc0135761, v9
	v_mul_f32_e32 v9, v12, v9
	v_exp_f32_e32 v9, v9
	s_nop 0
	v_add_f32_e32 v9, 1.0, v9
	v_rcp_f32_e32 v20, v9
	s_nop 0
	v_mul_f32_e32 v24, v12, v20
	s_nop 0
	s_nop 0
	v_mul_f32_e32 v9, v13, v13
	v_mul_f32_e32 v9, 0xbdd2d3e8, v9
	v_add_f32_e32 v9, 0xc0135761, v9
	v_mul_f32_e32 v9, v13, v9
	v_exp_f32_e32 v9, v9
	s_nop 0
	v_add_f32_e32 v9, 1.0, v9
	v_rcp_f32_e32 v20, v9
	s_nop 0
	v_mul_f32_e32 v25, v13, v20
	s_nop 0
	s_nop 0
	v_mul_f32_e32 v9, v10, v10
	v_mul_f32_e32 v9, 0xbdd2d3e8, v9
	v_add_f32_e32 v9, 0xc0135761, v9
	v_mul_f32_e32 v9, v10, v9
	v_exp_f32_e32 v9, v9
	s_nop 0
	v_add_f32_e32 v9, 1.0, v9
	v_rcp_f32_e32 v20, v9
	s_nop 0
	v_mul_f32_e32 v26, v10, v20
	s_nop 0
	s_nop 0
	v_mul_f32_e32 v9, v11, v11
	v_mul_f32_e32 v9, 0xbdd2d3e8, v9
	v_add_f32_e32 v9, 0xc0135761, v9
	v_mul_f32_e32 v9, v11, v9
	v_exp_f32_e32 v9, v9
	s_nop 0
	v_add_f32_e32 v9, 1.0, v9
	v_rcp_f32_e32 v20, v9
	s_nop 0
	v_mul_f32_e32 v27, v11, v20
	v_ashrrev_i32_e32 v9, 31, v8
	v_lshlrev_b64 v[20:21], 10, v[8:9]
	v_lshl_add_u64 v[20:21], s[36:37], 0, v[20:21]
	v_lshl_add_u64 v[20:21], s[8:9], 1, v[20:21]
	v_lshl_add_u64 v[20:21], v[20:21], 0, v[136:137]
	global_store_dwordx4 v[20:21], v[0:3], off offset:-2560
	s_nop 1
	v_cvt_pk_bf16_f32 v0, v18, v19
	v_cvt_pk_bf16_f32 v1, v22, v23
	v_cvt_pk_bf16_f32 v2, v24, v25
	v_cvt_pk_bf16_f32 v3, v26, v27
	global_store_dwordx4 v[20:21], v[0:3], off offset:-2496

; #define LAS __attribute__((address_space(3)))
; #define MFMA32(a, b, c) __builtin_amdgcn_mfma_f32_32x32x16_bf16((a), (b), (c), 0, 0, 0)
; __device__ __forceinline__ void phase4_attn(const Args& a, LAS unsigned char* lds) {
;     ...
;                 const float g0 = gates[(size_t)tok * 24 + head * 3 + 0], g1 = gates[(size_t)tok * 24 + head * 3 + 1], g2 = gates[(size_t)tok * 24 + head * 3 + 2];
;                 __syncthreads();
;                 {
;                     const bf16_t* kc = kcmp + (size_t)bh * 128 * 64; const bf16_t* vc = vcmpT + (size_t)bh * 64 * 128;
; #pragma unroll
;                     for (int i = 0; i < 2; ++i) { const int c = tid + 512 * i;
;                         const u32x4 kv = *(const u32x4*)(kc + (size_t)c * 8);
;                         *(LAS u32x4*)(lds + A_CMPK + (c >> 3) * A_KSTR + (c & 7) * 16) = kv;
;                         const u32x4 vv = *(const u32x4*)(vc + (size_t)c * 8);
;                         LAS unsigned char* vp = lds + A_CMPV + (c >> 4) * A_CVSTR + (c & 15) * 16;
;                         *(LAS u32x2*)vp = (u32x2){vv.x, vv.y}; *(LAS u32x2*)(vp + 8) = (u32x2){vv.z, vv.w}; }
;                 }
;                 bf16x8_t qf[4];
; #pragma unroll
;                 for (int ks = 0; ks < 4; ++ks) qf[ks] = __builtin_nontemporal_load((const bf16x8_t*)(qn + (size_t)tok * 512 + head * 64 + 16 * ks + 8 * h));
;                 __syncthreads();
;                 {
;                     f32x16 s4[4];
; #pragma unroll
;                     for (int mt = 0; mt < 4; ++mt) { s4[mt] = zero16();
; #pragma unroll
;                         for (int ks = 0; ks < 4; ++ks) { const bf16x8_t ka = *(const LAS bf16x8_t*)(lds + A_CMPK + (32 * mt + r) * A_KSTR + 32 * ks + 16 * h); s4[mt] = MFMA32(ka, qf[ks], s4[mt]); } }
.LBB0_715:
	s_and_b64 s[0:1], s[64:65], exec
	v_readlane_b32 s0, v254, 29
	v_readlane_b32 s1, v254, 30
	v_mov_b32_e32 v152, v184
	s_cselect_b32 s38, s0, s1
	s_lshl_b32 s24, s38, 6
	s_waitcnt vmcnt(0)
	v_and_b32_e32 v100, 31, v152
	v_or_b32_e32 v98, s79, v100
	v_or_b32_e32 v154, s24, v98
	v_or_b32_e32 v4, s39, v154
	v_mad_i64_i32 v[0:1], s[4:5], v4, s83, v[116:117]
	global_load_dwordx3 v[112:114], v[0:1], off
	v_lshlrev_b32_e32 v0, 4, v152
	v_ashrrev_i32_e32 v153, 31, v152
	v_readlane_b32 s6, v254, 39
	v_and_b32_e32 v1, 0x70, v0
	v_and_b32_e32 v0, 0xf0, v0
	v_lshlrev_b64 v[10:11], 4, v[152:153]
	v_readlane_b32 s7, v254, 40
	v_add_u32_e32 v6, s85, v1
	v_add_u32_e32 v8, s86, v0
	v_lshl_add_u64 v[0:1], s[6:7], 0, v[10:11]
	s_waitcnt lgkmcnt(0)
	s_barrier
	v_readlane_b32 s8, v254, 31
	v_readlane_b32 s9, v254, 32
	global_load_dwordx4 v[16:19], v[0:1], off
	v_add_u32_e32 v14, 0x200, v152
	v_ashrrev_i32_e32 v15, 31, v14
	v_lshlrev_b64 v[12:13], 4, v[14:15]
	v_lshl_add_u64 v[36:37], s[8:9], 0, v[10:11]
	global_load_dwordx4 v[20:23], v[36:37], off
	v_lshl_add_u64 v[36:37], s[6:7], 0, v[12:13]
	global_load_dwordx4 v[24:27], v[36:37], off
	v_lshl_add_u64 v[36:37], s[8:9], 0, v[12:13]
	global_load_dwordx4 v[28:31], v[36:37], off
	v_readlane_b32 s4, v254, 24
	v_readlane_b32 s5, v254, 25
	v_ashrrev_i32_e32 v5, 31, v4
	v_bfe_u32 v101, v152, 5, 1
	v_lshlrev_b64 v[72:73], 10, v[4:5]
	v_lshlrev_b32_e32 v118, 4, v101
	v_lshl_add_u64 v[0:1], s[4:5], 0, v[72:73]
	v_lshl_add_u64 v[4:5], v[0:1], 0, v[118:119]
	global_load_dwordx4 v[0:3], v[4:5], off nt
	global_load_dwordx4 v[74:77], v[4:5], off offset:32 nt
	global_load_dwordx4 v[68:71], v[4:5], off offset:64 nt
	global_load_dwordx4 v[64:67], v[4:5], off offset:96 nt
	v_ashrrev_i32_e32 v99, 3, v152
	v_ashrrev_i32_e32 v7, 4, v152
	v_mul_u32_u24_e32 v153, 0x90, v100
	v_add3_u32 v82, s85, v118, v153
	v_mad_u32_u24 v32, v99, s87, v6
	v_mad_u32_u24 v33, v7, s94, v8
	v_add_u32_e32 v35, 0x2100, v33
	s_cmp_gt_u32 s38, 15
	s_cselect_b64 s[0:1], -1, 0
	s_cmp_lt_u32 s38, 16
	s_mov_b64 s[2:3], -1
	s_cselect_b64 s[62:63], -1, 0
	s_waitcnt vmcnt(7)
	ds_write_b128 v32, v[16:19]
	s_waitcnt vmcnt(6)
	ds_write2_b64 v33, v[20:21], v[22:23] offset1:1
	s_waitcnt vmcnt(5)
	ds_write_b128 v32, v[24:27] offset:9216
	s_waitcnt vmcnt(4)
	ds_write2_b64 v35, v[28:29], v[30:31] offset1:1
	s_waitcnt lgkmcnt(0)
	s_barrier
	ds_read_b128 v[4:7], v82
	ds_read_b128 v[8:11], v82 offset:32
	s_waitcnt vmcnt(3) lgkmcnt(1)
	v_mfma_f32_32x32x16_bf16 v[48:63], v[4:7], v[0:3], 0
	ds_read_b128 v[4:7], v82 offset:64
	ds_read_b128 v[78:81], v82 offset:13856
	s_waitcnt vmcnt(2) lgkmcnt(2)
	v_mfma_f32_32x32x16_bf16 v[48:63], v[8:11], v[74:77], v[48:63]
	s_waitcnt vmcnt(1) lgkmcnt(1)
	v_mfma_f32_32x32x16_bf16 v[48:63], v[4:7], v[68:71], v[48:63]
	ds_read_b128 v[4:7], v82 offset:96
	s_waitcnt vmcnt(0) lgkmcnt(0)
	v_mfma_f32_32x32x16_bf16 v[48:63], v[4:7], v[64:67], v[48:63]
	ds_read_b128 v[4:7], v82 offset:4608
	s_waitcnt lgkmcnt(0)
	v_mfma_f32_32x32x16_bf16 v[32:47], v[4:7], v[0:3], 0
	ds_read_b128 v[4:7], v82 offset:4640
	s_nop 7
	v_exp_f32_e32 v48, v48
	v_exp_f32_e32 v49, v49
	v_exp_f32_e32 v50, v50
	v_exp_f32_e32 v51, v51
	v_exp_f32_e32 v52, v52
	v_exp_f32_e32 v53, v53
	s_waitcnt lgkmcnt(0)
	v_mfma_f32_32x32x16_bf16 v[32:47], v[4:7], v[74:77], v[32:47]
	ds_read_b128 v[4:7], v82 offset:4672
	v_exp_f32_e32 v54, v54
	v_exp_f32_e32 v55, v55
	v_exp_f32_e32 v56, v56
	v_exp_f32_e32 v57, v57
	v_exp_f32_e32 v58, v58
	v_exp_f32_e32 v59, v59
	s_waitcnt lgkmcnt(0)
	v_mfma_f32_32x32x16_bf16 v[32:47], v[4:7], v[68:71], v[32:47]
	ds_read_b128 v[4:7], v82 offset:4704
	v_exp_f32_e32 v60, v60
	v_exp_f32_e32 v61, v61
	v_exp_f32_e32 v62, v62
	v_exp_f32_e32 v63, v63
	s_waitcnt lgkmcnt(0)
	v_mfma_f32_32x32x16_bf16 v[32:47], v[4:7], v[64:67], v[32:47]
	ds_read_b128 v[4:7], v82 offset:9216
	s_waitcnt lgkmcnt(0)
	v_mfma_f32_32x32x16_bf16 v[16:31], v[4:7], v[0:3], 0
	ds_read_b128 v[4:7], v82 offset:9248
	s_nop 7
	v_exp_f32_e32 v32, v32
	v_exp_f32_e32 v33, v33
	v_exp_f32_e32 v34, v34
	v_exp_f32_e32 v35, v35
	v_exp_f32_e32 v36, v36
	v_exp_f32_e32 v37, v37
	s_waitcnt lgkmcnt(0)
	v_mfma_f32_32x32x16_bf16 v[16:31], v[4:7], v[74:77], v[16:31]
	ds_read_b128 v[4:7], v82 offset:9280
	v_exp_f32_e32 v38, v38
	v_exp_f32_e32 v39, v39
	v_exp_f32_e32 v40, v40
	v_exp_f32_e32 v41, v41
	v_exp_f32_e32 v42, v42
	v_exp_f32_e32 v43, v43
	s_waitcnt lgkmcnt(0)
	v_mfma_f32_32x32x16_bf16 v[16:31], v[4:7], v[68:71], v[16:31]
	ds_read_b128 v[4:7], v82 offset:9312
	v_exp_f32_e32 v44, v44
	v_exp_f32_e32 v45, v45
	v_exp_f32_e32 v46, v46
	v_exp_f32_e32 v47, v47
	s_waitcnt lgkmcnt(0)
	v_mfma_f32_32x32x16_bf16 v[16:31], v[4:7], v[64:67], v[16:31]
	ds_read_b128 v[4:7], v82 offset:13824
	s_waitcnt lgkmcnt(0)
	v_mfma_f32_32x32x16_bf16 v[0:15], v[4:7], v[0:3], 0
	s_nop 8
	v_exp_f32_e32 v16, v16
	v_exp_f32_e32 v17, v17
	v_exp_f32_e32 v18, v18
	v_exp_f32_e32 v19, v19
	v_exp_f32_e32 v20, v20
	v_exp_f32_e32 v21, v21
	v_exp_f32_e32 v22, v22
	v_mfma_f32_32x32x16_bf16 v[0:15], v[78:81], v[74:77], v[0:15]
	ds_read_b128 v[74:77], v82 offset:13888
	v_exp_f32_e32 v23, v23
	v_exp_f32_e32 v24, v24
	v_exp_f32_e32 v25, v25
	v_exp_f32_e32 v26, v26
	v_exp_f32_e32 v27, v27
	v_exp_f32_e32 v28, v28
	s_waitcnt lgkmcnt(0)
	v_mfma_f32_32x32x16_bf16 v[0:15], v[74:77], v[68:71], v[0:15]
	ds_read_b128 v[68:71], v82 offset:13920
	v_exp_f32_e32 v29, v29
	v_exp_f32_e32 v30, v30
	v_exp_f32_e32 v31, v31
	s_waitcnt lgkmcnt(0)
; __device__ __forceinline__ float ex2(float x) { return __builtin_amdgcn_exp2f(x); }
; __device__ __forceinline__ void phase4_attn(const Args& a, LAS unsigned char* lds) {
;     ...
;                     const int clim = (pos - 31 - 64 * h) >> 4;
;                     float ls = 0.f;
; #pragma unroll
;                     for (int mt = 0; mt < 4; ++mt)
; #pragma unroll
;                         for (int i = 0; i < 16; ++i) { const int ci = 32 * mt + (i & 3) + 8 * (i >> 2);
;                             const float p = (ci <= clim) ? ex2(s4[mt][i]) : 0.f; s4[mt][i] = p; ls += p; }
	v_mfma_f32_32x32x16_bf16 v[0:15], v[68:71], v[64:67], v[0:15]
	v_lshlrev_b32_e32 v64, 6, v101
	v_sub_u32_e32 v64, v154, v64
	v_subrev_u32_e32 v64, 31, v64
	v_ashrrev_i32_e32 v64, 4, v64
	v_cmp_lt_i32_e32 vcc, -1, v64
	s_nop 6
	v_exp_f32_e32 v0, v0
	v_cndmask_b32_e32 v48, 0, v48, vcc
	v_cmp_lt_i32_e32 vcc, 0, v64
	v_add_f32_e32 v65, 0, v48
	v_exp_f32_e32 v1, v1
	v_cndmask_b32_e32 v49, 0, v49, vcc
	v_cmp_lt_i32_e32 vcc, 1, v64
	v_add_f32_e32 v65, v49, v65
	s_nop 0
	v_cndmask_b32_e32 v50, 0, v50, vcc
	v_cmp_lt_i32_e32 vcc, 2, v64
	v_add_f32_e32 v65, v50, v65
	s_nop 0
	v_cndmask_b32_e32 v51, 0, v51, vcc
	v_cmp_lt_i32_e32 vcc, 7, v64
	v_add_f32_e32 v65, v51, v65
	s_nop 0
	v_cndmask_b32_e32 v52, 0, v52, vcc
	v_cmp_lt_i32_e32 vcc, 8, v64
	v_add_f32_e32 v65, v52, v65
	s_nop 0
	v_cndmask_b32_e32 v53, 0, v53, vcc
	v_cmp_lt_i32_e32 vcc, 9, v64
	v_add_f32_e32 v65, v53, v65
	s_nop 0
	v_cndmask_b32_e32 v54, 0, v54, vcc
	v_cmp_lt_i32_e32 vcc, 10, v64
	v_add_f32_e32 v65, v54, v65
	s_nop 0
	v_cndmask_b32_e32 v55, 0, v55, vcc
	v_cmp_lt_i32_e32 vcc, 15, v64
	v_add_f32_e32 v65, v55, v65
	s_nop 0
	v_cndmask_b32_e32 v56, 0, v56, vcc
	v_cmp_lt_i32_e32 vcc, 16, v64
	v_add_f32_e32 v65, v56, v65
	s_nop 0
	v_cndmask_b32_e32 v57, 0, v57, vcc
	v_cmp_lt_i32_e32 vcc, 17, v64
	v_add_f32_e32 v65, v57, v65
	s_nop 0
	v_cndmask_b32_e32 v58, 0, v58, vcc
	v_cmp_lt_i32_e32 vcc, 18, v64
	v_add_f32_e32 v65, v58, v65
	s_nop 0
	v_cndmask_b32_e32 v59, 0, v59, vcc
	v_cmp_lt_i32_e32 vcc, 23, v64
	v_add_f32_e32 v65, v59, v65
	s_nop 0
	v_cndmask_b32_e32 v60, 0, v60, vcc
	v_cmp_lt_i32_e32 vcc, 24, v64
	v_add_f32_e32 v65, v60, v65
	s_nop 0
	v_cndmask_b32_e32 v61, 0, v61, vcc
	v_cmp_lt_i32_e32 vcc, 25, v64
	v_add_f32_e32 v65, v61, v65
	s_nop 0
	v_cndmask_b32_e32 v62, 0, v62, vcc
	v_cmp_lt_i32_e32 vcc, 26, v64
	v_add_f32_e32 v65, v62, v65
	s_nop 0
	v_cndmask_b32_e32 v63, 0, v63, vcc
	v_cmp_lt_i32_e32 vcc, 31, v64
	v_add_f32_e32 v65, v63, v65
	s_nop 0
	v_cndmask_b32_e32 v32, 0, v32, vcc
	v_cmp_lt_i32_e32 vcc, 32, v64
	v_add_f32_e32 v65, v32, v65
	s_nop 0
	v_cndmask_b32_e32 v33, 0, v33, vcc
	v_cmp_lt_i32_e32 vcc, 33, v64
	v_add_f32_e32 v65, v33, v65
	s_nop 0
	v_cndmask_b32_e32 v34, 0, v34, vcc
	v_cmp_lt_i32_e32 vcc, 34, v64
	v_add_f32_e32 v65, v34, v65
	s_nop 0
	v_cndmask_b32_e32 v35, 0, v35, vcc
	v_cmp_lt_i32_e32 vcc, 39, v64
	v_add_f32_e32 v65, v35, v65
	s_nop 0
	v_cndmask_b32_e32 v36, 0, v36, vcc
	v_cmp_lt_i32_e32 vcc, 40, v64
	v_add_f32_e32 v65, v36, v65
	s_nop 0
	v_cndmask_b32_e32 v37, 0, v37, vcc
	v_cmp_lt_i32_e32 vcc, 41, v64
	v_add_f32_e32 v65, v37, v65
	s_nop 0
	v_cndmask_b32_e32 v38, 0, v38, vcc
	v_cmp_lt_i32_e32 vcc, 42, v64
	v_add_f32_e32 v65, v38, v65
	s_nop 0
	v_cndmask_b32_e32 v39, 0, v39, vcc
	v_cmp_lt_i32_e32 vcc, 47, v64
	v_add_f32_e32 v65, v39, v65
	s_nop 0
	v_cndmask_b32_e32 v40, 0, v40, vcc
	v_cmp_lt_i32_e32 vcc, 48, v64
	v_add_f32_e32 v65, v40, v65
	s_nop 0
	v_cndmask_b32_e32 v41, 0, v41, vcc
	v_cmp_lt_i32_e32 vcc, 49, v64
	v_add_f32_e32 v65, v41, v65
	s_nop 0
	v_cndmask_b32_e32 v42, 0, v42, vcc
	v_cmp_lt_i32_e32 vcc, 50, v64
	v_add_f32_e32 v65, v42, v65
	s_nop 0
	v_cndmask_b32_e32 v43, 0, v43, vcc
	v_cmp_lt_i32_e32 vcc, 55, v64
	v_add_f32_e32 v65, v43, v65
	s_nop 0
	v_cndmask_b32_e32 v44, 0, v44, vcc
	v_cmp_lt_i32_e32 vcc, 56, v64
	v_add_f32_e32 v65, v44, v65
	s_nop 0
	v_cndmask_b32_e32 v45, 0, v45, vcc
	v_cmp_lt_i32_e32 vcc, 57, v64
	v_add_f32_e32 v65, v45, v65
	s_nop 0
	v_cndmask_b32_e32 v46, 0, v46, vcc
	v_cmp_lt_i32_e32 vcc, 58, v64
	v_add_f32_e32 v65, v46, v65
	s_nop 0
	v_cndmask_b32_e32 v47, 0, v47, vcc
	v_cmp_lt_i32_e32 vcc, 63, v64
	v_add_f32_e32 v65, v47, v65
	s_nop 0
	v_cndmask_b32_e32 v16, 0, v16, vcc
	v_cmp_lt_i32_e32 vcc, 64, v64
	v_add_f32_e32 v65, v16, v65
	s_nop 0
	v_cndmask_b32_e32 v17, 0, v17, vcc
	v_cmp_lt_i32_e32 vcc, s96, v64
	v_add_f32_e32 v65, v17, v65
	s_nop 0
	v_cndmask_b32_e32 v18, 0, v18, vcc
	v_cmp_lt_i32_e32 vcc, s97, v64
	v_add_f32_e32 v65, v18, v65
	s_nop 0
	v_cndmask_b32_e32 v19, 0, v19, vcc
	v_cmp_lt_i32_e32 vcc, s18, v64
	v_add_f32_e32 v65, v19, v65
	s_nop 0
	v_cndmask_b32_e32 v20, 0, v20, vcc
	v_cmp_lt_i32_e32 vcc, s19, v64
	v_add_f32_e32 v65, v20, v65
	s_nop 0
	v_cndmask_b32_e32 v21, 0, v21, vcc
	v_cmp_lt_i32_e32 vcc, s14, v64
	v_add_f32_e32 v65, v21, v65
	s_nop 0
	v_cndmask_b32_e32 v22, 0, v22, vcc
	v_cmp_lt_i32_e32 vcc, s15, v64
	v_add_f32_e32 v65, v22, v65
	s_nop 0
	v_cndmask_b32_e32 v23, 0, v23, vcc
	v_cmp_lt_i32_e32 vcc, s16, v64
	v_add_f32_e32 v65, v23, v65
	s_nop 0
	v_cndmask_b32_e32 v24, 0, v24, vcc
	v_cmp_lt_i32_e32 vcc, s17, v64
	v_add_f32_e32 v65, v24, v65
	s_nop 0
	v_cndmask_b32_e32 v25, 0, v25, vcc
	v_cmp_lt_i32_e32 vcc, s92, v64
	v_add_f32_e32 v65, v25, v65
	s_nop 0
	v_cndmask_b32_e32 v26, 0, v26, vcc
	v_cmp_lt_i32_e32 vcc, s93, v64
	v_add_f32_e32 v65, v26, v65
	s_nop 0
	v_cndmask_b32_e32 v27, 0, v27, vcc
	v_cmp_lt_i32_e32 vcc, s66, v64
	v_add_f32_e32 v65, v27, v65
	s_nop 0
	v_cndmask_b32_e32 v28, 0, v28, vcc
; __device__ __forceinline__ float ex2(float x) { return __builtin_amdgcn_exp2f(x); }
; __device__ __forceinline__ void phase4_attn(const Args& a, LAS unsigned char* lds) {
;     ...
;                         for (int i = 0; i < 16; ++i) { const int ci = 32 * mt + (i & 3) + 8 * (i >> 2);
;                             const float p = (ci <= clim) ? ex2(s4[mt][i]) : 0.f; s4[mt][i] = p; ls += p; }
;                     ls += __shfl_xor(ls, 32);
;                     const float inv = 1.f / fmaxf(ls, 1e-20f);
; #pragma unroll
;                     for (int mt = 0; mt < 4; ++mt) s4[mt] *= inv;
;                     if (t >= 16) {
	v_cmp_lt_i32_e32 vcc, s67, v64
	v_add_f32_e32 v65, v28, v65
	s_nop 0
	v_cndmask_b32_e32 v29, 0, v29, vcc
	v_cmp_lt_i32_e32 vcc, s68, v64
	v_add_f32_e32 v65, v29, v65
	s_nop 0
	v_cndmask_b32_e32 v30, 0, v30, vcc
	v_cmp_lt_i32_e32 vcc, s69, v64
	v_add_f32_e32 v65, v30, v65
	s_nop 0
	v_cndmask_b32_e32 v31, 0, v31, vcc
	v_cmp_lt_i32_e32 vcc, s33, v64
	v_add_f32_e32 v65, v31, v65
	s_nop 0
	v_cndmask_b32_e32 v90, 0, v0, vcc
	v_cmp_lt_i32_e32 vcc, s83, v64
	v_add_f32_e32 v0, v90, v65
	s_nop 0
	v_cndmask_b32_e32 v91, 0, v1, vcc
	v_exp_f32_e32 v1, v2
	v_cmp_lt_i32_e32 vcc, s70, v64
	v_add_f32_e32 v0, v91, v0
	s_nop 0
	v_cndmask_b32_e32 v92, 0, v1, vcc
	v_exp_f32_e32 v1, v3
	v_cmp_lt_i32_e32 vcc, s81, v64
	v_add_f32_e32 v0, v92, v0
	s_nop 0
	v_cndmask_b32_e32 v93, 0, v1, vcc
	v_exp_f32_e32 v1, v4
	v_cmp_lt_i32_e32 vcc, s82, v64
	v_add_f32_e32 v0, v93, v0
	s_nop 0
	v_cndmask_b32_e32 v94, 0, v1, vcc
	v_exp_f32_e32 v1, v5
	v_cmp_lt_i32_e32 vcc, s20, v64
	v_add_f32_e32 v0, v94, v0
	s_nop 0
	v_cndmask_b32_e32 v95, 0, v1, vcc
	v_exp_f32_e32 v1, v6
	v_cmp_lt_i32_e32 vcc, s21, v64
	v_add_f32_e32 v0, v95, v0
	s_nop 0
	v_cndmask_b32_e32 v96, 0, v1, vcc
	v_exp_f32_e32 v1, v7
	v_cmp_lt_i32_e32 vcc, s26, v64
	v_add_f32_e32 v0, v96, v0
	s_nop 0
	v_cndmask_b32_e32 v97, 0, v1, vcc
	v_exp_f32_e32 v1, v8
	v_cmp_lt_i32_e32 vcc, s27, v64
	v_add_f32_e32 v0, v97, v0
	s_nop 0
	v_cndmask_b32_e32 v8, 0, v1, vcc
	v_exp_f32_e32 v1, v9
	v_cmp_lt_i32_e32 vcc, s84, v64
	v_add_f32_e32 v0, v8, v0
	s_nop 0
	v_cndmask_b32_e32 v9, 0, v1, vcc
	v_exp_f32_e32 v1, v10
	v_cmp_lt_i32_e32 vcc, s28, v64
	v_add_f32_e32 v0, v9, v0
	s_nop 0
	v_cndmask_b32_e32 v10, 0, v1, vcc
	v_exp_f32_e32 v1, v11
	v_cmp_lt_i32_e32 vcc, s29, v64
	v_add_f32_e32 v0, v10, v0
	s_nop 0
	v_cndmask_b32_e32 v11, 0, v1, vcc
	v_exp_f32_e32 v1, v12
	v_cmp_lt_i32_e32 vcc, s34, v64
	v_add_f32_e32 v0, v11, v0
	s_nop 0
	v_cndmask_b32_e32 v12, 0, v1, vcc
	v_exp_f32_e32 v1, v13
	v_cmp_lt_i32_e32 vcc, s35, v64
	v_add_f32_e32 v0, v12, v0
	s_nop 0
	v_cndmask_b32_e32 v13, 0, v1, vcc
	v_exp_f32_e32 v1, v14
	v_cmp_lt_i32_e32 vcc, s36, v64
	v_add_f32_e32 v0, v13, v0
	s_nop 0
	v_cndmask_b32_e32 v14, 0, v1, vcc
	v_exp_f32_e32 v1, v15
	v_cmp_lt_i32_e32 vcc, s37, v64
	v_add_f32_e32 v0, v14, v0
	s_nop 0
	v_cndmask_b32_e32 v15, 0, v1, vcc
	v_cmp_lt_i32_e32 vcc, v185, v188
	v_add_f32_e32 v0, v15, v0
	s_nop 0
	v_cndmask_b32_e32 v1, v115, v185, vcc
	v_lshlrev_b32_e32 v193, 2, v1
	ds_bpermute_b32 v1, v193, v0
	s_waitcnt lgkmcnt(0)
	v_add_f32_e32 v0, v0, v1
	v_max_f32_e32 v0, 0x1e3ce508, v0
	v_div_scale_f32 v1, s[4:5], v0, v0, 1.0
	v_rcp_f32_e32 v2, v1
	s_nop 0
	v_fma_f32 v3, -v1, v2, 1.0
	v_fmac_f32_e32 v2, v3, v2
	v_div_scale_f32 v3, vcc, 1.0, v0, 1.0
	v_mul_f32_e32 v4, v3, v2
	v_fma_f32 v5, -v1, v4, v3
	v_fmac_f32_e32 v4, v5, v2
	v_fma_f32 v1, -v1, v4, v3
	v_div_fmas_f32 v1, v1, v2, v4
	v_div_fixup_f32 v102, v1, v0, 1.0
	v_pk_mul_f32 v[0:1], v[48:49], v[102:103] op_sel_hi:[1,0]
	v_pk_mul_f32 v[2:3], v[50:51], v[102:103] op_sel_hi:[1,0]
	v_pk_mul_f32 v[4:5], v[52:53], v[102:103] op_sel_hi:[1,0]
	v_pk_mul_f32 v[6:7], v[54:55], v[102:103] op_sel_hi:[1,0]
	v_pk_mul_f32 v[78:79], v[56:57], v[102:103] op_sel_hi:[1,0]
	v_pk_mul_f32 v[82:83], v[58:59], v[102:103] op_sel_hi:[1,0]
	v_pk_mul_f32 v[86:87], v[60:61], v[102:103] op_sel_hi:[1,0]
	v_pk_mul_f32 v[88:89], v[62:63], v[102:103] op_sel_hi:[1,0]
	v_pk_mul_f32 v[74:75], v[32:33], v[102:103] op_sel_hi:[1,0]
	v_pk_mul_f32 v[76:77], v[34:35], v[102:103] op_sel_hi:[1,0]
	v_pk_mul_f32 v[80:81], v[36:37], v[102:103] op_sel_hi:[1,0]
	v_pk_mul_f32 v[84:85], v[38:39], v[102:103] op_sel_hi:[1,0]
	v_pk_mul_f32 v[58:59], v[40:41], v[102:103] op_sel_hi:[1,0]
	v_pk_mul_f32 v[62:63], v[42:43], v[102:103] op_sel_hi:[1,0]
	v_pk_mul_f32 v[66:67], v[44:45], v[102:103] op_sel_hi:[1,0]
	v_pk_mul_f32 v[70:71], v[46:47], v[102:103] op_sel_hi:[1,0]
	v_pk_mul_f32 v[56:57], v[16:17], v[102:103] op_sel_hi:[1,0]
	v_pk_mul_f32 v[60:61], v[18:19], v[102:103] op_sel_hi:[1,0]
	v_pk_mul_f32 v[64:65], v[20:21], v[102:103] op_sel_hi:[1,0]
	v_pk_mul_f32 v[68:69], v[22:23], v[102:103] op_sel_hi:[1,0]
	v_pk_mul_f32 v[42:43], v[24:25], v[102:103] op_sel_hi:[1,0]
	v_pk_mul_f32 v[46:47], v[26:27], v[102:103] op_sel_hi:[1,0]
	v_pk_mul_f32 v[50:51], v[28:29], v[102:103] op_sel_hi:[1,0]
	v_pk_mul_f32 v[54:55], v[30:31], v[102:103] op_sel_hi:[1,0]
	v_pk_mul_f32 v[40:41], v[90:91], v[102:103] op_sel_hi:[1,0]
	v_pk_mul_f32 v[44:45], v[92:93], v[102:103] op_sel_hi:[1,0]
	v_pk_mul_f32 v[48:49], v[94:95], v[102:103] op_sel_hi:[1,0]
	v_pk_mul_f32 v[52:53], v[96:97], v[102:103] op_sel_hi:[1,0]
	v_pk_mul_f32 v[32:33], v[8:9], v[102:103] op_sel_hi:[1,0]
	v_pk_mul_f32 v[34:35], v[10:11], v[102:103] op_sel_hi:[1,0]
	v_pk_mul_f32 v[36:37], v[12:13], v[102:103] op_sel_hi:[1,0]
	v_pk_mul_f32 v[38:39], v[14:15], v[102:103] op_sel_hi:[1,0]
	s_and_b64 vcc, exec, s[0:1]
	s_cbranch_vccnz .LBB0_717
	s_mov_b64 s[2:3], 0

; __device__ __forceinline__ void phase4_attn(const Args& a, LAS unsigned char* lds) {
;     ...
;                     const int st = issel ? i : wlo + (i - n_sel);
;                     const int dlt = 64 * t + ql - 128 * st - 4 * h;
;                     if (issel) {
;                         const bool b0 = (selw >> (2 * st)) & 1u, b1 = (selw >> (2 * st + 1)) & 1u;
;                         if (__ballot(b0 || b1) != 0ull) {
;                             if (2 * st + 1 < t) {
;                                 if (__ballot(b0 && b1) == ~0ull) attn_tile<2>(Kb, Vb, qf, oacc, l_run, r, h, dlt, dlt, (w & 4) != 0);
;                                 else attn_tile<3>(Kb, Vb, qf, oacc, l_run, r, h, __float_as_int(b0 ? 0.f : -1e30f), __float_as_int(b1 ? 0.f : -1e30f), (w & 4) != 0);
;                             } else attn_tile<0>(Kb, Vb, qf, oacc, l_run, r, h, b0 ? dlt : -1, b1 ? dlt : -1, (w & 4) != 0);
;                         }
.Lt1_disp:
	s_cmp_gt_u32 s44, s89
	s_cbranch_scc1 .Lt1_win
	s_lshl_b32 s0, s44, 2
	s_sub_i32 s49, s50, s0
	s_lshl_b32 s4, s44, 1
	v_lshrrev_b32_e32 v238, s4, v158
	v_and_b32_e32 v238, 3, v238
	v_cmp_ne_u32_e32 vcc, 0, v238
	s_cmp_eq_u64 vcc, 0
	s_cbranch_scc1 .Lt1_join
	s_cmp_le_i32 s49, 3
	s_cbranch_scc1 .Lt1_diag
	v_cmp_eq_u32_e32 vcc, 3, v238
	s_cmp_eq_u64 vcc, -1
	s_cbranch_scc1 .Lt1_full
	s_mov_b32 s49, s4
	s_branch .Lt1_bias

; #define LAS __attribute__((address_space(3)))
; #define MFMA32(a, b, c) __builtin_amdgcn_mfma_f32_32x32x16_bf16((a), (b), (c), 0, 0, 0)
; __device__ __forceinline__ float ex2(float x) { return __builtin_amdgcn_exp2f(x); }
; template <int MODE>
; __device__ __forceinline__ void attn_tile(const LAS unsigned char* Kb, const LAS unsigned char* Vb, const bf16x8_t (&qf)[4], f32x16 (&oacc)[2], float& l_run,
;                                           int r, int h, int dlt0, int dlt1, bool hiw) {
;     const unsigned ulim = (MODE == 0) ? 0x80000000u : 512u;
;     float ls = 0.f;
; #pragma unroll
;     for (int mt = 0; mt < 4; ++mt) {
;         if (mt == 0) { if (hiw) __builtin_amdgcn_s_setprio(1); else __builtin_amdgcn_s_setprio(0); }
;         if (mt == 2) { if (hiw) __builtin_amdgcn_s_setprio(0); else __builtin_amdgcn_s_setprio(1); }
;         const int dl = mt < 2 ? dlt0 : dlt1;
;         f32x16 sacc = zero16();
; #pragma unroll
;         for (int ks = 0; ks < 4; ++ks) { const bf16x8_t ka = *(const LAS bf16x8_t*)(Kb + (32 * mt + r) * A_KSTR + 32 * ks + 16 * h); sacc = MFMA32(ka, qf[ks], sacc); }
; #pragma unroll
;         for (int i = 0; i < 16; ++i) {
;             float p;
;             if (MODE == 2) p = ex2(sacc[i]);
;             else if (MODE == 3) p = ex2(sacc[i] + __int_as_float(dl));
;             else { const int ci = 32 * mt + (i & 3) + 8 * (i >> 2); p = ((unsigned)(dl - ci) < ulim) ? ex2(sacc[i]) : 0.f; }
;             sacc[i] = p; ls += p;
;         }
; #pragma unroll
;         for (int s = 0; s < 2; ++s) {
;             const bf16x8_t pf = pack8(sacc, 8 * s);
; #pragma unroll
;             for (int dt = 0; dt < 2; ++dt) {
;                 const LAS unsigned char* vp = Vb + (32 * dt + r) * A_CVSTR + (32 * mt + 16 * s + 4 * h) * 2;
;                 const s16x4_t lo = *(const LAS s16x4_t*)vp, hi = *(const LAS s16x4_t*)(vp + 16);
;                 oacc[dt] = MFMA32(__builtin_shufflevector(lo, hi, 0, 1, 2, 3, 4, 5, 6, 7), pf, oacc[dt]);
;             }
;         }
;     }
;     l_run += ls;
.Lt1_full:
	ds_read_b128 v[200:203], v72 offset:0
	ds_read_b128 v[204:207], v72 offset:32
	ds_read_b128 v[208:211], v72 offset:64
	ds_read_b128 v[212:215], v72 offset:96
	ds_read2_b64 v[216:219], v73 offset0:0 offset1:2
	ds_read2_b64 v[220:223], v74 offset0:32 offset1:34
	ds_read2_b64 v[224:227], v73 offset0:4 offset1:6
	ds_read2_b64 v[228:231], v74 offset0:36 offset1:38
	s_waitcnt lgkmcnt(7)
	v_mfma_f32_32x32x16_bf16 v[32:47], v[200:203], v[80:83], 0
	ds_read_b128 v[200:203], v72 offset:4608
	s_waitcnt lgkmcnt(7)
	v_mfma_f32_32x32x16_bf16 v[32:47], v[204:207], v[84:87], v[32:47]
	ds_read_b128 v[204:207], v72 offset:4640
	s_waitcnt lgkmcnt(7)
	v_mfma_f32_32x32x16_bf16 v[32:47], v[208:211], v[88:91], v[32:47]
	ds_read_b128 v[208:211], v72 offset:4672
	s_waitcnt lgkmcnt(7)
	v_mfma_f32_32x32x16_bf16 v[32:47], v[212:215], v[92:95], v[32:47]
	ds_read_b128 v[212:215], v72 offset:4704
	s_nop 7
	s_nop 3
	s_waitcnt lgkmcnt(3)
	v_mfma_f32_32x32x16_bf16 v[48:63], v[200:203], v[80:83], 0
	ds_read_b128 v[200:203], v72 offset:9216
	v_exp_f32_e32 v32, v32
	v_exp_f32_e32 v33, v33
	s_waitcnt lgkmcnt(3)
	v_mfma_f32_32x32x16_bf16 v[48:63], v[204:207], v[84:87], v[48:63]
	ds_read_b128 v[204:207], v72 offset:9248
	v_exp_f32_e32 v34, v34
	v_exp_f32_e32 v35, v35
	v_mov_b32_e32 v232, v32
	v_mov_b32_e32 v233, v33
	v_cvt_pk_bf16_f32 v64, v32, v33
	v_exp_f32_e32 v36, v36
	v_exp_f32_e32 v37, v37
	v_add_f32_e32 v232, v232, v34
	v_add_f32_e32 v233, v233, v35
	v_cvt_pk_bf16_f32 v65, v34, v35
	v_exp_f32_e32 v38, v38
	v_exp_f32_e32 v39, v39
	v_add_f32_e32 v232, v232, v36
	v_add_f32_e32 v233, v233, v37
	v_cvt_pk_bf16_f32 v66, v36, v37
	v_add_f32_e32 v232, v232, v38
	v_add_f32_e32 v233, v233, v39
	v_cvt_pk_bf16_f32 v67, v38, v39
	s_waitcnt lgkmcnt(3)
	v_mfma_f32_32x32x16_bf16 v[48:63], v[208:211], v[88:91], v[48:63]
	ds_read_b128 v[208:211], v72 offset:9280
	v_exp_f32_e32 v40, v40
	v_exp_f32_e32 v41, v41
	s_waitcnt lgkmcnt(3)
	v_mfma_f32_32x32x16_bf16 v[48:63], v[212:215], v[92:95], v[48:63]
	ds_read_b128 v[212:215], v72 offset:9312
	v_exp_f32_e32 v42, v42
	v_exp_f32_e32 v43, v43
	v_add_f32_e32 v232, v232, v40
	v_add_f32_e32 v233, v233, v41
	v_cvt_pk_bf16_f32 v68, v40, v41
	v_mfma_f32_32x32x16_bf16 v[0:15], v[216:219], v[64:67], v[0:15]
	ds_read2_b64 v[216:219], v73 offset0:8 offset1:10
	v_exp_f32_e32 v44, v44
	v_exp_f32_e32 v45, v45
	v_add_f32_e32 v232, v232, v42
	v_add_f32_e32 v233, v233, v43
	v_cvt_pk_bf16_f32 v69, v42, v43
	v_mfma_f32_32x32x16_bf16 v[16:31], v[220:223], v[64:67], v[16:31]
	ds_read2_b64 v[220:223], v74 offset0:40 offset1:42
	v_exp_f32_e32 v46, v46
	v_exp_f32_e32 v47, v47
	v_add_f32_e32 v232, v232, v44
	v_add_f32_e32 v233, v233, v45
	v_cvt_pk_bf16_f32 v70, v44, v45
	v_add_f32_e32 v232, v232, v46
	v_add_f32_e32 v233, v233, v47
	v_cvt_pk_bf16_f32 v71, v46, v47
	s_waitcnt lgkmcnt(5)
	v_mfma_f32_32x32x16_bf16 v[32:47], v[200:203], v[80:83], 0
	ds_read_b128 v[200:203], v72 offset:13824
	v_exp_f32_e32 v48, v48
	v_exp_f32_e32 v49, v49
	s_waitcnt lgkmcnt(5)
	v_mfma_f32_32x32x16_bf16 v[32:47], v[204:207], v[84:87], v[32:47]
	ds_read_b128 v[204:207], v72 offset:13856
	v_exp_f32_e32 v50, v50
	v_exp_f32_e32 v51, v51
	v_add_f32_e32 v232, v232, v48
	v_add_f32_e32 v233, v233, v49
	v_cvt_pk_bf16_f32 v64, v48, v49
	v_mfma_f32_32x32x16_bf16 v[0:15], v[224:227], v[68:71], v[0:15]
	ds_read2_b64 v[224:227], v73 offset0:12 offset1:14
	v_exp_f32_e32 v52, v52
	v_exp_f32_e32 v53, v53
	v_add_f32_e32 v232, v232, v50
	v_add_f32_e32 v233, v233, v51
	v_cvt_pk_bf16_f32 v65, v50, v51
	v_mfma_f32_32x32x16_bf16 v[16:31], v[228:231], v[68:71], v[16:31]
	ds_read2_b64 v[228:231], v74 offset0:44 offset1:46
	v_exp_f32_e32 v54, v54
	v_exp_f32_e32 v55, v55
	v_add_f32_e32 v232, v232, v52
	v_add_f32_e32 v233, v233, v53
	v_cvt_pk_bf16_f32 v66, v52, v53
	v_add_f32_e32 v232, v232, v54
	v_add_f32_e32 v233, v233, v55
	v_cvt_pk_bf16_f32 v67, v54, v55
	s_waitcnt lgkmcnt(7)
	v_mfma_f32_32x32x16_bf16 v[32:47], v[208:211], v[88:91], v[32:47]
	ds_read_b128 v[208:211], v72 offset:13888
	v_exp_f32_e32 v56, v56
	v_exp_f32_e32 v57, v57
	s_waitcnt lgkmcnt(7)
	v_mfma_f32_32x32x16_bf16 v[32:47], v[212:215], v[92:95], v[32:47]
	ds_read_b128 v[212:215], v72 offset:13920
	v_exp_f32_e32 v58, v58
	v_exp_f32_e32 v59, v59
	v_add_f32_e32 v232, v232, v56
	v_add_f32_e32 v233, v233, v57
	v_cvt_pk_bf16_f32 v68, v56, v57
	s_waitcnt lgkmcnt(7)
	v_mfma_f32_32x32x16_bf16 v[0:15], v[216:219], v[64:67], v[0:15]
	ds_read2_b64 v[216:219], v73 offset0:16 offset1:18
	v_exp_f32_e32 v60, v60
	v_exp_f32_e32 v61, v61
	v_add_f32_e32 v232, v232, v58
	v_add_f32_e32 v233, v233, v59
	v_cvt_pk_bf16_f32 v69, v58, v59
	s_waitcnt lgkmcnt(7)
	v_mfma_f32_32x32x16_bf16 v[16:31], v[220:223], v[64:67], v[16:31]
	ds_read2_b64 v[220:223], v74 offset0:48 offset1:50
	v_exp_f32_e32 v62, v62
	v_exp_f32_e32 v63, v63
	v_add_f32_e32 v232, v232, v60
	v_add_f32_e32 v233, v233, v61
	v_cvt_pk_bf16_f32 v70, v60, v61
	v_add_f32_e32 v232, v232, v62
	v_add_f32_e32 v233, v233, v63
	v_cvt_pk_bf16_f32 v71, v62, v63
	s_waitcnt lgkmcnt(7)
	v_mfma_f32_32x32x16_bf16 v[48:63], v[200:203], v[80:83], 0
	v_exp_f32_e32 v32, v32
	v_exp_f32_e32 v33, v33
	s_waitcnt lgkmcnt(6)
	v_mfma_f32_32x32x16_bf16 v[48:63], v[204:207], v[84:87], v[48:63]
	v_exp_f32_e32 v34, v34
	v_exp_f32_e32 v35, v35
	v_add_f32_e32 v232, v232, v32
	v_add_f32_e32 v233, v233, v33
	v_cvt_pk_bf16_f32 v64, v32, v33
	s_waitcnt lgkmcnt(5)
	v_mfma_f32_32x32x16_bf16 v[0:15], v[224:227], v[68:71], v[0:15]
	ds_read2_b64 v[224:227], v73 offset0:20 offset1:22
	v_exp_f32_e32 v36, v36
	v_exp_f32_e32 v37, v37
	v_add_f32_e32 v232, v232, v34
	v_add_f32_e32 v233, v233, v35
	v_cvt_pk_bf16_f32 v65, v34, v35
	s_waitcnt lgkmcnt(5)
; #define LAS __attribute__((address_space(3)))
; #define MFMA32(a, b, c) __builtin_amdgcn_mfma_f32_32x32x16_bf16((a), (b), (c), 0, 0, 0)
; __device__ __forceinline__ float ex2(float x) { return __builtin_amdgcn_exp2f(x); }
; template <int MODE>
; __device__ __forceinline__ void attn_tile(const LAS unsigned char* Kb, const LAS unsigned char* Vb, const bf16x8_t (&qf)[4], f32x16 (&oacc)[2], float& l_run,
;                                           int r, int h, int dlt0, int dlt1, bool hiw) {
;     const unsigned ulim = (MODE == 0) ? 0x80000000u : 512u;
;     float ls = 0.f;
; #pragma unroll
;     for (int mt = 0; mt < 4; ++mt) {
;         if (mt == 0) { if (hiw) __builtin_amdgcn_s_setprio(1); else __builtin_amdgcn_s_setprio(0); }
;         if (mt == 2) { if (hiw) __builtin_amdgcn_s_setprio(0); else __builtin_amdgcn_s_setprio(1); }
;         const int dl = mt < 2 ? dlt0 : dlt1;
;         f32x16 sacc = zero16();
; #pragma unroll
;         for (int ks = 0; ks < 4; ++ks) { const bf16x8_t ka = *(const LAS bf16x8_t*)(Kb + (32 * mt + r) * A_KSTR + 32 * ks + 16 * h); sacc = MFMA32(ka, qf[ks], sacc); }
; #pragma unroll
;         for (int i = 0; i < 16; ++i) {
;             float p;
;             if (MODE == 2) p = ex2(sacc[i]);
;             else if (MODE == 3) p = ex2(sacc[i] + __int_as_float(dl));
;             else { const int ci = 32 * mt + (i & 3) + 8 * (i >> 2); p = ((unsigned)(dl - ci) < ulim) ? ex2(sacc[i]) : 0.f; }
;             sacc[i] = p; ls += p;
;         }
; #pragma unroll
;         for (int s = 0; s < 2; ++s) {
;             const bf16x8_t pf = pack8(sacc, 8 * s);
; #pragma unroll
;             for (int dt = 0; dt < 2; ++dt) {
;                 const LAS unsigned char* vp = Vb + (32 * dt + r) * A_CVSTR + (32 * mt + 16 * s + 4 * h) * 2;
;                 const s16x4_t lo = *(const LAS s16x4_t*)vp, hi = *(const LAS s16x4_t*)(vp + 16);
;                 oacc[dt] = MFMA32(__builtin_shufflevector(lo, hi, 0, 1, 2, 3, 4, 5, 6, 7), pf, oacc[dt]);
;             }
;         }
;     }
;     l_run += ls;
	v_mfma_f32_32x32x16_bf16 v[16:31], v[228:231], v[68:71], v[16:31]
	ds_read2_b64 v[228:231], v74 offset0:52 offset1:54
	v_exp_f32_e32 v38, v38
	v_exp_f32_e32 v39, v39
	v_add_f32_e32 v232, v232, v36
	v_add_f32_e32 v233, v233, v37
	v_cvt_pk_bf16_f32 v66, v36, v37
	v_add_f32_e32 v232, v232, v38
	v_add_f32_e32 v233, v233, v39
	v_cvt_pk_bf16_f32 v67, v38, v39
	s_waitcnt lgkmcnt(5)
	v_mfma_f32_32x32x16_bf16 v[48:63], v[208:211], v[88:91], v[48:63]
	v_exp_f32_e32 v40, v40
	v_exp_f32_e32 v41, v41
	s_waitcnt lgkmcnt(4)
	v_mfma_f32_32x32x16_bf16 v[48:63], v[212:215], v[92:95], v[48:63]
	v_exp_f32_e32 v42, v42
	v_exp_f32_e32 v43, v43
	v_add_f32_e32 v232, v232, v40
	v_add_f32_e32 v233, v233, v41
	v_cvt_pk_bf16_f32 v68, v40, v41
	s_waitcnt lgkmcnt(3)
	v_mfma_f32_32x32x16_bf16 v[0:15], v[216:219], v[64:67], v[0:15]
	ds_read2_b64 v[216:219], v73 offset0:24 offset1:26
	v_exp_f32_e32 v44, v44
	v_exp_f32_e32 v45, v45
	v_add_f32_e32 v232, v232, v42
	v_add_f32_e32 v233, v233, v43
	v_cvt_pk_bf16_f32 v69, v42, v43
	s_waitcnt lgkmcnt(3)
	v_mfma_f32_32x32x16_bf16 v[16:31], v[220:223], v[64:67], v[16:31]
	ds_read2_b64 v[220:223], v74 offset0:56 offset1:58
	v_exp_f32_e32 v46, v46
	v_exp_f32_e32 v47, v47
	v_add_f32_e32 v232, v232, v44
	v_add_f32_e32 v233, v233, v45
	v_cvt_pk_bf16_f32 v70, v44, v45
	v_add_f32_e32 v232, v232, v46
	v_add_f32_e32 v233, v233, v47
	v_cvt_pk_bf16_f32 v71, v46, v47
	v_exp_f32_e32 v48, v48
	v_exp_f32_e32 v49, v49
	v_exp_f32_e32 v50, v50
	v_exp_f32_e32 v51, v51
	v_add_f32_e32 v232, v232, v48
	v_add_f32_e32 v233, v233, v49
	v_cvt_pk_bf16_f32 v64, v48, v49
	s_waitcnt lgkmcnt(3)
	v_mfma_f32_32x32x16_bf16 v[0:15], v[224:227], v[68:71], v[0:15]
	ds_read2_b64 v[224:227], v73 offset0:28 offset1:30
	v_exp_f32_e32 v52, v52
	v_exp_f32_e32 v53, v53
	v_add_f32_e32 v232, v232, v50
	v_add_f32_e32 v233, v233, v51
	v_cvt_pk_bf16_f32 v65, v50, v51
	s_waitcnt lgkmcnt(3)
	v_mfma_f32_32x32x16_bf16 v[16:31], v[228:231], v[68:71], v[16:31]
	ds_read2_b64 v[228:231], v74 offset0:60 offset1:62
	v_exp_f32_e32 v54, v54
	v_exp_f32_e32 v55, v55
	v_add_f32_e32 v232, v232, v52
	v_add_f32_e32 v233, v233, v53
	v_cvt_pk_bf16_f32 v66, v52, v53
	v_add_f32_e32 v232, v232, v54
	v_add_f32_e32 v233, v233, v55
	v_cvt_pk_bf16_f32 v67, v54, v55
	v_exp_f32_e32 v56, v56
	v_exp_f32_e32 v57, v57
	v_exp_f32_e32 v58, v58
	v_exp_f32_e32 v59, v59
	v_add_f32_e32 v232, v232, v56
	v_add_f32_e32 v233, v233, v57
	v_cvt_pk_bf16_f32 v68, v56, v57
	s_waitcnt lgkmcnt(3)
	v_mfma_f32_32x32x16_bf16 v[0:15], v[216:219], v[64:67], v[0:15]
	v_exp_f32_e32 v60, v60
	v_exp_f32_e32 v61, v61
	v_add_f32_e32 v232, v232, v58
	v_add_f32_e32 v233, v233, v59
	v_cvt_pk_bf16_f32 v69, v58, v59
	s_waitcnt lgkmcnt(2)
	v_mfma_f32_32x32x16_bf16 v[16:31], v[220:223], v[64:67], v[16:31]
	v_exp_f32_e32 v62, v62
	v_exp_f32_e32 v63, v63
	v_add_f32_e32 v232, v232, v60
	v_add_f32_e32 v233, v233, v61
	v_cvt_pk_bf16_f32 v70, v60, v61
	v_add_f32_e32 v232, v232, v62
	v_add_f32_e32 v233, v233, v63
	v_cvt_pk_bf16_f32 v71, v62, v63
	s_nop 1
	s_waitcnt lgkmcnt(1)
	v_mfma_f32_32x32x16_bf16 v[0:15], v[224:227], v[68:71], v[0:15]
	s_waitcnt lgkmcnt(0)
	v_mfma_f32_32x32x16_bf16 v[16:31], v[228:231], v[68:71], v[16:31]
	v_add_f32_e32 v232, v232, v233
	v_add_f32_e32 v112, v112, v232
	s_branch .Lt1_join
.Lt1_bias:
	ds_read_b128 v[200:203], v72 offset:0
	ds_read_b128 v[204:207], v72 offset:32
	ds_read_b128 v[208:211], v72 offset:64
	ds_read_b128 v[212:215], v72 offset:96
	ds_read2_b64 v[216:219], v73 offset0:0 offset1:2
	ds_read2_b64 v[220:223], v74 offset0:32 offset1:34
	ds_read2_b64 v[224:227], v73 offset0:4 offset1:6
	ds_read2_b64 v[228:231], v74 offset0:36 offset1:38
	v_bfe_i32 v236, v158, s49, 1
	s_add_i32 s49, s49, 1
	v_bfe_i32 v237, v158, s49, 1
	s_waitcnt lgkmcnt(7)
	v_mfma_f32_32x32x16_bf16 v[32:47], v[200:203], v[80:83], 0
	ds_read_b128 v[200:203], v72 offset:4608
	s_waitcnt lgkmcnt(7)
	v_mfma_f32_32x32x16_bf16 v[32:47], v[204:207], v[84:87], v[32:47]
	ds_read_b128 v[204:207], v72 offset:4640
	s_waitcnt lgkmcnt(7)
	v_mfma_f32_32x32x16_bf16 v[32:47], v[208:211], v[88:91], v[32:47]
	ds_read_b128 v[208:211], v72 offset:4672
	s_waitcnt lgkmcnt(7)
	v_mfma_f32_32x32x16_bf16 v[32:47], v[212:215], v[92:95], v[32:47]
	ds_read_b128 v[212:215], v72 offset:4704
	s_nop 7
	s_nop 3
	s_waitcnt lgkmcnt(3)
	v_mfma_f32_32x32x16_bf16 v[48:63], v[200:203], v[80:83], 0
	ds_read_b128 v[200:203], v72 offset:9216
	v_exp_f32_e32 v32, v32
	v_exp_f32_e32 v33, v33
	s_waitcnt lgkmcnt(3)
	v_mfma_f32_32x32x16_bf16 v[48:63], v[204:207], v[84:87], v[48:63]
	ds_read_b128 v[204:207], v72 offset:9248
	v_exp_f32_e32 v34, v34
	v_exp_f32_e32 v35, v35
	v_mov_b32_e32 v232, v32
	v_mov_b32_e32 v233, v33
	v_cvt_pk_bf16_f32 v64, v32, v33
	v_and_b32_e32 v64, v236, v64
	v_exp_f32_e32 v36, v36
	v_exp_f32_e32 v37, v37
	v_add_f32_e32 v232, v232, v34
	v_add_f32_e32 v233, v233, v35
	v_cvt_pk_bf16_f32 v65, v34, v35
	v_and_b32_e32 v65, v236, v65
	v_exp_f32_e32 v38, v38
	v_exp_f32_e32 v39, v39
	v_add_f32_e32 v232, v232, v36
	v_add_f32_e32 v233, v233, v37
	v_cvt_pk_bf16_f32 v66, v36, v37
	v_and_b32_e32 v66, v236, v66
	v_add_f32_e32 v232, v232, v38
	v_add_f32_e32 v233, v233, v39
	v_cvt_pk_bf16_f32 v67, v38, v39
	v_and_b32_e32 v67, v236, v67
	s_waitcnt lgkmcnt(3)
	v_mfma_f32_32x32x16_bf16 v[48:63], v[208:211], v[88:91], v[48:63]
	ds_read_b128 v[208:211], v72 offset:9280
	v_exp_f32_e32 v40, v40
	v_exp_f32_e32 v41, v41
	s_waitcnt lgkmcnt(3)
; #define LAS __attribute__((address_space(3)))
; #define MFMA32(a, b, c) __builtin_amdgcn_mfma_f32_32x32x16_bf16((a), (b), (c), 0, 0, 0)
; __device__ __forceinline__ float ex2(float x) { return __builtin_amdgcn_exp2f(x); }
; template <int MODE>
; __device__ __forceinline__ void attn_tile(const LAS unsigned char* Kb, const LAS unsigned char* Vb, const bf16x8_t (&qf)[4], f32x16 (&oacc)[2], float& l_run,
;                                           int r, int h, int dlt0, int dlt1, bool hiw) {
;     const unsigned ulim = (MODE == 0) ? 0x80000000u : 512u;
;     float ls = 0.f;
; #pragma unroll
;     for (int mt = 0; mt < 4; ++mt) {
;         if (mt == 0) { if (hiw) __builtin_amdgcn_s_setprio(1); else __builtin_amdgcn_s_setprio(0); }
;         if (mt == 2) { if (hiw) __builtin_amdgcn_s_setprio(0); else __builtin_amdgcn_s_setprio(1); }
;         const int dl = mt < 2 ? dlt0 : dlt1;
;         f32x16 sacc = zero16();
; #pragma unroll
;         for (int ks = 0; ks < 4; ++ks) { const bf16x8_t ka = *(const LAS bf16x8_t*)(Kb + (32 * mt + r) * A_KSTR + 32 * ks + 16 * h); sacc = MFMA32(ka, qf[ks], sacc); }
; #pragma unroll
;         for (int i = 0; i < 16; ++i) {
;             float p;
;             if (MODE == 2) p = ex2(sacc[i]);
;             else if (MODE == 3) p = ex2(sacc[i] + __int_as_float(dl));
;             else { const int ci = 32 * mt + (i & 3) + 8 * (i >> 2); p = ((unsigned)(dl - ci) < ulim) ? ex2(sacc[i]) : 0.f; }
;             sacc[i] = p; ls += p;
;         }
; #pragma unroll
;         for (int s = 0; s < 2; ++s) {
;             const bf16x8_t pf = pack8(sacc, 8 * s);
; #pragma unroll
;             for (int dt = 0; dt < 2; ++dt) {
;                 const LAS unsigned char* vp = Vb + (32 * dt + r) * A_CVSTR + (32 * mt + 16 * s + 4 * h) * 2;
;                 const s16x4_t lo = *(const LAS s16x4_t*)vp, hi = *(const LAS s16x4_t*)(vp + 16);
;                 oacc[dt] = MFMA32(__builtin_shufflevector(lo, hi, 0, 1, 2, 3, 4, 5, 6, 7), pf, oacc[dt]);
;             }
;         }
;     }
;     l_run += ls;
	v_mfma_f32_32x32x16_bf16 v[48:63], v[212:215], v[92:95], v[48:63]
	ds_read_b128 v[212:215], v72 offset:9312
	v_exp_f32_e32 v42, v42
	v_exp_f32_e32 v43, v43
	v_add_f32_e32 v232, v232, v40
	v_add_f32_e32 v233, v233, v41
	v_cvt_pk_bf16_f32 v68, v40, v41
	v_and_b32_e32 v68, v236, v68
	v_mfma_f32_32x32x16_bf16 v[0:15], v[216:219], v[64:67], v[0:15]
	ds_read2_b64 v[216:219], v73 offset0:8 offset1:10
	v_exp_f32_e32 v44, v44
	v_exp_f32_e32 v45, v45
	v_add_f32_e32 v232, v232, v42
	v_add_f32_e32 v233, v233, v43
	v_cvt_pk_bf16_f32 v69, v42, v43
	v_and_b32_e32 v69, v236, v69
	v_mfma_f32_32x32x16_bf16 v[16:31], v[220:223], v[64:67], v[16:31]
	ds_read2_b64 v[220:223], v74 offset0:40 offset1:42
	v_exp_f32_e32 v46, v46
	v_exp_f32_e32 v47, v47
	v_add_f32_e32 v232, v232, v44
	v_add_f32_e32 v233, v233, v45
	v_cvt_pk_bf16_f32 v70, v44, v45
	v_and_b32_e32 v70, v236, v70
	v_add_f32_e32 v232, v232, v46
	v_add_f32_e32 v233, v233, v47
	v_cvt_pk_bf16_f32 v71, v46, v47
	v_and_b32_e32 v71, v236, v71
	s_waitcnt lgkmcnt(5)
	v_mfma_f32_32x32x16_bf16 v[32:47], v[200:203], v[80:83], 0
	ds_read_b128 v[200:203], v72 offset:13824
	v_exp_f32_e32 v48, v48
	v_exp_f32_e32 v49, v49
	s_waitcnt lgkmcnt(5)
	v_mfma_f32_32x32x16_bf16 v[32:47], v[204:207], v[84:87], v[32:47]
	ds_read_b128 v[204:207], v72 offset:13856
	v_exp_f32_e32 v50, v50
	v_exp_f32_e32 v51, v51
	v_add_f32_e32 v232, v232, v48
	v_add_f32_e32 v233, v233, v49
	v_cvt_pk_bf16_f32 v64, v48, v49
	v_and_b32_e32 v64, v236, v64
	v_mfma_f32_32x32x16_bf16 v[0:15], v[224:227], v[68:71], v[0:15]
	ds_read2_b64 v[224:227], v73 offset0:12 offset1:14
	v_exp_f32_e32 v52, v52
	v_exp_f32_e32 v53, v53
	v_add_f32_e32 v232, v232, v50
	v_add_f32_e32 v233, v233, v51
	v_cvt_pk_bf16_f32 v65, v50, v51
	v_and_b32_e32 v65, v236, v65
	v_mfma_f32_32x32x16_bf16 v[16:31], v[228:231], v[68:71], v[16:31]
	ds_read2_b64 v[228:231], v74 offset0:44 offset1:46
	v_exp_f32_e32 v54, v54
	v_exp_f32_e32 v55, v55
	v_add_f32_e32 v232, v232, v52
	v_add_f32_e32 v233, v233, v53
	v_cvt_pk_bf16_f32 v66, v52, v53
	v_and_b32_e32 v66, v236, v66
	v_add_f32_e32 v232, v232, v54
	v_add_f32_e32 v233, v233, v55
	v_cvt_pk_bf16_f32 v67, v54, v55
	v_and_b32_e32 v67, v236, v67
	s_waitcnt lgkmcnt(7)
	v_mfma_f32_32x32x16_bf16 v[32:47], v[208:211], v[88:91], v[32:47]
	ds_read_b128 v[208:211], v72 offset:13888
	v_exp_f32_e32 v56, v56
	v_exp_f32_e32 v57, v57
	s_waitcnt lgkmcnt(7)
	v_mfma_f32_32x32x16_bf16 v[32:47], v[212:215], v[92:95], v[32:47]
	ds_read_b128 v[212:215], v72 offset:13920
	v_exp_f32_e32 v58, v58
	v_exp_f32_e32 v59, v59
	v_add_f32_e32 v232, v232, v56
	v_add_f32_e32 v233, v233, v57
	v_cvt_pk_bf16_f32 v68, v56, v57
	v_and_b32_e32 v68, v236, v68
	s_waitcnt lgkmcnt(7)
	v_mfma_f32_32x32x16_bf16 v[0:15], v[216:219], v[64:67], v[0:15]
	ds_read2_b64 v[216:219], v73 offset0:16 offset1:18
	v_exp_f32_e32 v60, v60
	v_exp_f32_e32 v61, v61
	v_add_f32_e32 v232, v232, v58
	v_add_f32_e32 v233, v233, v59
	v_cvt_pk_bf16_f32 v69, v58, v59
	v_and_b32_e32 v69, v236, v69
	s_waitcnt lgkmcnt(7)
	v_mfma_f32_32x32x16_bf16 v[16:31], v[220:223], v[64:67], v[16:31]
	ds_read2_b64 v[220:223], v74 offset0:48 offset1:50
	v_exp_f32_e32 v62, v62
	v_exp_f32_e32 v63, v63
	v_add_f32_e32 v232, v232, v60
	v_add_f32_e32 v233, v233, v61
	v_cvt_pk_bf16_f32 v70, v60, v61
	v_and_b32_e32 v70, v236, v70
	v_add_f32_e32 v232, v232, v62
	v_add_f32_e32 v233, v233, v63
	v_cvt_pk_bf16_f32 v71, v62, v63
	v_and_b32_e32 v71, v236, v71
	s_waitcnt lgkmcnt(7)
	v_mfma_f32_32x32x16_bf16 v[48:63], v[200:203], v[80:83], 0
	v_exp_f32_e32 v32, v32
	v_exp_f32_e32 v33, v33
	s_waitcnt lgkmcnt(6)
	v_mfma_f32_32x32x16_bf16 v[48:63], v[204:207], v[84:87], v[48:63]
	v_exp_f32_e32 v34, v34
	v_exp_f32_e32 v35, v35
	v_mov_b32_e32 v234, v32
	v_mov_b32_e32 v235, v33
	v_cvt_pk_bf16_f32 v64, v32, v33
	v_and_b32_e32 v64, v237, v64
	s_waitcnt lgkmcnt(5)
; #define LAS __attribute__((address_space(3)))
; #define MFMA32(a, b, c) __builtin_amdgcn_mfma_f32_32x32x16_bf16((a), (b), (c), 0, 0, 0)
; __device__ __forceinline__ float ex2(float x) { return __builtin_amdgcn_exp2f(x); }
; template <int MODE>
; __device__ __forceinline__ void attn_tile(const LAS unsigned char* Kb, const LAS unsigned char* Vb, const bf16x8_t (&qf)[4], f32x16 (&oacc)[2], float& l_run,
;                                           int r, int h, int dlt0, int dlt1, bool hiw) {
;     const unsigned ulim = (MODE == 0) ? 0x80000000u : 512u;
;     float ls = 0.f;
; #pragma unroll
;     for (int mt = 0; mt < 4; ++mt) {
;         if (mt == 0) { if (hiw) __builtin_amdgcn_s_setprio(1); else __builtin_amdgcn_s_setprio(0); }
;         if (mt == 2) { if (hiw) __builtin_amdgcn_s_setprio(0); else __builtin_amdgcn_s_setprio(1); }
;         const int dl = mt < 2 ? dlt0 : dlt1;
;         f32x16 sacc = zero16();
; #pragma unroll
;         for (int ks = 0; ks < 4; ++ks) { const bf16x8_t ka = *(const LAS bf16x8_t*)(Kb + (32 * mt + r) * A_KSTR + 32 * ks + 16 * h); sacc = MFMA32(ka, qf[ks], sacc); }
; #pragma unroll
;         for (int i = 0; i < 16; ++i) {
;             float p;
;             if (MODE == 2) p = ex2(sacc[i]);
;             else if (MODE == 3) p = ex2(sacc[i] + __int_as_float(dl));
;             else { const int ci = 32 * mt + (i & 3) + 8 * (i >> 2); p = ((unsigned)(dl - ci) < ulim) ? ex2(sacc[i]) : 0.f; }
;             sacc[i] = p; ls += p;
;         }
; #pragma unroll
;         for (int s = 0; s < 2; ++s) {
;             const bf16x8_t pf = pack8(sacc, 8 * s);
; #pragma unroll
;             for (int dt = 0; dt < 2; ++dt) {
;                 const LAS unsigned char* vp = Vb + (32 * dt + r) * A_CVSTR + (32 * mt + 16 * s + 4 * h) * 2;
;                 const s16x4_t lo = *(const LAS s16x4_t*)vp, hi = *(const LAS s16x4_t*)(vp + 16);
;                 oacc[dt] = MFMA32(__builtin_shufflevector(lo, hi, 0, 1, 2, 3, 4, 5, 6, 7), pf, oacc[dt]);
;             }
;         }
;     }
;     l_run += ls;
	v_mfma_f32_32x32x16_bf16 v[0:15], v[224:227], v[68:71], v[0:15]
	ds_read2_b64 v[224:227], v73 offset0:20 offset1:22
	v_exp_f32_e32 v36, v36
	v_exp_f32_e32 v37, v37
	v_add_f32_e32 v234, v234, v34
	v_add_f32_e32 v235, v235, v35
	v_cvt_pk_bf16_f32 v65, v34, v35
	v_and_b32_e32 v65, v237, v65
	s_waitcnt lgkmcnt(5)
	v_mfma_f32_32x32x16_bf16 v[16:31], v[228:231], v[68:71], v[16:31]
	ds_read2_b64 v[228:231], v74 offset0:52 offset1:54
	v_exp_f32_e32 v38, v38
	v_exp_f32_e32 v39, v39
	v_add_f32_e32 v234, v234, v36
	v_add_f32_e32 v235, v235, v37
	v_cvt_pk_bf16_f32 v66, v36, v37
	v_and_b32_e32 v66, v237, v66
	v_add_f32_e32 v234, v234, v38
	v_add_f32_e32 v235, v235, v39
	v_cvt_pk_bf16_f32 v67, v38, v39
	v_and_b32_e32 v67, v237, v67
	s_waitcnt lgkmcnt(5)
	v_mfma_f32_32x32x16_bf16 v[48:63], v[208:211], v[88:91], v[48:63]
	v_exp_f32_e32 v40, v40
	v_exp_f32_e32 v41, v41
	s_waitcnt lgkmcnt(4)
	v_mfma_f32_32x32x16_bf16 v[48:63], v[212:215], v[92:95], v[48:63]
	v_exp_f32_e32 v42, v42
	v_exp_f32_e32 v43, v43
	v_add_f32_e32 v234, v234, v40
	v_add_f32_e32 v235, v235, v41
	v_cvt_pk_bf16_f32 v68, v40, v41
	v_and_b32_e32 v68, v237, v68
	s_waitcnt lgkmcnt(3)
	v_mfma_f32_32x32x16_bf16 v[0:15], v[216:219], v[64:67], v[0:15]
	ds_read2_b64 v[216:219], v73 offset0:24 offset1:26
	v_exp_f32_e32 v44, v44
	v_exp_f32_e32 v45, v45
	v_add_f32_e32 v234, v234, v42
	v_add_f32_e32 v235, v235, v43
	v_cvt_pk_bf16_f32 v69, v42, v43
	v_and_b32_e32 v69, v237, v69
	s_waitcnt lgkmcnt(3)
	v_mfma_f32_32x32x16_bf16 v[16:31], v[220:223], v[64:67], v[16:31]
	ds_read2_b64 v[220:223], v74 offset0:56 offset1:58
	v_exp_f32_e32 v46, v46
	v_exp_f32_e32 v47, v47
	v_add_f32_e32 v234, v234, v44
	v_add_f32_e32 v235, v235, v45
	v_cvt_pk_bf16_f32 v70, v44, v45
	v_and_b32_e32 v70, v237, v70
	v_add_f32_e32 v234, v234, v46
	v_add_f32_e32 v235, v235, v47
	v_cvt_pk_bf16_f32 v71, v46, v47
	v_and_b32_e32 v71, v237, v71
	v_exp_f32_e32 v48, v48
	v_exp_f32_e32 v49, v49
	v_exp_f32_e32 v50, v50
	v_exp_f32_e32 v51, v51
	v_add_f32_e32 v234, v234, v48
	v_add_f32_e32 v235, v235, v49
	v_cvt_pk_bf16_f32 v64, v48, v49
	v_and_b32_e32 v64, v237, v64
	s_waitcnt lgkmcnt(3)
	v_mfma_f32_32x32x16_bf16 v[0:15], v[224:227], v[68:71], v[0:15]
	ds_read2_b64 v[224:227], v73 offset0:28 offset1:30
	v_exp_f32_e32 v52, v52
	v_exp_f32_e32 v53, v53
	v_add_f32_e32 v234, v234, v50
	v_add_f32_e32 v235, v235, v51
	v_cvt_pk_bf16_f32 v65, v50, v51
	v_and_b32_e32 v65, v237, v65
	s_waitcnt lgkmcnt(3)
	v_mfma_f32_32x32x16_bf16 v[16:31], v[228:231], v[68:71], v[16:31]
	ds_read2_b64 v[228:231], v74 offset0:60 offset1:62
	v_exp_f32_e32 v54, v54
	v_exp_f32_e32 v55, v55
	v_add_f32_e32 v234, v234, v52
	v_add_f32_e32 v235, v235, v53
	v_cvt_pk_bf16_f32 v66, v52, v53
	v_and_b32_e32 v66, v237, v66
	v_add_f32_e32 v234, v234, v54
	v_add_f32_e32 v235, v235, v55
	v_cvt_pk_bf16_f32 v67, v54, v55
	v_and_b32_e32 v67, v237, v67
	v_exp_f32_e32 v56, v56
	v_exp_f32_e32 v57, v57
	v_exp_f32_e32 v58, v58
	v_exp_f32_e32 v59, v59
	v_add_f32_e32 v234, v234, v56
	v_add_f32_e32 v235, v235, v57
	v_cvt_pk_bf16_f32 v68, v56, v57
	v_and_b32_e32 v68, v237, v68
	s_waitcnt lgkmcnt(3)
	v_mfma_f32_32x32x16_bf16 v[0:15], v[216:219], v[64:67], v[0:15]
	v_exp_f32_e32 v60, v60
	v_exp_f32_e32 v61, v61
	v_add_f32_e32 v234, v234, v58
	v_add_f32_e32 v235, v235, v59
	v_cvt_pk_bf16_f32 v69, v58, v59
	v_and_b32_e32 v69, v237, v69
	s_waitcnt lgkmcnt(2)
	v_mfma_f32_32x32x16_bf16 v[16:31], v[220:223], v[64:67], v[16:31]
	v_exp_f32_e32 v62, v62
	v_exp_f32_e32 v63, v63
	v_add_f32_e32 v234, v234, v60
	v_add_f32_e32 v235, v235, v61
	v_cvt_pk_bf16_f32 v70, v60, v61
	v_and_b32_e32 v70, v237, v70
	v_add_f32_e32 v234, v234, v62
	v_add_f32_e32 v235, v235, v63
	v_cvt_pk_bf16_f32 v71, v62, v63
	v_and_b32_e32 v71, v237, v71
	s_nop 1
	s_waitcnt lgkmcnt(1)
	v_mfma_f32_32x32x16_bf16 v[0:15], v[224:227], v[68:71], v[0:15]
	s_waitcnt lgkmcnt(0)
	v_mfma_f32_32x32x16_bf16 v[16:31], v[228:231], v[68:71], v[16:31]
	v_add_f32_e32 v232, v232, v233
	v_add_f32_e32 v234, v234, v235
	v_and_b32_e32 v239, 1.0, v236
	v_and_b32_e32 v240, 1.0, v237
	v_fmac_f32_e32 v112, v232, v239
	v_fmac_f32_e32 v112, v234, v240
	s_branch .Lt1_join

; #define LAS __attribute__((address_space(3)))
; #define MFMA32(a, b, c) __builtin_amdgcn_mfma_f32_32x32x16_bf16((a), (b), (c), 0, 0, 0)
; __device__ __forceinline__ float ex2(float x) { return __builtin_amdgcn_exp2f(x); }
; template <int MODE>
; __device__ __forceinline__ void attn_tile(const LAS unsigned char* Kb, const LAS unsigned char* Vb, const bf16x8_t (&qf)[4], f32x16 (&oacc)[2], float& l_run,
;                                           int r, int h, int dlt0, int dlt1, bool hiw) {
;     const unsigned ulim = (MODE == 0) ? 0x80000000u : 512u;
;     float ls = 0.f;
; #pragma unroll
;     for (int mt = 0; mt < 4; ++mt) {
;         if (mt == 0) { if (hiw) __builtin_amdgcn_s_setprio(1); else __builtin_amdgcn_s_setprio(0); }
;         if (mt == 2) { if (hiw) __builtin_amdgcn_s_setprio(0); else __builtin_amdgcn_s_setprio(1); }
;         const int dl = mt < 2 ? dlt0 : dlt1;
;         f32x16 sacc = zero16();
; #pragma unroll
;         for (int ks = 0; ks < 4; ++ks) { const bf16x8_t ka = *(const LAS bf16x8_t*)(Kb + (32 * mt + r) * A_KSTR + 32 * ks + 16 * h); sacc = MFMA32(ka, qf[ks], sacc); }
; #pragma unroll
;         for (int i = 0; i < 16; ++i) {
;             float p;
;             if (MODE == 2) p = ex2(sacc[i]);
;             else if (MODE == 3) p = ex2(sacc[i] + __int_as_float(dl));
;             else { const int ci = 32 * mt + (i & 3) + 8 * (i >> 2); p = ((unsigned)(dl - ci) < ulim) ? ex2(sacc[i]) : 0.f; }
;             sacc[i] = p; ls += p;
;         }
; #pragma unroll
;         for (int s = 0; s < 2; ++s) {
;             const bf16x8_t pf = pack8(sacc, 8 * s);
; #pragma unroll
;             for (int dt = 0; dt < 2; ++dt) {
;                 const LAS unsigned char* vp = Vb + (32 * dt + r) * A_CVSTR + (32 * mt + 16 * s + 4 * h) * 2;
;                 const s16x4_t lo = *(const LAS s16x4_t*)vp, hi = *(const LAS s16x4_t*)(vp + 16);
;                 oacc[dt] = MFMA32(__builtin_shufflevector(lo, hi, 0, 1, 2, 3, 4, 5, 6, 7), pf, oacc[dt]);
;             }
;         }
;     }
;     l_run += ls;
.Lt1_d1:
	ds_read_b128 v[200:203], v72 offset:0
	ds_read_b128 v[204:207], v72 offset:32
	ds_read_b128 v[208:211], v72 offset:64
	ds_read_b128 v[212:215], v72 offset:96
	ds_read2_b64 v[216:219], v73 offset0:0 offset1:2
	ds_read2_b64 v[220:223], v74 offset0:32 offset1:34
	ds_read2_b64 v[224:227], v73 offset0:4 offset1:6
	ds_read2_b64 v[228:231], v74 offset0:36 offset1:38
	s_waitcnt lgkmcnt(7)
	v_mfma_f32_32x32x16_bf16 v[32:47], v[200:203], v[80:83], 0
	ds_read_b128 v[200:203], v72 offset:4608
	s_waitcnt lgkmcnt(7)
	v_mfma_f32_32x32x16_bf16 v[32:47], v[204:207], v[84:87], v[32:47]
	ds_read_b128 v[204:207], v72 offset:4640
	s_waitcnt lgkmcnt(7)
	v_mfma_f32_32x32x16_bf16 v[32:47], v[208:211], v[88:91], v[32:47]
	ds_read_b128 v[208:211], v72 offset:4672
	s_waitcnt lgkmcnt(7)
	v_mfma_f32_32x32x16_bf16 v[32:47], v[212:215], v[92:95], v[32:47]
	ds_read_b128 v[212:215], v72 offset:4704
	s_nop 7
	s_nop 3
	s_waitcnt lgkmcnt(3)
	v_mfma_f32_32x32x16_bf16 v[48:63], v[200:203], v[80:83], 0
	v_exp_f32_e32 v32, v32
	v_exp_f32_e32 v33, v33
	s_waitcnt lgkmcnt(2)
	v_mfma_f32_32x32x16_bf16 v[48:63], v[204:207], v[84:87], v[48:63]
	v_exp_f32_e32 v34, v34
	v_exp_f32_e32 v35, v35
	v_mov_b32_e32 v232, v32
	v_mov_b32_e32 v233, v33
	v_cvt_pk_bf16_f32 v64, v32, v33
	v_exp_f32_e32 v36, v36
	v_exp_f32_e32 v37, v37
	v_add_f32_e32 v232, v232, v34
	v_add_f32_e32 v233, v233, v35
	v_cvt_pk_bf16_f32 v65, v34, v35
	v_exp_f32_e32 v38, v38
	v_exp_f32_e32 v39, v39
	v_add_f32_e32 v232, v232, v36
	v_add_f32_e32 v233, v233, v37
	v_cvt_pk_bf16_f32 v66, v36, v37
	v_add_f32_e32 v232, v232, v38
	v_add_f32_e32 v233, v233, v39
	v_cvt_pk_bf16_f32 v67, v38, v39
	s_waitcnt lgkmcnt(1)
	v_mfma_f32_32x32x16_bf16 v[48:63], v[208:211], v[88:91], v[48:63]
	v_exp_f32_e32 v40, v40
	v_exp_f32_e32 v41, v41
	s_waitcnt lgkmcnt(0)
	v_mfma_f32_32x32x16_bf16 v[48:63], v[212:215], v[92:95], v[48:63]
	v_exp_f32_e32 v42, v42
	v_exp_f32_e32 v43, v43
	v_add_f32_e32 v232, v232, v40
	v_add_f32_e32 v233, v233, v41
	v_cvt_pk_bf16_f32 v68, v40, v41
	v_mfma_f32_32x32x16_bf16 v[0:15], v[216:219], v[64:67], v[0:15]
	ds_read2_b64 v[216:219], v73 offset0:8 offset1:10
	v_exp_f32_e32 v44, v44
	v_exp_f32_e32 v45, v45
	v_add_f32_e32 v232, v232, v42
	v_add_f32_e32 v233, v233, v43
	v_cvt_pk_bf16_f32 v69, v42, v43
	v_mfma_f32_32x32x16_bf16 v[16:31], v[220:223], v[64:67], v[16:31]
	ds_read2_b64 v[220:223], v74 offset0:40 offset1:42
	v_exp_f32_e32 v46, v46
	v_exp_f32_e32 v47, v47
	v_add_f32_e32 v232, v232, v44
	v_add_f32_e32 v233, v233, v45
	v_cvt_pk_bf16_f32 v70, v44, v45
	v_add_f32_e32 v232, v232, v46
	v_add_f32_e32 v233, v233, v47
	v_cvt_pk_bf16_f32 v71, v46, v47
	v_cmp_le_i32_e64 s[0:1], 0, v250
	v_cmp_le_i32_e64 s[4:5], 1, v250
	v_exp_f32_e32 v48, v48
	v_exp_f32_e32 v49, v49
	v_cmp_le_i32_e64 s[6:7], 2, v250
	v_cmp_le_i32_e64 s[48:49], 3, v250
	v_exp_f32_e32 v50, v50
	v_exp_f32_e32 v51, v51
	v_cndmask_b32_e64 v48, 0, v48, s[0:1]
	v_cndmask_b32_e64 v49, 0, v49, s[4:5]
	v_add_f32_e32 v232, v232, v48
	v_add_f32_e32 v233, v233, v49
	v_cvt_pk_bf16_f32 v64, v48, v49
	v_mfma_f32_32x32x16_bf16 v[0:15], v[224:227], v[68:71], v[0:15]
	ds_read2_b64 v[224:227], v73 offset0:12 offset1:14
	v_cmp_le_i32_e64 s[0:1], 8, v250
	v_cmp_le_i32_e64 s[4:5], 9, v250
	v_exp_f32_e32 v52, v52
	v_exp_f32_e32 v53, v53
	v_cndmask_b32_e64 v50, 0, v50, s[6:7]
	v_cndmask_b32_e64 v51, 0, v51, s[48:49]
	v_add_f32_e32 v232, v232, v50
	v_add_f32_e32 v233, v233, v51
	v_cvt_pk_bf16_f32 v65, v50, v51
	v_mfma_f32_32x32x16_bf16 v[16:31], v[228:231], v[68:71], v[16:31]
	ds_read2_b64 v[228:231], v74 offset0:44 offset1:46
	v_cmp_le_i32_e64 s[6:7], 10, v250
	v_cmp_le_i32_e64 s[48:49], 11, v250
	v_exp_f32_e32 v54, v54
	v_exp_f32_e32 v55, v55
	v_cndmask_b32_e64 v52, 0, v52, s[0:1]
	v_cndmask_b32_e64 v53, 0, v53, s[4:5]
	v_add_f32_e32 v232, v232, v52
	v_add_f32_e32 v233, v233, v53
	v_cvt_pk_bf16_f32 v66, v52, v53
	v_cndmask_b32_e64 v54, 0, v54, s[6:7]
	v_cndmask_b32_e64 v55, 0, v55, s[48:49]
	v_add_f32_e32 v232, v232, v54
	v_add_f32_e32 v233, v233, v55
	v_cvt_pk_bf16_f32 v67, v54, v55
	v_cmp_le_i32_e64 s[0:1], 16, v250
	v_cmp_le_i32_e64 s[4:5], 17, v250
	v_exp_f32_e32 v56, v56
	v_exp_f32_e32 v57, v57
	v_cmp_le_i32_e64 s[6:7], 18, v250
	v_cmp_le_i32_e64 s[48:49], 19, v250
	v_exp_f32_e32 v58, v58
	v_exp_f32_e32 v59, v59
	v_cndmask_b32_e64 v56, 0, v56, s[0:1]
	v_cndmask_b32_e64 v57, 0, v57, s[4:5]
	v_add_f32_e32 v232, v232, v56
	v_add_f32_e32 v233, v233, v57
	v_cvt_pk_bf16_f32 v68, v56, v57
	s_waitcnt lgkmcnt(3)
	v_mfma_f32_32x32x16_bf16 v[0:15], v[216:219], v[64:67], v[0:15]
	v_cmp_le_i32_e64 s[0:1], 24, v250
	v_cmp_le_i32_e64 s[4:5], 25, v250
	v_exp_f32_e32 v60, v60
	v_exp_f32_e32 v61, v61
	v_cndmask_b32_e64 v58, 0, v58, s[6:7]
	v_cndmask_b32_e64 v59, 0, v59, s[48:49]
	v_add_f32_e32 v232, v232, v58
	v_add_f32_e32 v233, v233, v59
	v_cvt_pk_bf16_f32 v69, v58, v59
	s_waitcnt lgkmcnt(2)
	v_mfma_f32_32x32x16_bf16 v[16:31], v[220:223], v[64:67], v[16:31]
	v_cmp_le_i32_e64 s[6:7], 26, v250
	v_cmp_le_i32_e64 s[48:49], 27, v250
	v_exp_f32_e32 v62, v62
	v_exp_f32_e32 v63, v63
	v_cndmask_b32_e64 v60, 0, v60, s[0:1]
	v_cndmask_b32_e64 v61, 0, v61, s[4:5]
	v_add_f32_e32 v232, v232, v60
	v_add_f32_e32 v233, v233, v61
	v_cvt_pk_bf16_f32 v70, v60, v61
	v_cndmask_b32_e64 v62, 0, v62, s[6:7]
	v_cndmask_b32_e64 v63, 0, v63, s[48:49]
	v_add_f32_e32 v232, v232, v62
	v_add_f32_e32 v233, v233, v63
	v_cvt_pk_bf16_f32 v71, v62, v63
	s_nop 1
	s_waitcnt lgkmcnt(1)
	v_mfma_f32_32x32x16_bf16 v[0:15], v[224:227], v[68:71], v[0:15]
	s_waitcnt lgkmcnt(0)
	v_mfma_f32_32x32x16_bf16 v[16:31], v[228:231], v[68:71], v[16:31]
	v_add_f32_e32 v232, v232, v233
	v_add_f32_e32 v112, v112, v232
	s_branch .Lt1_join
; #define LAS __attribute__((address_space(3)))
; #define MFMA32(a, b, c) __builtin_amdgcn_mfma_f32_32x32x16_bf16((a), (b), (c), 0, 0, 0)
; __device__ __forceinline__ float ex2(float x) { return __builtin_amdgcn_exp2f(x); }
; template <int MODE>
; __device__ __forceinline__ void attn_tile(const LAS unsigned char* Kb, const LAS unsigned char* Vb, const bf16x8_t (&qf)[4], f32x16 (&oacc)[2], float& l_run,
;                                           int r, int h, int dlt0, int dlt1, bool hiw) {
;     const unsigned ulim = (MODE == 0) ? 0x80000000u : 512u;
;     float ls = 0.f;
; #pragma unroll
;     for (int mt = 0; mt < 4; ++mt) {
;         if (mt == 0) { if (hiw) __builtin_amdgcn_s_setprio(1); else __builtin_amdgcn_s_setprio(0); }
;         if (mt == 2) { if (hiw) __builtin_amdgcn_s_setprio(0); else __builtin_amdgcn_s_setprio(1); }
;         const int dl = mt < 2 ? dlt0 : dlt1;
;         f32x16 sacc = zero16();
; #pragma unroll
;         for (int ks = 0; ks < 4; ++ks) { const bf16x8_t ka = *(const LAS bf16x8_t*)(Kb + (32 * mt + r) * A_KSTR + 32 * ks + 16 * h); sacc = MFMA32(ka, qf[ks], sacc); }
; #pragma unroll
;         for (int i = 0; i < 16; ++i) {
;             float p;
;             if (MODE == 2) p = ex2(sacc[i]);
;             else if (MODE == 3) p = ex2(sacc[i] + __int_as_float(dl));
;             else { const int ci = 32 * mt + (i & 3) + 8 * (i >> 2); p = ((unsigned)(dl - ci) < ulim) ? ex2(sacc[i]) : 0.f; }
;             sacc[i] = p; ls += p;
;         }
; #pragma unroll
;         for (int s = 0; s < 2; ++s) {
;             const bf16x8_t pf = pack8(sacc, 8 * s);
; #pragma unroll
;             for (int dt = 0; dt < 2; ++dt) {
;                 const LAS unsigned char* vp = Vb + (32 * dt + r) * A_CVSTR + (32 * mt + 16 * s + 4 * h) * 2;
;                 const s16x4_t lo = *(const LAS s16x4_t*)vp, hi = *(const LAS s16x4_t*)(vp + 16);
;                 oacc[dt] = MFMA32(__builtin_shufflevector(lo, hi, 0, 1, 2, 3, 4, 5, 6, 7), pf, oacc[dt]);
;             }
;         }
;     }
;     l_run += ls;
.Lt1_d2:
	ds_read_b128 v[200:203], v72 offset:0
	ds_read_b128 v[204:207], v72 offset:32
	ds_read_b128 v[208:211], v72 offset:64
	ds_read_b128 v[212:215], v72 offset:96
	ds_read2_b64 v[216:219], v73 offset0:0 offset1:2
	ds_read2_b64 v[220:223], v74 offset0:32 offset1:34
	ds_read2_b64 v[224:227], v73 offset0:4 offset1:6
	ds_read2_b64 v[228:231], v74 offset0:36 offset1:38
	s_waitcnt lgkmcnt(7)
	v_mfma_f32_32x32x16_bf16 v[32:47], v[200:203], v[80:83], 0
	ds_read_b128 v[200:203], v72 offset:4608
	s_waitcnt lgkmcnt(7)
	v_mfma_f32_32x32x16_bf16 v[32:47], v[204:207], v[84:87], v[32:47]
	ds_read_b128 v[204:207], v72 offset:4640
	s_waitcnt lgkmcnt(7)
	v_mfma_f32_32x32x16_bf16 v[32:47], v[208:211], v[88:91], v[32:47]
	ds_read_b128 v[208:211], v72 offset:4672
	s_waitcnt lgkmcnt(7)
	v_mfma_f32_32x32x16_bf16 v[32:47], v[212:215], v[92:95], v[32:47]
	ds_read_b128 v[212:215], v72 offset:4704
	s_nop 7
	s_nop 3
	s_waitcnt lgkmcnt(3)
	v_mfma_f32_32x32x16_bf16 v[48:63], v[200:203], v[80:83], 0
	ds_read_b128 v[200:203], v72 offset:9216
	v_exp_f32_e32 v32, v32
	v_exp_f32_e32 v33, v33
	s_waitcnt lgkmcnt(3)
	v_mfma_f32_32x32x16_bf16 v[48:63], v[204:207], v[84:87], v[48:63]
	ds_read_b128 v[204:207], v72 offset:9248
	v_exp_f32_e32 v34, v34
	v_exp_f32_e32 v35, v35
	v_mov_b32_e32 v232, v32
	v_mov_b32_e32 v233, v33
	v_cvt_pk_bf16_f32 v64, v32, v33
	v_exp_f32_e32 v36, v36
	v_exp_f32_e32 v37, v37
	v_add_f32_e32 v232, v232, v34
	v_add_f32_e32 v233, v233, v35
	v_cvt_pk_bf16_f32 v65, v34, v35
	v_exp_f32_e32 v38, v38
	v_exp_f32_e32 v39, v39
	v_add_f32_e32 v232, v232, v36
	v_add_f32_e32 v233, v233, v37
	v_cvt_pk_bf16_f32 v66, v36, v37
	v_add_f32_e32 v232, v232, v38
	v_add_f32_e32 v233, v233, v39
	v_cvt_pk_bf16_f32 v67, v38, v39
	s_waitcnt lgkmcnt(3)
	v_mfma_f32_32x32x16_bf16 v[48:63], v[208:211], v[88:91], v[48:63]
	ds_read_b128 v[208:211], v72 offset:9280
	v_exp_f32_e32 v40, v40
	v_exp_f32_e32 v41, v41
	s_waitcnt lgkmcnt(3)
	v_mfma_f32_32x32x16_bf16 v[48:63], v[212:215], v[92:95], v[48:63]
	ds_read_b128 v[212:215], v72 offset:9312
	v_exp_f32_e32 v42, v42
	v_exp_f32_e32 v43, v43
	v_add_f32_e32 v232, v232, v40
	v_add_f32_e32 v233, v233, v41
	v_cvt_pk_bf16_f32 v68, v40, v41
	v_mfma_f32_32x32x16_bf16 v[0:15], v[216:219], v[64:67], v[0:15]
	ds_read2_b64 v[216:219], v73 offset0:8 offset1:10
	v_exp_f32_e32 v44, v44
	v_exp_f32_e32 v45, v45
	v_add_f32_e32 v232, v232, v42
	v_add_f32_e32 v233, v233, v43
	v_cvt_pk_bf16_f32 v69, v42, v43
	v_mfma_f32_32x32x16_bf16 v[16:31], v[220:223], v[64:67], v[16:31]
	ds_read2_b64 v[220:223], v74 offset0:40 offset1:42
	v_exp_f32_e32 v46, v46
	v_exp_f32_e32 v47, v47
	v_add_f32_e32 v232, v232, v44
	v_add_f32_e32 v233, v233, v45
	v_cvt_pk_bf16_f32 v70, v44, v45
	v_add_f32_e32 v232, v232, v46
	v_add_f32_e32 v233, v233, v47
	v_cvt_pk_bf16_f32 v71, v46, v47
	s_waitcnt lgkmcnt(5)
	v_mfma_f32_32x32x16_bf16 v[32:47], v[200:203], v[80:83], 0
	v_exp_f32_e32 v48, v48
	v_exp_f32_e32 v49, v49
	s_waitcnt lgkmcnt(4)
	v_mfma_f32_32x32x16_bf16 v[32:47], v[204:207], v[84:87], v[32:47]
	v_exp_f32_e32 v50, v50
	v_exp_f32_e32 v51, v51
	v_add_f32_e32 v232, v232, v48
	v_add_f32_e32 v233, v233, v49
	v_cvt_pk_bf16_f32 v64, v48, v49
	v_mfma_f32_32x32x16_bf16 v[0:15], v[224:227], v[68:71], v[0:15]
	ds_read2_b64 v[224:227], v73 offset0:12 offset1:14
	v_exp_f32_e32 v52, v52
	v_exp_f32_e32 v53, v53
	v_add_f32_e32 v232, v232, v50
	v_add_f32_e32 v233, v233, v51
	v_cvt_pk_bf16_f32 v65, v50, v51
	v_mfma_f32_32x32x16_bf16 v[16:31], v[228:231], v[68:71], v[16:31]
	ds_read2_b64 v[228:231], v74 offset0:44 offset1:46
	v_exp_f32_e32 v54, v54
	v_exp_f32_e32 v55, v55
	v_add_f32_e32 v232, v232, v52
	v_add_f32_e32 v233, v233, v53
	v_cvt_pk_bf16_f32 v66, v52, v53
	v_add_f32_e32 v232, v232, v54
	v_add_f32_e32 v233, v233, v55
	v_cvt_pk_bf16_f32 v67, v54, v55
	s_waitcnt lgkmcnt(5)
	v_mfma_f32_32x32x16_bf16 v[32:47], v[208:211], v[88:91], v[32:47]
	v_exp_f32_e32 v56, v56
	v_exp_f32_e32 v57, v57
	s_waitcnt lgkmcnt(4)
	v_mfma_f32_32x32x16_bf16 v[32:47], v[212:215], v[92:95], v[32:47]
	v_exp_f32_e32 v58, v58
	v_exp_f32_e32 v59, v59
	v_add_f32_e32 v232, v232, v56
	v_add_f32_e32 v233, v233, v57
	v_cvt_pk_bf16_f32 v68, v56, v57
	s_waitcnt lgkmcnt(3)
	v_mfma_f32_32x32x16_bf16 v[0:15], v[216:219], v[64:67], v[0:15]
	ds_read2_b64 v[216:219], v73 offset0:16 offset1:18
	v_exp_f32_e32 v60, v60
	v_exp_f32_e32 v61, v61
	v_add_f32_e32 v232, v232, v58
	v_add_f32_e32 v233, v233, v59
	v_cvt_pk_bf16_f32 v69, v58, v59
	s_waitcnt lgkmcnt(3)
	v_mfma_f32_32x32x16_bf16 v[16:31], v[220:223], v[64:67], v[16:31]
	ds_read2_b64 v[220:223], v74 offset0:48 offset1:50
	v_exp_f32_e32 v62, v62
	v_exp_f32_e32 v63, v63
	v_add_f32_e32 v232, v232, v60
	v_add_f32_e32 v233, v233, v61
	v_cvt_pk_bf16_f32 v70, v60, v61
	v_add_f32_e32 v232, v232, v62
	v_add_f32_e32 v233, v233, v63
	v_cvt_pk_bf16_f32 v71, v62, v63
	v_cmp_le_i32_e64 s[0:1], 0, v250
	v_cmp_le_i32_e64 s[4:5], 1, v250
	v_exp_f32_e32 v32, v32
	v_exp_f32_e32 v33, v33
	v_cmp_le_i32_e64 s[6:7], 2, v250
	v_cmp_le_i32_e64 s[48:49], 3, v250
	v_exp_f32_e32 v34, v34
	v_exp_f32_e32 v35, v35
	v_cndmask_b32_e64 v32, 0, v32, s[0:1]
	v_cndmask_b32_e64 v33, 0, v33, s[4:5]
	v_add_f32_e32 v232, v232, v32
	v_add_f32_e32 v233, v233, v33
	v_cvt_pk_bf16_f32 v64, v32, v33
	s_waitcnt lgkmcnt(3)
	v_mfma_f32_32x32x16_bf16 v[0:15], v[224:227], v[68:71], v[0:15]
	ds_read2_b64 v[224:227], v73 offset0:20 offset1:22
	v_cmp_le_i32_e64 s[0:1], 8, v250
	v_cmp_le_i32_e64 s[4:5], 9, v250
	v_exp_f32_e32 v36, v36
	v_exp_f32_e32 v37, v37
	v_cndmask_b32_e64 v34, 0, v34, s[6:7]
	v_cndmask_b32_e64 v35, 0, v35, s[48:49]
	v_add_f32_e32 v232, v232, v34
	v_add_f32_e32 v233, v233, v35
	v_cvt_pk_bf16_f32 v65, v34, v35
	s_waitcnt lgkmcnt(3)
; #define LAS __attribute__((address_space(3)))
; #define MFMA32(a, b, c) __builtin_amdgcn_mfma_f32_32x32x16_bf16((a), (b), (c), 0, 0, 0)
; __device__ __forceinline__ float ex2(float x) { return __builtin_amdgcn_exp2f(x); }
; template <int MODE>
; __device__ __forceinline__ void attn_tile(const LAS unsigned char* Kb, const LAS unsigned char* Vb, const bf16x8_t (&qf)[4], f32x16 (&oacc)[2], float& l_run,
;                                           int r, int h, int dlt0, int dlt1, bool hiw) {
;     const unsigned ulim = (MODE == 0) ? 0x80000000u : 512u;
;     float ls = 0.f;
; #pragma unroll
;     for (int mt = 0; mt < 4; ++mt) {
;         if (mt == 0) { if (hiw) __builtin_amdgcn_s_setprio(1); else __builtin_amdgcn_s_setprio(0); }
;         if (mt == 2) { if (hiw) __builtin_amdgcn_s_setprio(0); else __builtin_amdgcn_s_setprio(1); }
;         const int dl = mt < 2 ? dlt0 : dlt1;
;         f32x16 sacc = zero16();
; #pragma unroll
;         for (int ks = 0; ks < 4; ++ks) { const bf16x8_t ka = *(const LAS bf16x8_t*)(Kb + (32 * mt + r) * A_KSTR + 32 * ks + 16 * h); sacc = MFMA32(ka, qf[ks], sacc); }
; #pragma unroll
;         for (int i = 0; i < 16; ++i) {
;             float p;
;             if (MODE == 2) p = ex2(sacc[i]);
;             else if (MODE == 3) p = ex2(sacc[i] + __int_as_float(dl));
;             else { const int ci = 32 * mt + (i & 3) + 8 * (i >> 2); p = ((unsigned)(dl - ci) < ulim) ? ex2(sacc[i]) : 0.f; }
;             sacc[i] = p; ls += p;
;         }
; #pragma unroll
;         for (int s = 0; s < 2; ++s) {
;             const bf16x8_t pf = pack8(sacc, 8 * s);
; #pragma unroll
;             for (int dt = 0; dt < 2; ++dt) {
;                 const LAS unsigned char* vp = Vb + (32 * dt + r) * A_CVSTR + (32 * mt + 16 * s + 4 * h) * 2;
;                 const s16x4_t lo = *(const LAS s16x4_t*)vp, hi = *(const LAS s16x4_t*)(vp + 16);
;                 oacc[dt] = MFMA32(__builtin_shufflevector(lo, hi, 0, 1, 2, 3, 4, 5, 6, 7), pf, oacc[dt]);
;             }
;         }
;     }
;     l_run += ls;
	v_mfma_f32_32x32x16_bf16 v[16:31], v[228:231], v[68:71], v[16:31]
	ds_read2_b64 v[228:231], v74 offset0:52 offset1:54
	v_cmp_le_i32_e64 s[6:7], 10, v250
	v_cmp_le_i32_e64 s[48:49], 11, v250
	v_exp_f32_e32 v38, v38
	v_exp_f32_e32 v39, v39
	v_cndmask_b32_e64 v36, 0, v36, s[0:1]
	v_cndmask_b32_e64 v37, 0, v37, s[4:5]
	v_add_f32_e32 v232, v232, v36
	v_add_f32_e32 v233, v233, v37
	v_cvt_pk_bf16_f32 v66, v36, v37
	v_cndmask_b32_e64 v38, 0, v38, s[6:7]
	v_cndmask_b32_e64 v39, 0, v39, s[48:49]
	v_add_f32_e32 v232, v232, v38
	v_add_f32_e32 v233, v233, v39
	v_cvt_pk_bf16_f32 v67, v38, v39
	v_cmp_le_i32_e64 s[0:1], 16, v250
	v_cmp_le_i32_e64 s[4:5], 17, v250
	v_exp_f32_e32 v40, v40
	v_exp_f32_e32 v41, v41
	v_cmp_le_i32_e64 s[6:7], 18, v250
	v_cmp_le_i32_e64 s[48:49], 19, v250
	v_exp_f32_e32 v42, v42
	v_exp_f32_e32 v43, v43
	v_cndmask_b32_e64 v40, 0, v40, s[0:1]
	v_cndmask_b32_e64 v41, 0, v41, s[4:5]
	v_add_f32_e32 v232, v232, v40
	v_add_f32_e32 v233, v233, v41
	v_cvt_pk_bf16_f32 v68, v40, v41
	s_waitcnt lgkmcnt(3)
	v_mfma_f32_32x32x16_bf16 v[0:15], v[216:219], v[64:67], v[0:15]
	v_cmp_le_i32_e64 s[0:1], 24, v250
	v_cmp_le_i32_e64 s[4:5], 25, v250
	v_exp_f32_e32 v44, v44
	v_exp_f32_e32 v45, v45
	v_cndmask_b32_e64 v42, 0, v42, s[6:7]
	v_cndmask_b32_e64 v43, 0, v43, s[48:49]
	v_add_f32_e32 v232, v232, v42
	v_add_f32_e32 v233, v233, v43
	v_cvt_pk_bf16_f32 v69, v42, v43
	s_waitcnt lgkmcnt(2)
	v_mfma_f32_32x32x16_bf16 v[16:31], v[220:223], v[64:67], v[16:31]
	v_cmp_le_i32_e64 s[6:7], 26, v250
	v_cmp_le_i32_e64 s[48:49], 27, v250
	v_exp_f32_e32 v46, v46
	v_exp_f32_e32 v47, v47
	v_cndmask_b32_e64 v44, 0, v44, s[0:1]
	v_cndmask_b32_e64 v45, 0, v45, s[4:5]
	v_add_f32_e32 v232, v232, v44
	v_add_f32_e32 v233, v233, v45
	v_cvt_pk_bf16_f32 v70, v44, v45
	v_cndmask_b32_e64 v46, 0, v46, s[6:7]
	v_cndmask_b32_e64 v47, 0, v47, s[48:49]
	v_add_f32_e32 v232, v232, v46
	v_add_f32_e32 v233, v233, v47
	v_cvt_pk_bf16_f32 v71, v46, v47
	s_nop 1
	s_waitcnt lgkmcnt(1)
	v_mfma_f32_32x32x16_bf16 v[0:15], v[224:227], v[68:71], v[0:15]
	s_waitcnt lgkmcnt(0)
	v_mfma_f32_32x32x16_bf16 v[16:31], v[228:231], v[68:71], v[16:31]
	v_add_f32_e32 v232, v232, v233
	v_add_f32_e32 v112, v112, v232
	s_branch .Lt1_join
.Lt1_d3:
	ds_read_b128 v[200:203], v72 offset:0
	ds_read_b128 v[204:207], v72 offset:32
	ds_read_b128 v[208:211], v72 offset:64
	ds_read_b128 v[212:215], v72 offset:96
	ds_read2_b64 v[216:219], v73 offset0:0 offset1:2
	ds_read2_b64 v[220:223], v74 offset0:32 offset1:34
	ds_read2_b64 v[224:227], v73 offset0:4 offset1:6
	ds_read2_b64 v[228:231], v74 offset0:36 offset1:38
	s_waitcnt lgkmcnt(7)
	v_mfma_f32_32x32x16_bf16 v[32:47], v[200:203], v[80:83], 0
	ds_read_b128 v[200:203], v72 offset:4608
	s_waitcnt lgkmcnt(7)
	v_mfma_f32_32x32x16_bf16 v[32:47], v[204:207], v[84:87], v[32:47]
	ds_read_b128 v[204:207], v72 offset:4640
	s_waitcnt lgkmcnt(7)
	v_mfma_f32_32x32x16_bf16 v[32:47], v[208:211], v[88:91], v[32:47]
	ds_read_b128 v[208:211], v72 offset:4672
	s_waitcnt lgkmcnt(7)
	v_mfma_f32_32x32x16_bf16 v[32:47], v[212:215], v[92:95], v[32:47]
	ds_read_b128 v[212:215], v72 offset:4704
	s_nop 7
	s_nop 3
	s_waitcnt lgkmcnt(3)
	v_mfma_f32_32x32x16_bf16 v[48:63], v[200:203], v[80:83], 0
	ds_read_b128 v[200:203], v72 offset:9216
	v_exp_f32_e32 v32, v32
	v_exp_f32_e32 v33, v33
	s_waitcnt lgkmcnt(3)
	v_mfma_f32_32x32x16_bf16 v[48:63], v[204:207], v[84:87], v[48:63]
	ds_read_b128 v[204:207], v72 offset:9248
	v_exp_f32_e32 v34, v34
	v_exp_f32_e32 v35, v35
	v_mov_b32_e32 v232, v32
	v_mov_b32_e32 v233, v33
	v_cvt_pk_bf16_f32 v64, v32, v33
	v_exp_f32_e32 v36, v36
	v_exp_f32_e32 v37, v37
	v_add_f32_e32 v232, v232, v34
	v_add_f32_e32 v233, v233, v35
	v_cvt_pk_bf16_f32 v65, v34, v35
	v_exp_f32_e32 v38, v38
	v_exp_f32_e32 v39, v39
	v_add_f32_e32 v232, v232, v36
	v_add_f32_e32 v233, v233, v37
	v_cvt_pk_bf16_f32 v66, v36, v37
	v_add_f32_e32 v232, v232, v38
	v_add_f32_e32 v233, v233, v39
	v_cvt_pk_bf16_f32 v67, v38, v39
	s_waitcnt lgkmcnt(3)
	v_mfma_f32_32x32x16_bf16 v[48:63], v[208:211], v[88:91], v[48:63]
	ds_read_b128 v[208:211], v72 offset:9280
	v_exp_f32_e32 v40, v40
	v_exp_f32_e32 v41, v41
	s_waitcnt lgkmcnt(3)
	v_mfma_f32_32x32x16_bf16 v[48:63], v[212:215], v[92:95], v[48:63]
	ds_read_b128 v[212:215], v72 offset:9312
	v_exp_f32_e32 v42, v42
	v_exp_f32_e32 v43, v43
	v_add_f32_e32 v232, v232, v40
	v_add_f32_e32 v233, v233, v41
	v_cvt_pk_bf16_f32 v68, v40, v41
	v_mfma_f32_32x32x16_bf16 v[0:15], v[216:219], v[64:67], v[0:15]
	ds_read2_b64 v[216:219], v73 offset0:8 offset1:10
	v_exp_f32_e32 v44, v44
	v_exp_f32_e32 v45, v45
	v_add_f32_e32 v232, v232, v42
	v_add_f32_e32 v233, v233, v43
	v_cvt_pk_bf16_f32 v69, v42, v43
	v_mfma_f32_32x32x16_bf16 v[16:31], v[220:223], v[64:67], v[16:31]
	ds_read2_b64 v[220:223], v74 offset0:40 offset1:42
	v_exp_f32_e32 v46, v46
	v_exp_f32_e32 v47, v47
	v_add_f32_e32 v232, v232, v44
	v_add_f32_e32 v233, v233, v45
	v_cvt_pk_bf16_f32 v70, v44, v45
	v_add_f32_e32 v232, v232, v46
	v_add_f32_e32 v233, v233, v47
	v_cvt_pk_bf16_f32 v71, v46, v47
	s_waitcnt lgkmcnt(5)
	v_mfma_f32_32x32x16_bf16 v[32:47], v[200:203], v[80:83], 0
	ds_read_b128 v[200:203], v72 offset:13824
	v_exp_f32_e32 v48, v48
	v_exp_f32_e32 v49, v49
	s_waitcnt lgkmcnt(5)
	v_mfma_f32_32x32x16_bf16 v[32:47], v[204:207], v[84:87], v[32:47]
	ds_read_b128 v[204:207], v72 offset:13856
	v_exp_f32_e32 v50, v50
	v_exp_f32_e32 v51, v51
	v_add_f32_e32 v232, v232, v48
	v_add_f32_e32 v233, v233, v49
	v_cvt_pk_bf16_f32 v64, v48, v49
	v_mfma_f32_32x32x16_bf16 v[0:15], v[224:227], v[68:71], v[0:15]
	ds_read2_b64 v[224:227], v73 offset0:12 offset1:14
	v_exp_f32_e32 v52, v52
	v_exp_f32_e32 v53, v53
	v_add_f32_e32 v232, v232, v50
	v_add_f32_e32 v233, v233, v51
	v_cvt_pk_bf16_f32 v65, v50, v51
	v_mfma_f32_32x32x16_bf16 v[16:31], v[228:231], v[68:71], v[16:31]
	ds_read2_b64 v[228:231], v74 offset0:44 offset1:46
	v_exp_f32_e32 v54, v54
	v_exp_f32_e32 v55, v55
	v_add_f32_e32 v232, v232, v52
	v_add_f32_e32 v233, v233, v53
	v_cvt_pk_bf16_f32 v66, v52, v53
	v_add_f32_e32 v232, v232, v54
	v_add_f32_e32 v233, v233, v55
	v_cvt_pk_bf16_f32 v67, v54, v55
	s_waitcnt lgkmcnt(7)
; #define LAS __attribute__((address_space(3)))
; #define MFMA32(a, b, c) __builtin_amdgcn_mfma_f32_32x32x16_bf16((a), (b), (c), 0, 0, 0)
; __device__ __forceinline__ float ex2(float x) { return __builtin_amdgcn_exp2f(x); }
; template <int MODE>
; __device__ __forceinline__ void attn_tile(const LAS unsigned char* Kb, const LAS unsigned char* Vb, const bf16x8_t (&qf)[4], f32x16 (&oacc)[2], float& l_run,
;                                           int r, int h, int dlt0, int dlt1, bool hiw) {
;     const unsigned ulim = (MODE == 0) ? 0x80000000u : 512u;
;     float ls = 0.f;
; #pragma unroll
;     for (int mt = 0; mt < 4; ++mt) {
;         if (mt == 0) { if (hiw) __builtin_amdgcn_s_setprio(1); else __builtin_amdgcn_s_setprio(0); }
;         if (mt == 2) { if (hiw) __builtin_amdgcn_s_setprio(0); else __builtin_amdgcn_s_setprio(1); }
;         const int dl = mt < 2 ? dlt0 : dlt1;
;         f32x16 sacc = zero16();
; #pragma unroll
;         for (int ks = 0; ks < 4; ++ks) { const bf16x8_t ka = *(const LAS bf16x8_t*)(Kb + (32 * mt + r) * A_KSTR + 32 * ks + 16 * h); sacc = MFMA32(ka, qf[ks], sacc); }
; #pragma unroll
;         for (int i = 0; i < 16; ++i) {
;             float p;
;             if (MODE == 2) p = ex2(sacc[i]);
;             else if (MODE == 3) p = ex2(sacc[i] + __int_as_float(dl));
;             else { const int ci = 32 * mt + (i & 3) + 8 * (i >> 2); p = ((unsigned)(dl - ci) < ulim) ? ex2(sacc[i]) : 0.f; }
;             sacc[i] = p; ls += p;
;         }
; #pragma unroll
;         for (int s = 0; s < 2; ++s) {
;             const bf16x8_t pf = pack8(sacc, 8 * s);
; #pragma unroll
;             for (int dt = 0; dt < 2; ++dt) {
;                 const LAS unsigned char* vp = Vb + (32 * dt + r) * A_CVSTR + (32 * mt + 16 * s + 4 * h) * 2;
;                 const s16x4_t lo = *(const LAS s16x4_t*)vp, hi = *(const LAS s16x4_t*)(vp + 16);
;                 oacc[dt] = MFMA32(__builtin_shufflevector(lo, hi, 0, 1, 2, 3, 4, 5, 6, 7), pf, oacc[dt]);
;             }
;         }
;     }
;     l_run += ls;
	v_mfma_f32_32x32x16_bf16 v[32:47], v[208:211], v[88:91], v[32:47]
	ds_read_b128 v[208:211], v72 offset:13888
	v_exp_f32_e32 v56, v56
	v_exp_f32_e32 v57, v57
	s_waitcnt lgkmcnt(7)
	v_mfma_f32_32x32x16_bf16 v[32:47], v[212:215], v[92:95], v[32:47]
	ds_read_b128 v[212:215], v72 offset:13920
	v_exp_f32_e32 v58, v58
	v_exp_f32_e32 v59, v59
	v_add_f32_e32 v232, v232, v56
	v_add_f32_e32 v233, v233, v57
	v_cvt_pk_bf16_f32 v68, v56, v57
	s_waitcnt lgkmcnt(7)
	v_mfma_f32_32x32x16_bf16 v[0:15], v[216:219], v[64:67], v[0:15]
	ds_read2_b64 v[216:219], v73 offset0:16 offset1:18
	v_exp_f32_e32 v60, v60
	v_exp_f32_e32 v61, v61
	v_add_f32_e32 v232, v232, v58
	v_add_f32_e32 v233, v233, v59
	v_cvt_pk_bf16_f32 v69, v58, v59
	s_waitcnt lgkmcnt(7)
	v_mfma_f32_32x32x16_bf16 v[16:31], v[220:223], v[64:67], v[16:31]
	ds_read2_b64 v[220:223], v74 offset0:48 offset1:50
	v_exp_f32_e32 v62, v62
	v_exp_f32_e32 v63, v63
	v_add_f32_e32 v232, v232, v60
	v_add_f32_e32 v233, v233, v61
	v_cvt_pk_bf16_f32 v70, v60, v61
	v_add_f32_e32 v232, v232, v62
	v_add_f32_e32 v233, v233, v63
	v_cvt_pk_bf16_f32 v71, v62, v63
	s_waitcnt lgkmcnt(7)
	v_mfma_f32_32x32x16_bf16 v[48:63], v[200:203], v[80:83], 0
	v_exp_f32_e32 v32, v32
	v_exp_f32_e32 v33, v33
	s_waitcnt lgkmcnt(6)
	v_mfma_f32_32x32x16_bf16 v[48:63], v[204:207], v[84:87], v[48:63]
	v_exp_f32_e32 v34, v34
	v_exp_f32_e32 v35, v35
	v_add_f32_e32 v232, v232, v32
	v_add_f32_e32 v233, v233, v33
	v_cvt_pk_bf16_f32 v64, v32, v33
	s_waitcnt lgkmcnt(5)
	v_mfma_f32_32x32x16_bf16 v[0:15], v[224:227], v[68:71], v[0:15]
	ds_read2_b64 v[224:227], v73 offset0:20 offset1:22
	v_exp_f32_e32 v36, v36
	v_exp_f32_e32 v37, v37
	v_add_f32_e32 v232, v232, v34
	v_add_f32_e32 v233, v233, v35
	v_cvt_pk_bf16_f32 v65, v34, v35
	s_waitcnt lgkmcnt(5)
	v_mfma_f32_32x32x16_bf16 v[16:31], v[228:231], v[68:71], v[16:31]
	ds_read2_b64 v[228:231], v74 offset0:52 offset1:54
	v_exp_f32_e32 v38, v38
	v_exp_f32_e32 v39, v39
	v_add_f32_e32 v232, v232, v36
	v_add_f32_e32 v233, v233, v37
	v_cvt_pk_bf16_f32 v66, v36, v37
	v_add_f32_e32 v232, v232, v38
	v_add_f32_e32 v233, v233, v39
	v_cvt_pk_bf16_f32 v67, v38, v39
	s_waitcnt lgkmcnt(5)
	v_mfma_f32_32x32x16_bf16 v[48:63], v[208:211], v[88:91], v[48:63]
	v_exp_f32_e32 v40, v40
	v_exp_f32_e32 v41, v41
	s_waitcnt lgkmcnt(4)
	v_mfma_f32_32x32x16_bf16 v[48:63], v[212:215], v[92:95], v[48:63]
	v_exp_f32_e32 v42, v42
	v_exp_f32_e32 v43, v43
	v_add_f32_e32 v232, v232, v40
	v_add_f32_e32 v233, v233, v41
	v_cvt_pk_bf16_f32 v68, v40, v41
	s_waitcnt lgkmcnt(3)
	v_mfma_f32_32x32x16_bf16 v[0:15], v[216:219], v[64:67], v[0:15]
	ds_read2_b64 v[216:219], v73 offset0:24 offset1:26
	v_exp_f32_e32 v44, v44
	v_exp_f32_e32 v45, v45
	v_add_f32_e32 v232, v232, v42
	v_add_f32_e32 v233, v233, v43
	v_cvt_pk_bf16_f32 v69, v42, v43
	s_waitcnt lgkmcnt(3)
	v_mfma_f32_32x32x16_bf16 v[16:31], v[220:223], v[64:67], v[16:31]
	ds_read2_b64 v[220:223], v74 offset0:56 offset1:58
	v_exp_f32_e32 v46, v46
	v_exp_f32_e32 v47, v47
	v_add_f32_e32 v232, v232, v44
	v_add_f32_e32 v233, v233, v45
	v_cvt_pk_bf16_f32 v70, v44, v45
	v_add_f32_e32 v232, v232, v46
	v_add_f32_e32 v233, v233, v47
	v_cvt_pk_bf16_f32 v71, v46, v47
	v_cmp_le_i32_e64 s[0:1], 0, v250
	v_cmp_le_i32_e64 s[4:5], 1, v250
	v_exp_f32_e32 v48, v48
	v_exp_f32_e32 v49, v49
	v_cmp_le_i32_e64 s[6:7], 2, v250
	v_cmp_le_i32_e64 s[48:49], 3, v250
	v_exp_f32_e32 v50, v50
	v_exp_f32_e32 v51, v51
	v_cndmask_b32_e64 v48, 0, v48, s[0:1]
	v_cndmask_b32_e64 v49, 0, v49, s[4:5]
	v_add_f32_e32 v232, v232, v48
	v_add_f32_e32 v233, v233, v49
	v_cvt_pk_bf16_f32 v64, v48, v49
	s_waitcnt lgkmcnt(3)
	v_mfma_f32_32x32x16_bf16 v[0:15], v[224:227], v[68:71], v[0:15]
	ds_read2_b64 v[224:227], v73 offset0:28 offset1:30
	v_cmp_le_i32_e64 s[0:1], 8, v250
	v_cmp_le_i32_e64 s[4:5], 9, v250
	v_exp_f32_e32 v52, v52
	v_exp_f32_e32 v53, v53
	v_cndmask_b32_e64 v50, 0, v50, s[6:7]
	v_cndmask_b32_e64 v51, 0, v51, s[48:49]
	v_add_f32_e32 v232, v232, v50
	v_add_f32_e32 v233, v233, v51
	v_cvt_pk_bf16_f32 v65, v50, v51
	s_waitcnt lgkmcnt(3)
	v_mfma_f32_32x32x16_bf16 v[16:31], v[228:231], v[68:71], v[16:31]
	ds_read2_b64 v[228:231], v74 offset0:60 offset1:62
	v_cmp_le_i32_e64 s[6:7], 10, v250
	v_cmp_le_i32_e64 s[48:49], 11, v250
	v_exp_f32_e32 v54, v54
	v_exp_f32_e32 v55, v55
	v_cndmask_b32_e64 v52, 0, v52, s[0:1]
	v_cndmask_b32_e64 v53, 0, v53, s[4:5]
	v_add_f32_e32 v232, v232, v52
	v_add_f32_e32 v233, v233, v53
	v_cvt_pk_bf16_f32 v66, v52, v53
	v_cndmask_b32_e64 v54, 0, v54, s[6:7]
	v_cndmask_b32_e64 v55, 0, v55, s[48:49]
	v_add_f32_e32 v232, v232, v54
	v_add_f32_e32 v233, v233, v55
	v_cvt_pk_bf16_f32 v67, v54, v55
	v_cmp_le_i32_e64 s[0:1], 16, v250
	v_cmp_le_i32_e64 s[4:5], 17, v250
	v_exp_f32_e32 v56, v56
	v_exp_f32_e32 v57, v57
	v_cmp_le_i32_e64 s[6:7], 18, v250
	v_cmp_le_i32_e64 s[48:49], 19, v250
	v_exp_f32_e32 v58, v58
	v_exp_f32_e32 v59, v59
	v_cndmask_b32_e64 v56, 0, v56, s[0:1]
	v_cndmask_b32_e64 v57, 0, v57, s[4:5]
	v_add_f32_e32 v232, v232, v56
	v_add_f32_e32 v233, v233, v57
	v_cvt_pk_bf16_f32 v68, v56, v57
	s_waitcnt lgkmcnt(3)
	v_mfma_f32_32x32x16_bf16 v[0:15], v[216:219], v[64:67], v[0:15]
	v_cmp_le_i32_e64 s[0:1], 24, v250
	v_cmp_le_i32_e64 s[4:5], 25, v250
	v_exp_f32_e32 v60, v60
	v_exp_f32_e32 v61, v61
	v_cndmask_b32_e64 v58, 0, v58, s[6:7]
	v_cndmask_b32_e64 v59, 0, v59, s[48:49]
	v_add_f32_e32 v232, v232, v58
	v_add_f32_e32 v233, v233, v59
	v_cvt_pk_bf16_f32 v69, v58, v59
	s_waitcnt lgkmcnt(2)
	v_mfma_f32_32x32x16_bf16 v[16:31], v[220:223], v[64:67], v[16:31]
	v_cmp_le_i32_e64 s[6:7], 26, v250
	v_cmp_le_i32_e64 s[48:49], 27, v250
	v_exp_f32_e32 v62, v62
	v_exp_f32_e32 v63, v63
	v_cndmask_b32_e64 v60, 0, v60, s[0:1]
	v_cndmask_b32_e64 v61, 0, v61, s[4:5]
	v_add_f32_e32 v232, v232, v60
	v_add_f32_e32 v233, v233, v61
	v_cvt_pk_bf16_f32 v70, v60, v61
	v_cndmask_b32_e64 v62, 0, v62, s[6:7]
	v_cndmask_b32_e64 v63, 0, v63, s[48:49]
	v_add_f32_e32 v232, v232, v62
	v_add_f32_e32 v233, v233, v63
	v_cvt_pk_bf16_f32 v71, v62, v63
	s_nop 1
	s_waitcnt lgkmcnt(1)
	v_mfma_f32_32x32x16_bf16 v[0:15], v[224:227], v[68:71], v[0:15]
	s_waitcnt lgkmcnt(0)
	v_mfma_f32_32x32x16_bf16 v[16:31], v[228:231], v[68:71], v[16:31]
	v_add_f32_e32 v232, v232, v233
	v_add_f32_e32 v112, v112, v232
	s_branch .Lt1_join
; #define LAS __attribute__((address_space(3)))
; #define MFMA32(a, b, c) __builtin_amdgcn_mfma_f32_32x32x16_bf16((a), (b), (c), 0, 0, 0)
; __device__ __forceinline__ float ex2(float x) { return __builtin_amdgcn_exp2f(x); }
; template <int MODE>
; __device__ __forceinline__ void attn_tile(const LAS unsigned char* Kb, const LAS unsigned char* Vb, const bf16x8_t (&qf)[4], f32x16 (&oacc)[2], float& l_run,
;                                           int r, int h, int dlt0, int dlt1, bool hiw) {
;     const unsigned ulim = (MODE == 0) ? 0x80000000u : 512u;
;     float ls = 0.f;
; #pragma unroll
;     for (int mt = 0; mt < 4; ++mt) {
;         if (mt == 0) { if (hiw) __builtin_amdgcn_s_setprio(1); else __builtin_amdgcn_s_setprio(0); }
;         if (mt == 2) { if (hiw) __builtin_amdgcn_s_setprio(0); else __builtin_amdgcn_s_setprio(1); }
;         const int dl = mt < 2 ? dlt0 : dlt1;
;         f32x16 sacc = zero16();
; #pragma unroll
;         for (int ks = 0; ks < 4; ++ks) { const bf16x8_t ka = *(const LAS bf16x8_t*)(Kb + (32 * mt + r) * A_KSTR + 32 * ks + 16 * h); sacc = MFMA32(ka, qf[ks], sacc); }
; #pragma unroll
;         for (int i = 0; i < 16; ++i) {
;             float p;
;             if (MODE == 2) p = ex2(sacc[i]);
;             else if (MODE == 3) p = ex2(sacc[i] + __int_as_float(dl));
;             else { const int ci = 32 * mt + (i & 3) + 8 * (i >> 2); p = ((unsigned)(dl - ci) < ulim) ? ex2(sacc[i]) : 0.f; }
;             sacc[i] = p; ls += p;
;         }
; #pragma unroll
;         for (int s = 0; s < 2; ++s) {
;             const bf16x8_t pf = pack8(sacc, 8 * s);
; #pragma unroll
;             for (int dt = 0; dt < 2; ++dt) {
;                 const LAS unsigned char* vp = Vb + (32 * dt + r) * A_CVSTR + (32 * mt + 16 * s + 4 * h) * 2;
;                 const s16x4_t lo = *(const LAS s16x4_t*)vp, hi = *(const LAS s16x4_t*)(vp + 16);
;                 oacc[dt] = MFMA32(__builtin_shufflevector(lo, hi, 0, 1, 2, 3, 4, 5, 6, 7), pf, oacc[dt]);
;             }
;         }
;     }
;     l_run += ls;
.Lt1_e0:
	ds_read_b128 v[200:203], v72 offset:0
	ds_read_b128 v[204:207], v72 offset:32
	ds_read_b128 v[208:211], v72 offset:64
	ds_read_b128 v[212:215], v72 offset:96
	ds_read2_b64 v[216:219], v73 offset0:0 offset1:2
	ds_read2_b64 v[220:223], v74 offset0:32 offset1:34
	ds_read2_b64 v[224:227], v73 offset0:4 offset1:6
	ds_read2_b64 v[228:231], v74 offset0:36 offset1:38
	s_waitcnt lgkmcnt(7)
	v_mfma_f32_32x32x16_bf16 v[32:47], v[200:203], v[80:83], 0
	ds_read_b128 v[200:203], v72 offset:4608
	s_waitcnt lgkmcnt(7)
	v_mfma_f32_32x32x16_bf16 v[32:47], v[204:207], v[84:87], v[32:47]
	ds_read_b128 v[204:207], v72 offset:4640
	s_waitcnt lgkmcnt(7)
	v_mfma_f32_32x32x16_bf16 v[32:47], v[208:211], v[88:91], v[32:47]
	ds_read_b128 v[208:211], v72 offset:4672
	s_waitcnt lgkmcnt(7)
	v_mfma_f32_32x32x16_bf16 v[32:47], v[212:215], v[92:95], v[32:47]
	ds_read_b128 v[212:215], v72 offset:4704
	s_nop 7
	s_nop 3
	s_waitcnt lgkmcnt(3)
	v_mfma_f32_32x32x16_bf16 v[48:63], v[200:203], v[80:83], 0
	ds_read_b128 v[200:203], v72 offset:9216
	v_cmp_le_i32_e64 s[0:1], 0, v250
	v_cmp_le_i32_e64 s[4:5], 1, v250
	v_exp_f32_e32 v32, v32
	v_exp_f32_e32 v33, v33
	s_waitcnt lgkmcnt(3)
	v_mfma_f32_32x32x16_bf16 v[48:63], v[204:207], v[84:87], v[48:63]
	ds_read_b128 v[204:207], v72 offset:9248
	v_cmp_le_i32_e64 s[6:7], 2, v250
	v_cmp_le_i32_e64 s[48:49], 3, v250
	v_exp_f32_e32 v34, v34
	v_exp_f32_e32 v35, v35
	v_cndmask_b32_e64 v32, v32, 0, s[0:1]
	v_cndmask_b32_e64 v33, v33, 0, s[4:5]
	v_mov_b32_e32 v232, v32
	v_mov_b32_e32 v233, v33
	v_cvt_pk_bf16_f32 v64, v32, v33
	v_cmp_le_i32_e64 s[0:1], 8, v250
	v_cmp_le_i32_e64 s[4:5], 9, v250
	v_exp_f32_e32 v36, v36
	v_exp_f32_e32 v37, v37
	v_cndmask_b32_e64 v34, v34, 0, s[6:7]
	v_cndmask_b32_e64 v35, v35, 0, s[48:49]
	v_add_f32_e32 v232, v232, v34
	v_add_f32_e32 v233, v233, v35
	v_cvt_pk_bf16_f32 v65, v34, v35
	v_cmp_le_i32_e64 s[6:7], 10, v250
	v_cmp_le_i32_e64 s[48:49], 11, v250
	v_exp_f32_e32 v38, v38
	v_exp_f32_e32 v39, v39
	v_cndmask_b32_e64 v36, v36, 0, s[0:1]
	v_cndmask_b32_e64 v37, v37, 0, s[4:5]
	v_add_f32_e32 v232, v232, v36
	v_add_f32_e32 v233, v233, v37
	v_cvt_pk_bf16_f32 v66, v36, v37
	v_cndmask_b32_e64 v38, v38, 0, s[6:7]
	v_cndmask_b32_e64 v39, v39, 0, s[48:49]
	v_add_f32_e32 v232, v232, v38
	v_add_f32_e32 v233, v233, v39
	v_cvt_pk_bf16_f32 v67, v38, v39
	s_waitcnt lgkmcnt(3)
	v_mfma_f32_32x32x16_bf16 v[48:63], v[208:211], v[88:91], v[48:63]
	ds_read_b128 v[208:211], v72 offset:9280
	v_cmp_le_i32_e64 s[0:1], 16, v250
	v_cmp_le_i32_e64 s[4:5], 17, v250
	v_exp_f32_e32 v40, v40
	v_exp_f32_e32 v41, v41
	s_waitcnt lgkmcnt(3)
	v_mfma_f32_32x32x16_bf16 v[48:63], v[212:215], v[92:95], v[48:63]
	ds_read_b128 v[212:215], v72 offset:9312
	v_cmp_le_i32_e64 s[6:7], 18, v250
	v_cmp_le_i32_e64 s[48:49], 19, v250
	v_exp_f32_e32 v42, v42
	v_exp_f32_e32 v43, v43
	v_cndmask_b32_e64 v40, v40, 0, s[0:1]
	v_cndmask_b32_e64 v41, v41, 0, s[4:5]
	v_add_f32_e32 v232, v232, v40
	v_add_f32_e32 v233, v233, v41
	v_cvt_pk_bf16_f32 v68, v40, v41
	v_mfma_f32_32x32x16_bf16 v[0:15], v[216:219], v[64:67], v[0:15]
	ds_read2_b64 v[216:219], v73 offset0:8 offset1:10
	v_cmp_le_i32_e64 s[0:1], 24, v250
	v_cmp_le_i32_e64 s[4:5], 25, v250
	v_exp_f32_e32 v44, v44
	v_exp_f32_e32 v45, v45
	v_cndmask_b32_e64 v42, v42, 0, s[6:7]
	v_cndmask_b32_e64 v43, v43, 0, s[48:49]
	v_add_f32_e32 v232, v232, v42
	v_add_f32_e32 v233, v233, v43
	v_cvt_pk_bf16_f32 v69, v42, v43
	v_mfma_f32_32x32x16_bf16 v[16:31], v[220:223], v[64:67], v[16:31]
	ds_read2_b64 v[220:223], v74 offset0:40 offset1:42
	v_cmp_le_i32_e64 s[6:7], 26, v250
	v_cmp_le_i32_e64 s[48:49], 27, v250
	v_exp_f32_e32 v46, v46
	v_exp_f32_e32 v47, v47
	v_cndmask_b32_e64 v44, v44, 0, s[0:1]
	v_cndmask_b32_e64 v45, v45, 0, s[4:5]
	v_add_f32_e32 v232, v232, v44
	v_add_f32_e32 v233, v233, v45
	v_cvt_pk_bf16_f32 v70, v44, v45
	v_cndmask_b32_e64 v46, v46, 0, s[6:7]
	v_cndmask_b32_e64 v47, v47, 0, s[48:49]
	v_add_f32_e32 v232, v232, v46
	v_add_f32_e32 v233, v233, v47
	v_cvt_pk_bf16_f32 v71, v46, v47
	s_waitcnt lgkmcnt(5)
	v_mfma_f32_32x32x16_bf16 v[32:47], v[200:203], v[80:83], 0
	ds_read_b128 v[200:203], v72 offset:13824
	v_exp_f32_e32 v48, v48
	v_exp_f32_e32 v49, v49
	s_waitcnt lgkmcnt(5)
	v_mfma_f32_32x32x16_bf16 v[32:47], v[204:207], v[84:87], v[32:47]
	ds_read_b128 v[204:207], v72 offset:13856
	v_exp_f32_e32 v50, v50
	v_exp_f32_e32 v51, v51
	v_add_f32_e32 v232, v232, v48
	v_add_f32_e32 v233, v233, v49
	v_cvt_pk_bf16_f32 v64, v48, v49
	v_mfma_f32_32x32x16_bf16 v[0:15], v[224:227], v[68:71], v[0:15]
	ds_read2_b64 v[224:227], v73 offset0:12 offset1:14
	v_exp_f32_e32 v52, v52
	v_exp_f32_e32 v53, v53
	v_add_f32_e32 v232, v232, v50
	v_add_f32_e32 v233, v233, v51
	v_cvt_pk_bf16_f32 v65, v50, v51
	v_mfma_f32_32x32x16_bf16 v[16:31], v[228:231], v[68:71], v[16:31]
	ds_read2_b64 v[228:231], v74 offset0:44 offset1:46
	v_exp_f32_e32 v54, v54
	v_exp_f32_e32 v55, v55
	v_add_f32_e32 v232, v232, v52
	v_add_f32_e32 v233, v233, v53
	v_cvt_pk_bf16_f32 v66, v52, v53
	v_add_f32_e32 v232, v232, v54
	v_add_f32_e32 v233, v233, v55
	v_cvt_pk_bf16_f32 v67, v54, v55
	s_waitcnt lgkmcnt(7)
	v_mfma_f32_32x32x16_bf16 v[32:47], v[208:211], v[88:91], v[32:47]
	ds_read_b128 v[208:211], v72 offset:13888
	v_exp_f32_e32 v56, v56
	v_exp_f32_e32 v57, v57
	s_waitcnt lgkmcnt(7)
	v_mfma_f32_32x32x16_bf16 v[32:47], v[212:215], v[92:95], v[32:47]
	ds_read_b128 v[212:215], v72 offset:13920
	v_exp_f32_e32 v58, v58
	v_exp_f32_e32 v59, v59
	v_add_f32_e32 v232, v232, v56
	v_add_f32_e32 v233, v233, v57
	v_cvt_pk_bf16_f32 v68, v56, v57
	s_waitcnt lgkmcnt(7)
; #define LAS __attribute__((address_space(3)))
; #define MFMA32(a, b, c) __builtin_amdgcn_mfma_f32_32x32x16_bf16((a), (b), (c), 0, 0, 0)
; __device__ __forceinline__ float ex2(float x) { return __builtin_amdgcn_exp2f(x); }
; template <int MODE>
; __device__ __forceinline__ void attn_tile(const LAS unsigned char* Kb, const LAS unsigned char* Vb, const bf16x8_t (&qf)[4], f32x16 (&oacc)[2], float& l_run,
;                                           int r, int h, int dlt0, int dlt1, bool hiw) {
;     const unsigned ulim = (MODE == 0) ? 0x80000000u : 512u;
;     float ls = 0.f;
; #pragma unroll
;     for (int mt = 0; mt < 4; ++mt) {
;         if (mt == 0) { if (hiw) __builtin_amdgcn_s_setprio(1); else __builtin_amdgcn_s_setprio(0); }
;         if (mt == 2) { if (hiw) __builtin_amdgcn_s_setprio(0); else __builtin_amdgcn_s_setprio(1); }
;         const int dl = mt < 2 ? dlt0 : dlt1;
;         f32x16 sacc = zero16();
; #pragma unroll
;         for (int ks = 0; ks < 4; ++ks) { const bf16x8_t ka = *(const LAS bf16x8_t*)(Kb + (32 * mt + r) * A_KSTR + 32 * ks + 16 * h); sacc = MFMA32(ka, qf[ks], sacc); }
; #pragma unroll
;         for (int i = 0; i < 16; ++i) {
;             float p;
;             if (MODE == 2) p = ex2(sacc[i]);
;             else if (MODE == 3) p = ex2(sacc[i] + __int_as_float(dl));
;             else { const int ci = 32 * mt + (i & 3) + 8 * (i >> 2); p = ((unsigned)(dl - ci) < ulim) ? ex2(sacc[i]) : 0.f; }
;             sacc[i] = p; ls += p;
;         }
; #pragma unroll
;         for (int s = 0; s < 2; ++s) {
;             const bf16x8_t pf = pack8(sacc, 8 * s);
; #pragma unroll
;             for (int dt = 0; dt < 2; ++dt) {
;                 const LAS unsigned char* vp = Vb + (32 * dt + r) * A_CVSTR + (32 * mt + 16 * s + 4 * h) * 2;
;                 const s16x4_t lo = *(const LAS s16x4_t*)vp, hi = *(const LAS s16x4_t*)(vp + 16);
;                 oacc[dt] = MFMA32(__builtin_shufflevector(lo, hi, 0, 1, 2, 3, 4, 5, 6, 7), pf, oacc[dt]);
;             }
;         }
;     }
;     l_run += ls;
	v_mfma_f32_32x32x16_bf16 v[0:15], v[216:219], v[64:67], v[0:15]
	ds_read2_b64 v[216:219], v73 offset0:16 offset1:18
	v_exp_f32_e32 v60, v60
	v_exp_f32_e32 v61, v61
	v_add_f32_e32 v232, v232, v58
	v_add_f32_e32 v233, v233, v59
	v_cvt_pk_bf16_f32 v69, v58, v59
	s_waitcnt lgkmcnt(7)
	v_mfma_f32_32x32x16_bf16 v[16:31], v[220:223], v[64:67], v[16:31]
	ds_read2_b64 v[220:223], v74 offset0:48 offset1:50
	v_exp_f32_e32 v62, v62
	v_exp_f32_e32 v63, v63
	v_add_f32_e32 v232, v232, v60
	v_add_f32_e32 v233, v233, v61
	v_cvt_pk_bf16_f32 v70, v60, v61
	v_add_f32_e32 v232, v232, v62
	v_add_f32_e32 v233, v233, v63
	v_cvt_pk_bf16_f32 v71, v62, v63
	s_waitcnt lgkmcnt(7)
	v_mfma_f32_32x32x16_bf16 v[48:63], v[200:203], v[80:83], 0
	v_exp_f32_e32 v32, v32
	v_exp_f32_e32 v33, v33
	s_waitcnt lgkmcnt(6)
	v_mfma_f32_32x32x16_bf16 v[48:63], v[204:207], v[84:87], v[48:63]
	v_exp_f32_e32 v34, v34
	v_exp_f32_e32 v35, v35
	v_add_f32_e32 v232, v232, v32
	v_add_f32_e32 v233, v233, v33
	v_cvt_pk_bf16_f32 v64, v32, v33
	s_waitcnt lgkmcnt(5)
	v_mfma_f32_32x32x16_bf16 v[0:15], v[224:227], v[68:71], v[0:15]
	ds_read2_b64 v[224:227], v73 offset0:20 offset1:22
	v_exp_f32_e32 v36, v36
	v_exp_f32_e32 v37, v37
	v_add_f32_e32 v232, v232, v34
	v_add_f32_e32 v233, v233, v35
	v_cvt_pk_bf16_f32 v65, v34, v35
	s_waitcnt lgkmcnt(5)
	v_mfma_f32_32x32x16_bf16 v[16:31], v[228:231], v[68:71], v[16:31]
	ds_read2_b64 v[228:231], v74 offset0:52 offset1:54
	v_exp_f32_e32 v38, v38
	v_exp_f32_e32 v39, v39
	v_add_f32_e32 v232, v232, v36
	v_add_f32_e32 v233, v233, v37
	v_cvt_pk_bf16_f32 v66, v36, v37
	v_add_f32_e32 v232, v232, v38
	v_add_f32_e32 v233, v233, v39
	v_cvt_pk_bf16_f32 v67, v38, v39
	s_waitcnt lgkmcnt(5)
	v_mfma_f32_32x32x16_bf16 v[48:63], v[208:211], v[88:91], v[48:63]
	v_exp_f32_e32 v40, v40
	v_exp_f32_e32 v41, v41
	s_waitcnt lgkmcnt(4)
	v_mfma_f32_32x32x16_bf16 v[48:63], v[212:215], v[92:95], v[48:63]
	v_exp_f32_e32 v42, v42
	v_exp_f32_e32 v43, v43
	v_add_f32_e32 v232, v232, v40
	v_add_f32_e32 v233, v233, v41
	v_cvt_pk_bf16_f32 v68, v40, v41
	s_waitcnt lgkmcnt(3)
	v_mfma_f32_32x32x16_bf16 v[0:15], v[216:219], v[64:67], v[0:15]
	ds_read2_b64 v[216:219], v73 offset0:24 offset1:26
	v_exp_f32_e32 v44, v44
	v_exp_f32_e32 v45, v45
	v_add_f32_e32 v232, v232, v42
	v_add_f32_e32 v233, v233, v43
	v_cvt_pk_bf16_f32 v69, v42, v43
	s_waitcnt lgkmcnt(3)
	v_mfma_f32_32x32x16_bf16 v[16:31], v[220:223], v[64:67], v[16:31]
	ds_read2_b64 v[220:223], v74 offset0:56 offset1:58
	v_exp_f32_e32 v46, v46
	v_exp_f32_e32 v47, v47
	v_add_f32_e32 v232, v232, v44
	v_add_f32_e32 v233, v233, v45
	v_cvt_pk_bf16_f32 v70, v44, v45
	v_add_f32_e32 v232, v232, v46
	v_add_f32_e32 v233, v233, v47
	v_cvt_pk_bf16_f32 v71, v46, v47
	v_exp_f32_e32 v48, v48
	v_exp_f32_e32 v49, v49
	v_exp_f32_e32 v50, v50
	v_exp_f32_e32 v51, v51
	v_add_f32_e32 v232, v232, v48
	v_add_f32_e32 v233, v233, v49
	v_cvt_pk_bf16_f32 v64, v48, v49
	s_waitcnt lgkmcnt(3)
	v_mfma_f32_32x32x16_bf16 v[0:15], v[224:227], v[68:71], v[0:15]
	ds_read2_b64 v[224:227], v73 offset0:28 offset1:30
	v_exp_f32_e32 v52, v52
	v_exp_f32_e32 v53, v53
	v_add_f32_e32 v232, v232, v50
	v_add_f32_e32 v233, v233, v51
	v_cvt_pk_bf16_f32 v65, v50, v51
	s_waitcnt lgkmcnt(3)
	v_mfma_f32_32x32x16_bf16 v[16:31], v[228:231], v[68:71], v[16:31]
	ds_read2_b64 v[228:231], v74 offset0:60 offset1:62
	v_exp_f32_e32 v54, v54
	v_exp_f32_e32 v55, v55
	v_add_f32_e32 v232, v232, v52
	v_add_f32_e32 v233, v233, v53
	v_cvt_pk_bf16_f32 v66, v52, v53
	v_add_f32_e32 v232, v232, v54
	v_add_f32_e32 v233, v233, v55
	v_cvt_pk_bf16_f32 v67, v54, v55
	v_exp_f32_e32 v56, v56
	v_exp_f32_e32 v57, v57
	v_exp_f32_e32 v58, v58
	v_exp_f32_e32 v59, v59
	v_add_f32_e32 v232, v232, v56
	v_add_f32_e32 v233, v233, v57
	v_cvt_pk_bf16_f32 v68, v56, v57
	s_waitcnt lgkmcnt(3)
	v_mfma_f32_32x32x16_bf16 v[0:15], v[216:219], v[64:67], v[0:15]
	v_exp_f32_e32 v60, v60
	v_exp_f32_e32 v61, v61
	v_add_f32_e32 v232, v232, v58
	v_add_f32_e32 v233, v233, v59
	v_cvt_pk_bf16_f32 v69, v58, v59
	s_waitcnt lgkmcnt(2)
	v_mfma_f32_32x32x16_bf16 v[16:31], v[220:223], v[64:67], v[16:31]
	v_exp_f32_e32 v62, v62
	v_exp_f32_e32 v63, v63
	v_add_f32_e32 v232, v232, v60
	v_add_f32_e32 v233, v233, v61
	v_cvt_pk_bf16_f32 v70, v60, v61
	v_add_f32_e32 v232, v232, v62
	v_add_f32_e32 v233, v233, v63
	v_cvt_pk_bf16_f32 v71, v62, v63
	s_nop 1
	s_waitcnt lgkmcnt(1)
	v_mfma_f32_32x32x16_bf16 v[0:15], v[224:227], v[68:71], v[0:15]
	s_waitcnt lgkmcnt(0)
	v_mfma_f32_32x32x16_bf16 v[16:31], v[228:231], v[68:71], v[16:31]
	v_add_f32_e32 v232, v232, v233
	v_add_f32_e32 v112, v112, v232
	s_branch .Lt1_join
; #define LAS __attribute__((address_space(3)))
; #define MFMA32(a, b, c) __builtin_amdgcn_mfma_f32_32x32x16_bf16((a), (b), (c), 0, 0, 0)
; __device__ __forceinline__ float ex2(float x) { return __builtin_amdgcn_exp2f(x); }
; template <int MODE>
; __device__ __forceinline__ void attn_tile(const LAS unsigned char* Kb, const LAS unsigned char* Vb, const bf16x8_t (&qf)[4], f32x16 (&oacc)[2], float& l_run,
;                                           int r, int h, int dlt0, int dlt1, bool hiw) {
;     const unsigned ulim = (MODE == 0) ? 0x80000000u : 512u;
;     float ls = 0.f;
; #pragma unroll
;     for (int mt = 0; mt < 4; ++mt) {
;         if (mt == 0) { if (hiw) __builtin_amdgcn_s_setprio(1); else __builtin_amdgcn_s_setprio(0); }
;         if (mt == 2) { if (hiw) __builtin_amdgcn_s_setprio(0); else __builtin_amdgcn_s_setprio(1); }
;         const int dl = mt < 2 ? dlt0 : dlt1;
;         f32x16 sacc = zero16();
; #pragma unroll
;         for (int ks = 0; ks < 4; ++ks) { const bf16x8_t ka = *(const LAS bf16x8_t*)(Kb + (32 * mt + r) * A_KSTR + 32 * ks + 16 * h); sacc = MFMA32(ka, qf[ks], sacc); }
; #pragma unroll
;         for (int i = 0; i < 16; ++i) {
;             float p;
;             if (MODE == 2) p = ex2(sacc[i]);
;             else if (MODE == 3) p = ex2(sacc[i] + __int_as_float(dl));
;             else { const int ci = 32 * mt + (i & 3) + 8 * (i >> 2); p = ((unsigned)(dl - ci) < ulim) ? ex2(sacc[i]) : 0.f; }
;             sacc[i] = p; ls += p;
;         }
; #pragma unroll
;         for (int s = 0; s < 2; ++s) {
;             const bf16x8_t pf = pack8(sacc, 8 * s);
; #pragma unroll
;             for (int dt = 0; dt < 2; ++dt) {
;                 const LAS unsigned char* vp = Vb + (32 * dt + r) * A_CVSTR + (32 * mt + 16 * s + 4 * h) * 2;
;                 const s16x4_t lo = *(const LAS s16x4_t*)vp, hi = *(const LAS s16x4_t*)(vp + 16);
;                 oacc[dt] = MFMA32(__builtin_shufflevector(lo, hi, 0, 1, 2, 3, 4, 5, 6, 7), pf, oacc[dt]);
;             }
;         }
;     }
;     l_run += ls;
.Lt1_e1:
	ds_read_b128 v[200:203], v72 offset:4608
	ds_read_b128 v[204:207], v72 offset:4640
	ds_read_b128 v[208:211], v72 offset:4672
	ds_read_b128 v[212:215], v72 offset:4704
	ds_read2_b64 v[216:219], v73 offset0:8 offset1:10
	ds_read2_b64 v[220:223], v74 offset0:40 offset1:42
	ds_read2_b64 v[224:227], v73 offset0:12 offset1:14
	ds_read2_b64 v[228:231], v74 offset0:44 offset1:46
	s_waitcnt lgkmcnt(7)
	v_mfma_f32_32x32x16_bf16 v[32:47], v[200:203], v[80:83], 0
	ds_read_b128 v[200:203], v72 offset:9216
	s_waitcnt lgkmcnt(7)
	v_mfma_f32_32x32x16_bf16 v[32:47], v[204:207], v[84:87], v[32:47]
	ds_read_b128 v[204:207], v72 offset:9248
	s_waitcnt lgkmcnt(7)
	v_mfma_f32_32x32x16_bf16 v[32:47], v[208:211], v[88:91], v[32:47]
	ds_read_b128 v[208:211], v72 offset:9280
	s_waitcnt lgkmcnt(7)
	v_mfma_f32_32x32x16_bf16 v[32:47], v[212:215], v[92:95], v[32:47]
	ds_read_b128 v[212:215], v72 offset:9312
	s_nop 7
	s_nop 3
	s_waitcnt lgkmcnt(3)
	v_mfma_f32_32x32x16_bf16 v[48:63], v[200:203], v[80:83], 0
	ds_read_b128 v[200:203], v72 offset:13824
	v_cmp_le_i32_e64 s[0:1], 0, v250
	v_cmp_le_i32_e64 s[4:5], 1, v250
	v_exp_f32_e32 v32, v32
	v_exp_f32_e32 v33, v33
	s_waitcnt lgkmcnt(3)
	v_mfma_f32_32x32x16_bf16 v[48:63], v[204:207], v[84:87], v[48:63]
	ds_read_b128 v[204:207], v72 offset:13856
	v_cmp_le_i32_e64 s[6:7], 2, v250
	v_cmp_le_i32_e64 s[48:49], 3, v250
	v_exp_f32_e32 v34, v34
	v_exp_f32_e32 v35, v35
	v_cndmask_b32_e64 v32, v32, 0, s[0:1]
	v_cndmask_b32_e64 v33, v33, 0, s[4:5]
	v_mov_b32_e32 v232, v32
	v_mov_b32_e32 v233, v33
	v_cvt_pk_bf16_f32 v64, v32, v33
	v_cmp_le_i32_e64 s[0:1], 8, v250
	v_cmp_le_i32_e64 s[4:5], 9, v250
	v_exp_f32_e32 v36, v36
	v_exp_f32_e32 v37, v37
	v_cndmask_b32_e64 v34, v34, 0, s[6:7]
	v_cndmask_b32_e64 v35, v35, 0, s[48:49]
	v_add_f32_e32 v232, v232, v34
	v_add_f32_e32 v233, v233, v35
	v_cvt_pk_bf16_f32 v65, v34, v35
	v_cmp_le_i32_e64 s[6:7], 10, v250
	v_cmp_le_i32_e64 s[48:49], 11, v250
	v_exp_f32_e32 v38, v38
	v_exp_f32_e32 v39, v39
	v_cndmask_b32_e64 v36, v36, 0, s[0:1]
	v_cndmask_b32_e64 v37, v37, 0, s[4:5]
	v_add_f32_e32 v232, v232, v36
	v_add_f32_e32 v233, v233, v37
	v_cvt_pk_bf16_f32 v66, v36, v37
	v_cndmask_b32_e64 v38, v38, 0, s[6:7]
	v_cndmask_b32_e64 v39, v39, 0, s[48:49]
	v_add_f32_e32 v232, v232, v38
	v_add_f32_e32 v233, v233, v39
	v_cvt_pk_bf16_f32 v67, v38, v39
	s_waitcnt lgkmcnt(3)
	v_mfma_f32_32x32x16_bf16 v[48:63], v[208:211], v[88:91], v[48:63]
	ds_read_b128 v[208:211], v72 offset:13888
	v_cmp_le_i32_e64 s[0:1], 16, v250
	v_cmp_le_i32_e64 s[4:5], 17, v250
	v_exp_f32_e32 v40, v40
	v_exp_f32_e32 v41, v41
	s_waitcnt lgkmcnt(3)
	v_mfma_f32_32x32x16_bf16 v[48:63], v[212:215], v[92:95], v[48:63]
	ds_read_b128 v[212:215], v72 offset:13920
	v_cmp_le_i32_e64 s[6:7], 18, v250
	v_cmp_le_i32_e64 s[48:49], 19, v250
	v_exp_f32_e32 v42, v42
	v_exp_f32_e32 v43, v43
	v_cndmask_b32_e64 v40, v40, 0, s[0:1]
	v_cndmask_b32_e64 v41, v41, 0, s[4:5]
	v_add_f32_e32 v232, v232, v40
	v_add_f32_e32 v233, v233, v41
	v_cvt_pk_bf16_f32 v68, v40, v41
	v_mfma_f32_32x32x16_bf16 v[0:15], v[216:219], v[64:67], v[0:15]
	ds_read2_b64 v[216:219], v73 offset0:16 offset1:18
	v_cmp_le_i32_e64 s[0:1], 24, v250
	v_cmp_le_i32_e64 s[4:5], 25, v250
	v_exp_f32_e32 v44, v44
	v_exp_f32_e32 v45, v45
	v_cndmask_b32_e64 v42, v42, 0, s[6:7]
	v_cndmask_b32_e64 v43, v43, 0, s[48:49]
	v_add_f32_e32 v232, v232, v42
	v_add_f32_e32 v233, v233, v43
	v_cvt_pk_bf16_f32 v69, v42, v43
	v_mfma_f32_32x32x16_bf16 v[16:31], v[220:223], v[64:67], v[16:31]
	ds_read2_b64 v[220:223], v74 offset0:48 offset1:50
	v_cmp_le_i32_e64 s[6:7], 26, v250
	v_cmp_le_i32_e64 s[48:49], 27, v250
	v_exp_f32_e32 v46, v46
	v_exp_f32_e32 v47, v47
	v_cndmask_b32_e64 v44, v44, 0, s[0:1]
	v_cndmask_b32_e64 v45, v45, 0, s[4:5]
	v_add_f32_e32 v232, v232, v44
	v_add_f32_e32 v233, v233, v45
	v_cvt_pk_bf16_f32 v70, v44, v45
	v_cndmask_b32_e64 v46, v46, 0, s[6:7]
	v_cndmask_b32_e64 v47, v47, 0, s[48:49]
	v_add_f32_e32 v232, v232, v46
	v_add_f32_e32 v233, v233, v47
	v_cvt_pk_bf16_f32 v71, v46, v47
	s_waitcnt lgkmcnt(5)
	v_mfma_f32_32x32x16_bf16 v[32:47], v[200:203], v[80:83], 0
	v_exp_f32_e32 v48, v48
	v_exp_f32_e32 v49, v49
	s_waitcnt lgkmcnt(4)
	v_mfma_f32_32x32x16_bf16 v[32:47], v[204:207], v[84:87], v[32:47]
	v_exp_f32_e32 v50, v50
	v_exp_f32_e32 v51, v51
	v_add_f32_e32 v232, v232, v48
	v_add_f32_e32 v233, v233, v49
	v_cvt_pk_bf16_f32 v64, v48, v49
	v_mfma_f32_32x32x16_bf16 v[0:15], v[224:227], v[68:71], v[0:15]
	ds_read2_b64 v[224:227], v73 offset0:20 offset1:22
	v_exp_f32_e32 v52, v52
	v_exp_f32_e32 v53, v53
	v_add_f32_e32 v232, v232, v50
	v_add_f32_e32 v233, v233, v51
	v_cvt_pk_bf16_f32 v65, v50, v51
	v_mfma_f32_32x32x16_bf16 v[16:31], v[228:231], v[68:71], v[16:31]
	ds_read2_b64 v[228:231], v74 offset0:52 offset1:54
	v_exp_f32_e32 v54, v54
	v_exp_f32_e32 v55, v55
	v_add_f32_e32 v232, v232, v52
	v_add_f32_e32 v233, v233, v53
	v_cvt_pk_bf16_f32 v66, v52, v53
	v_add_f32_e32 v232, v232, v54
	v_add_f32_e32 v233, v233, v55
	v_cvt_pk_bf16_f32 v67, v54, v55
	s_waitcnt lgkmcnt(5)
	v_mfma_f32_32x32x16_bf16 v[32:47], v[208:211], v[88:91], v[32:47]
	v_exp_f32_e32 v56, v56
	v_exp_f32_e32 v57, v57
	s_waitcnt lgkmcnt(4)
	v_mfma_f32_32x32x16_bf16 v[32:47], v[212:215], v[92:95], v[32:47]
	v_exp_f32_e32 v58, v58
	v_exp_f32_e32 v59, v59
	v_add_f32_e32 v232, v232, v56
	v_add_f32_e32 v233, v233, v57
	v_cvt_pk_bf16_f32 v68, v56, v57
	s_waitcnt lgkmcnt(3)
	v_mfma_f32_32x32x16_bf16 v[0:15], v[216:219], v[64:67], v[0:15]
	ds_read2_b64 v[216:219], v73 offset0:24 offset1:26
	v_exp_f32_e32 v60, v60
	v_exp_f32_e32 v61, v61
	v_add_f32_e32 v232, v232, v58
	v_add_f32_e32 v233, v233, v59
	v_cvt_pk_bf16_f32 v69, v58, v59
	s_waitcnt lgkmcnt(3)
; #define LAS __attribute__((address_space(3)))
; #define MFMA32(a, b, c) __builtin_amdgcn_mfma_f32_32x32x16_bf16((a), (b), (c), 0, 0, 0)
; __device__ __forceinline__ float ex2(float x) { return __builtin_amdgcn_exp2f(x); }
; template <int MODE>
; __device__ __forceinline__ void attn_tile(const LAS unsigned char* Kb, const LAS unsigned char* Vb, const bf16x8_t (&qf)[4], f32x16 (&oacc)[2], float& l_run,
;                                           int r, int h, int dlt0, int dlt1, bool hiw) {
;     const unsigned ulim = (MODE == 0) ? 0x80000000u : 512u;
;     float ls = 0.f;
; #pragma unroll
;     for (int mt = 0; mt < 4; ++mt) {
;         if (mt == 0) { if (hiw) __builtin_amdgcn_s_setprio(1); else __builtin_amdgcn_s_setprio(0); }
;         if (mt == 2) { if (hiw) __builtin_amdgcn_s_setprio(0); else __builtin_amdgcn_s_setprio(1); }
;         const int dl = mt < 2 ? dlt0 : dlt1;
;         f32x16 sacc = zero16();
; #pragma unroll
;         for (int ks = 0; ks < 4; ++ks) { const bf16x8_t ka = *(const LAS bf16x8_t*)(Kb + (32 * mt + r) * A_KSTR + 32 * ks + 16 * h); sacc = MFMA32(ka, qf[ks], sacc); }
; #pragma unroll
;         for (int i = 0; i < 16; ++i) {
;             float p;
;             if (MODE == 2) p = ex2(sacc[i]);
;             else if (MODE == 3) p = ex2(sacc[i] + __int_as_float(dl));
;             else { const int ci = 32 * mt + (i & 3) + 8 * (i >> 2); p = ((unsigned)(dl - ci) < ulim) ? ex2(sacc[i]) : 0.f; }
;             sacc[i] = p; ls += p;
;         }
; #pragma unroll
;         for (int s = 0; s < 2; ++s) {
;             const bf16x8_t pf = pack8(sacc, 8 * s);
; #pragma unroll
;             for (int dt = 0; dt < 2; ++dt) {
;                 const LAS unsigned char* vp = Vb + (32 * dt + r) * A_CVSTR + (32 * mt + 16 * s + 4 * h) * 2;
;                 const s16x4_t lo = *(const LAS s16x4_t*)vp, hi = *(const LAS s16x4_t*)(vp + 16);
;                 oacc[dt] = MFMA32(__builtin_shufflevector(lo, hi, 0, 1, 2, 3, 4, 5, 6, 7), pf, oacc[dt]);
;             }
;         }
;     }
;     l_run += ls;
	v_mfma_f32_32x32x16_bf16 v[16:31], v[220:223], v[64:67], v[16:31]
	ds_read2_b64 v[220:223], v74 offset0:56 offset1:58
	v_exp_f32_e32 v62, v62
	v_exp_f32_e32 v63, v63
	v_add_f32_e32 v232, v232, v60
	v_add_f32_e32 v233, v233, v61
	v_cvt_pk_bf16_f32 v70, v60, v61
	v_add_f32_e32 v232, v232, v62
	v_add_f32_e32 v233, v233, v63
	v_cvt_pk_bf16_f32 v71, v62, v63
	v_exp_f32_e32 v32, v32
	v_exp_f32_e32 v33, v33
	v_exp_f32_e32 v34, v34
	v_exp_f32_e32 v35, v35
	v_add_f32_e32 v232, v232, v32
	v_add_f32_e32 v233, v233, v33
	v_cvt_pk_bf16_f32 v64, v32, v33
	s_waitcnt lgkmcnt(3)
	v_mfma_f32_32x32x16_bf16 v[0:15], v[224:227], v[68:71], v[0:15]
	ds_read2_b64 v[224:227], v73 offset0:28 offset1:30
	v_exp_f32_e32 v36, v36
	v_exp_f32_e32 v37, v37
	v_add_f32_e32 v232, v232, v34
	v_add_f32_e32 v233, v233, v35
	v_cvt_pk_bf16_f32 v65, v34, v35
	s_waitcnt lgkmcnt(3)
	v_mfma_f32_32x32x16_bf16 v[16:31], v[228:231], v[68:71], v[16:31]
	ds_read2_b64 v[228:231], v74 offset0:60 offset1:62
	v_exp_f32_e32 v38, v38
	v_exp_f32_e32 v39, v39
	v_add_f32_e32 v232, v232, v36
	v_add_f32_e32 v233, v233, v37
	v_cvt_pk_bf16_f32 v66, v36, v37
	v_add_f32_e32 v232, v232, v38
	v_add_f32_e32 v233, v233, v39
	v_cvt_pk_bf16_f32 v67, v38, v39
	v_exp_f32_e32 v40, v40
	v_exp_f32_e32 v41, v41
	v_exp_f32_e32 v42, v42
	v_exp_f32_e32 v43, v43
	v_add_f32_e32 v232, v232, v40
	v_add_f32_e32 v233, v233, v41
	v_cvt_pk_bf16_f32 v68, v40, v41
	s_waitcnt lgkmcnt(3)
	v_mfma_f32_32x32x16_bf16 v[0:15], v[216:219], v[64:67], v[0:15]
	v_exp_f32_e32 v44, v44
	v_exp_f32_e32 v45, v45
	v_add_f32_e32 v232, v232, v42
	v_add_f32_e32 v233, v233, v43
	v_cvt_pk_bf16_f32 v69, v42, v43
	s_waitcnt lgkmcnt(2)
	v_mfma_f32_32x32x16_bf16 v[16:31], v[220:223], v[64:67], v[16:31]
	v_exp_f32_e32 v46, v46
	v_exp_f32_e32 v47, v47
	v_add_f32_e32 v232, v232, v44
	v_add_f32_e32 v233, v233, v45
	v_cvt_pk_bf16_f32 v70, v44, v45
	v_add_f32_e32 v232, v232, v46
	v_add_f32_e32 v233, v233, v47
	v_cvt_pk_bf16_f32 v71, v46, v47
	s_nop 1
	s_waitcnt lgkmcnt(1)
	v_mfma_f32_32x32x16_bf16 v[0:15], v[224:227], v[68:71], v[0:15]
	s_waitcnt lgkmcnt(0)
	v_mfma_f32_32x32x16_bf16 v[16:31], v[228:231], v[68:71], v[16:31]
	v_add_f32_e32 v232, v232, v233
	v_add_f32_e32 v112, v112, v232
	s_branch .Lt1_join
; #define LAS __attribute__((address_space(3)))
; #define MFMA32(a, b, c) __builtin_amdgcn_mfma_f32_32x32x16_bf16((a), (b), (c), 0, 0, 0)
; __device__ __forceinline__ float ex2(float x) { return __builtin_amdgcn_exp2f(x); }
; template <int MODE>
; __device__ __forceinline__ void attn_tile(const LAS unsigned char* Kb, const LAS unsigned char* Vb, const bf16x8_t (&qf)[4], f32x16 (&oacc)[2], float& l_run,
;                                           int r, int h, int dlt0, int dlt1, bool hiw) {
;     const unsigned ulim = (MODE == 0) ? 0x80000000u : 512u;
;     float ls = 0.f;
; #pragma unroll
;     for (int mt = 0; mt < 4; ++mt) {
;         if (mt == 0) { if (hiw) __builtin_amdgcn_s_setprio(1); else __builtin_amdgcn_s_setprio(0); }
;         if (mt == 2) { if (hiw) __builtin_amdgcn_s_setprio(0); else __builtin_amdgcn_s_setprio(1); }
;         const int dl = mt < 2 ? dlt0 : dlt1;
;         f32x16 sacc = zero16();
; #pragma unroll
;         for (int ks = 0; ks < 4; ++ks) { const bf16x8_t ka = *(const LAS bf16x8_t*)(Kb + (32 * mt + r) * A_KSTR + 32 * ks + 16 * h); sacc = MFMA32(ka, qf[ks], sacc); }
; #pragma unroll
;         for (int i = 0; i < 16; ++i) {
;             float p;
;             if (MODE == 2) p = ex2(sacc[i]);
;             else if (MODE == 3) p = ex2(sacc[i] + __int_as_float(dl));
;             else { const int ci = 32 * mt + (i & 3) + 8 * (i >> 2); p = ((unsigned)(dl - ci) < ulim) ? ex2(sacc[i]) : 0.f; }
;             sacc[i] = p; ls += p;
;         }
; #pragma unroll
;         for (int s = 0; s < 2; ++s) {
;             const bf16x8_t pf = pack8(sacc, 8 * s);
; #pragma unroll
;             for (int dt = 0; dt < 2; ++dt) {
;                 const LAS unsigned char* vp = Vb + (32 * dt + r) * A_CVSTR + (32 * mt + 16 * s + 4 * h) * 2;
;                 const s16x4_t lo = *(const LAS s16x4_t*)vp, hi = *(const LAS s16x4_t*)(vp + 16);
;                 oacc[dt] = MFMA32(__builtin_shufflevector(lo, hi, 0, 1, 2, 3, 4, 5, 6, 7), pf, oacc[dt]);
;             }
;         }
;     }
;     l_run += ls;
.Lt1_e2:
	ds_read_b128 v[200:203], v72 offset:9216
	ds_read_b128 v[204:207], v72 offset:9248
	ds_read_b128 v[208:211], v72 offset:9280
	ds_read_b128 v[212:215], v72 offset:9312
	ds_read2_b64 v[216:219], v73 offset0:16 offset1:18
	ds_read2_b64 v[220:223], v74 offset0:48 offset1:50
	ds_read2_b64 v[224:227], v73 offset0:20 offset1:22
	ds_read2_b64 v[228:231], v74 offset0:52 offset1:54
	s_waitcnt lgkmcnt(7)
	v_mfma_f32_32x32x16_bf16 v[32:47], v[200:203], v[80:83], 0
	ds_read_b128 v[200:203], v72 offset:13824
	s_waitcnt lgkmcnt(7)
	v_mfma_f32_32x32x16_bf16 v[32:47], v[204:207], v[84:87], v[32:47]
	ds_read_b128 v[204:207], v72 offset:13856
	s_waitcnt lgkmcnt(7)
	v_mfma_f32_32x32x16_bf16 v[32:47], v[208:211], v[88:91], v[32:47]
	ds_read_b128 v[208:211], v72 offset:13888
	s_waitcnt lgkmcnt(7)
	v_mfma_f32_32x32x16_bf16 v[32:47], v[212:215], v[92:95], v[32:47]
	ds_read_b128 v[212:215], v72 offset:13920
	s_nop 7
	s_nop 3
	s_waitcnt lgkmcnt(3)
	v_mfma_f32_32x32x16_bf16 v[48:63], v[200:203], v[80:83], 0
	v_cmp_le_i32_e64 s[0:1], 0, v250
	v_cmp_le_i32_e64 s[4:5], 1, v250
	v_exp_f32_e32 v32, v32
	v_exp_f32_e32 v33, v33
	s_waitcnt lgkmcnt(2)
	v_mfma_f32_32x32x16_bf16 v[48:63], v[204:207], v[84:87], v[48:63]
	v_cmp_le_i32_e64 s[6:7], 2, v250
	v_cmp_le_i32_e64 s[48:49], 3, v250
	v_exp_f32_e32 v34, v34
	v_exp_f32_e32 v35, v35
	v_cndmask_b32_e64 v32, v32, 0, s[0:1]
	v_cndmask_b32_e64 v33, v33, 0, s[4:5]
	v_mov_b32_e32 v232, v32
	v_mov_b32_e32 v233, v33
	v_cvt_pk_bf16_f32 v64, v32, v33
	v_cmp_le_i32_e64 s[0:1], 8, v250
	v_cmp_le_i32_e64 s[4:5], 9, v250
	v_exp_f32_e32 v36, v36
	v_exp_f32_e32 v37, v37
	v_cndmask_b32_e64 v34, v34, 0, s[6:7]
	v_cndmask_b32_e64 v35, v35, 0, s[48:49]
	v_add_f32_e32 v232, v232, v34
	v_add_f32_e32 v233, v233, v35
	v_cvt_pk_bf16_f32 v65, v34, v35
	v_cmp_le_i32_e64 s[6:7], 10, v250
	v_cmp_le_i32_e64 s[48:49], 11, v250
	v_exp_f32_e32 v38, v38
	v_exp_f32_e32 v39, v39
	v_cndmask_b32_e64 v36, v36, 0, s[0:1]
	v_cndmask_b32_e64 v37, v37, 0, s[4:5]
	v_add_f32_e32 v232, v232, v36
	v_add_f32_e32 v233, v233, v37
	v_cvt_pk_bf16_f32 v66, v36, v37
	v_cndmask_b32_e64 v38, v38, 0, s[6:7]
	v_cndmask_b32_e64 v39, v39, 0, s[48:49]
	v_add_f32_e32 v232, v232, v38
	v_add_f32_e32 v233, v233, v39
	v_cvt_pk_bf16_f32 v67, v38, v39
	s_waitcnt lgkmcnt(1)
	v_mfma_f32_32x32x16_bf16 v[48:63], v[208:211], v[88:91], v[48:63]
	v_cmp_le_i32_e64 s[0:1], 16, v250
	v_cmp_le_i32_e64 s[4:5], 17, v250
	v_exp_f32_e32 v40, v40
	v_exp_f32_e32 v41, v41
	s_waitcnt lgkmcnt(0)
	v_mfma_f32_32x32x16_bf16 v[48:63], v[212:215], v[92:95], v[48:63]
	v_cmp_le_i32_e64 s[6:7], 18, v250
	v_cmp_le_i32_e64 s[48:49], 19, v250
	v_exp_f32_e32 v42, v42
	v_exp_f32_e32 v43, v43
	v_cndmask_b32_e64 v40, v40, 0, s[0:1]
	v_cndmask_b32_e64 v41, v41, 0, s[4:5]
	v_add_f32_e32 v232, v232, v40
	v_add_f32_e32 v233, v233, v41
	v_cvt_pk_bf16_f32 v68, v40, v41
	v_mfma_f32_32x32x16_bf16 v[0:15], v[216:219], v[64:67], v[0:15]
	ds_read2_b64 v[216:219], v73 offset0:24 offset1:26
	v_cmp_le_i32_e64 s[0:1], 24, v250
	v_cmp_le_i32_e64 s[4:5], 25, v250
	v_exp_f32_e32 v44, v44
	v_exp_f32_e32 v45, v45
	v_cndmask_b32_e64 v42, v42, 0, s[6:7]
	v_cndmask_b32_e64 v43, v43, 0, s[48:49]
	v_add_f32_e32 v232, v232, v42
	v_add_f32_e32 v233, v233, v43
	v_cvt_pk_bf16_f32 v69, v42, v43
	v_mfma_f32_32x32x16_bf16 v[16:31], v[220:223], v[64:67], v[16:31]
	ds_read2_b64 v[220:223], v74 offset0:56 offset1:58
	v_cmp_le_i32_e64 s[6:7], 26, v250
	v_cmp_le_i32_e64 s[48:49], 27, v250
	v_exp_f32_e32 v46, v46
	v_exp_f32_e32 v47, v47
	v_cndmask_b32_e64 v44, v44, 0, s[0:1]
	v_cndmask_b32_e64 v45, v45, 0, s[4:5]
	v_add_f32_e32 v232, v232, v44
	v_add_f32_e32 v233, v233, v45
	v_cvt_pk_bf16_f32 v70, v44, v45
	v_cndmask_b32_e64 v46, v46, 0, s[6:7]
	v_cndmask_b32_e64 v47, v47, 0, s[48:49]
	v_add_f32_e32 v232, v232, v46
	v_add_f32_e32 v233, v233, v47
	v_cvt_pk_bf16_f32 v71, v46, v47
	v_exp_f32_e32 v48, v48
	v_exp_f32_e32 v49, v49
	v_exp_f32_e32 v50, v50
	v_exp_f32_e32 v51, v51
	v_add_f32_e32 v232, v232, v48
	v_add_f32_e32 v233, v233, v49
	v_cvt_pk_bf16_f32 v64, v48, v49
	v_mfma_f32_32x32x16_bf16 v[0:15], v[224:227], v[68:71], v[0:15]
	ds_read2_b64 v[224:227], v73 offset0:28 offset1:30
	v_exp_f32_e32 v52, v52
	v_exp_f32_e32 v53, v53
	v_add_f32_e32 v232, v232, v50
	v_add_f32_e32 v233, v233, v51
	v_cvt_pk_bf16_f32 v65, v50, v51
	v_mfma_f32_32x32x16_bf16 v[16:31], v[228:231], v[68:71], v[16:31]
	ds_read2_b64 v[228:231], v74 offset0:60 offset1:62
	v_exp_f32_e32 v54, v54
	v_exp_f32_e32 v55, v55
	v_add_f32_e32 v232, v232, v52
	v_add_f32_e32 v233, v233, v53
	v_cvt_pk_bf16_f32 v66, v52, v53
	v_add_f32_e32 v232, v232, v54
	v_add_f32_e32 v233, v233, v55
	v_cvt_pk_bf16_f32 v67, v54, v55
	v_exp_f32_e32 v56, v56
	v_exp_f32_e32 v57, v57
	v_exp_f32_e32 v58, v58
	v_exp_f32_e32 v59, v59
	v_add_f32_e32 v232, v232, v56
	v_add_f32_e32 v233, v233, v57
	v_cvt_pk_bf16_f32 v68, v56, v57
	s_waitcnt lgkmcnt(3)
	v_mfma_f32_32x32x16_bf16 v[0:15], v[216:219], v[64:67], v[0:15]
	v_exp_f32_e32 v60, v60
	v_exp_f32_e32 v61, v61
	v_add_f32_e32 v232, v232, v58
	v_add_f32_e32 v233, v233, v59
	v_cvt_pk_bf16_f32 v69, v58, v59
	s_waitcnt lgkmcnt(2)
	v_mfma_f32_32x32x16_bf16 v[16:31], v[220:223], v[64:67], v[16:31]
	v_exp_f32_e32 v62, v62
	v_exp_f32_e32 v63, v63
	v_add_f32_e32 v232, v232, v60
	v_add_f32_e32 v233, v233, v61
	v_cvt_pk_bf16_f32 v70, v60, v61
	v_add_f32_e32 v232, v232, v62
	v_add_f32_e32 v233, v233, v63
	v_cvt_pk_bf16_f32 v71, v62, v63
	s_nop 1
	s_waitcnt lgkmcnt(1)
	v_mfma_f32_32x32x16_bf16 v[0:15], v[224:227], v[68:71], v[0:15]
	s_waitcnt lgkmcnt(0)
	v_mfma_f32_32x32x16_bf16 v[16:31], v[228:231], v[68:71], v[16:31]
	v_add_f32_e32 v232, v232, v233
	v_add_f32_e32 v112, v112, v232
	s_branch .Lt1_join

; #define LAS __attribute__((address_space(3)))
; #define MFMA32(a, b, c) __builtin_amdgcn_mfma_f32_32x32x16_bf16((a), (b), (c), 0, 0, 0)
; __device__ __forceinline__ void phase4_attn(const Args& a, LAS unsigned char* lds) {
;     ...
;                 const float g0 = gates[(size_t)tok * 24 + head * 3 + 0], g1 = gates[(size_t)tok * 24 + head * 3 + 1], g2 = gates[(size_t)tok * 24 + head * 3 + 2];
;                 __syncthreads();
;                 {
;                     const bf16_t* kc = kcmp + (size_t)bh * 128 * 64; const bf16_t* vc = vcmpT + (size_t)bh * 64 * 128;
; #pragma unroll
;                     for (int i = 0; i < 2; ++i) { const int c = tid + 512 * i;
;                         const u32x4 kv = *(const u32x4*)(kc + (size_t)c * 8);
;                         *(LAS u32x4*)(lds + A_CMPK + (c >> 3) * A_KSTR + (c & 7) * 16) = kv;
;                         const u32x4 vv = *(const u32x4*)(vc + (size_t)c * 8);
;                         LAS unsigned char* vp = lds + A_CMPV + (c >> 4) * A_CVSTR + (c & 15) * 16;
;                         *(LAS u32x2*)vp = (u32x2){vv.x, vv.y}; *(LAS u32x2*)(vp + 8) = (u32x2){vv.z, vv.w}; }
;                 }
;                 bf16x8_t qf[4];
; #pragma unroll
;                 for (int ks = 0; ks < 4; ++ks) qf[ks] = __builtin_nontemporal_load((const bf16x8_t*)(qn + (size_t)tok * 512 + head * 64 + 16 * ks + 8 * h));
;                 __syncthreads();
;                 {
;                     f32x16 s4[4];
; #pragma unroll
;                     for (int mt = 0; mt < 4; ++mt) { s4[mt] = zero16();
; #pragma unroll
;                         for (int ks = 0; ks < 4; ++ks) { const bf16x8_t ka = *(const LAS bf16x8_t*)(lds + A_CMPK + (32 * mt + r) * A_KSTR + 32 * ks + 16 * h); s4[mt] = MFMA32(ka, qf[ks], s4[mt]); } }
.LBB0_794:
	v_mov_b32_e32 v152, v184
	v_readlane_b32 s0, v254, 57
	s_waitcnt vmcnt(2)
	v_and_b32_e32 v100, 31, v152
	v_or_b32_e32 v98, s79, v100
	v_or_b32_e32 v194, s24, v98
	v_readlane_b32 s1, v254, 58
	v_or_b32_e32 v4, s39, v194
	v_ashrrev_i32_e32 v153, 31, v152
	v_mov_b64_e32 v[0:1], s[0:1]
	v_mad_i64_i32 v[0:1], s[0:1], v4, s83, v[0:1]
	global_load_dwordx3 v[112:114], v[0:1], off
	v_lshlrev_b32_e32 v0, 4, v152
	v_readlane_b32 s4, v254, 35
	v_and_b32_e32 v1, 0x70, v0
	v_and_b32_e32 v0, 0xf0, v0
	v_lshlrev_b64 v[10:11], 4, v[152:153]
	v_readlane_b32 s5, v254, 36
	v_add_u32_e32 v6, s85, v1
	v_add_u32_e32 v8, s86, v0
	v_lshl_add_u64 v[0:1], s[4:5], 0, v[10:11]
	s_nop 0
	s_barrier
	global_load_dwordx4 v[16:19], v[0:1], off
	v_add_u32_e32 v14, 0x200, v152
	v_ashrrev_i32_e32 v15, 31, v14
	v_lshlrev_b64 v[12:13], 4, v[14:15]
	v_lshl_add_u64 v[36:37], s[52:53], 0, v[10:11]
	global_load_dwordx4 v[20:23], v[36:37], off
	v_lshl_add_u64 v[36:37], s[4:5], 0, v[12:13]
	global_load_dwordx4 v[24:27], v[36:37], off
	v_lshl_add_u64 v[36:37], s[52:53], 0, v[12:13]
	global_load_dwordx4 v[28:31], v[36:37], off
	v_readlane_b32 s0, v254, 59
	v_readlane_b32 s1, v254, 60
	v_ashrrev_i32_e32 v5, 31, v4
	v_bfe_u32 v101, v152, 5, 1
	v_lshlrev_b64 v[72:73], 10, v[4:5]
	v_lshlrev_b32_e32 v118, 4, v101
	v_lshl_add_u64 v[0:1], s[0:1], 0, v[72:73]
	v_lshl_add_u64 v[4:5], v[0:1], 0, v[118:119]
	global_load_dwordx4 v[0:3], v[4:5], off nt
	global_load_dwordx4 v[74:77], v[4:5], off offset:32 nt
	global_load_dwordx4 v[68:71], v[4:5], off offset:64 nt
	global_load_dwordx4 v[64:67], v[4:5], off offset:96 nt
	v_ashrrev_i32_e32 v99, 3, v152
	v_ashrrev_i32_e32 v7, 4, v152
	v_mul_u32_u24_e32 v153, 0x90, v100
	v_add3_u32 v82, s85, v118, v153
	v_mad_u32_u24 v32, v99, s87, v6
	v_mad_u32_u24 v33, v7, s94, v8
	v_add_u32_e32 v35, 0x2100, v33
	s_waitcnt vmcnt(7)
	ds_write_b128 v32, v[16:19]
	s_waitcnt vmcnt(6)
	ds_write2_b64 v33, v[20:21], v[22:23] offset1:1
	s_waitcnt vmcnt(5)
	ds_write_b128 v32, v[24:27] offset:9216
	s_waitcnt vmcnt(4)
	ds_write2_b64 v35, v[28:29], v[30:31] offset1:1
	s_waitcnt lgkmcnt(0)
	s_barrier
	ds_read_b128 v[4:7], v82
	ds_read_b128 v[8:11], v82 offset:32
	s_waitcnt vmcnt(3) lgkmcnt(1)
	v_mfma_f32_32x32x16_bf16 v[48:63], v[4:7], v[0:3], 0
	ds_read_b128 v[4:7], v82 offset:64
	ds_read_b128 v[78:81], v82 offset:13856
	s_waitcnt vmcnt(2) lgkmcnt(2)
	v_mfma_f32_32x32x16_bf16 v[48:63], v[8:11], v[74:77], v[48:63]
	s_waitcnt vmcnt(1) lgkmcnt(1)
	v_mfma_f32_32x32x16_bf16 v[48:63], v[4:7], v[68:71], v[48:63]
	ds_read_b128 v[4:7], v82 offset:96
	s_waitcnt vmcnt(0) lgkmcnt(0)
	v_mfma_f32_32x32x16_bf16 v[48:63], v[4:7], v[64:67], v[48:63]
	ds_read_b128 v[4:7], v82 offset:4608
	s_waitcnt lgkmcnt(0)
	v_mfma_f32_32x32x16_bf16 v[32:47], v[4:7], v[0:3], 0
	ds_read_b128 v[4:7], v82 offset:4640
	s_nop 7
	v_exp_f32_e32 v48, v48
	v_exp_f32_e32 v49, v49
	v_exp_f32_e32 v50, v50
	v_exp_f32_e32 v51, v51
	v_exp_f32_e32 v52, v52
	v_exp_f32_e32 v53, v53
	s_waitcnt lgkmcnt(0)
	v_mfma_f32_32x32x16_bf16 v[32:47], v[4:7], v[74:77], v[32:47]
	ds_read_b128 v[4:7], v82 offset:4672
	v_exp_f32_e32 v54, v54
	v_exp_f32_e32 v55, v55
	v_exp_f32_e32 v56, v56
	v_exp_f32_e32 v57, v57
	v_exp_f32_e32 v58, v58
	v_exp_f32_e32 v59, v59
	s_waitcnt lgkmcnt(0)
	v_mfma_f32_32x32x16_bf16 v[32:47], v[4:7], v[68:71], v[32:47]
	ds_read_b128 v[4:7], v82 offset:4704
	v_exp_f32_e32 v60, v60
	v_exp_f32_e32 v61, v61
	v_exp_f32_e32 v62, v62
	v_exp_f32_e32 v63, v63
	s_waitcnt lgkmcnt(0)
	v_mfma_f32_32x32x16_bf16 v[32:47], v[4:7], v[64:67], v[32:47]
	ds_read_b128 v[4:7], v82 offset:9216
	s_waitcnt lgkmcnt(0)
	v_mfma_f32_32x32x16_bf16 v[16:31], v[4:7], v[0:3], 0
	ds_read_b128 v[4:7], v82 offset:9248
	s_nop 7
	v_exp_f32_e32 v32, v32
	v_exp_f32_e32 v33, v33
	v_exp_f32_e32 v34, v34
	v_exp_f32_e32 v35, v35
	v_exp_f32_e32 v36, v36
	v_exp_f32_e32 v37, v37
	s_waitcnt lgkmcnt(0)
	v_mfma_f32_32x32x16_bf16 v[16:31], v[4:7], v[74:77], v[16:31]
	ds_read_b128 v[4:7], v82 offset:9280
	v_exp_f32_e32 v38, v38
	v_exp_f32_e32 v39, v39
	v_exp_f32_e32 v40, v40
	v_exp_f32_e32 v41, v41
	v_exp_f32_e32 v42, v42
	v_exp_f32_e32 v43, v43
	s_waitcnt lgkmcnt(0)
	v_mfma_f32_32x32x16_bf16 v[16:31], v[4:7], v[68:71], v[16:31]
	ds_read_b128 v[4:7], v82 offset:9312
	v_exp_f32_e32 v44, v44
	v_exp_f32_e32 v45, v45
	v_exp_f32_e32 v46, v46
	v_exp_f32_e32 v47, v47
	s_waitcnt lgkmcnt(0)
	v_mfma_f32_32x32x16_bf16 v[16:31], v[4:7], v[64:67], v[16:31]
	ds_read_b128 v[4:7], v82 offset:13824
	s_waitcnt lgkmcnt(0)
	v_mfma_f32_32x32x16_bf16 v[0:15], v[4:7], v[0:3], 0
	s_nop 8
	v_exp_f32_e32 v16, v16
	v_exp_f32_e32 v17, v17
	v_exp_f32_e32 v18, v18
	v_exp_f32_e32 v19, v19
	v_exp_f32_e32 v20, v20
	v_exp_f32_e32 v21, v21
	v_exp_f32_e32 v22, v22
	v_mfma_f32_32x32x16_bf16 v[0:15], v[78:81], v[74:77], v[0:15]
	ds_read_b128 v[74:77], v82 offset:13888
	v_exp_f32_e32 v23, v23
	v_exp_f32_e32 v24, v24
	v_exp_f32_e32 v25, v25
	v_exp_f32_e32 v26, v26
	v_exp_f32_e32 v27, v27
	v_exp_f32_e32 v28, v28
	s_waitcnt lgkmcnt(0)
	v_mfma_f32_32x32x16_bf16 v[0:15], v[74:77], v[68:71], v[0:15]
	ds_read_b128 v[68:71], v82 offset:13920
	v_exp_f32_e32 v29, v29
	v_exp_f32_e32 v30, v30
	v_exp_f32_e32 v31, v31
	s_waitcnt lgkmcnt(0)
; #define LAS __attribute__((address_space(3)))
; #define MFMA32(a, b, c) __builtin_amdgcn_mfma_f32_32x32x16_bf16((a), (b), (c), 0, 0, 0)
; __device__ __forceinline__ float ex2(float x) { return __builtin_amdgcn_exp2f(x); }
; __device__ __forceinline__ void phase4_attn(const Args& a, LAS unsigned char* lds) {
;     ...
;                         for (int ks = 0; ks < 4; ++ks) { const bf16x8_t ka = *(const LAS bf16x8_t*)(lds + A_CMPK + (32 * mt + r) * A_KSTR + 32 * ks + 16 * h); s4[mt] = MFMA32(ka, qf[ks], s4[mt]); } }
;                     const int clim = (pos - 31 - 64 * h) >> 4;
;                     float ls = 0.f;
; #pragma unroll
;                     for (int mt = 0; mt < 4; ++mt)
; #pragma unroll
;                         for (int i = 0; i < 16; ++i) { const int ci = 32 * mt + (i & 3) + 8 * (i >> 2);
;                             const float p = (ci <= clim) ? ex2(s4[mt][i]) : 0.f; s4[mt][i] = p; ls += p; }
	v_mfma_f32_32x32x16_bf16 v[0:15], v[68:71], v[64:67], v[0:15]
	v_lshlrev_b32_e32 v64, 6, v101
	v_sub_u32_e32 v64, v194, v64
	v_subrev_u32_e32 v64, 31, v64
	v_ashrrev_i32_e32 v64, 4, v64
	v_cmp_lt_i32_e32 vcc, -1, v64
	s_nop 6
	v_exp_f32_e32 v0, v0
	v_cndmask_b32_e32 v48, 0, v48, vcc
	v_cmp_lt_i32_e32 vcc, 0, v64
	v_add_f32_e32 v65, 0, v48
	v_exp_f32_e32 v1, v1
	v_cndmask_b32_e32 v49, 0, v49, vcc
	v_cmp_lt_i32_e32 vcc, 1, v64
	v_add_f32_e32 v65, v49, v65
	s_nop 0
	v_cndmask_b32_e32 v50, 0, v50, vcc
	v_cmp_lt_i32_e32 vcc, 2, v64
	v_add_f32_e32 v65, v50, v65
	s_nop 0
	v_cndmask_b32_e32 v51, 0, v51, vcc
	v_cmp_lt_i32_e32 vcc, 7, v64
	v_add_f32_e32 v65, v51, v65
	s_nop 0
	v_cndmask_b32_e32 v52, 0, v52, vcc
	v_cmp_lt_i32_e32 vcc, 8, v64
	v_add_f32_e32 v65, v52, v65
	s_nop 0
	v_cndmask_b32_e32 v53, 0, v53, vcc
	v_cmp_lt_i32_e32 vcc, 9, v64
	v_add_f32_e32 v65, v53, v65
	s_nop 0
	v_cndmask_b32_e32 v54, 0, v54, vcc
	v_cmp_lt_i32_e32 vcc, 10, v64
	v_add_f32_e32 v65, v54, v65
	s_nop 0
	v_cndmask_b32_e32 v55, 0, v55, vcc
	v_cmp_lt_i32_e32 vcc, 15, v64
	v_add_f32_e32 v65, v55, v65
	s_nop 0
	v_cndmask_b32_e32 v56, 0, v56, vcc
	v_cmp_lt_i32_e32 vcc, 16, v64
	v_add_f32_e32 v65, v56, v65
	s_nop 0
	v_cndmask_b32_e32 v57, 0, v57, vcc
	v_cmp_lt_i32_e32 vcc, 17, v64
	v_add_f32_e32 v65, v57, v65
	s_nop 0
	v_cndmask_b32_e32 v58, 0, v58, vcc
	v_cmp_lt_i32_e32 vcc, 18, v64
	v_add_f32_e32 v65, v58, v65
	s_nop 0
	v_cndmask_b32_e32 v59, 0, v59, vcc
	v_cmp_lt_i32_e32 vcc, 23, v64
	v_add_f32_e32 v65, v59, v65
	s_nop 0
	v_cndmask_b32_e32 v60, 0, v60, vcc
	v_cmp_lt_i32_e32 vcc, 24, v64
	v_add_f32_e32 v65, v60, v65
	s_nop 0
	v_cndmask_b32_e32 v61, 0, v61, vcc
	v_cmp_lt_i32_e32 vcc, 25, v64
	v_add_f32_e32 v65, v61, v65
	s_nop 0
	v_cndmask_b32_e32 v62, 0, v62, vcc
	v_cmp_lt_i32_e32 vcc, 26, v64
	v_add_f32_e32 v65, v62, v65
	s_nop 0
	v_cndmask_b32_e32 v63, 0, v63, vcc
	v_cmp_lt_i32_e32 vcc, 31, v64
	v_add_f32_e32 v65, v63, v65
	s_nop 0
	v_cndmask_b32_e32 v32, 0, v32, vcc
	v_cmp_lt_i32_e32 vcc, 32, v64
	v_add_f32_e32 v65, v32, v65
	s_nop 0
	v_cndmask_b32_e32 v33, 0, v33, vcc
	v_cmp_lt_i32_e32 vcc, 33, v64
	v_add_f32_e32 v65, v33, v65
	s_nop 0
	v_cndmask_b32_e32 v34, 0, v34, vcc
	v_cmp_lt_i32_e32 vcc, 34, v64
	v_add_f32_e32 v65, v34, v65
	s_nop 0
	v_cndmask_b32_e32 v35, 0, v35, vcc
	v_cmp_lt_i32_e32 vcc, 39, v64
	v_add_f32_e32 v65, v35, v65
	s_nop 0
	v_cndmask_b32_e32 v36, 0, v36, vcc
	v_cmp_lt_i32_e32 vcc, 40, v64
	v_add_f32_e32 v65, v36, v65
	s_nop 0
	v_cndmask_b32_e32 v37, 0, v37, vcc
	v_cmp_lt_i32_e32 vcc, 41, v64
	v_add_f32_e32 v65, v37, v65
	s_nop 0
	v_cndmask_b32_e32 v38, 0, v38, vcc
	v_cmp_lt_i32_e32 vcc, 42, v64
	v_add_f32_e32 v65, v38, v65
	s_nop 0
	v_cndmask_b32_e32 v39, 0, v39, vcc
	v_cmp_lt_i32_e32 vcc, 47, v64
	v_add_f32_e32 v65, v39, v65
	s_nop 0
	v_cndmask_b32_e32 v40, 0, v40, vcc
	v_cmp_lt_i32_e32 vcc, 48, v64
	v_add_f32_e32 v65, v40, v65
	s_nop 0
	v_cndmask_b32_e32 v41, 0, v41, vcc
	v_cmp_lt_i32_e32 vcc, 49, v64
	v_add_f32_e32 v65, v41, v65
	s_nop 0
	v_cndmask_b32_e32 v42, 0, v42, vcc
	v_cmp_lt_i32_e32 vcc, 50, v64
	v_add_f32_e32 v65, v42, v65
	s_nop 0
	v_cndmask_b32_e32 v43, 0, v43, vcc
	v_cmp_lt_i32_e32 vcc, 55, v64
	v_add_f32_e32 v65, v43, v65
	s_nop 0
	v_cndmask_b32_e32 v44, 0, v44, vcc
	v_cmp_lt_i32_e32 vcc, 56, v64
	v_add_f32_e32 v65, v44, v65
	s_nop 0
	v_cndmask_b32_e32 v45, 0, v45, vcc
	v_cmp_lt_i32_e32 vcc, 57, v64
	v_add_f32_e32 v65, v45, v65
	s_nop 0
	v_cndmask_b32_e32 v46, 0, v46, vcc
	v_cmp_lt_i32_e32 vcc, 58, v64
	v_add_f32_e32 v65, v46, v65
	s_nop 0
	v_cndmask_b32_e32 v47, 0, v47, vcc
	v_cmp_lt_i32_e32 vcc, 63, v64
	v_add_f32_e32 v65, v47, v65
	s_nop 0
	v_cndmask_b32_e32 v16, 0, v16, vcc
	v_cmp_lt_i32_e32 vcc, 64, v64
	v_add_f32_e32 v65, v16, v65
	s_nop 0
	v_cndmask_b32_e32 v17, 0, v17, vcc
	v_cmp_lt_i32_e32 vcc, s96, v64
	v_add_f32_e32 v65, v17, v65
	s_nop 0
	v_cndmask_b32_e32 v18, 0, v18, vcc
	v_cmp_lt_i32_e32 vcc, s97, v64
	v_add_f32_e32 v65, v18, v65
	s_nop 0
	v_cndmask_b32_e32 v19, 0, v19, vcc
	v_cmp_lt_i32_e32 vcc, s18, v64
	v_add_f32_e32 v65, v19, v65
	s_nop 0
	v_cndmask_b32_e32 v20, 0, v20, vcc
	v_cmp_lt_i32_e32 vcc, s19, v64
	v_add_f32_e32 v65, v20, v65
	s_nop 0
	v_cndmask_b32_e32 v21, 0, v21, vcc
	v_cmp_lt_i32_e32 vcc, s14, v64
	v_add_f32_e32 v65, v21, v65
	s_nop 0
	v_cndmask_b32_e32 v22, 0, v22, vcc
	v_cmp_lt_i32_e32 vcc, s15, v64
	v_add_f32_e32 v65, v22, v65
	s_nop 0
	v_cndmask_b32_e32 v23, 0, v23, vcc
	v_cmp_lt_i32_e32 vcc, s16, v64
	v_add_f32_e32 v65, v23, v65
	s_nop 0
	v_cndmask_b32_e32 v24, 0, v24, vcc
	v_cmp_lt_i32_e32 vcc, s17, v64
	v_add_f32_e32 v65, v24, v65
	s_nop 0
	v_cndmask_b32_e32 v25, 0, v25, vcc
	v_cmp_lt_i32_e32 vcc, s92, v64
	v_add_f32_e32 v65, v25, v65
	s_nop 0
	v_cndmask_b32_e32 v26, 0, v26, vcc
	v_cmp_lt_i32_e32 vcc, s93, v64
	v_add_f32_e32 v65, v26, v65
	s_nop 0
	v_cndmask_b32_e32 v27, 0, v27, vcc
	v_cmp_lt_i32_e32 vcc, s66, v64
; __device__ __forceinline__ float ex2(float x) { return __builtin_amdgcn_exp2f(x); }
; __device__ __forceinline__ void phase4_attn(const Args& a, LAS unsigned char* lds) {
;     ...
;                         for (int i = 0; i < 16; ++i) { const int ci = 32 * mt + (i & 3) + 8 * (i >> 2);
;                             const float p = (ci <= clim) ? ex2(s4[mt][i]) : 0.f; s4[mt][i] = p; ls += p; }
;                     ls += __shfl_xor(ls, 32);
;                     const float inv = 1.f / fmaxf(ls, 1e-20f);
; #pragma unroll
;                     for (int mt = 0; mt < 4; ++mt) s4[mt] *= inv;
;                     if (t >= 16) {
	v_add_f32_e32 v65, v27, v65
	s_nop 0
	v_cndmask_b32_e32 v28, 0, v28, vcc
	v_cmp_lt_i32_e32 vcc, s67, v64
	v_add_f32_e32 v65, v28, v65
	s_nop 0
	v_cndmask_b32_e32 v29, 0, v29, vcc
	v_cmp_lt_i32_e32 vcc, s68, v64
	v_add_f32_e32 v65, v29, v65
	s_nop 0
	v_cndmask_b32_e32 v30, 0, v30, vcc
	v_cmp_lt_i32_e32 vcc, s69, v64
	v_add_f32_e32 v65, v30, v65
	s_nop 0
	v_cndmask_b32_e32 v31, 0, v31, vcc
	v_cmp_lt_i32_e32 vcc, s33, v64
	v_add_f32_e32 v65, v31, v65
	s_nop 0
	v_cndmask_b32_e32 v90, 0, v0, vcc
	v_cmp_lt_i32_e32 vcc, s83, v64
	v_add_f32_e32 v0, v90, v65
	s_nop 0
	v_cndmask_b32_e32 v91, 0, v1, vcc
	v_exp_f32_e32 v1, v2
	v_cmp_lt_i32_e32 vcc, s70, v64
	v_add_f32_e32 v0, v91, v0
	s_nop 0
	v_cndmask_b32_e32 v92, 0, v1, vcc
	v_exp_f32_e32 v1, v3
	v_cmp_lt_i32_e32 vcc, s81, v64
	v_add_f32_e32 v0, v92, v0
	s_nop 0
	v_cndmask_b32_e32 v93, 0, v1, vcc
	v_exp_f32_e32 v1, v4
	v_cmp_lt_i32_e32 vcc, s82, v64
	v_add_f32_e32 v0, v93, v0
	s_nop 0
	v_cndmask_b32_e32 v94, 0, v1, vcc
	v_exp_f32_e32 v1, v5
	v_cmp_lt_i32_e32 vcc, s20, v64
	v_add_f32_e32 v0, v94, v0
	s_nop 0
	v_cndmask_b32_e32 v95, 0, v1, vcc
	v_exp_f32_e32 v1, v6
	v_cmp_lt_i32_e32 vcc, s21, v64
	v_add_f32_e32 v0, v95, v0
	s_nop 0
	v_cndmask_b32_e32 v96, 0, v1, vcc
	v_exp_f32_e32 v1, v7
	v_cmp_lt_i32_e32 vcc, s26, v64
	v_add_f32_e32 v0, v96, v0
	s_nop 0
	v_cndmask_b32_e32 v97, 0, v1, vcc
	v_exp_f32_e32 v1, v8
	v_cmp_lt_i32_e32 vcc, s27, v64
	v_add_f32_e32 v0, v97, v0
	s_nop 0
	v_cndmask_b32_e32 v8, 0, v1, vcc
	v_exp_f32_e32 v1, v9
	v_cmp_lt_i32_e32 vcc, s84, v64
	v_add_f32_e32 v0, v8, v0
	s_nop 0
	v_cndmask_b32_e32 v9, 0, v1, vcc
	v_exp_f32_e32 v1, v10
	v_cmp_lt_i32_e32 vcc, s28, v64
	v_add_f32_e32 v0, v9, v0
	s_nop 0
	v_cndmask_b32_e32 v10, 0, v1, vcc
	v_exp_f32_e32 v1, v11
	v_cmp_lt_i32_e32 vcc, s29, v64
	v_add_f32_e32 v0, v10, v0
	s_nop 0
	v_cndmask_b32_e32 v11, 0, v1, vcc
	v_exp_f32_e32 v1, v12
	v_cmp_lt_i32_e32 vcc, s34, v64
	v_add_f32_e32 v0, v11, v0
	s_nop 0
	v_cndmask_b32_e32 v12, 0, v1, vcc
	v_exp_f32_e32 v1, v13
	v_cmp_lt_i32_e32 vcc, s35, v64
	v_add_f32_e32 v0, v12, v0
	s_nop 0
	v_cndmask_b32_e32 v13, 0, v1, vcc
	v_exp_f32_e32 v1, v14
	v_cmp_lt_i32_e32 vcc, s36, v64
	v_add_f32_e32 v0, v13, v0
	s_nop 0
	v_cndmask_b32_e32 v14, 0, v1, vcc
	v_exp_f32_e32 v1, v15
	v_cmp_lt_i32_e32 vcc, s37, v64
	v_add_f32_e32 v0, v14, v0
	s_nop 0
	v_cndmask_b32_e32 v15, 0, v1, vcc
	v_add_f32_e32 v0, v15, v0
	ds_bpermute_b32 v1, v193, v0
	s_waitcnt lgkmcnt(0)
	v_add_f32_e32 v0, v0, v1
	v_max_f32_e32 v0, 0x1e3ce508, v0
	v_div_scale_f32 v1, s[0:1], v0, v0, 1.0
	v_rcp_f32_e32 v2, v1
	s_mov_b64 s[0:1], -1
	v_fma_f32 v3, -v1, v2, 1.0
	v_fmac_f32_e32 v2, v3, v2
	v_div_scale_f32 v3, vcc, 1.0, v0, 1.0
	v_mul_f32_e32 v4, v3, v2
	v_fma_f32 v5, -v1, v4, v3
	v_fmac_f32_e32 v4, v5, v2
	v_fma_f32 v1, -v1, v4, v3
	v_div_fmas_f32 v1, v1, v2, v4
	v_div_fixup_f32 v102, v1, v0, 1.0
	v_pk_mul_f32 v[0:1], v[48:49], v[102:103] op_sel_hi:[1,0]
	v_pk_mul_f32 v[2:3], v[50:51], v[102:103] op_sel_hi:[1,0]
	v_pk_mul_f32 v[4:5], v[52:53], v[102:103] op_sel_hi:[1,0]
	v_pk_mul_f32 v[6:7], v[54:55], v[102:103] op_sel_hi:[1,0]
	v_pk_mul_f32 v[78:79], v[56:57], v[102:103] op_sel_hi:[1,0]
	v_pk_mul_f32 v[82:83], v[58:59], v[102:103] op_sel_hi:[1,0]
	v_pk_mul_f32 v[86:87], v[60:61], v[102:103] op_sel_hi:[1,0]
	v_pk_mul_f32 v[88:89], v[62:63], v[102:103] op_sel_hi:[1,0]
	v_pk_mul_f32 v[74:75], v[32:33], v[102:103] op_sel_hi:[1,0]
	v_pk_mul_f32 v[76:77], v[34:35], v[102:103] op_sel_hi:[1,0]
	v_pk_mul_f32 v[80:81], v[36:37], v[102:103] op_sel_hi:[1,0]
	v_pk_mul_f32 v[84:85], v[38:39], v[102:103] op_sel_hi:[1,0]
	v_pk_mul_f32 v[58:59], v[40:41], v[102:103] op_sel_hi:[1,0]
	v_pk_mul_f32 v[62:63], v[42:43], v[102:103] op_sel_hi:[1,0]
	v_pk_mul_f32 v[66:67], v[44:45], v[102:103] op_sel_hi:[1,0]
	v_pk_mul_f32 v[70:71], v[46:47], v[102:103] op_sel_hi:[1,0]
	v_pk_mul_f32 v[56:57], v[16:17], v[102:103] op_sel_hi:[1,0]
	v_pk_mul_f32 v[60:61], v[18:19], v[102:103] op_sel_hi:[1,0]
	v_pk_mul_f32 v[64:65], v[20:21], v[102:103] op_sel_hi:[1,0]
	v_pk_mul_f32 v[68:69], v[22:23], v[102:103] op_sel_hi:[1,0]
	v_pk_mul_f32 v[42:43], v[24:25], v[102:103] op_sel_hi:[1,0]
	v_pk_mul_f32 v[46:47], v[26:27], v[102:103] op_sel_hi:[1,0]
	v_pk_mul_f32 v[50:51], v[28:29], v[102:103] op_sel_hi:[1,0]
	v_pk_mul_f32 v[54:55], v[30:31], v[102:103] op_sel_hi:[1,0]
	v_pk_mul_f32 v[40:41], v[90:91], v[102:103] op_sel_hi:[1,0]
	v_pk_mul_f32 v[44:45], v[92:93], v[102:103] op_sel_hi:[1,0]
	v_pk_mul_f32 v[48:49], v[94:95], v[102:103] op_sel_hi:[1,0]
	v_pk_mul_f32 v[52:53], v[96:97], v[102:103] op_sel_hi:[1,0]
	v_pk_mul_f32 v[32:33], v[8:9], v[102:103] op_sel_hi:[1,0]
	v_pk_mul_f32 v[34:35], v[10:11], v[102:103] op_sel_hi:[1,0]
	v_pk_mul_f32 v[36:37], v[12:13], v[102:103] op_sel_hi:[1,0]
	v_pk_mul_f32 v[38:39], v[14:15], v[102:103] op_sel_hi:[1,0]
	s_andn2_b64 vcc, exec, s[62:63]
	s_cbranch_vccnz .LBB0_796
	s_mov_b64 s[0:1], 0

; __device__ __forceinline__ void phase4_attn(const Args& a, LAS unsigned char* lds) {
;     ...
;                     const bool issel = i < n_sel;
;                     const int st = issel ? i : wlo + (i - n_sel);
;                     const int dlt = 64 * t + ql - 128 * st - 4 * h;
;                     if (issel) {
;                         const bool b0 = (selw >> (2 * st)) & 1u, b1 = (selw >> (2 * st + 1)) & 1u;
;                         if (__ballot(b0 || b1) != 0ull) {
;                             if (2 * st + 1 < t) {
;                                 if (__ballot(b0 && b1) == ~0ull) attn_tile<2>(Kb, Vb, qf, oacc, l_run, r, h, dlt, dlt, (w & 4) != 0);
;                                 else attn_tile<3>(Kb, Vb, qf, oacc, l_run, r, h, __float_as_int(b0 ? 0.f : -1e30f), __float_as_int(b1 ? 0.f : -1e30f), (w & 4) != 0);
;                             } else attn_tile<0>(Kb, Vb, qf, oacc, l_run, r, h, b0 ? dlt : -1, b1 ? dlt : -1, (w & 4) != 0);
;                         }
.Lt2_disp:
	s_cmp_gt_u32 s44, s89
	s_cbranch_scc1 .Lt2_win
	s_lshl_b32 s0, s44, 2
	s_sub_i32 s49, s50, s0
	s_lshl_b32 s4, s44, 1
	v_lshrrev_b32_e32 v238, s4, v198
	v_and_b32_e32 v238, 3, v238
	v_cmp_ne_u32_e32 vcc, 0, v238
	s_cmp_eq_u64 vcc, 0
	s_cbranch_scc1 .Lt2_join
	s_cmp_le_i32 s49, 3
	s_cbranch_scc1 .Lt2_diag
	v_cmp_eq_u32_e32 vcc, 3, v238
	s_cmp_eq_u64 vcc, -1
	s_cbranch_scc1 .Lt2_full
	s_mov_b32 s49, s4
	s_branch .Lt2_bias

; #define LAS __attribute__((address_space(3)))
; #define MFMA32(a, b, c) __builtin_amdgcn_mfma_f32_32x32x16_bf16((a), (b), (c), 0, 0, 0)
; __device__ __forceinline__ float ex2(float x) { return __builtin_amdgcn_exp2f(x); }
; template <int MODE>
; __device__ __forceinline__ void attn_tile(const LAS unsigned char* Kb, const LAS unsigned char* Vb, const bf16x8_t (&qf)[4], f32x16 (&oacc)[2], float& l_run,
;                                           int r, int h, int dlt0, int dlt1, bool hiw) {
;     const unsigned ulim = (MODE == 0) ? 0x80000000u : 512u;
;     float ls = 0.f;
; #pragma unroll
;     for (int mt = 0; mt < 4; ++mt) {
;         if (mt == 0) { if (hiw) __builtin_amdgcn_s_setprio(1); else __builtin_amdgcn_s_setprio(0); }
;         if (mt == 2) { if (hiw) __builtin_amdgcn_s_setprio(0); else __builtin_amdgcn_s_setprio(1); }
;         const int dl = mt < 2 ? dlt0 : dlt1;
;         f32x16 sacc = zero16();
; #pragma unroll
;         for (int ks = 0; ks < 4; ++ks) { const bf16x8_t ka = *(const LAS bf16x8_t*)(Kb + (32 * mt + r) * A_KSTR + 32 * ks + 16 * h); sacc = MFMA32(ka, qf[ks], sacc); }
; #pragma unroll
;         for (int i = 0; i < 16; ++i) {
;             float p;
;             if (MODE == 2) p = ex2(sacc[i]);
;             else if (MODE == 3) p = ex2(sacc[i] + __int_as_float(dl));
;             else { const int ci = 32 * mt + (i & 3) + 8 * (i >> 2); p = ((unsigned)(dl - ci) < ulim) ? ex2(sacc[i]) : 0.f; }
;             sacc[i] = p; ls += p;
;         }
; #pragma unroll
;         for (int s = 0; s < 2; ++s) {
;             const bf16x8_t pf = pack8(sacc, 8 * s);
; #pragma unroll
;             for (int dt = 0; dt < 2; ++dt) {
;                 const LAS unsigned char* vp = Vb + (32 * dt + r) * A_CVSTR + (32 * mt + 16 * s + 4 * h) * 2;
;                 const s16x4_t lo = *(const LAS s16x4_t*)vp, hi = *(const LAS s16x4_t*)(vp + 16);
;                 oacc[dt] = MFMA32(__builtin_shufflevector(lo, hi, 0, 1, 2, 3, 4, 5, 6, 7), pf, oacc[dt]);
;             }
;         }
.Lt2_bias:
	ds_read_b128 v[200:203], v72 offset:0
	ds_read_b128 v[204:207], v72 offset:32
	ds_read_b128 v[208:211], v72 offset:64
	ds_read_b128 v[212:215], v72 offset:96
	ds_read2_b64 v[216:219], v73 offset0:0 offset1:2
	ds_read2_b64 v[220:223], v74 offset0:32 offset1:34
	ds_read2_b64 v[224:227], v73 offset0:4 offset1:6
	ds_read2_b64 v[228:231], v74 offset0:36 offset1:38
	v_bfe_i32 v236, v198, s49, 1
	s_add_i32 s49, s49, 1
	v_bfe_i32 v237, v198, s49, 1
	s_waitcnt lgkmcnt(7)
	v_mfma_f32_32x32x16_bf16 v[32:47], v[200:203], v[80:83], 0
	ds_read_b128 v[200:203], v72 offset:4608
	s_waitcnt lgkmcnt(7)
	v_mfma_f32_32x32x16_bf16 v[32:47], v[204:207], v[84:87], v[32:47]
	ds_read_b128 v[204:207], v72 offset:4640
	s_waitcnt lgkmcnt(7)
	v_mfma_f32_32x32x16_bf16 v[32:47], v[208:211], v[88:91], v[32:47]
	ds_read_b128 v[208:211], v72 offset:4672
	s_waitcnt lgkmcnt(7)
	v_mfma_f32_32x32x16_bf16 v[32:47], v[212:215], v[92:95], v[32:47]
	ds_read_b128 v[212:215], v72 offset:4704
	s_nop 7
	s_nop 3
	s_waitcnt lgkmcnt(3)
	v_mfma_f32_32x32x16_bf16 v[48:63], v[200:203], v[80:83], 0
	ds_read_b128 v[200:203], v72 offset:9216
	v_exp_f32_e32 v32, v32
	v_exp_f32_e32 v33, v33
	s_waitcnt lgkmcnt(3)
	v_mfma_f32_32x32x16_bf16 v[48:63], v[204:207], v[84:87], v[48:63]
	ds_read_b128 v[204:207], v72 offset:9248
	v_exp_f32_e32 v34, v34
	v_exp_f32_e32 v35, v35
	v_mov_b32_e32 v232, v32
	v_mov_b32_e32 v233, v33
	v_cvt_pk_bf16_f32 v64, v32, v33
	v_and_b32_e32 v64, v236, v64
	v_exp_f32_e32 v36, v36
	v_exp_f32_e32 v37, v37
	v_add_f32_e32 v232, v232, v34
	v_add_f32_e32 v233, v233, v35
	v_cvt_pk_bf16_f32 v65, v34, v35
	v_and_b32_e32 v65, v236, v65
	v_exp_f32_e32 v38, v38
	v_exp_f32_e32 v39, v39
	v_add_f32_e32 v232, v232, v36
	v_add_f32_e32 v233, v233, v37
	v_cvt_pk_bf16_f32 v66, v36, v37
	v_and_b32_e32 v66, v236, v66
	v_add_f32_e32 v232, v232, v38
	v_add_f32_e32 v233, v233, v39
	v_cvt_pk_bf16_f32 v67, v38, v39
	v_and_b32_e32 v67, v236, v67
	s_waitcnt lgkmcnt(3)
	v_mfma_f32_32x32x16_bf16 v[48:63], v[208:211], v[88:91], v[48:63]
	ds_read_b128 v[208:211], v72 offset:9280
	v_exp_f32_e32 v40, v40
	v_exp_f32_e32 v41, v41
	s_waitcnt lgkmcnt(3)
	v_mfma_f32_32x32x16_bf16 v[48:63], v[212:215], v[92:95], v[48:63]
	ds_read_b128 v[212:215], v72 offset:9312
	v_exp_f32_e32 v42, v42
	v_exp_f32_e32 v43, v43
	v_add_f32_e32 v232, v232, v40
	v_add_f32_e32 v233, v233, v41
	v_cvt_pk_bf16_f32 v68, v40, v41
	v_and_b32_e32 v68, v236, v68
	v_mfma_f32_32x32x16_bf16 v[0:15], v[216:219], v[64:67], v[0:15]
	ds_read2_b64 v[216:219], v73 offset0:8 offset1:10
	v_exp_f32_e32 v44, v44
	v_exp_f32_e32 v45, v45
	v_add_f32_e32 v232, v232, v42
	v_add_f32_e32 v233, v233, v43
	v_cvt_pk_bf16_f32 v69, v42, v43
	v_and_b32_e32 v69, v236, v69
	v_mfma_f32_32x32x16_bf16 v[16:31], v[220:223], v[64:67], v[16:31]
	ds_read2_b64 v[220:223], v74 offset0:40 offset1:42
	v_exp_f32_e32 v46, v46
	v_exp_f32_e32 v47, v47
	v_add_f32_e32 v232, v232, v44
	v_add_f32_e32 v233, v233, v45
	v_cvt_pk_bf16_f32 v70, v44, v45
	v_and_b32_e32 v70, v236, v70
	v_add_f32_e32 v232, v232, v46
	v_add_f32_e32 v233, v233, v47
	v_cvt_pk_bf16_f32 v71, v46, v47
	v_and_b32_e32 v71, v236, v71
	s_waitcnt lgkmcnt(5)
	v_mfma_f32_32x32x16_bf16 v[32:47], v[200:203], v[80:83], 0
	ds_read_b128 v[200:203], v72 offset:13824
	v_exp_f32_e32 v48, v48
	v_exp_f32_e32 v49, v49
	s_waitcnt lgkmcnt(5)
	v_mfma_f32_32x32x16_bf16 v[32:47], v[204:207], v[84:87], v[32:47]
	ds_read_b128 v[204:207], v72 offset:13856
	v_exp_f32_e32 v50, v50
	v_exp_f32_e32 v51, v51
	v_add_f32_e32 v232, v232, v48
	v_add_f32_e32 v233, v233, v49
	v_cvt_pk_bf16_f32 v64, v48, v49
	v_and_b32_e32 v64, v236, v64
	v_mfma_f32_32x32x16_bf16 v[0:15], v[224:227], v[68:71], v[0:15]
	ds_read2_b64 v[224:227], v73 offset0:12 offset1:14
	v_exp_f32_e32 v52, v52
	v_exp_f32_e32 v53, v53
	v_add_f32_e32 v232, v232, v50
	v_add_f32_e32 v233, v233, v51
	v_cvt_pk_bf16_f32 v65, v50, v51
	v_and_b32_e32 v65, v236, v65
	v_mfma_f32_32x32x16_bf16 v[16:31], v[228:231], v[68:71], v[16:31]
	ds_read2_b64 v[228:231], v74 offset0:44 offset1:46
	v_exp_f32_e32 v54, v54
	v_exp_f32_e32 v55, v55
	v_add_f32_e32 v232, v232, v52
	v_add_f32_e32 v233, v233, v53
	v_cvt_pk_bf16_f32 v66, v52, v53
	v_and_b32_e32 v66, v236, v66
	v_add_f32_e32 v232, v232, v54
	v_add_f32_e32 v233, v233, v55
	v_cvt_pk_bf16_f32 v67, v54, v55
	v_and_b32_e32 v67, v236, v67
	s_waitcnt lgkmcnt(7)
	v_mfma_f32_32x32x16_bf16 v[32:47], v[208:211], v[88:91], v[32:47]
	ds_read_b128 v[208:211], v72 offset:13888
	v_exp_f32_e32 v56, v56
	v_exp_f32_e32 v57, v57
	s_waitcnt lgkmcnt(7)
	v_mfma_f32_32x32x16_bf16 v[32:47], v[212:215], v[92:95], v[32:47]
	ds_read_b128 v[212:215], v72 offset:13920
	v_exp_f32_e32 v58, v58
	v_exp_f32_e32 v59, v59
	v_add_f32_e32 v232, v232, v56
	v_add_f32_e32 v233, v233, v57
	v_cvt_pk_bf16_f32 v68, v56, v57
	v_and_b32_e32 v68, v236, v68
	s_waitcnt lgkmcnt(7)
	v_mfma_f32_32x32x16_bf16 v[0:15], v[216:219], v[64:67], v[0:15]
	ds_read2_b64 v[216:219], v73 offset0:16 offset1:18
	v_exp_f32_e32 v60, v60
	v_exp_f32_e32 v61, v61
	v_add_f32_e32 v232, v232, v58
	v_add_f32_e32 v233, v233, v59
	v_cvt_pk_bf16_f32 v69, v58, v59
	v_and_b32_e32 v69, v236, v69
	s_waitcnt lgkmcnt(7)
; #define LAS __attribute__((address_space(3)))
; #define MFMA32(a, b, c) __builtin_amdgcn_mfma_f32_32x32x16_bf16((a), (b), (c), 0, 0, 0)
; __device__ __forceinline__ float ex2(float x) { return __builtin_amdgcn_exp2f(x); }
; template <int MODE>
; __device__ __forceinline__ void attn_tile(const LAS unsigned char* Kb, const LAS unsigned char* Vb, const bf16x8_t (&qf)[4], f32x16 (&oacc)[2], float& l_run,
;                                           int r, int h, int dlt0, int dlt1, bool hiw) {
;     ...
; #pragma unroll
;     for (int mt = 0; mt < 4; ++mt) {
;         if (mt == 0) { if (hiw) __builtin_amdgcn_s_setprio(1); else __builtin_amdgcn_s_setprio(0); }
;         if (mt == 2) { if (hiw) __builtin_amdgcn_s_setprio(0); else __builtin_amdgcn_s_setprio(1); }
;         const int dl = mt < 2 ? dlt0 : dlt1;
;         f32x16 sacc = zero16();
; #pragma unroll
;         for (int ks = 0; ks < 4; ++ks) { const bf16x8_t ka = *(const LAS bf16x8_t*)(Kb + (32 * mt + r) * A_KSTR + 32 * ks + 16 * h); sacc = MFMA32(ka, qf[ks], sacc); }
; #pragma unroll
;         for (int i = 0; i < 16; ++i) {
;             float p;
;             if (MODE == 2) p = ex2(sacc[i]);
;             else if (MODE == 3) p = ex2(sacc[i] + __int_as_float(dl));
;             else { const int ci = 32 * mt + (i & 3) + 8 * (i >> 2); p = ((unsigned)(dl - ci) < ulim) ? ex2(sacc[i]) : 0.f; }
;             sacc[i] = p; ls += p;
;         }
; #pragma unroll
;         for (int s = 0; s < 2; ++s) {
;             const bf16x8_t pf = pack8(sacc, 8 * s);
; #pragma unroll
;             for (int dt = 0; dt < 2; ++dt) {
;                 const LAS unsigned char* vp = Vb + (32 * dt + r) * A_CVSTR + (32 * mt + 16 * s + 4 * h) * 2;
;                 const s16x4_t lo = *(const LAS s16x4_t*)vp, hi = *(const LAS s16x4_t*)(vp + 16);
;                 oacc[dt] = MFMA32(__builtin_shufflevector(lo, hi, 0, 1, 2, 3, 4, 5, 6, 7), pf, oacc[dt]);
;             }
;         }
;     }
;     l_run += ls;
	v_mfma_f32_32x32x16_bf16 v[16:31], v[220:223], v[64:67], v[16:31]
	ds_read2_b64 v[220:223], v74 offset0:48 offset1:50
	v_exp_f32_e32 v62, v62
	v_exp_f32_e32 v63, v63
	v_add_f32_e32 v232, v232, v60
	v_add_f32_e32 v233, v233, v61
	v_cvt_pk_bf16_f32 v70, v60, v61
	v_and_b32_e32 v70, v236, v70
	v_add_f32_e32 v232, v232, v62
	v_add_f32_e32 v233, v233, v63
	v_cvt_pk_bf16_f32 v71, v62, v63
	v_and_b32_e32 v71, v236, v71
	s_waitcnt lgkmcnt(7)
	v_mfma_f32_32x32x16_bf16 v[48:63], v[200:203], v[80:83], 0
	v_exp_f32_e32 v32, v32
	v_exp_f32_e32 v33, v33
	s_waitcnt lgkmcnt(6)
	v_mfma_f32_32x32x16_bf16 v[48:63], v[204:207], v[84:87], v[48:63]
	v_exp_f32_e32 v34, v34
	v_exp_f32_e32 v35, v35
	v_mov_b32_e32 v234, v32
	v_mov_b32_e32 v235, v33
	v_cvt_pk_bf16_f32 v64, v32, v33
	v_and_b32_e32 v64, v237, v64
	s_waitcnt lgkmcnt(5)
	v_mfma_f32_32x32x16_bf16 v[0:15], v[224:227], v[68:71], v[0:15]
	ds_read2_b64 v[224:227], v73 offset0:20 offset1:22
	v_exp_f32_e32 v36, v36
	v_exp_f32_e32 v37, v37
	v_add_f32_e32 v234, v234, v34
	v_add_f32_e32 v235, v235, v35
	v_cvt_pk_bf16_f32 v65, v34, v35
	v_and_b32_e32 v65, v237, v65
	s_waitcnt lgkmcnt(5)
	v_mfma_f32_32x32x16_bf16 v[16:31], v[228:231], v[68:71], v[16:31]
	ds_read2_b64 v[228:231], v74 offset0:52 offset1:54
	v_exp_f32_e32 v38, v38
	v_exp_f32_e32 v39, v39
	v_add_f32_e32 v234, v234, v36
	v_add_f32_e32 v235, v235, v37
	v_cvt_pk_bf16_f32 v66, v36, v37
	v_and_b32_e32 v66, v237, v66
	v_add_f32_e32 v234, v234, v38
	v_add_f32_e32 v235, v235, v39
	v_cvt_pk_bf16_f32 v67, v38, v39
	v_and_b32_e32 v67, v237, v67
	s_waitcnt lgkmcnt(5)
	v_mfma_f32_32x32x16_bf16 v[48:63], v[208:211], v[88:91], v[48:63]
	v_exp_f32_e32 v40, v40
	v_exp_f32_e32 v41, v41
	s_waitcnt lgkmcnt(4)
	v_mfma_f32_32x32x16_bf16 v[48:63], v[212:215], v[92:95], v[48:63]
	v_exp_f32_e32 v42, v42
	v_exp_f32_e32 v43, v43
	v_add_f32_e32 v234, v234, v40
	v_add_f32_e32 v235, v235, v41
	v_cvt_pk_bf16_f32 v68, v40, v41
	v_and_b32_e32 v68, v237, v68
	s_waitcnt lgkmcnt(3)
	v_mfma_f32_32x32x16_bf16 v[0:15], v[216:219], v[64:67], v[0:15]
	ds_read2_b64 v[216:219], v73 offset0:24 offset1:26
	v_exp_f32_e32 v44, v44
	v_exp_f32_e32 v45, v45
	v_add_f32_e32 v234, v234, v42
	v_add_f32_e32 v235, v235, v43
	v_cvt_pk_bf16_f32 v69, v42, v43
	v_and_b32_e32 v69, v237, v69
	s_waitcnt lgkmcnt(3)
	v_mfma_f32_32x32x16_bf16 v[16:31], v[220:223], v[64:67], v[16:31]
	ds_read2_b64 v[220:223], v74 offset0:56 offset1:58
	v_exp_f32_e32 v46, v46
	v_exp_f32_e32 v47, v47
	v_add_f32_e32 v234, v234, v44
	v_add_f32_e32 v235, v235, v45
	v_cvt_pk_bf16_f32 v70, v44, v45
	v_and_b32_e32 v70, v237, v70
	v_add_f32_e32 v234, v234, v46
	v_add_f32_e32 v235, v235, v47
	v_cvt_pk_bf16_f32 v71, v46, v47
	v_and_b32_e32 v71, v237, v71
	v_exp_f32_e32 v48, v48
	v_exp_f32_e32 v49, v49
	v_exp_f32_e32 v50, v50
	v_exp_f32_e32 v51, v51
	v_add_f32_e32 v234, v234, v48
	v_add_f32_e32 v235, v235, v49
	v_cvt_pk_bf16_f32 v64, v48, v49
	v_and_b32_e32 v64, v237, v64
	s_waitcnt lgkmcnt(3)
	v_mfma_f32_32x32x16_bf16 v[0:15], v[224:227], v[68:71], v[0:15]
	ds_read2_b64 v[224:227], v73 offset0:28 offset1:30
	v_exp_f32_e32 v52, v52
	v_exp_f32_e32 v53, v53
	v_add_f32_e32 v234, v234, v50
	v_add_f32_e32 v235, v235, v51
	v_cvt_pk_bf16_f32 v65, v50, v51
	v_and_b32_e32 v65, v237, v65
	s_waitcnt lgkmcnt(3)
	v_mfma_f32_32x32x16_bf16 v[16:31], v[228:231], v[68:71], v[16:31]
	ds_read2_b64 v[228:231], v74 offset0:60 offset1:62
	v_exp_f32_e32 v54, v54
	v_exp_f32_e32 v55, v55
	v_add_f32_e32 v234, v234, v52
	v_add_f32_e32 v235, v235, v53
	v_cvt_pk_bf16_f32 v66, v52, v53
	v_and_b32_e32 v66, v237, v66
	v_add_f32_e32 v234, v234, v54
	v_add_f32_e32 v235, v235, v55
	v_cvt_pk_bf16_f32 v67, v54, v55
	v_and_b32_e32 v67, v237, v67
	v_exp_f32_e32 v56, v56
	v_exp_f32_e32 v57, v57
	v_exp_f32_e32 v58, v58
	v_exp_f32_e32 v59, v59
	v_add_f32_e32 v234, v234, v56
	v_add_f32_e32 v235, v235, v57
	v_cvt_pk_bf16_f32 v68, v56, v57
	v_and_b32_e32 v68, v237, v68
	s_waitcnt lgkmcnt(3)
	v_mfma_f32_32x32x16_bf16 v[0:15], v[216:219], v[64:67], v[0:15]
	v_exp_f32_e32 v60, v60
	v_exp_f32_e32 v61, v61
	v_add_f32_e32 v234, v234, v58
	v_add_f32_e32 v235, v235, v59
	v_cvt_pk_bf16_f32 v69, v58, v59
	v_and_b32_e32 v69, v237, v69
	s_waitcnt lgkmcnt(2)
	v_mfma_f32_32x32x16_bf16 v[16:31], v[220:223], v[64:67], v[16:31]
	v_exp_f32_e32 v62, v62
	v_exp_f32_e32 v63, v63
	v_add_f32_e32 v234, v234, v60
	v_add_f32_e32 v235, v235, v61
	v_cvt_pk_bf16_f32 v70, v60, v61
	v_and_b32_e32 v70, v237, v70
	v_add_f32_e32 v234, v234, v62
	v_add_f32_e32 v235, v235, v63
	v_cvt_pk_bf16_f32 v71, v62, v63
	v_and_b32_e32 v71, v237, v71
	s_nop 1
	s_waitcnt lgkmcnt(1)
	v_mfma_f32_32x32x16_bf16 v[0:15], v[224:227], v[68:71], v[0:15]
	s_waitcnt lgkmcnt(0)
	v_mfma_f32_32x32x16_bf16 v[16:31], v[228:231], v[68:71], v[16:31]
	v_add_f32_e32 v232, v232, v233
	v_add_f32_e32 v234, v234, v235
	v_and_b32_e32 v239, 1.0, v236
	v_and_b32_e32 v240, 1.0, v237
	v_fmac_f32_e32 v112, v232, v239
	v_fmac_f32_e32 v112, v234, v240
	s_branch .Lt2_join
